# attention: diagonal (masked / single sub-step) tiles also take a hand-scheduled body, so no wave runs the compiler's latency-exposed tile body any more
# baseline (speedup 1.0000x reference)
.LBB0_845:
	s_cmp_ge_u32 s42, s82
	s_cselect_b64 s[18:19], -1, 0
	v_mov_b32_e32 v203, v176
	s_and_b64 vcc, exec, s[18:19]
	s_cbranch_vccnz .LBB0_847
	s_cmp_le_i32 s43, s84
	s_cbranch_scc1 .LBB0_847
	v_sub_co_u32_e64 v128, s[34:35], s88, 1
	s_nop 1
	v_cndmask_b32_e64 v130, v128, 2, s[34:35]
	v_lshlrev_b32_e32 v128, 14, v130
	v_add_u32_e32 v131, s85, v128
	v_lshl_add_u64 v[128:129], s[14:15], 0, v[178:179]
	s_add_u32 s34, s14, 0x1000
	v_readfirstlane_b32 s89, v131
	s_mov_b32 s90, m0
	s_mov_b32 m0, s89
	s_nop 0
	global_load_lds_dwordx4 v[128:129], off
	s_mov_b32 m0, s90
	v_lshl_add_u64 v[128:129], s[14:15], 0, v[180:181]
	s_addc_u32 s35, s15, 0
	s_addk_i32 s89, 0x400
	s_mov_b32 s90, m0
	s_mov_b32 m0, s89
	s_nop 0
	global_load_lds_dwordx4 v[128:129], off
	s_mov_b32 m0, s90
	v_lshlrev_b32_e32 v128, 15, v130
	v_add_u32_e32 v130, s86, v128
	v_lshl_add_u64 v[128:129], s[34:35], 0, v[182:183]
	v_readfirstlane_b32 s89, v130
	s_mov_b32 s90, m0
	s_mov_b32 m0, s89
	s_nop 0
	global_load_lds_dwordx4 v[128:129], off
	s_mov_b32 m0, s90
	v_lshl_add_u64 v[128:129], s[34:35], 0, v[184:185]
	s_add_i32 s90, s89, 0x400
	s_mov_b32 s91, m0
	s_mov_b32 m0, s90
	s_nop 0
	global_load_lds_dwordx4 v[128:129], off
	s_mov_b32 m0, s91
	v_lshl_add_u64 v[128:129], s[34:35], 0, v[186:187]
	s_add_i32 s90, s89, 0x800
	s_mov_b32 s91, m0
	s_mov_b32 m0, s90
	s_nop 0
	global_load_lds_dwordx4 v[128:129], off
	s_mov_b32 m0, s91
	v_lshl_add_u64 v[128:129], s[34:35], 0, v[188:189]
	s_add_i32 s34, s89, 0xc00
	s_mov_b32 s35, m0
	s_mov_b32 m0, s34
	s_nop 0
	global_load_lds_dwordx4 v[128:129], off
	s_mov_b32 m0, s35
.LBB0_847:
	s_cmp_gt_i32 s43, s84
	s_cbranch_scc1 .LBB0_858
	s_add_i32 s100, s43, 63
	s_cmp_le_i32 s100, s83
	s_cbranch_scc1 .Latt_full_0
	s_add_i32 s100, s43, 32
	s_cmp_le_i32 s100, s84
	s_cbranch_scc1 .Latt_diagA_0
	s_lshl_b32 s98, s88, 14
	s_lshl_b32 s99, s88, 15
	s_add_i32 s99, s99, 0xc000
	v_add_u32_e32 v206, s98, v194
	ds_read_b128 v[206:209], v206
	v_add_u32_e32 v210, s98, v195
	ds_read_b128 v[210:213], v210
	v_add_u32_e32 v214, s98, v196
	ds_read_b128 v[214:217], v214
	v_add_u32_e32 v238, s98, v197
	ds_read_b128 v[238:241], v238
	v_add_u32_e32 v242, s98, v198
	ds_read_b128 v[242:245], v242
	v_add_u32_e32 v250, s98, v199
	ds_read_b128 v[250:253], v250
	v_add_u32_e32 v222, s98, v200
	ds_read_b128 v[222:225], v222
	v_add_u32_e32 v226, s98, v201
	ds_read_b128 v[226:229], v226
	v_bfe_u32 v246, v203, 2, 2
	v_bfe_u32 v247, v203, 5, 1
	v_lshl_or_b32 v247, v247, 2, v246
	v_and_b32_e32 v249, 3, v203
	v_and_b32_e32 v254, 16, v203
	v_lshl_or_b32 v249, v249, 2, v254
	v_lshlrev_b32_e32 v249, 1, v249
	v_lshl_add_u32 v247, v247, 9, v249
	v_add_u32_e32 v247, s99, v247
	v_lshlrev_b32_e32 v246, 6, v246
	v_add_u32_e32 v205, v247, v246
	v_xor_b32_e32 v249, 64, v246
	v_add_u32_e32 v218, v247, v249
	v_xor_b32_e32 v249, 0x80, v246
	v_add_u32_e32 v219, v247, v249
	v_xor_b32_e32 v249, 0xc0, v246
	v_add_u32_e32 v221, v247, v249
	s_waitcnt lgkmcnt(7)
	v_mfma_f32_32x32x16_bf16 v[128:143], v[206:209], v[144:147], 0
	ds_read_b64_tr_b16 v[206:207], v205
	ds_read_b64_tr_b16 v[208:209], v205 offset:4096
	s_waitcnt lgkmcnt(8)
	v_mfma_f32_32x32x16_bf16 v[128:143], v[210:213], v[148:151], v[128:143]
	ds_read_b64_tr_b16 v[210:211], v218
	ds_read_b64_tr_b16 v[212:213], v218 offset:4096
	s_waitcnt lgkmcnt(9)
	v_mfma_f32_32x32x16_bf16 v[128:143], v[214:217], v[152:155], v[128:143]
	s_waitcnt lgkmcnt(8)
	v_mfma_f32_32x32x16_bf16 v[128:143], v[238:241], v[156:159], v[128:143]
	ds_read_b64_tr_b16 v[214:215], v219
	ds_read_b64_tr_b16 v[216:217], v219 offset:4096
	s_waitcnt lgkmcnt(9)
	v_mfma_f32_32x32x16_bf16 v[128:143], v[242:245], v[160:163], v[128:143]
	s_waitcnt lgkmcnt(8)
	v_mfma_f32_32x32x16_bf16 v[128:143], v[250:253], v[164:167], v[128:143]
	ds_read_b64_tr_b16 v[238:239], v221
	ds_read_b64_tr_b16 v[240:241], v221 offset:4096
	s_waitcnt lgkmcnt(9)
	v_mfma_f32_32x32x16_bf16 v[128:143], v[222:225], v[168:171], v[128:143]
	s_waitcnt lgkmcnt(8)
	v_mfma_f32_32x32x16_bf16 v[128:143], v[226:229], v[172:175], v[128:143]
	s_nop 11
	v_and_or_b32 v246, v203, 31, s83
	v_bfe_u32 v247, v203, 5, 1
	s_add_i32 s100, s43, 0
	v_lshl_add_u32 v247, v247, 2, s100
	v_add_u32_e32 v249, 0, v247
	v_cmp_le_i32_e32 vcc, v249, v246
	v_add_u32_e32 v254, 1, v247
	s_nop 0
	v_cndmask_b32_e32 v128, v192, v128, vcc
	v_cmp_le_i32_e32 vcc, v254, v246
	v_add_u32_e32 v249, 2, v247
	s_nop 0
	v_cndmask_b32_e32 v129, v192, v129, vcc
	v_cmp_le_i32_e32 vcc, v249, v246
	v_add_u32_e32 v254, 3, v247
	s_nop 0
	v_cndmask_b32_e32 v130, v192, v130, vcc
	v_cmp_le_i32_e32 vcc, v254, v246
	v_add_u32_e32 v249, 8, v247
	s_nop 0
	v_cndmask_b32_e32 v131, v192, v131, vcc
	v_cmp_le_i32_e32 vcc, v249, v246
	v_add_u32_e32 v254, 9, v247
	s_nop 0
	v_cndmask_b32_e32 v132, v192, v132, vcc
	v_cmp_le_i32_e32 vcc, v254, v246
	v_add_u32_e32 v249, 10, v247
	s_nop 0
	v_cndmask_b32_e32 v133, v192, v133, vcc
	v_cmp_le_i32_e32 vcc, v249, v246
	v_add_u32_e32 v254, 11, v247
	s_nop 0
	v_cndmask_b32_e32 v134, v192, v134, vcc
	v_cmp_le_i32_e32 vcc, v254, v246
	v_add_u32_e32 v249, 16, v247
	s_nop 0
	v_cndmask_b32_e32 v135, v192, v135, vcc
	v_cmp_le_i32_e32 vcc, v249, v246
	v_add_u32_e32 v254, 17, v247
	s_nop 0
	v_cndmask_b32_e32 v136, v192, v136, vcc
	v_cmp_le_i32_e32 vcc, v254, v246
	v_add_u32_e32 v249, 18, v247
	s_nop 0
	v_cndmask_b32_e32 v137, v192, v137, vcc
	v_cmp_le_i32_e32 vcc, v249, v246
	v_add_u32_e32 v254, 19, v247
	s_nop 0
	v_cndmask_b32_e32 v138, v192, v138, vcc
	v_cmp_le_i32_e32 vcc, v254, v246
	v_add_u32_e32 v249, 24, v247
	s_nop 0
	v_cndmask_b32_e32 v139, v192, v139, vcc
	v_cmp_le_i32_e32 vcc, v249, v246
	v_add_u32_e32 v254, 25, v247
	s_nop 0
	v_cndmask_b32_e32 v140, v192, v140, vcc
	v_cmp_le_i32_e32 vcc, v254, v246
	v_add_u32_e32 v249, 26, v247
	s_nop 0
	v_cndmask_b32_e32 v141, v192, v141, vcc
	v_cmp_le_i32_e32 vcc, v249, v246
	v_add_u32_e32 v254, 27, v247
	s_nop 0
	v_cndmask_b32_e32 v142, v192, v142, vcc
	v_cmp_le_i32_e32 vcc, v254, v246
	s_nop 1
	v_cndmask_b32_e32 v143, v192, v143, vcc
	v_max3_f32 v246, v128, v129, v130
	v_max3_f32 v247, v131, v132, v133
	v_max3_f32 v246, v246, v134, v135
	v_max3_f32 v247, v247, v136, v137
	v_max3_f32 v246, v246, v138, v139
	v_max3_f32 v247, v247, v140, v141
	v_max3_f32 v246, v246, v142, v143
	v_max_f32_e32 v246, v246, v247
	v_mov_b32_e32 v247, v246
	v_add_f32_e32 v249, 0x41000000, v190
	s_nop 1
	v_permlane32_swap_b32_e32 v246, v247
	v_max_f32_e32 v246, v246, v247
	v_cmp_gt_f32_e32 vcc, v246, v249
	s_cbranch_vccz .Latt_nr0_0B
	v_max_f32_e32 v246, v190, v246
	v_sub_f32_e32 v190, v190, v246
	v_exp_f32_e32 v190, v190
	s_nop 0
	v_pk_mul_f32 v[126:127], v[126:127], v[190:191] op_sel_hi:[1,0]
	v_pk_mul_f32 v[124:125], v[124:125], v[190:191] op_sel_hi:[1,0]
	v_pk_mul_f32 v[122:123], v[122:123], v[190:191] op_sel_hi:[1,0]
	v_pk_mul_f32 v[120:121], v[120:121], v[190:191] op_sel_hi:[1,0]
	v_pk_mul_f32 v[118:119], v[118:119], v[190:191] op_sel_hi:[1,0]
	v_pk_mul_f32 v[116:117], v[116:117], v[190:191] op_sel_hi:[1,0]
	v_pk_mul_f32 v[114:115], v[114:115], v[190:191] op_sel_hi:[1,0]
	v_pk_mul_f32 v[112:113], v[112:113], v[190:191] op_sel_hi:[1,0]
	v_pk_mul_f32 v[110:111], v[110:111], v[190:191] op_sel_hi:[1,0]
	v_pk_mul_f32 v[108:109], v[108:109], v[190:191] op_sel_hi:[1,0]
	v_pk_mul_f32 v[106:107], v[106:107], v[190:191] op_sel_hi:[1,0]
	v_pk_mul_f32 v[104:105], v[104:105], v[190:191] op_sel_hi:[1,0]
	v_pk_mul_f32 v[102:103], v[102:103], v[190:191] op_sel_hi:[1,0]
	v_pk_mul_f32 v[100:101], v[100:101], v[190:191] op_sel_hi:[1,0]
	v_pk_mul_f32 v[98:99], v[98:99], v[190:191] op_sel_hi:[1,0]
	v_pk_mul_f32 v[96:97], v[96:97], v[190:191] op_sel_hi:[1,0]
	v_pk_mul_f32 v[94:95], v[94:95], v[190:191] op_sel_hi:[1,0]
	v_pk_mul_f32 v[92:93], v[92:93], v[190:191] op_sel_hi:[1,0]
	v_pk_mul_f32 v[90:91], v[90:91], v[190:191] op_sel_hi:[1,0]
	v_pk_mul_f32 v[88:89], v[88:89], v[190:191] op_sel_hi:[1,0]
	v_pk_mul_f32 v[86:87], v[86:87], v[190:191] op_sel_hi:[1,0]
	v_pk_mul_f32 v[84:85], v[84:85], v[190:191] op_sel_hi:[1,0]
	v_pk_mul_f32 v[82:83], v[82:83], v[190:191] op_sel_hi:[1,0]
	v_pk_mul_f32 v[80:81], v[80:81], v[190:191] op_sel_hi:[1,0]
	v_pk_mul_f32 v[78:79], v[78:79], v[190:191] op_sel_hi:[1,0]
	v_pk_mul_f32 v[76:77], v[76:77], v[190:191] op_sel_hi:[1,0]
	v_pk_mul_f32 v[74:75], v[74:75], v[190:191] op_sel_hi:[1,0]
	v_pk_mul_f32 v[72:73], v[72:73], v[190:191] op_sel_hi:[1,0]
	v_pk_mul_f32 v[70:71], v[70:71], v[190:191] op_sel_hi:[1,0]
	v_pk_mul_f32 v[68:69], v[68:69], v[190:191] op_sel_hi:[1,0]
	v_pk_mul_f32 v[66:67], v[66:67], v[190:191] op_sel_hi:[1,0]
	v_pk_mul_f32 v[64:65], v[64:65], v[190:191] op_sel_hi:[1,0]
	v_pk_mul_f32 v[62:63], v[62:63], v[190:191] op_sel_hi:[1,0]
	v_pk_mul_f32 v[60:61], v[60:61], v[190:191] op_sel_hi:[1,0]
	v_pk_mul_f32 v[58:59], v[58:59], v[190:191] op_sel_hi:[1,0]
	v_pk_mul_f32 v[56:57], v[56:57], v[190:191] op_sel_hi:[1,0]
	v_pk_mul_f32 v[54:55], v[54:55], v[190:191] op_sel_hi:[1,0]
	v_pk_mul_f32 v[52:53], v[52:53], v[190:191] op_sel_hi:[1,0]
	v_pk_mul_f32 v[50:51], v[50:51], v[190:191] op_sel_hi:[1,0]
	v_pk_mul_f32 v[48:49], v[48:49], v[190:191] op_sel_hi:[1,0]
	v_pk_mul_f32 v[46:47], v[46:47], v[190:191] op_sel_hi:[1,0]
	v_pk_mul_f32 v[44:45], v[44:45], v[190:191] op_sel_hi:[1,0]
	v_pk_mul_f32 v[42:43], v[42:43], v[190:191] op_sel_hi:[1,0]
	v_pk_mul_f32 v[40:41], v[40:41], v[190:191] op_sel_hi:[1,0]
	v_pk_mul_f32 v[38:39], v[38:39], v[190:191] op_sel_hi:[1,0]
	v_pk_mul_f32 v[36:37], v[36:37], v[190:191] op_sel_hi:[1,0]
	v_pk_mul_f32 v[34:35], v[34:35], v[190:191] op_sel_hi:[1,0]
	v_pk_mul_f32 v[32:33], v[32:33], v[190:191] op_sel_hi:[1,0]
	v_pk_mul_f32 v[30:31], v[30:31], v[190:191] op_sel_hi:[1,0]
	v_pk_mul_f32 v[28:29], v[28:29], v[190:191] op_sel_hi:[1,0]
	v_pk_mul_f32 v[26:27], v[26:27], v[190:191] op_sel_hi:[1,0]
	v_pk_mul_f32 v[24:25], v[24:25], v[190:191] op_sel_hi:[1,0]
	v_pk_mul_f32 v[22:23], v[22:23], v[190:191] op_sel_hi:[1,0]
	v_pk_mul_f32 v[20:21], v[20:21], v[190:191] op_sel_hi:[1,0]
	v_pk_mul_f32 v[18:19], v[18:19], v[190:191] op_sel_hi:[1,0]
	v_pk_mul_f32 v[16:17], v[16:17], v[190:191] op_sel_hi:[1,0]
	v_pk_mul_f32 v[14:15], v[14:15], v[190:191] op_sel_hi:[1,0]
	v_pk_mul_f32 v[12:13], v[12:13], v[190:191] op_sel_hi:[1,0]
	v_pk_mul_f32 v[10:11], v[10:11], v[190:191] op_sel_hi:[1,0]
	v_pk_mul_f32 v[8:9], v[8:9], v[190:191] op_sel_hi:[1,0]
	v_pk_mul_f32 v[6:7], v[6:7], v[190:191] op_sel_hi:[1,0]
	v_pk_mul_f32 v[4:5], v[4:5], v[190:191] op_sel_hi:[1,0]
	v_pk_mul_f32 v[2:3], v[2:3], v[190:191] op_sel_hi:[1,0]
	v_pk_mul_f32 v[0:1], v[0:1], v[190:191] op_sel_hi:[1,0]
	v_mul_f32_e32 v202, v202, v190
	v_mov_b32_e32 v190, v246
.Latt_nr0_0B:
	v_sub_f32_e32 v128, v128, v190
	v_exp_f32_e32 v128, v128
	v_sub_f32_e32 v129, v129, v190
	v_exp_f32_e32 v129, v129
	v_sub_f32_e32 v130, v130, v190
	v_add_f32_e32 v254, 0, v128
	v_exp_f32_e32 v130, v130
	v_sub_f32_e32 v131, v131, v190
	v_add_f32_e32 v254, v129, v254
	v_exp_f32_e32 v131, v131
	v_sub_f32_e32 v132, v132, v190
	v_add_f32_e32 v254, v130, v254
	v_exp_f32_e32 v132, v132
	v_sub_f32_e32 v133, v133, v190
	v_add_f32_e32 v254, v131, v254
	v_exp_f32_e32 v133, v133
	v_sub_f32_e32 v134, v134, v190
	v_add_f32_e32 v254, v132, v254
	v_exp_f32_e32 v134, v134
	v_sub_f32_e32 v135, v135, v190
	v_add_f32_e32 v254, v133, v254
	v_exp_f32_e32 v135, v135
	v_sub_f32_e32 v136, v136, v190
	v_add_f32_e32 v254, v134, v254
	v_exp_f32_e32 v136, v136
	v_sub_f32_e32 v137, v137, v190
	v_add_f32_e32 v254, v135, v254
	v_exp_f32_e32 v137, v137
	v_sub_f32_e32 v138, v138, v190
	v_add_f32_e32 v254, v136, v254
	v_exp_f32_e32 v138, v138
	v_sub_f32_e32 v139, v139, v190
	v_add_f32_e32 v254, v137, v254
	v_exp_f32_e32 v139, v139
	v_sub_f32_e32 v140, v140, v190
	v_add_f32_e32 v254, v138, v254
	v_exp_f32_e32 v140, v140
	v_sub_f32_e32 v141, v141, v190
	v_add_f32_e32 v254, v139, v254
	v_exp_f32_e32 v141, v141
	v_sub_f32_e32 v142, v142, v190
	v_add_f32_e32 v254, v140, v254
	v_exp_f32_e32 v142, v142
	v_sub_f32_e32 v143, v143, v190
	v_add_f32_e32 v254, v141, v254
	v_exp_f32_e32 v143, v143
	v_add_f32_e32 v254, v142, v254
	v_add_f32_e32 v254, v143, v254
	v_cvt_pk_bf16_f32 v242, v128, v129
	v_cvt_pk_bf16_f32 v243, v130, v131
	v_cvt_pk_bf16_f32 v244, v132, v133
	v_cvt_pk_bf16_f32 v245, v134, v135
	v_cvt_pk_bf16_f32 v250, v136, v137
	v_cvt_pk_bf16_f32 v251, v138, v139
	v_cvt_pk_bf16_f32 v252, v140, v141
	v_cvt_pk_bf16_f32 v253, v142, v143
	v_add_f32_e32 v202, v202, v254
	s_nop 1
	ds_read_b64_tr_b16 v[128:129], v205 offset:256
	ds_read_b64_tr_b16 v[130:131], v205 offset:4352
	s_waitcnt lgkmcnt(8)
	v_mfma_f32_32x32x16_bf16 v[112:127], v[206:209], v[242:245], v[112:127]
	ds_read_b64_tr_b16 v[206:207], v218 offset:256
	ds_read_b64_tr_b16 v[208:209], v218 offset:4352
	s_waitcnt lgkmcnt(8)
	v_mfma_f32_32x32x16_bf16 v[96:111], v[210:213], v[242:245], v[96:111]
	ds_read_b64_tr_b16 v[210:211], v219 offset:256
	ds_read_b64_tr_b16 v[212:213], v219 offset:4352
	s_cmp_lg_u64 s[18:19], 0
	s_cbranch_scc1 .Latt_nd0_0B
	s_sub_i32 s100, s88, 1
	s_cmp_eq_u32 s88, 0
	s_cselect_b32 s100, 2, s100
	s_lshl_b32 s101, s100, 14
	s_add_i32 m0, s85, s101
	s_nop 0
	global_load_lds_dwordx4 v178, s[14:15]
.Latt_nd0_0B:
	s_waitcnt lgkmcnt(8)
	v_mfma_f32_32x32x16_bf16 v[80:95], v[214:217], v[242:245], v[80:95]
	ds_read_b64_tr_b16 v[214:215], v221 offset:256
	ds_read_b64_tr_b16 v[216:217], v221 offset:4352
	s_waitcnt lgkmcnt(8)
	v_mfma_f32_32x32x16_bf16 v[64:79], v[238:241], v[242:245], v[64:79]
	ds_read_b64_tr_b16 v[238:239], v205 offset:8192
	ds_read_b64_tr_b16 v[240:241], v205 offset:12288
	s_cmp_lg_u64 s[18:19], 0
	s_cbranch_scc1 .Latt_nd1_0B
	s_add_i32 m0, m0, 0x400
	s_nop 0
	global_load_lds_dwordx4 v180, s[14:15]
.Latt_nd1_0B:
	s_waitcnt lgkmcnt(8)
	v_mfma_f32_32x32x16_bf16 v[48:63], v[128:131], v[242:245], v[48:63]
	ds_read_b64_tr_b16 v[128:129], v218 offset:8192
	ds_read_b64_tr_b16 v[130:131], v218 offset:12288
	s_waitcnt lgkmcnt(8)
	v_mfma_f32_32x32x16_bf16 v[32:47], v[206:209], v[242:245], v[32:47]
	ds_read_b64_tr_b16 v[206:207], v219 offset:8192
	ds_read_b64_tr_b16 v[208:209], v219 offset:12288
	s_cmp_lg_u64 s[18:19], 0
	s_cbranch_scc1 .Latt_nd2_0B
	s_lshl_b32 s101, s100, 15
	s_add_i32 m0, s86, s101
	s_add_u32 s100, s14, 0x1000
	s_addc_u32 s101, s15, 0
	global_load_lds_dwordx4 v182, s[100:101]
.Latt_nd2_0B:
	s_waitcnt lgkmcnt(8)
	v_mfma_f32_32x32x16_bf16 v[16:31], v[210:213], v[242:245], v[16:31]
	ds_read_b64_tr_b16 v[210:211], v221 offset:8192
	ds_read_b64_tr_b16 v[212:213], v221 offset:12288
	s_waitcnt lgkmcnt(8)
	v_mfma_f32_32x32x16_bf16 v[0:15], v[214:217], v[242:245], v[0:15]
	ds_read_b64_tr_b16 v[214:215], v205 offset:8448
	ds_read_b64_tr_b16 v[216:217], v205 offset:12544
	s_cmp_lg_u64 s[18:19], 0
	s_cbranch_scc1 .Latt_nd3_0B
	s_add_i32 m0, m0, 0x400
	s_nop 0
	global_load_lds_dwordx4 v184, s[100:101]
.Latt_nd3_0B:
	s_waitcnt lgkmcnt(8)
	v_mfma_f32_32x32x16_bf16 v[112:127], v[238:241], v[250:253], v[112:127]
	ds_read_b64_tr_b16 v[238:239], v218 offset:8448
	ds_read_b64_tr_b16 v[240:241], v218 offset:12544
	s_waitcnt lgkmcnt(8)
	v_mfma_f32_32x32x16_bf16 v[96:111], v[128:131], v[250:253], v[96:111]
	ds_read_b64_tr_b16 v[128:129], v219 offset:8448
	ds_read_b64_tr_b16 v[130:131], v219 offset:12544
	s_cmp_lg_u64 s[18:19], 0
	s_cbranch_scc1 .Latt_nd4_0B
	s_add_i32 m0, m0, 0x400
	s_nop 0
	global_load_lds_dwordx4 v186, s[100:101]
.Latt_nd4_0B:
	s_waitcnt lgkmcnt(8)
	v_mfma_f32_32x32x16_bf16 v[80:95], v[206:209], v[250:253], v[80:95]
	ds_read_b64_tr_b16 v[206:207], v221 offset:8448
	ds_read_b64_tr_b16 v[208:209], v221 offset:12544
	s_waitcnt lgkmcnt(8)
	v_mfma_f32_32x32x16_bf16 v[64:79], v[210:213], v[250:253], v[64:79]
	s_cmp_lg_u64 s[18:19], 0
	s_cbranch_scc1 .Latt_nd5_0B
	s_add_i32 m0, m0, 0x400
	s_nop 0
	global_load_lds_dwordx4 v188, s[100:101]
.Latt_nd5_0B:
	s_waitcnt lgkmcnt(6)
	v_mfma_f32_32x32x16_bf16 v[48:63], v[214:217], v[250:253], v[48:63]
	s_waitcnt lgkmcnt(4)
	v_mfma_f32_32x32x16_bf16 v[32:47], v[238:241], v[250:253], v[32:47]
	s_waitcnt lgkmcnt(2)
	v_mfma_f32_32x32x16_bf16 v[16:31], v[128:131], v[250:253], v[16:31]
	s_waitcnt lgkmcnt(0)
	v_mfma_f32_32x32x16_bf16 v[0:15], v[206:209], v[250:253], v[0:15]
	s_branch .LBB0_858
.Latt_diagA_0:
	s_lshl_b32 s98, s88, 14
	s_lshl_b32 s99, s88, 15
	s_add_i32 s99, s99, 0xc000
	v_add_u32_e32 v206, s98, v194
	ds_read_b128 v[206:209], v206
	v_add_u32_e32 v210, s98, v195
	ds_read_b128 v[210:213], v210
	v_add_u32_e32 v214, s98, v196
	ds_read_b128 v[214:217], v214
	v_add_u32_e32 v238, s98, v197
	ds_read_b128 v[238:241], v238
	v_add_u32_e32 v242, s98, v198
	ds_read_b128 v[242:245], v242
	v_add_u32_e32 v250, s98, v199
	ds_read_b128 v[250:253], v250
	v_add_u32_e32 v222, s98, v200
	ds_read_b128 v[222:225], v222
	v_add_u32_e32 v226, s98, v201
	ds_read_b128 v[226:229], v226
	v_bfe_u32 v246, v203, 2, 2
	v_bfe_u32 v247, v203, 5, 1
	v_lshl_or_b32 v247, v247, 2, v246
	v_and_b32_e32 v249, 3, v203
	v_and_b32_e32 v254, 16, v203
	v_lshl_or_b32 v249, v249, 2, v254
	v_lshlrev_b32_e32 v249, 1, v249
	v_lshl_add_u32 v247, v247, 9, v249
	v_add_u32_e32 v247, s99, v247
	v_lshlrev_b32_e32 v246, 6, v246
	v_add_u32_e32 v205, v247, v246
	v_xor_b32_e32 v249, 64, v246
	v_add_u32_e32 v218, v247, v249
	v_xor_b32_e32 v249, 0x80, v246
	v_add_u32_e32 v219, v247, v249
	v_xor_b32_e32 v249, 0xc0, v246
	v_add_u32_e32 v221, v247, v249
	s_waitcnt lgkmcnt(7)
	v_mfma_f32_32x32x16_bf16 v[128:143], v[206:209], v[144:147], 0
	v_add_u32_e32 v206, s98, v194
	ds_read_b128 v[206:209], v206 offset:8192
	s_waitcnt lgkmcnt(7)
	v_mfma_f32_32x32x16_bf16 v[128:143], v[210:213], v[148:151], v[128:143]
	v_add_u32_e32 v210, s98, v195
	ds_read_b128 v[210:213], v210 offset:8192
	s_waitcnt lgkmcnt(7)
	v_mfma_f32_32x32x16_bf16 v[128:143], v[214:217], v[152:155], v[128:143]
	v_add_u32_e32 v214, s98, v196
	ds_read_b128 v[214:217], v214 offset:8192
	s_waitcnt lgkmcnt(7)
	v_mfma_f32_32x32x16_bf16 v[128:143], v[238:241], v[156:159], v[128:143]
	v_add_u32_e32 v238, s98, v197
	ds_read_b128 v[238:241], v238 offset:8192
	s_waitcnt lgkmcnt(7)
	v_mfma_f32_32x32x16_bf16 v[128:143], v[242:245], v[160:163], v[128:143]
	v_add_u32_e32 v242, s98, v198
	ds_read_b128 v[242:245], v242 offset:8192
	s_waitcnt lgkmcnt(7)
	v_mfma_f32_32x32x16_bf16 v[128:143], v[250:253], v[164:167], v[128:143]
	v_add_u32_e32 v250, s98, v199
	ds_read_b128 v[250:253], v250 offset:8192
	s_waitcnt lgkmcnt(7)
	v_mfma_f32_32x32x16_bf16 v[128:143], v[222:225], v[168:171], v[128:143]
	s_waitcnt lgkmcnt(6)
	v_mfma_f32_32x32x16_bf16 v[128:143], v[226:229], v[172:175], v[128:143]
	s_waitcnt lgkmcnt(5)
	v_mfma_f32_32x32x16_bf16 v[222:237], v[206:209], v[144:147], 0
	v_add_u32_e32 v206, s98, v200
	ds_read_b128 v[206:209], v206 offset:8192
	s_nop 7
	v_max3_f32 v246, v128, v129, v130
	v_max3_f32 v247, v131, v132, v133
	v_max3_f32 v246, v246, v134, v135
	v_max3_f32 v247, v247, v136, v137
	v_max3_f32 v246, v246, v138, v139
	v_max3_f32 v247, v247, v140, v141
	v_max3_f32 v246, v246, v142, v143
	s_waitcnt lgkmcnt(5)
	v_mfma_f32_32x32x16_bf16 v[222:237], v[210:213], v[148:151], v[222:237]
	v_add_u32_e32 v210, s98, v201
	ds_read_b128 v[210:213], v210 offset:8192
	v_max_f32_e32 v246, v246, v247
	v_mov_b32_e32 v247, v246
	v_add_f32_e32 v249, 0x41000000, v190
	s_nop 1
	v_permlane32_swap_b32_e32 v246, v247
	v_max_f32_e32 v246, v246, v247
	v_cmp_gt_f32_e32 vcc, v246, v249
	s_cbranch_vccz .Latt_nr0_0A
	v_max_f32_e32 v246, v190, v246
	v_sub_f32_e32 v190, v190, v246
	v_exp_f32_e32 v190, v190
	s_nop 0
	v_pk_mul_f32 v[126:127], v[126:127], v[190:191] op_sel_hi:[1,0]
	v_pk_mul_f32 v[124:125], v[124:125], v[190:191] op_sel_hi:[1,0]
	v_pk_mul_f32 v[122:123], v[122:123], v[190:191] op_sel_hi:[1,0]
	v_pk_mul_f32 v[120:121], v[120:121], v[190:191] op_sel_hi:[1,0]
	v_pk_mul_f32 v[118:119], v[118:119], v[190:191] op_sel_hi:[1,0]
	v_pk_mul_f32 v[116:117], v[116:117], v[190:191] op_sel_hi:[1,0]
	v_pk_mul_f32 v[114:115], v[114:115], v[190:191] op_sel_hi:[1,0]
	v_pk_mul_f32 v[112:113], v[112:113], v[190:191] op_sel_hi:[1,0]
	v_pk_mul_f32 v[110:111], v[110:111], v[190:191] op_sel_hi:[1,0]
	v_pk_mul_f32 v[108:109], v[108:109], v[190:191] op_sel_hi:[1,0]
	v_pk_mul_f32 v[106:107], v[106:107], v[190:191] op_sel_hi:[1,0]
	v_pk_mul_f32 v[104:105], v[104:105], v[190:191] op_sel_hi:[1,0]
	v_pk_mul_f32 v[102:103], v[102:103], v[190:191] op_sel_hi:[1,0]
	v_pk_mul_f32 v[100:101], v[100:101], v[190:191] op_sel_hi:[1,0]
	v_pk_mul_f32 v[98:99], v[98:99], v[190:191] op_sel_hi:[1,0]
	v_pk_mul_f32 v[96:97], v[96:97], v[190:191] op_sel_hi:[1,0]
	v_pk_mul_f32 v[94:95], v[94:95], v[190:191] op_sel_hi:[1,0]
	v_pk_mul_f32 v[92:93], v[92:93], v[190:191] op_sel_hi:[1,0]
	v_pk_mul_f32 v[90:91], v[90:91], v[190:191] op_sel_hi:[1,0]
	v_pk_mul_f32 v[88:89], v[88:89], v[190:191] op_sel_hi:[1,0]
	v_pk_mul_f32 v[86:87], v[86:87], v[190:191] op_sel_hi:[1,0]
	v_pk_mul_f32 v[84:85], v[84:85], v[190:191] op_sel_hi:[1,0]
	v_pk_mul_f32 v[82:83], v[82:83], v[190:191] op_sel_hi:[1,0]
	v_pk_mul_f32 v[80:81], v[80:81], v[190:191] op_sel_hi:[1,0]
	v_pk_mul_f32 v[78:79], v[78:79], v[190:191] op_sel_hi:[1,0]
	v_pk_mul_f32 v[76:77], v[76:77], v[190:191] op_sel_hi:[1,0]
	v_pk_mul_f32 v[74:75], v[74:75], v[190:191] op_sel_hi:[1,0]
	v_pk_mul_f32 v[72:73], v[72:73], v[190:191] op_sel_hi:[1,0]
	v_pk_mul_f32 v[70:71], v[70:71], v[190:191] op_sel_hi:[1,0]
	v_pk_mul_f32 v[68:69], v[68:69], v[190:191] op_sel_hi:[1,0]
	v_pk_mul_f32 v[66:67], v[66:67], v[190:191] op_sel_hi:[1,0]
	v_pk_mul_f32 v[64:65], v[64:65], v[190:191] op_sel_hi:[1,0]
	v_pk_mul_f32 v[62:63], v[62:63], v[190:191] op_sel_hi:[1,0]
	v_pk_mul_f32 v[60:61], v[60:61], v[190:191] op_sel_hi:[1,0]
	v_pk_mul_f32 v[58:59], v[58:59], v[190:191] op_sel_hi:[1,0]
	v_pk_mul_f32 v[56:57], v[56:57], v[190:191] op_sel_hi:[1,0]
	v_pk_mul_f32 v[54:55], v[54:55], v[190:191] op_sel_hi:[1,0]
	v_pk_mul_f32 v[52:53], v[52:53], v[190:191] op_sel_hi:[1,0]
	v_pk_mul_f32 v[50:51], v[50:51], v[190:191] op_sel_hi:[1,0]
	v_pk_mul_f32 v[48:49], v[48:49], v[190:191] op_sel_hi:[1,0]
	v_pk_mul_f32 v[46:47], v[46:47], v[190:191] op_sel_hi:[1,0]
	v_pk_mul_f32 v[44:45], v[44:45], v[190:191] op_sel_hi:[1,0]
	v_pk_mul_f32 v[42:43], v[42:43], v[190:191] op_sel_hi:[1,0]
	v_pk_mul_f32 v[40:41], v[40:41], v[190:191] op_sel_hi:[1,0]
	v_pk_mul_f32 v[38:39], v[38:39], v[190:191] op_sel_hi:[1,0]
	v_pk_mul_f32 v[36:37], v[36:37], v[190:191] op_sel_hi:[1,0]
	v_pk_mul_f32 v[34:35], v[34:35], v[190:191] op_sel_hi:[1,0]
	v_pk_mul_f32 v[32:33], v[32:33], v[190:191] op_sel_hi:[1,0]
	v_pk_mul_f32 v[30:31], v[30:31], v[190:191] op_sel_hi:[1,0]
	v_pk_mul_f32 v[28:29], v[28:29], v[190:191] op_sel_hi:[1,0]
	v_pk_mul_f32 v[26:27], v[26:27], v[190:191] op_sel_hi:[1,0]
	v_pk_mul_f32 v[24:25], v[24:25], v[190:191] op_sel_hi:[1,0]
	v_pk_mul_f32 v[22:23], v[22:23], v[190:191] op_sel_hi:[1,0]
	v_pk_mul_f32 v[20:21], v[20:21], v[190:191] op_sel_hi:[1,0]
	v_pk_mul_f32 v[18:19], v[18:19], v[190:191] op_sel_hi:[1,0]
	v_pk_mul_f32 v[16:17], v[16:17], v[190:191] op_sel_hi:[1,0]
	v_pk_mul_f32 v[14:15], v[14:15], v[190:191] op_sel_hi:[1,0]
	v_pk_mul_f32 v[12:13], v[12:13], v[190:191] op_sel_hi:[1,0]
	v_pk_mul_f32 v[10:11], v[10:11], v[190:191] op_sel_hi:[1,0]
	v_pk_mul_f32 v[8:9], v[8:9], v[190:191] op_sel_hi:[1,0]
	v_pk_mul_f32 v[6:7], v[6:7], v[190:191] op_sel_hi:[1,0]
	v_pk_mul_f32 v[4:5], v[4:5], v[190:191] op_sel_hi:[1,0]
	v_pk_mul_f32 v[2:3], v[2:3], v[190:191] op_sel_hi:[1,0]
	v_pk_mul_f32 v[0:1], v[0:1], v[190:191] op_sel_hi:[1,0]
	v_mul_f32_e32 v202, v202, v190
	v_mov_b32_e32 v190, v246
.Latt_nr0_0A:
	s_waitcnt lgkmcnt(5)
	v_mfma_f32_32x32x16_bf16 v[222:237], v[214:217], v[152:155], v[222:237]
	ds_read_b64_tr_b16 v[214:215], v205
	ds_read_b64_tr_b16 v[216:217], v205 offset:4096
	v_sub_f32_e32 v128, v128, v190
	v_exp_f32_e32 v128, v128
	v_sub_f32_e32 v129, v129, v190
	v_exp_f32_e32 v129, v129
	v_sub_f32_e32 v130, v130, v190
	v_add_f32_e32 v254, 0, v128
	v_exp_f32_e32 v130, v130
	v_sub_f32_e32 v131, v131, v190
	s_waitcnt lgkmcnt(6)
	v_mfma_f32_32x32x16_bf16 v[222:237], v[238:241], v[156:159], v[222:237]
	ds_read_b64_tr_b16 v[238:239], v218
	ds_read_b64_tr_b16 v[240:241], v218 offset:4096
	v_add_f32_e32 v254, v129, v254
	v_exp_f32_e32 v131, v131
	v_sub_f32_e32 v132, v132, v190
	v_add_f32_e32 v254, v130, v254
	v_exp_f32_e32 v132, v132
	v_sub_f32_e32 v133, v133, v190
	v_add_f32_e32 v254, v131, v254
	v_exp_f32_e32 v133, v133
	s_waitcnt lgkmcnt(7)
	v_mfma_f32_32x32x16_bf16 v[222:237], v[242:245], v[160:163], v[222:237]
	v_sub_f32_e32 v134, v134, v190
	v_add_f32_e32 v254, v132, v254
	v_exp_f32_e32 v134, v134
	v_sub_f32_e32 v135, v135, v190
	v_add_f32_e32 v254, v133, v254
	v_exp_f32_e32 v135, v135
	v_sub_f32_e32 v136, v136, v190
	v_add_f32_e32 v254, v134, v254
	s_waitcnt lgkmcnt(6)
	v_mfma_f32_32x32x16_bf16 v[222:237], v[250:253], v[164:167], v[222:237]
	v_exp_f32_e32 v136, v136
	v_sub_f32_e32 v137, v137, v190
	v_add_f32_e32 v254, v135, v254
	v_exp_f32_e32 v137, v137
	v_sub_f32_e32 v138, v138, v190
	v_add_f32_e32 v254, v136, v254
	v_exp_f32_e32 v138, v138
	v_sub_f32_e32 v139, v139, v190
	s_waitcnt lgkmcnt(5)
	v_mfma_f32_32x32x16_bf16 v[222:237], v[206:209], v[168:171], v[222:237]
	ds_read_b64_tr_b16 v[206:207], v219
	ds_read_b64_tr_b16 v[208:209], v219 offset:4096
	v_add_f32_e32 v254, v137, v254
	v_exp_f32_e32 v139, v139
	v_sub_f32_e32 v140, v140, v190
	v_add_f32_e32 v254, v138, v254
	v_exp_f32_e32 v140, v140
	v_sub_f32_e32 v141, v141, v190
	v_add_f32_e32 v254, v139, v254
	v_exp_f32_e32 v141, v141
	s_waitcnt lgkmcnt(6)
	v_mfma_f32_32x32x16_bf16 v[222:237], v[210:213], v[172:175], v[222:237]
	ds_read_b64_tr_b16 v[210:211], v221
	ds_read_b64_tr_b16 v[212:213], v221 offset:4096
	v_sub_f32_e32 v142, v142, v190
	v_add_f32_e32 v254, v140, v254
	v_exp_f32_e32 v142, v142
	v_sub_f32_e32 v143, v143, v190
	v_add_f32_e32 v254, v141, v254
	v_exp_f32_e32 v143, v143
	v_add_f32_e32 v254, v142, v254
	v_add_f32_e32 v254, v143, v254
	v_cvt_pk_bf16_f32 v242, v128, v129
	v_cvt_pk_bf16_f32 v243, v130, v131
	v_cvt_pk_bf16_f32 v244, v132, v133
	v_cvt_pk_bf16_f32 v245, v134, v135
	v_cvt_pk_bf16_f32 v250, v136, v137
	v_cvt_pk_bf16_f32 v251, v138, v139
	v_cvt_pk_bf16_f32 v252, v140, v141
	v_cvt_pk_bf16_f32 v253, v142, v143
	v_add_f32_e32 v202, v202, v254
	s_nop 1
	ds_read_b64_tr_b16 v[128:129], v205 offset:256
	ds_read_b64_tr_b16 v[130:131], v205 offset:4352
	s_waitcnt lgkmcnt(8)
	v_mfma_f32_32x32x16_bf16 v[112:127], v[214:217], v[242:245], v[112:127]
	ds_read_b64_tr_b16 v[214:215], v218 offset:256
	ds_read_b64_tr_b16 v[216:217], v218 offset:4352
	v_and_or_b32 v246, v203, 31, s83
	v_bfe_u32 v247, v203, 5, 1
	s_add_i32 s100, s43, 32
	v_lshl_add_u32 v247, v247, 2, s100
	v_add_u32_e32 v249, 0, v247
	v_cmp_le_i32_e32 vcc, v249, v246
	v_add_u32_e32 v254, 1, v247
	s_nop 0
	v_cndmask_b32_e32 v222, v192, v222, vcc
	v_cmp_le_i32_e32 vcc, v254, v246
	v_add_u32_e32 v249, 2, v247
	s_nop 0
	v_cndmask_b32_e32 v223, v192, v223, vcc
	v_cmp_le_i32_e32 vcc, v249, v246
	v_add_u32_e32 v254, 3, v247
	s_nop 0
	v_cndmask_b32_e32 v224, v192, v224, vcc
	v_cmp_le_i32_e32 vcc, v254, v246
	v_add_u32_e32 v249, 8, v247
	s_nop 0
	v_cndmask_b32_e32 v225, v192, v225, vcc
	v_cmp_le_i32_e32 vcc, v249, v246
	v_add_u32_e32 v254, 9, v247
	s_nop 0
	v_cndmask_b32_e32 v226, v192, v226, vcc
	v_cmp_le_i32_e32 vcc, v254, v246
	v_add_u32_e32 v249, 10, v247
	s_nop 0
	v_cndmask_b32_e32 v227, v192, v227, vcc
	v_cmp_le_i32_e32 vcc, v249, v246
	v_add_u32_e32 v254, 11, v247
	s_nop 0
	v_cndmask_b32_e32 v228, v192, v228, vcc
	v_cmp_le_i32_e32 vcc, v254, v246
	s_waitcnt lgkmcnt(8)
	v_mfma_f32_32x32x16_bf16 v[96:111], v[238:241], v[242:245], v[96:111]
	ds_read_b64_tr_b16 v[238:239], v219 offset:256
	ds_read_b64_tr_b16 v[240:241], v219 offset:4352
	v_add_u32_e32 v249, 16, v247
	s_nop 0
	v_cndmask_b32_e32 v229, v192, v229, vcc
	v_cmp_le_i32_e32 vcc, v249, v246
	v_add_u32_e32 v254, 17, v247
	s_nop 0
	v_cndmask_b32_e32 v230, v192, v230, vcc
	v_cmp_le_i32_e32 vcc, v254, v246
	v_add_u32_e32 v249, 18, v247
	s_nop 0
	v_cndmask_b32_e32 v231, v192, v231, vcc
	v_cmp_le_i32_e32 vcc, v249, v246
	v_add_u32_e32 v254, 19, v247
	s_nop 0
	v_cndmask_b32_e32 v232, v192, v232, vcc
	v_cmp_le_i32_e32 vcc, v254, v246
	v_add_u32_e32 v249, 24, v247
	s_nop 0
	v_cndmask_b32_e32 v233, v192, v233, vcc
	v_cmp_le_i32_e32 vcc, v249, v246
	v_add_u32_e32 v254, 25, v247
	s_nop 0
	v_cndmask_b32_e32 v234, v192, v234, vcc
	v_cmp_le_i32_e32 vcc, v254, v246
	v_add_u32_e32 v249, 26, v247
	s_nop 0
	v_cndmask_b32_e32 v235, v192, v235, vcc
	v_cmp_le_i32_e32 vcc, v249, v246
	v_add_u32_e32 v254, 27, v247
	s_nop 0
	v_cndmask_b32_e32 v236, v192, v236, vcc
	v_cmp_le_i32_e32 vcc, v254, v246
	s_nop 1
	v_cndmask_b32_e32 v237, v192, v237, vcc
	s_waitcnt lgkmcnt(8)
	v_mfma_f32_32x32x16_bf16 v[80:95], v[206:209], v[242:245], v[80:95]
	ds_read_b64_tr_b16 v[206:207], v221 offset:256
	ds_read_b64_tr_b16 v[208:209], v221 offset:4352
	v_max3_f32 v246, v222, v223, v224
	v_max3_f32 v247, v225, v226, v227
	v_max3_f32 v246, v246, v228, v229
	v_max3_f32 v247, v247, v230, v231
	v_max3_f32 v246, v246, v232, v233
	v_max3_f32 v247, v247, v234, v235
	s_waitcnt lgkmcnt(8)
	v_mfma_f32_32x32x16_bf16 v[64:79], v[210:213], v[242:245], v[64:79]
	ds_read_b64_tr_b16 v[210:211], v205 offset:8192
	ds_read_b64_tr_b16 v[212:213], v205 offset:12288
	v_max3_f32 v246, v246, v236, v237
	v_max_f32_e32 v246, v246, v247
	v_mov_b32_e32 v247, v246
	v_add_f32_e32 v249, 0x41000000, v190
	s_nop 1
	s_waitcnt lgkmcnt(8)
	v_mfma_f32_32x32x16_bf16 v[48:63], v[128:131], v[242:245], v[48:63]
	ds_read_b64_tr_b16 v[128:129], v218 offset:8192
	ds_read_b64_tr_b16 v[130:131], v218 offset:12288
	v_permlane32_swap_b32_e32 v246, v247
	v_max_f32_e32 v246, v246, v247
	v_cmp_gt_f32_e32 vcc, v246, v249
	s_cbranch_vccnz .Latt_rs1_0A
	s_waitcnt lgkmcnt(8)
	v_mfma_f32_32x32x16_bf16 v[32:47], v[214:217], v[242:245], v[32:47]
	ds_read_b64_tr_b16 v[214:215], v219 offset:8192
	ds_read_b64_tr_b16 v[216:217], v219 offset:12288
	v_sub_f32_e32 v222, v222, v190
	v_exp_f32_e32 v222, v222
	v_sub_f32_e32 v223, v223, v190
	v_exp_f32_e32 v223, v223
	v_sub_f32_e32 v224, v224, v190
	s_waitcnt lgkmcnt(8)
	v_mfma_f32_32x32x16_bf16 v[16:31], v[238:241], v[242:245], v[16:31]
	ds_read_b64_tr_b16 v[238:239], v221 offset:8192
	ds_read_b64_tr_b16 v[240:241], v221 offset:12288
	v_add_f32_e32 v254, 0, v222
	v_exp_f32_e32 v224, v224
	v_sub_f32_e32 v225, v225, v190
	v_add_f32_e32 v254, v223, v254
	v_exp_f32_e32 v225, v225
	s_waitcnt lgkmcnt(8)
	v_mfma_f32_32x32x16_bf16 v[0:15], v[206:209], v[242:245], v[0:15]
	ds_read_b64_tr_b16 v[206:207], v205 offset:8448
	ds_read_b64_tr_b16 v[208:209], v205 offset:12544
	v_sub_f32_e32 v226, v226, v190
	v_add_f32_e32 v254, v224, v254
	v_exp_f32_e32 v226, v226
	v_sub_f32_e32 v227, v227, v190
	v_add_f32_e32 v254, v225, v254
	s_waitcnt lgkmcnt(8)
	v_mfma_f32_32x32x16_bf16 v[112:127], v[210:213], v[250:253], v[112:127]
	ds_read_b64_tr_b16 v[210:211], v218 offset:8448
	ds_read_b64_tr_b16 v[212:213], v218 offset:12544
	v_exp_f32_e32 v227, v227
	v_sub_f32_e32 v228, v228, v190
	v_add_f32_e32 v254, v226, v254
	v_exp_f32_e32 v228, v228
	v_sub_f32_e32 v229, v229, v190
	s_waitcnt lgkmcnt(8)
	v_mfma_f32_32x32x16_bf16 v[96:111], v[128:131], v[250:253], v[96:111]
	ds_read_b64_tr_b16 v[128:129], v219 offset:8448
	ds_read_b64_tr_b16 v[130:131], v219 offset:12544
	v_add_f32_e32 v254, v227, v254
	v_exp_f32_e32 v229, v229
	v_sub_f32_e32 v230, v230, v190
	v_add_f32_e32 v254, v228, v254
	s_waitcnt lgkmcnt(8)
	v_mfma_f32_32x32x16_bf16 v[80:95], v[214:217], v[250:253], v[80:95]
	ds_read_b64_tr_b16 v[214:215], v221 offset:8448
	ds_read_b64_tr_b16 v[216:217], v221 offset:12544
	v_exp_f32_e32 v230, v230
	v_sub_f32_e32 v231, v231, v190
	v_add_f32_e32 v254, v229, v254
	v_exp_f32_e32 v231, v231
	s_waitcnt lgkmcnt(8)
	v_mfma_f32_32x32x16_bf16 v[64:79], v[238:241], v[250:253], v[64:79]
	ds_read_b64_tr_b16 v[238:239], v205 offset:16384
	ds_read_b64_tr_b16 v[240:241], v205 offset:20480
	v_sub_f32_e32 v232, v232, v190
	v_add_f32_e32 v254, v230, v254
	v_exp_f32_e32 v232, v232
	v_sub_f32_e32 v233, v233, v190
	s_waitcnt lgkmcnt(8)
	v_mfma_f32_32x32x16_bf16 v[48:63], v[206:209], v[250:253], v[48:63]
	ds_read_b64_tr_b16 v[206:207], v218 offset:16384
	ds_read_b64_tr_b16 v[208:209], v218 offset:20480
	v_add_f32_e32 v254, v231, v254
	v_exp_f32_e32 v233, v233
	v_sub_f32_e32 v234, v234, v190
	v_add_f32_e32 v254, v232, v254
	s_waitcnt lgkmcnt(8)
	v_mfma_f32_32x32x16_bf16 v[32:47], v[210:213], v[250:253], v[32:47]
	ds_read_b64_tr_b16 v[210:211], v219 offset:16384
	ds_read_b64_tr_b16 v[212:213], v219 offset:20480
	v_exp_f32_e32 v234, v234
	v_sub_f32_e32 v235, v235, v190
	v_add_f32_e32 v254, v233, v254
	v_exp_f32_e32 v235, v235
	s_waitcnt lgkmcnt(8)
	v_mfma_f32_32x32x16_bf16 v[16:31], v[128:131], v[250:253], v[16:31]
	ds_read_b64_tr_b16 v[128:129], v221 offset:16384
	ds_read_b64_tr_b16 v[130:131], v221 offset:20480
	v_sub_f32_e32 v236, v236, v190
	v_add_f32_e32 v254, v234, v254
	v_exp_f32_e32 v236, v236
	v_sub_f32_e32 v237, v237, v190
	s_waitcnt lgkmcnt(8)
	v_mfma_f32_32x32x16_bf16 v[0:15], v[214:217], v[250:253], v[0:15]
	ds_read_b64_tr_b16 v[214:215], v205 offset:16640
	ds_read_b64_tr_b16 v[216:217], v205 offset:20736
	v_add_f32_e32 v254, v235, v254
	v_exp_f32_e32 v237, v237
	v_add_f32_e32 v254, v236, v254
	v_add_f32_e32 v254, v237, v254
	v_cvt_pk_bf16_f32 v242, v222, v223
	v_cvt_pk_bf16_f32 v243, v224, v225
	v_cvt_pk_bf16_f32 v244, v226, v227
	v_cvt_pk_bf16_f32 v245, v228, v229
	v_cvt_pk_bf16_f32 v250, v230, v231
	v_cvt_pk_bf16_f32 v251, v232, v233
	v_cvt_pk_bf16_f32 v252, v234, v235
	v_cvt_pk_bf16_f32 v253, v236, v237
	v_add_f32_e32 v202, v202, v254
	s_nop 1

.Latt_rs1_0F:
	s_waitcnt lgkmcnt(8)
	v_mfma_f32_32x32x16_bf16 v[32:47], v[214:217], v[242:245], v[32:47]
	ds_read_b64_tr_b16 v[214:215], v219 offset:8192
	ds_read_b64_tr_b16 v[216:217], v219 offset:12288
	s_waitcnt lgkmcnt(8)
	v_mfma_f32_32x32x16_bf16 v[16:31], v[238:241], v[242:245], v[16:31]
	ds_read_b64_tr_b16 v[238:239], v221 offset:8192
	ds_read_b64_tr_b16 v[240:241], v221 offset:12288
	s_waitcnt lgkmcnt(8)
	v_mfma_f32_32x32x16_bf16 v[0:15], v[206:209], v[242:245], v[0:15]
	ds_read_b64_tr_b16 v[206:207], v205 offset:8448
	ds_read_b64_tr_b16 v[208:209], v205 offset:12544
	s_waitcnt lgkmcnt(8)
	v_mfma_f32_32x32x16_bf16 v[112:127], v[210:213], v[250:253], v[112:127]
	ds_read_b64_tr_b16 v[210:211], v218 offset:8448
	ds_read_b64_tr_b16 v[212:213], v218 offset:12544
	s_waitcnt lgkmcnt(8)
	v_mfma_f32_32x32x16_bf16 v[96:111], v[128:131], v[250:253], v[96:111]
	ds_read_b64_tr_b16 v[128:129], v219 offset:8448
	ds_read_b64_tr_b16 v[130:131], v219 offset:12544
	s_waitcnt lgkmcnt(8)
	v_mfma_f32_32x32x16_bf16 v[80:95], v[214:217], v[250:253], v[80:95]
	ds_read_b64_tr_b16 v[214:215], v221 offset:8448
	ds_read_b64_tr_b16 v[216:217], v221 offset:12544
	s_waitcnt lgkmcnt(8)
	v_mfma_f32_32x32x16_bf16 v[64:79], v[238:241], v[250:253], v[64:79]
	ds_read_b64_tr_b16 v[238:239], v205 offset:16384
	ds_read_b64_tr_b16 v[240:241], v205 offset:20480
	s_waitcnt lgkmcnt(8)
	v_mfma_f32_32x32x16_bf16 v[48:63], v[206:209], v[250:253], v[48:63]
	ds_read_b64_tr_b16 v[206:207], v218 offset:16384
	ds_read_b64_tr_b16 v[208:209], v218 offset:20480
	s_waitcnt lgkmcnt(8)
	v_mfma_f32_32x32x16_bf16 v[32:47], v[210:213], v[250:253], v[32:47]
	ds_read_b64_tr_b16 v[210:211], v219 offset:16384
	ds_read_b64_tr_b16 v[212:213], v219 offset:20480
	s_waitcnt lgkmcnt(8)
	v_mfma_f32_32x32x16_bf16 v[16:31], v[128:131], v[250:253], v[16:31]
	ds_read_b64_tr_b16 v[128:129], v221 offset:16384
	ds_read_b64_tr_b16 v[130:131], v221 offset:20480
	s_waitcnt lgkmcnt(8)
	v_mfma_f32_32x32x16_bf16 v[0:15], v[214:217], v[250:253], v[0:15]
	ds_read_b64_tr_b16 v[214:215], v205 offset:16640
	ds_read_b64_tr_b16 v[216:217], v205 offset:20736
	s_nop 11
	v_max_f32_e32 v246, v190, v246
	v_sub_f32_e32 v190, v190, v246
	v_exp_f32_e32 v190, v190
	s_nop 0
	v_pk_mul_f32 v[126:127], v[126:127], v[190:191] op_sel_hi:[1,0]
	v_pk_mul_f32 v[124:125], v[124:125], v[190:191] op_sel_hi:[1,0]
	v_pk_mul_f32 v[122:123], v[122:123], v[190:191] op_sel_hi:[1,0]
	v_pk_mul_f32 v[120:121], v[120:121], v[190:191] op_sel_hi:[1,0]
	v_pk_mul_f32 v[118:119], v[118:119], v[190:191] op_sel_hi:[1,0]
	v_pk_mul_f32 v[116:117], v[116:117], v[190:191] op_sel_hi:[1,0]
	v_pk_mul_f32 v[114:115], v[114:115], v[190:191] op_sel_hi:[1,0]
	v_pk_mul_f32 v[112:113], v[112:113], v[190:191] op_sel_hi:[1,0]
	v_pk_mul_f32 v[110:111], v[110:111], v[190:191] op_sel_hi:[1,0]
	v_pk_mul_f32 v[108:109], v[108:109], v[190:191] op_sel_hi:[1,0]
	v_pk_mul_f32 v[106:107], v[106:107], v[190:191] op_sel_hi:[1,0]
	v_pk_mul_f32 v[104:105], v[104:105], v[190:191] op_sel_hi:[1,0]
	v_pk_mul_f32 v[102:103], v[102:103], v[190:191] op_sel_hi:[1,0]
	v_pk_mul_f32 v[100:101], v[100:101], v[190:191] op_sel_hi:[1,0]
	v_pk_mul_f32 v[98:99], v[98:99], v[190:191] op_sel_hi:[1,0]
	v_pk_mul_f32 v[96:97], v[96:97], v[190:191] op_sel_hi:[1,0]
	v_pk_mul_f32 v[94:95], v[94:95], v[190:191] op_sel_hi:[1,0]
	v_pk_mul_f32 v[92:93], v[92:93], v[190:191] op_sel_hi:[1,0]
	v_pk_mul_f32 v[90:91], v[90:91], v[190:191] op_sel_hi:[1,0]
	v_pk_mul_f32 v[88:89], v[88:89], v[190:191] op_sel_hi:[1,0]
	v_pk_mul_f32 v[86:87], v[86:87], v[190:191] op_sel_hi:[1,0]
	v_pk_mul_f32 v[84:85], v[84:85], v[190:191] op_sel_hi:[1,0]
	v_pk_mul_f32 v[82:83], v[82:83], v[190:191] op_sel_hi:[1,0]
	v_pk_mul_f32 v[80:81], v[80:81], v[190:191] op_sel_hi:[1,0]
	v_pk_mul_f32 v[78:79], v[78:79], v[190:191] op_sel_hi:[1,0]
	v_pk_mul_f32 v[76:77], v[76:77], v[190:191] op_sel_hi:[1,0]
	v_pk_mul_f32 v[74:75], v[74:75], v[190:191] op_sel_hi:[1,0]
	v_pk_mul_f32 v[72:73], v[72:73], v[190:191] op_sel_hi:[1,0]
	v_pk_mul_f32 v[70:71], v[70:71], v[190:191] op_sel_hi:[1,0]
	v_pk_mul_f32 v[68:69], v[68:69], v[190:191] op_sel_hi:[1,0]
	v_pk_mul_f32 v[66:67], v[66:67], v[190:191] op_sel_hi:[1,0]
	v_pk_mul_f32 v[64:65], v[64:65], v[190:191] op_sel_hi:[1,0]
	v_pk_mul_f32 v[62:63], v[62:63], v[190:191] op_sel_hi:[1,0]
	v_pk_mul_f32 v[60:61], v[60:61], v[190:191] op_sel_hi:[1,0]
	v_pk_mul_f32 v[58:59], v[58:59], v[190:191] op_sel_hi:[1,0]
	v_pk_mul_f32 v[56:57], v[56:57], v[190:191] op_sel_hi:[1,0]
	v_pk_mul_f32 v[54:55], v[54:55], v[190:191] op_sel_hi:[1,0]
	v_pk_mul_f32 v[52:53], v[52:53], v[190:191] op_sel_hi:[1,0]
	v_pk_mul_f32 v[50:51], v[50:51], v[190:191] op_sel_hi:[1,0]
	v_pk_mul_f32 v[48:49], v[48:49], v[190:191] op_sel_hi:[1,0]
	v_pk_mul_f32 v[46:47], v[46:47], v[190:191] op_sel_hi:[1,0]
	v_pk_mul_f32 v[44:45], v[44:45], v[190:191] op_sel_hi:[1,0]
	v_pk_mul_f32 v[42:43], v[42:43], v[190:191] op_sel_hi:[1,0]
	v_pk_mul_f32 v[40:41], v[40:41], v[190:191] op_sel_hi:[1,0]
	v_pk_mul_f32 v[38:39], v[38:39], v[190:191] op_sel_hi:[1,0]
	v_pk_mul_f32 v[36:37], v[36:37], v[190:191] op_sel_hi:[1,0]
	v_pk_mul_f32 v[34:35], v[34:35], v[190:191] op_sel_hi:[1,0]
	v_pk_mul_f32 v[32:33], v[32:33], v[190:191] op_sel_hi:[1,0]
	v_pk_mul_f32 v[30:31], v[30:31], v[190:191] op_sel_hi:[1,0]
	v_pk_mul_f32 v[28:29], v[28:29], v[190:191] op_sel_hi:[1,0]
	v_pk_mul_f32 v[26:27], v[26:27], v[190:191] op_sel_hi:[1,0]
	v_pk_mul_f32 v[24:25], v[24:25], v[190:191] op_sel_hi:[1,0]
	v_pk_mul_f32 v[22:23], v[22:23], v[190:191] op_sel_hi:[1,0]
	v_pk_mul_f32 v[20:21], v[20:21], v[190:191] op_sel_hi:[1,0]
	v_pk_mul_f32 v[18:19], v[18:19], v[190:191] op_sel_hi:[1,0]
	v_pk_mul_f32 v[16:17], v[16:17], v[190:191] op_sel_hi:[1,0]
	v_pk_mul_f32 v[14:15], v[14:15], v[190:191] op_sel_hi:[1,0]
	v_pk_mul_f32 v[12:13], v[12:13], v[190:191] op_sel_hi:[1,0]
	v_pk_mul_f32 v[10:11], v[10:11], v[190:191] op_sel_hi:[1,0]
	v_pk_mul_f32 v[8:9], v[8:9], v[190:191] op_sel_hi:[1,0]
	v_pk_mul_f32 v[6:7], v[6:7], v[190:191] op_sel_hi:[1,0]
	v_pk_mul_f32 v[4:5], v[4:5], v[190:191] op_sel_hi:[1,0]
	v_pk_mul_f32 v[2:3], v[2:3], v[190:191] op_sel_hi:[1,0]
	v_pk_mul_f32 v[0:1], v[0:1], v[190:191] op_sel_hi:[1,0]
	v_mul_f32_e32 v202, v202, v190
	v_mov_b32_e32 v190, v246
	v_sub_f32_e32 v222, v222, v190
	v_exp_f32_e32 v222, v222
	v_sub_f32_e32 v223, v223, v190
	v_exp_f32_e32 v223, v223
	v_sub_f32_e32 v224, v224, v190
	v_add_f32_e32 v254, 0, v222
	v_exp_f32_e32 v224, v224
	v_sub_f32_e32 v225, v225, v190
	v_add_f32_e32 v254, v223, v254
	v_exp_f32_e32 v225, v225
	v_sub_f32_e32 v226, v226, v190
	v_add_f32_e32 v254, v224, v254
	v_exp_f32_e32 v226, v226
	v_sub_f32_e32 v227, v227, v190
	v_add_f32_e32 v254, v225, v254
	v_exp_f32_e32 v227, v227
	v_sub_f32_e32 v228, v228, v190
	v_add_f32_e32 v254, v226, v254
	v_exp_f32_e32 v228, v228
	v_sub_f32_e32 v229, v229, v190
	v_add_f32_e32 v254, v227, v254
	v_exp_f32_e32 v229, v229
	v_sub_f32_e32 v230, v230, v190
	v_add_f32_e32 v254, v228, v254
	v_exp_f32_e32 v230, v230
	v_sub_f32_e32 v231, v231, v190
	v_add_f32_e32 v254, v229, v254
	v_exp_f32_e32 v231, v231
	v_sub_f32_e32 v232, v232, v190
	v_add_f32_e32 v254, v230, v254
	v_exp_f32_e32 v232, v232
	v_sub_f32_e32 v233, v233, v190
	v_add_f32_e32 v254, v231, v254
	v_exp_f32_e32 v233, v233
	v_sub_f32_e32 v234, v234, v190
	v_add_f32_e32 v254, v232, v254
	v_exp_f32_e32 v234, v234
	v_sub_f32_e32 v235, v235, v190
	v_add_f32_e32 v254, v233, v254
	v_exp_f32_e32 v235, v235
	v_sub_f32_e32 v236, v236, v190
	v_add_f32_e32 v254, v234, v254
	v_exp_f32_e32 v236, v236
	v_sub_f32_e32 v237, v237, v190
	v_add_f32_e32 v254, v235, v254
	v_exp_f32_e32 v237, v237
	v_add_f32_e32 v254, v236, v254
	v_add_f32_e32 v254, v237, v254
	v_cvt_pk_bf16_f32 v242, v222, v223
	v_cvt_pk_bf16_f32 v243, v224, v225
	v_cvt_pk_bf16_f32 v244, v226, v227
	v_cvt_pk_bf16_f32 v245, v228, v229
	v_cvt_pk_bf16_f32 v250, v230, v231
	v_cvt_pk_bf16_f32 v251, v232, v233
	v_cvt_pk_bf16_f32 v252, v234, v235
	v_cvt_pk_bf16_f32 v253, v236, v237
	v_add_f32_e32 v202, v202, v254
	s_nop 1
	s_branch .Latt_pv1_0F
	s_lshl_b32 s34, s88, 14
	s_add_i32 s35, s34, 0
	v_add_u32_e32 v206, s35, v194
	ds_read_b128 v[128:131], v206
	v_add_u32_e32 v207, s35, v195
	ds_read_b128 v[210:213], v207
	v_add_u32_e32 v208, s35, v196
	v_add_u32_e32 v209, s35, v197
	v_lshrrev_b32_e32 v204, 3, v203
	s_add_i32 s89, s43, 31
	v_and_or_b32 v205, v203, 31, s83
	s_cmp_le_i32 s89, s83
	s_waitcnt lgkmcnt(1)
	v_mfma_f32_32x32x16_bf16 v[128:143], v[128:131], v[144:147], 0
	ds_read_b128 v[214:217], v209
	s_waitcnt lgkmcnt(1)
	v_mfma_f32_32x32x16_bf16 v[128:143], v[210:213], v[148:151], v[128:143]
	ds_read_b128 v[210:213], v208
	s_waitcnt lgkmcnt(0)
	v_mfma_f32_32x32x16_bf16 v[128:143], v[210:213], v[152:155], v[128:143]
	v_add_u32_e32 v210, s35, v198
	v_add_u32_e32 v212, s35, v199
	v_add_u32_e32 v213, s35, v200
	v_and_b32_e32 v211, 4, v204
	ds_read_b128 v[222:225], v212
	v_mfma_f32_32x32x16_bf16 v[128:143], v[214:217], v[156:159], v[128:143]
	ds_read_b128 v[214:217], v210
	s_waitcnt lgkmcnt(0)
	v_mfma_f32_32x32x16_bf16 v[128:143], v[214:217], v[160:163], v[128:143]
	ds_read_b128 v[216:219], v213
	v_add_u32_e32 v214, s35, v201
	v_mfma_f32_32x32x16_bf16 v[128:143], v[222:225], v[164:167], v[128:143]
	ds_read_b128 v[222:225], v214
	s_waitcnt lgkmcnt(1)
	v_mfma_f32_32x32x16_bf16 v[128:143], v[216:219], v[168:171], v[128:143]
	s_waitcnt lgkmcnt(0)
	v_mfma_f32_32x32x16_bf16 v[128:143], v[222:225], v[172:175], v[128:143]
	s_cbranch_scc1 .LBB0_850
	v_add_u32_e32 v204, s43, v211
	v_cmp_lt_i32_e32 vcc, v204, v205
	v_add_u32_e32 v215, 2, v204
	s_nop 7
	v_cndmask_b32_e32 v129, v192, v129, vcc
	v_cmp_le_i32_e32 vcc, v204, v205
	s_nop 1
	v_cndmask_b32_e32 v128, v192, v128, vcc
	v_cmp_le_i32_e32 vcc, v215, v205
	v_add_u32_e32 v215, 3, v204
	s_nop 0
	v_cndmask_b32_e32 v130, v192, v130, vcc
	v_cmp_le_i32_e32 vcc, v215, v205
	v_add_u32_e32 v215, 8, v204
	s_nop 0
	v_cndmask_b32_e32 v131, v192, v131, vcc
	v_cmp_le_i32_e32 vcc, v215, v205
	v_add_u32_e32 v215, 9, v204
	s_nop 0
	v_cndmask_b32_e32 v132, v192, v132, vcc
	v_cmp_le_i32_e32 vcc, v215, v205
	v_add_u32_e32 v215, 10, v204
	s_nop 0
	v_cndmask_b32_e32 v133, v192, v133, vcc
	v_cmp_le_i32_e32 vcc, v215, v205
	v_add_u32_e32 v215, 11, v204
	s_nop 0
	v_cndmask_b32_e32 v134, v192, v134, vcc
	v_cmp_le_i32_e32 vcc, v215, v205
	v_add_u32_e32 v215, 16, v204
	s_nop 0
	v_cndmask_b32_e32 v135, v192, v135, vcc
	v_cmp_le_i32_e32 vcc, v215, v205
	v_add_u32_e32 v215, 17, v204
	s_nop 0
	v_cndmask_b32_e32 v136, v192, v136, vcc
	v_cmp_le_i32_e32 vcc, v215, v205
	v_add_u32_e32 v215, 18, v204
	s_nop 0
	v_cndmask_b32_e32 v137, v192, v137, vcc
	v_cmp_le_i32_e32 vcc, v215, v205
	v_add_u32_e32 v215, 19, v204
	s_nop 0
	v_cndmask_b32_e32 v138, v192, v138, vcc
	v_cmp_le_i32_e32 vcc, v215, v205
	v_add_u32_e32 v215, 24, v204
	s_nop 0
	v_cndmask_b32_e32 v139, v192, v139, vcc
	v_cmp_le_i32_e32 vcc, v215, v205
	v_add_u32_e32 v215, 25, v204
	s_nop 0
	v_cndmask_b32_e32 v140, v192, v140, vcc
	v_cmp_le_i32_e32 vcc, v215, v205
	v_add_u32_e32 v215, 26, v204
	v_add_u32_e32 v204, 27, v204
	v_cndmask_b32_e32 v141, v192, v141, vcc
	v_cmp_le_i32_e32 vcc, v215, v205
	s_nop 1
	v_cndmask_b32_e32 v142, v192, v142, vcc
	v_cmp_le_i32_e32 vcc, v204, v205
	s_nop 1
	v_cndmask_b32_e32 v143, v192, v143, vcc

.LBB0_864:
	s_cmp_ge_u32 s88, s82
	s_cselect_b64 s[18:19], -1, 0
	v_mov_b32_e32 v204, v176
	s_and_b64 vcc, exec, s[18:19]
	s_cbranch_vccnz .LBB0_866
	s_cmp_le_i32 s4, s84
	s_cbranch_scc1 .LBB0_866
	v_sub_co_u32_e64 v128, s[90:91], s33, 1
	s_nop 1
	v_cndmask_b32_e64 v130, v128, 2, s[90:91]
	v_lshlrev_b32_e32 v128, 14, v130
	v_add_u32_e32 v131, s85, v128
	v_lshl_add_u64 v[128:129], s[12:13], 0, v[178:179]
	s_add_u32 s90, s12, 0xf00
	v_readfirstlane_b32 s89, v131
	s_mov_b32 s92, m0
	s_mov_b32 m0, s89
	s_nop 0
	global_load_lds_dwordx4 v[128:129], off
	s_mov_b32 m0, s92
	v_lshl_add_u64 v[128:129], s[12:13], 0, v[180:181]
	s_addc_u32 s91, s13, 0
	s_addk_i32 s89, 0x400
	s_mov_b32 s92, m0
	s_mov_b32 m0, s89
	s_nop 0
	global_load_lds_dwordx4 v[128:129], off
	s_mov_b32 m0, s92
	v_lshlrev_b32_e32 v128, 15, v130
	v_add_u32_e32 v130, s86, v128
	v_lshl_add_u64 v[128:129], s[90:91], 0, v[182:183]
	v_readfirstlane_b32 s89, v130
	s_mov_b32 s92, m0
	s_mov_b32 m0, s89
	s_nop 0
	global_load_lds_dwordx4 v[128:129], off
	s_mov_b32 m0, s92
	v_lshl_add_u64 v[128:129], s[90:91], 0, v[184:185]
	s_add_i32 s92, s89, 0x400
	s_mov_b32 s93, m0
	s_mov_b32 m0, s92
	s_nop 0
	global_load_lds_dwordx4 v[128:129], off
	s_mov_b32 m0, s93
	v_lshl_add_u64 v[128:129], s[90:91], 0, v[186:187]
	s_add_i32 s92, s89, 0x800
	s_mov_b32 s93, m0
	s_mov_b32 m0, s92
	s_nop 0
	global_load_lds_dwordx4 v[128:129], off
	s_mov_b32 m0, s93
	v_lshl_add_u64 v[128:129], s[90:91], 0, v[188:189]
	s_addk_i32 s89, 0xc00
	s_mov_b32 s90, m0
	s_mov_b32 m0, s89
	s_nop 0
	global_load_lds_dwordx4 v[128:129], off
	s_mov_b32 m0, s90
.LBB0_866:
	s_cmp_gt_i32 s4, s84
	s_cbranch_scc1 .LBB0_877
	s_add_i32 s100, s4, 63
	s_cmp_le_i32 s100, s83
	s_cbranch_scc1 .Latt_full_1
	s_add_i32 s100, s4, 32
	s_cmp_le_i32 s100, s84
	s_cbranch_scc1 .Latt_diagA_1
	s_lshl_b32 s98, s33, 14
	s_lshl_b32 s99, s33, 15
	s_add_i32 s99, s99, 0xc000
	v_add_u32_e32 v206, s98, v196
	ds_read_b128 v[206:209], v206
	v_add_u32_e32 v210, s98, v197
	ds_read_b128 v[210:213], v210
	v_add_u32_e32 v214, s98, v198
	ds_read_b128 v[214:217], v214
	v_add_u32_e32 v238, s98, v199
	ds_read_b128 v[238:241], v238
	v_add_u32_e32 v242, s98, v200
	ds_read_b128 v[242:245], v242
	v_add_u32_e32 v250, s98, v201
	ds_read_b128 v[250:253], v250
	v_add_u32_e32 v222, s98, v202
	ds_read_b128 v[222:225], v222
	v_add_u32_e32 v226, s98, v203
	ds_read_b128 v[226:229], v226
	v_bfe_u32 v246, v204, 2, 2
	v_bfe_u32 v247, v204, 5, 1
	v_lshl_or_b32 v247, v247, 2, v246
	v_and_b32_e32 v249, 3, v204
	v_and_b32_e32 v254, 16, v204
	v_lshl_or_b32 v249, v249, 2, v254
	v_lshlrev_b32_e32 v249, 1, v249
	v_lshl_add_u32 v247, v247, 9, v249
	v_add_u32_e32 v247, s99, v247
	v_lshlrev_b32_e32 v246, 6, v246
	v_add_u32_e32 v205, v247, v246
	v_xor_b32_e32 v249, 64, v246
	v_add_u32_e32 v218, v247, v249
	v_xor_b32_e32 v249, 0x80, v246
	v_add_u32_e32 v219, v247, v249
	v_xor_b32_e32 v249, 0xc0, v246
	v_add_u32_e32 v221, v247, v249
	s_waitcnt lgkmcnt(7)
	v_mfma_f32_32x32x16_bf16 v[128:143], v[206:209], v[144:147], 0
	ds_read_b64_tr_b16 v[206:207], v205
	ds_read_b64_tr_b16 v[208:209], v205 offset:4096
	s_waitcnt lgkmcnt(8)
	v_mfma_f32_32x32x16_bf16 v[128:143], v[210:213], v[148:151], v[128:143]
	ds_read_b64_tr_b16 v[210:211], v218
	ds_read_b64_tr_b16 v[212:213], v218 offset:4096
	s_waitcnt lgkmcnt(9)
	v_mfma_f32_32x32x16_bf16 v[128:143], v[214:217], v[152:155], v[128:143]
	s_waitcnt lgkmcnt(8)
	v_mfma_f32_32x32x16_bf16 v[128:143], v[238:241], v[156:159], v[128:143]
	ds_read_b64_tr_b16 v[214:215], v219
	ds_read_b64_tr_b16 v[216:217], v219 offset:4096
	s_waitcnt lgkmcnt(9)
	v_mfma_f32_32x32x16_bf16 v[128:143], v[242:245], v[160:163], v[128:143]
	s_waitcnt lgkmcnt(8)
	v_mfma_f32_32x32x16_bf16 v[128:143], v[250:253], v[164:167], v[128:143]
	ds_read_b64_tr_b16 v[238:239], v221
	ds_read_b64_tr_b16 v[240:241], v221 offset:4096
	s_waitcnt lgkmcnt(9)
	v_mfma_f32_32x32x16_bf16 v[128:143], v[222:225], v[168:171], v[128:143]
	s_waitcnt lgkmcnt(8)
	v_mfma_f32_32x32x16_bf16 v[128:143], v[226:229], v[172:175], v[128:143]
	s_nop 11
	v_and_or_b32 v246, v204, 31, s83
	v_bfe_u32 v247, v204, 5, 1
	s_add_i32 s100, s4, 0
	v_lshl_add_u32 v247, v247, 2, s100
	v_add_u32_e32 v249, 0, v247
	v_cmp_le_i32_e32 vcc, v249, v246
	v_add_u32_e32 v254, 1, v247
	s_nop 0
	v_cndmask_b32_e32 v128, v192, v128, vcc
	v_cmp_le_i32_e32 vcc, v254, v246
	v_add_u32_e32 v249, 2, v247
	s_nop 0
	v_cndmask_b32_e32 v129, v192, v129, vcc
	v_cmp_le_i32_e32 vcc, v249, v246
	v_add_u32_e32 v254, 3, v247
	s_nop 0
	v_cndmask_b32_e32 v130, v192, v130, vcc
	v_cmp_le_i32_e32 vcc, v254, v246
	v_add_u32_e32 v249, 8, v247
	s_nop 0
	v_cndmask_b32_e32 v131, v192, v131, vcc
	v_cmp_le_i32_e32 vcc, v249, v246
	v_add_u32_e32 v254, 9, v247
	s_nop 0
	v_cndmask_b32_e32 v132, v192, v132, vcc
	v_cmp_le_i32_e32 vcc, v254, v246
	v_add_u32_e32 v249, 10, v247
	s_nop 0
	v_cndmask_b32_e32 v133, v192, v133, vcc
	v_cmp_le_i32_e32 vcc, v249, v246
	v_add_u32_e32 v254, 11, v247
	s_nop 0
	v_cndmask_b32_e32 v134, v192, v134, vcc
	v_cmp_le_i32_e32 vcc, v254, v246
	v_add_u32_e32 v249, 16, v247
	s_nop 0
	v_cndmask_b32_e32 v135, v192, v135, vcc
	v_cmp_le_i32_e32 vcc, v249, v246
	v_add_u32_e32 v254, 17, v247
	s_nop 0
	v_cndmask_b32_e32 v136, v192, v136, vcc
	v_cmp_le_i32_e32 vcc, v254, v246
	v_add_u32_e32 v249, 18, v247
	s_nop 0
	v_cndmask_b32_e32 v137, v192, v137, vcc
	v_cmp_le_i32_e32 vcc, v249, v246
	v_add_u32_e32 v254, 19, v247
	s_nop 0
	v_cndmask_b32_e32 v138, v192, v138, vcc
	v_cmp_le_i32_e32 vcc, v254, v246
	v_add_u32_e32 v249, 24, v247
	s_nop 0
	v_cndmask_b32_e32 v139, v192, v139, vcc
	v_cmp_le_i32_e32 vcc, v249, v246
	v_add_u32_e32 v254, 25, v247
	s_nop 0
	v_cndmask_b32_e32 v140, v192, v140, vcc
	v_cmp_le_i32_e32 vcc, v254, v246
	v_add_u32_e32 v249, 26, v247
	s_nop 0
	v_cndmask_b32_e32 v141, v192, v141, vcc
	v_cmp_le_i32_e32 vcc, v249, v246
	v_add_u32_e32 v254, 27, v247
	s_nop 0
	v_cndmask_b32_e32 v142, v192, v142, vcc
	v_cmp_le_i32_e32 vcc, v254, v246
	s_nop 1
	v_cndmask_b32_e32 v143, v192, v143, vcc
	v_max3_f32 v246, v128, v129, v130
	v_max3_f32 v247, v131, v132, v133
	v_max3_f32 v246, v246, v134, v135
	v_max3_f32 v247, v247, v136, v137
	v_max3_f32 v246, v246, v138, v139
	v_max3_f32 v247, v247, v140, v141
	v_max3_f32 v246, v246, v142, v143
	v_max_f32_e32 v246, v246, v247
	v_mov_b32_e32 v247, v246
	v_add_f32_e32 v249, 0x41000000, v190
	s_nop 1
	v_permlane32_swap_b32_e32 v246, v247
	v_max_f32_e32 v246, v246, v247
	v_cmp_gt_f32_e32 vcc, v246, v249
	s_cbranch_vccz .Latt_nr0_1B
	v_max_f32_e32 v246, v190, v246
	v_sub_f32_e32 v190, v190, v246
	v_exp_f32_e32 v190, v190
	s_nop 0
	v_pk_mul_f32 v[126:127], v[126:127], v[190:191] op_sel_hi:[1,0]
	v_pk_mul_f32 v[124:125], v[124:125], v[190:191] op_sel_hi:[1,0]
	v_pk_mul_f32 v[122:123], v[122:123], v[190:191] op_sel_hi:[1,0]
	v_pk_mul_f32 v[120:121], v[120:121], v[190:191] op_sel_hi:[1,0]
	v_pk_mul_f32 v[118:119], v[118:119], v[190:191] op_sel_hi:[1,0]
	v_pk_mul_f32 v[116:117], v[116:117], v[190:191] op_sel_hi:[1,0]
	v_pk_mul_f32 v[114:115], v[114:115], v[190:191] op_sel_hi:[1,0]
	v_pk_mul_f32 v[112:113], v[112:113], v[190:191] op_sel_hi:[1,0]
	v_pk_mul_f32 v[110:111], v[110:111], v[190:191] op_sel_hi:[1,0]
	v_pk_mul_f32 v[108:109], v[108:109], v[190:191] op_sel_hi:[1,0]
	v_pk_mul_f32 v[106:107], v[106:107], v[190:191] op_sel_hi:[1,0]
	v_pk_mul_f32 v[104:105], v[104:105], v[190:191] op_sel_hi:[1,0]
	v_pk_mul_f32 v[102:103], v[102:103], v[190:191] op_sel_hi:[1,0]
	v_pk_mul_f32 v[100:101], v[100:101], v[190:191] op_sel_hi:[1,0]
	v_pk_mul_f32 v[98:99], v[98:99], v[190:191] op_sel_hi:[1,0]
	v_pk_mul_f32 v[96:97], v[96:97], v[190:191] op_sel_hi:[1,0]
	v_pk_mul_f32 v[94:95], v[94:95], v[190:191] op_sel_hi:[1,0]
	v_pk_mul_f32 v[92:93], v[92:93], v[190:191] op_sel_hi:[1,0]
	v_pk_mul_f32 v[90:91], v[90:91], v[190:191] op_sel_hi:[1,0]
	v_pk_mul_f32 v[88:89], v[88:89], v[190:191] op_sel_hi:[1,0]
	v_pk_mul_f32 v[86:87], v[86:87], v[190:191] op_sel_hi:[1,0]
	v_pk_mul_f32 v[84:85], v[84:85], v[190:191] op_sel_hi:[1,0]
	v_pk_mul_f32 v[82:83], v[82:83], v[190:191] op_sel_hi:[1,0]
	v_pk_mul_f32 v[80:81], v[80:81], v[190:191] op_sel_hi:[1,0]
	v_pk_mul_f32 v[78:79], v[78:79], v[190:191] op_sel_hi:[1,0]
	v_pk_mul_f32 v[76:77], v[76:77], v[190:191] op_sel_hi:[1,0]
	v_pk_mul_f32 v[74:75], v[74:75], v[190:191] op_sel_hi:[1,0]
	v_pk_mul_f32 v[72:73], v[72:73], v[190:191] op_sel_hi:[1,0]
	v_pk_mul_f32 v[70:71], v[70:71], v[190:191] op_sel_hi:[1,0]
	v_pk_mul_f32 v[68:69], v[68:69], v[190:191] op_sel_hi:[1,0]
	v_pk_mul_f32 v[66:67], v[66:67], v[190:191] op_sel_hi:[1,0]
	v_pk_mul_f32 v[64:65], v[64:65], v[190:191] op_sel_hi:[1,0]
	v_pk_mul_f32 v[62:63], v[62:63], v[190:191] op_sel_hi:[1,0]
	v_pk_mul_f32 v[60:61], v[60:61], v[190:191] op_sel_hi:[1,0]
	v_pk_mul_f32 v[58:59], v[58:59], v[190:191] op_sel_hi:[1,0]
	v_pk_mul_f32 v[56:57], v[56:57], v[190:191] op_sel_hi:[1,0]
	v_pk_mul_f32 v[54:55], v[54:55], v[190:191] op_sel_hi:[1,0]
	v_pk_mul_f32 v[52:53], v[52:53], v[190:191] op_sel_hi:[1,0]
	v_pk_mul_f32 v[50:51], v[50:51], v[190:191] op_sel_hi:[1,0]
	v_pk_mul_f32 v[48:49], v[48:49], v[190:191] op_sel_hi:[1,0]
	v_pk_mul_f32 v[46:47], v[46:47], v[190:191] op_sel_hi:[1,0]
	v_pk_mul_f32 v[44:45], v[44:45], v[190:191] op_sel_hi:[1,0]
	v_pk_mul_f32 v[42:43], v[42:43], v[190:191] op_sel_hi:[1,0]
	v_pk_mul_f32 v[40:41], v[40:41], v[190:191] op_sel_hi:[1,0]
	v_pk_mul_f32 v[38:39], v[38:39], v[190:191] op_sel_hi:[1,0]
	v_pk_mul_f32 v[36:37], v[36:37], v[190:191] op_sel_hi:[1,0]
	v_pk_mul_f32 v[34:35], v[34:35], v[190:191] op_sel_hi:[1,0]
	v_pk_mul_f32 v[32:33], v[32:33], v[190:191] op_sel_hi:[1,0]
	v_pk_mul_f32 v[30:31], v[30:31], v[190:191] op_sel_hi:[1,0]
	v_pk_mul_f32 v[28:29], v[28:29], v[190:191] op_sel_hi:[1,0]
	v_pk_mul_f32 v[26:27], v[26:27], v[190:191] op_sel_hi:[1,0]
	v_pk_mul_f32 v[24:25], v[24:25], v[190:191] op_sel_hi:[1,0]
	v_pk_mul_f32 v[22:23], v[22:23], v[190:191] op_sel_hi:[1,0]
	v_pk_mul_f32 v[20:21], v[20:21], v[190:191] op_sel_hi:[1,0]
	v_pk_mul_f32 v[18:19], v[18:19], v[190:191] op_sel_hi:[1,0]
	v_pk_mul_f32 v[16:17], v[16:17], v[190:191] op_sel_hi:[1,0]
	v_pk_mul_f32 v[14:15], v[14:15], v[190:191] op_sel_hi:[1,0]
	v_pk_mul_f32 v[12:13], v[12:13], v[190:191] op_sel_hi:[1,0]
	v_pk_mul_f32 v[10:11], v[10:11], v[190:191] op_sel_hi:[1,0]
	v_pk_mul_f32 v[8:9], v[8:9], v[190:191] op_sel_hi:[1,0]
	v_pk_mul_f32 v[6:7], v[6:7], v[190:191] op_sel_hi:[1,0]
	v_pk_mul_f32 v[4:5], v[4:5], v[190:191] op_sel_hi:[1,0]
	v_pk_mul_f32 v[2:3], v[2:3], v[190:191] op_sel_hi:[1,0]
	v_pk_mul_f32 v[0:1], v[0:1], v[190:191] op_sel_hi:[1,0]
	v_mul_f32_e32 v195, v195, v190
	v_mov_b32_e32 v190, v246
.Latt_nr0_1B:
	v_sub_f32_e32 v128, v128, v190
	v_exp_f32_e32 v128, v128
	v_sub_f32_e32 v129, v129, v190
	v_exp_f32_e32 v129, v129
	v_sub_f32_e32 v130, v130, v190
	v_add_f32_e32 v254, 0, v128
	v_exp_f32_e32 v130, v130
	v_sub_f32_e32 v131, v131, v190
	v_add_f32_e32 v254, v129, v254
	v_exp_f32_e32 v131, v131
	v_sub_f32_e32 v132, v132, v190
	v_add_f32_e32 v254, v130, v254
	v_exp_f32_e32 v132, v132
	v_sub_f32_e32 v133, v133, v190
	v_add_f32_e32 v254, v131, v254
	v_exp_f32_e32 v133, v133
	v_sub_f32_e32 v134, v134, v190
	v_add_f32_e32 v254, v132, v254
	v_exp_f32_e32 v134, v134
	v_sub_f32_e32 v135, v135, v190
	v_add_f32_e32 v254, v133, v254
	v_exp_f32_e32 v135, v135
	v_sub_f32_e32 v136, v136, v190
	v_add_f32_e32 v254, v134, v254
	v_exp_f32_e32 v136, v136
	v_sub_f32_e32 v137, v137, v190
	v_add_f32_e32 v254, v135, v254
	v_exp_f32_e32 v137, v137
	v_sub_f32_e32 v138, v138, v190
	v_add_f32_e32 v254, v136, v254
	v_exp_f32_e32 v138, v138
	v_sub_f32_e32 v139, v139, v190
	v_add_f32_e32 v254, v137, v254
	v_exp_f32_e32 v139, v139
	v_sub_f32_e32 v140, v140, v190
	v_add_f32_e32 v254, v138, v254
	v_exp_f32_e32 v140, v140
	v_sub_f32_e32 v141, v141, v190
	v_add_f32_e32 v254, v139, v254
	v_exp_f32_e32 v141, v141
	v_sub_f32_e32 v142, v142, v190
	v_add_f32_e32 v254, v140, v254
	v_exp_f32_e32 v142, v142
	v_sub_f32_e32 v143, v143, v190
	v_add_f32_e32 v254, v141, v254
	v_exp_f32_e32 v143, v143
	v_add_f32_e32 v254, v142, v254
	v_add_f32_e32 v254, v143, v254
	v_cvt_pk_bf16_f32 v242, v128, v129
	v_cvt_pk_bf16_f32 v243, v130, v131
	v_cvt_pk_bf16_f32 v244, v132, v133
	v_cvt_pk_bf16_f32 v245, v134, v135
	v_cvt_pk_bf16_f32 v250, v136, v137
	v_cvt_pk_bf16_f32 v251, v138, v139
	v_cvt_pk_bf16_f32 v252, v140, v141
	v_cvt_pk_bf16_f32 v253, v142, v143
	v_add_f32_e32 v195, v195, v254
	s_nop 1
	ds_read_b64_tr_b16 v[128:129], v205 offset:256
	ds_read_b64_tr_b16 v[130:131], v205 offset:4352
	s_waitcnt lgkmcnt(8)
	v_mfma_f32_32x32x16_bf16 v[112:127], v[206:209], v[242:245], v[112:127]
	ds_read_b64_tr_b16 v[206:207], v218 offset:256
	ds_read_b64_tr_b16 v[208:209], v218 offset:4352
	s_waitcnt lgkmcnt(8)
	v_mfma_f32_32x32x16_bf16 v[96:111], v[210:213], v[242:245], v[96:111]
	ds_read_b64_tr_b16 v[210:211], v219 offset:256
	ds_read_b64_tr_b16 v[212:213], v219 offset:4352
	s_cmp_lg_u64 s[18:19], 0
	s_cbranch_scc1 .Latt_nd0_1B
	s_sub_i32 s100, s33, 1
	s_cmp_eq_u32 s33, 0
	s_cselect_b32 s100, 2, s100
	s_lshl_b32 s101, s100, 14
	s_add_i32 m0, s85, s101
	s_nop 0
	global_load_lds_dwordx4 v178, s[12:13]
.Latt_nd0_1B:
	s_waitcnt lgkmcnt(8)
	v_mfma_f32_32x32x16_bf16 v[80:95], v[214:217], v[242:245], v[80:95]
	ds_read_b64_tr_b16 v[214:215], v221 offset:256
	ds_read_b64_tr_b16 v[216:217], v221 offset:4352
	s_waitcnt lgkmcnt(8)
	v_mfma_f32_32x32x16_bf16 v[64:79], v[238:241], v[242:245], v[64:79]
	ds_read_b64_tr_b16 v[238:239], v205 offset:8192
	ds_read_b64_tr_b16 v[240:241], v205 offset:12288
	s_cmp_lg_u64 s[18:19], 0
	s_cbranch_scc1 .Latt_nd1_1B
	s_add_i32 m0, m0, 0x400
	s_nop 0
	global_load_lds_dwordx4 v180, s[12:13]
.Latt_nd1_1B:
	s_waitcnt lgkmcnt(8)
	v_mfma_f32_32x32x16_bf16 v[48:63], v[128:131], v[242:245], v[48:63]
	ds_read_b64_tr_b16 v[128:129], v218 offset:8192
	ds_read_b64_tr_b16 v[130:131], v218 offset:12288
	s_waitcnt lgkmcnt(8)
	v_mfma_f32_32x32x16_bf16 v[32:47], v[206:209], v[242:245], v[32:47]
	ds_read_b64_tr_b16 v[206:207], v219 offset:8192
	ds_read_b64_tr_b16 v[208:209], v219 offset:12288
	s_cmp_lg_u64 s[18:19], 0
	s_cbranch_scc1 .Latt_nd2_1B
	s_lshl_b32 s101, s100, 15
	s_add_i32 m0, s86, s101
	s_add_u32 s100, s12, 0xf00
	s_addc_u32 s101, s13, 0
	global_load_lds_dwordx4 v182, s[100:101]

.Latt_diagA_1:
	s_lshl_b32 s98, s33, 14
	s_lshl_b32 s99, s33, 15
	s_add_i32 s99, s99, 0xc000
	v_add_u32_e32 v206, s98, v196
	ds_read_b128 v[206:209], v206
	v_add_u32_e32 v210, s98, v197
	ds_read_b128 v[210:213], v210
	v_add_u32_e32 v214, s98, v198
	ds_read_b128 v[214:217], v214
	v_add_u32_e32 v238, s98, v199
	ds_read_b128 v[238:241], v238
	v_add_u32_e32 v242, s98, v200
	ds_read_b128 v[242:245], v242
	v_add_u32_e32 v250, s98, v201
	ds_read_b128 v[250:253], v250
	v_add_u32_e32 v222, s98, v202
	ds_read_b128 v[222:225], v222
	v_add_u32_e32 v226, s98, v203
	ds_read_b128 v[226:229], v226
	v_bfe_u32 v246, v204, 2, 2
	v_bfe_u32 v247, v204, 5, 1
	v_lshl_or_b32 v247, v247, 2, v246
	v_and_b32_e32 v249, 3, v204
	v_and_b32_e32 v254, 16, v204
	v_lshl_or_b32 v249, v249, 2, v254
	v_lshlrev_b32_e32 v249, 1, v249
	v_lshl_add_u32 v247, v247, 9, v249
	v_add_u32_e32 v247, s99, v247
	v_lshlrev_b32_e32 v246, 6, v246
	v_add_u32_e32 v205, v247, v246
	v_xor_b32_e32 v249, 64, v246
	v_add_u32_e32 v218, v247, v249
	v_xor_b32_e32 v249, 0x80, v246
	v_add_u32_e32 v219, v247, v249
	v_xor_b32_e32 v249, 0xc0, v246
	v_add_u32_e32 v221, v247, v249
	s_waitcnt lgkmcnt(7)
	v_mfma_f32_32x32x16_bf16 v[128:143], v[206:209], v[144:147], 0
	v_add_u32_e32 v206, s98, v196
	ds_read_b128 v[206:209], v206 offset:8192
	s_waitcnt lgkmcnt(7)
	v_mfma_f32_32x32x16_bf16 v[128:143], v[210:213], v[148:151], v[128:143]
	v_add_u32_e32 v210, s98, v197
	ds_read_b128 v[210:213], v210 offset:8192
	s_waitcnt lgkmcnt(7)
	v_mfma_f32_32x32x16_bf16 v[128:143], v[214:217], v[152:155], v[128:143]
	v_add_u32_e32 v214, s98, v198
	ds_read_b128 v[214:217], v214 offset:8192
	s_waitcnt lgkmcnt(7)
	v_mfma_f32_32x32x16_bf16 v[128:143], v[238:241], v[156:159], v[128:143]
	v_add_u32_e32 v238, s98, v199
	ds_read_b128 v[238:241], v238 offset:8192
	s_waitcnt lgkmcnt(7)
	v_mfma_f32_32x32x16_bf16 v[128:143], v[242:245], v[160:163], v[128:143]
	v_add_u32_e32 v242, s98, v200
	ds_read_b128 v[242:245], v242 offset:8192
	s_waitcnt lgkmcnt(7)
	v_mfma_f32_32x32x16_bf16 v[128:143], v[250:253], v[164:167], v[128:143]
	v_add_u32_e32 v250, s98, v201
	ds_read_b128 v[250:253], v250 offset:8192
	s_waitcnt lgkmcnt(7)
	v_mfma_f32_32x32x16_bf16 v[128:143], v[222:225], v[168:171], v[128:143]
	s_waitcnt lgkmcnt(6)
	v_mfma_f32_32x32x16_bf16 v[128:143], v[226:229], v[172:175], v[128:143]
	s_waitcnt lgkmcnt(5)
	v_mfma_f32_32x32x16_bf16 v[222:237], v[206:209], v[144:147], 0
	v_add_u32_e32 v206, s98, v202
	ds_read_b128 v[206:209], v206 offset:8192
	s_nop 7
	v_max3_f32 v246, v128, v129, v130
	v_max3_f32 v247, v131, v132, v133
	v_max3_f32 v246, v246, v134, v135
	v_max3_f32 v247, v247, v136, v137
	v_max3_f32 v246, v246, v138, v139
	v_max3_f32 v247, v247, v140, v141
	v_max3_f32 v246, v246, v142, v143
	s_waitcnt lgkmcnt(5)
	v_mfma_f32_32x32x16_bf16 v[222:237], v[210:213], v[148:151], v[222:237]
	v_add_u32_e32 v210, s98, v203
	ds_read_b128 v[210:213], v210 offset:8192
	v_max_f32_e32 v246, v246, v247
	v_mov_b32_e32 v247, v246
	v_add_f32_e32 v249, 0x41000000, v190
	s_nop 1
	v_permlane32_swap_b32_e32 v246, v247
	v_max_f32_e32 v246, v246, v247
	v_cmp_gt_f32_e32 vcc, v246, v249
	s_cbranch_vccz .Latt_nr0_1A
	v_max_f32_e32 v246, v190, v246
	v_sub_f32_e32 v190, v190, v246
	v_exp_f32_e32 v190, v190
	s_nop 0
	v_pk_mul_f32 v[126:127], v[126:127], v[190:191] op_sel_hi:[1,0]
	v_pk_mul_f32 v[124:125], v[124:125], v[190:191] op_sel_hi:[1,0]
	v_pk_mul_f32 v[122:123], v[122:123], v[190:191] op_sel_hi:[1,0]
	v_pk_mul_f32 v[120:121], v[120:121], v[190:191] op_sel_hi:[1,0]
	v_pk_mul_f32 v[118:119], v[118:119], v[190:191] op_sel_hi:[1,0]
	v_pk_mul_f32 v[116:117], v[116:117], v[190:191] op_sel_hi:[1,0]
	v_pk_mul_f32 v[114:115], v[114:115], v[190:191] op_sel_hi:[1,0]
	v_pk_mul_f32 v[112:113], v[112:113], v[190:191] op_sel_hi:[1,0]
	v_pk_mul_f32 v[110:111], v[110:111], v[190:191] op_sel_hi:[1,0]
	v_pk_mul_f32 v[108:109], v[108:109], v[190:191] op_sel_hi:[1,0]
	v_pk_mul_f32 v[106:107], v[106:107], v[190:191] op_sel_hi:[1,0]
	v_pk_mul_f32 v[104:105], v[104:105], v[190:191] op_sel_hi:[1,0]
	v_pk_mul_f32 v[102:103], v[102:103], v[190:191] op_sel_hi:[1,0]
	v_pk_mul_f32 v[100:101], v[100:101], v[190:191] op_sel_hi:[1,0]
	v_pk_mul_f32 v[98:99], v[98:99], v[190:191] op_sel_hi:[1,0]
	v_pk_mul_f32 v[96:97], v[96:97], v[190:191] op_sel_hi:[1,0]
	v_pk_mul_f32 v[94:95], v[94:95], v[190:191] op_sel_hi:[1,0]
	v_pk_mul_f32 v[92:93], v[92:93], v[190:191] op_sel_hi:[1,0]
	v_pk_mul_f32 v[90:91], v[90:91], v[190:191] op_sel_hi:[1,0]
	v_pk_mul_f32 v[88:89], v[88:89], v[190:191] op_sel_hi:[1,0]
	v_pk_mul_f32 v[86:87], v[86:87], v[190:191] op_sel_hi:[1,0]
	v_pk_mul_f32 v[84:85], v[84:85], v[190:191] op_sel_hi:[1,0]
	v_pk_mul_f32 v[82:83], v[82:83], v[190:191] op_sel_hi:[1,0]
	v_pk_mul_f32 v[80:81], v[80:81], v[190:191] op_sel_hi:[1,0]
	v_pk_mul_f32 v[78:79], v[78:79], v[190:191] op_sel_hi:[1,0]
	v_pk_mul_f32 v[76:77], v[76:77], v[190:191] op_sel_hi:[1,0]
	v_pk_mul_f32 v[74:75], v[74:75], v[190:191] op_sel_hi:[1,0]
	v_pk_mul_f32 v[72:73], v[72:73], v[190:191] op_sel_hi:[1,0]
	v_pk_mul_f32 v[70:71], v[70:71], v[190:191] op_sel_hi:[1,0]
	v_pk_mul_f32 v[68:69], v[68:69], v[190:191] op_sel_hi:[1,0]
	v_pk_mul_f32 v[66:67], v[66:67], v[190:191] op_sel_hi:[1,0]
	v_pk_mul_f32 v[64:65], v[64:65], v[190:191] op_sel_hi:[1,0]
	v_pk_mul_f32 v[62:63], v[62:63], v[190:191] op_sel_hi:[1,0]
	v_pk_mul_f32 v[60:61], v[60:61], v[190:191] op_sel_hi:[1,0]
	v_pk_mul_f32 v[58:59], v[58:59], v[190:191] op_sel_hi:[1,0]
	v_pk_mul_f32 v[56:57], v[56:57], v[190:191] op_sel_hi:[1,0]
	v_pk_mul_f32 v[54:55], v[54:55], v[190:191] op_sel_hi:[1,0]
	v_pk_mul_f32 v[52:53], v[52:53], v[190:191] op_sel_hi:[1,0]
	v_pk_mul_f32 v[50:51], v[50:51], v[190:191] op_sel_hi:[1,0]
	v_pk_mul_f32 v[48:49], v[48:49], v[190:191] op_sel_hi:[1,0]
	v_pk_mul_f32 v[46:47], v[46:47], v[190:191] op_sel_hi:[1,0]
	v_pk_mul_f32 v[44:45], v[44:45], v[190:191] op_sel_hi:[1,0]
	v_pk_mul_f32 v[42:43], v[42:43], v[190:191] op_sel_hi:[1,0]
	v_pk_mul_f32 v[40:41], v[40:41], v[190:191] op_sel_hi:[1,0]
	v_pk_mul_f32 v[38:39], v[38:39], v[190:191] op_sel_hi:[1,0]
	v_pk_mul_f32 v[36:37], v[36:37], v[190:191] op_sel_hi:[1,0]
	v_pk_mul_f32 v[34:35], v[34:35], v[190:191] op_sel_hi:[1,0]
	v_pk_mul_f32 v[32:33], v[32:33], v[190:191] op_sel_hi:[1,0]
	v_pk_mul_f32 v[30:31], v[30:31], v[190:191] op_sel_hi:[1,0]
	v_pk_mul_f32 v[28:29], v[28:29], v[190:191] op_sel_hi:[1,0]
	v_pk_mul_f32 v[26:27], v[26:27], v[190:191] op_sel_hi:[1,0]
	v_pk_mul_f32 v[24:25], v[24:25], v[190:191] op_sel_hi:[1,0]
	v_pk_mul_f32 v[22:23], v[22:23], v[190:191] op_sel_hi:[1,0]
	v_pk_mul_f32 v[20:21], v[20:21], v[190:191] op_sel_hi:[1,0]
	v_pk_mul_f32 v[18:19], v[18:19], v[190:191] op_sel_hi:[1,0]
	v_pk_mul_f32 v[16:17], v[16:17], v[190:191] op_sel_hi:[1,0]
	v_pk_mul_f32 v[14:15], v[14:15], v[190:191] op_sel_hi:[1,0]
	v_pk_mul_f32 v[12:13], v[12:13], v[190:191] op_sel_hi:[1,0]
	v_pk_mul_f32 v[10:11], v[10:11], v[190:191] op_sel_hi:[1,0]
	v_pk_mul_f32 v[8:9], v[8:9], v[190:191] op_sel_hi:[1,0]
	v_pk_mul_f32 v[6:7], v[6:7], v[190:191] op_sel_hi:[1,0]
	v_pk_mul_f32 v[4:5], v[4:5], v[190:191] op_sel_hi:[1,0]
	v_pk_mul_f32 v[2:3], v[2:3], v[190:191] op_sel_hi:[1,0]
	v_pk_mul_f32 v[0:1], v[0:1], v[190:191] op_sel_hi:[1,0]
	v_mul_f32_e32 v195, v195, v190
	v_mov_b32_e32 v190, v246
.Latt_nr0_1A:
	s_waitcnt lgkmcnt(5)
	v_mfma_f32_32x32x16_bf16 v[222:237], v[214:217], v[152:155], v[222:237]
	ds_read_b64_tr_b16 v[214:215], v205
	ds_read_b64_tr_b16 v[216:217], v205 offset:4096
	v_sub_f32_e32 v128, v128, v190
	v_exp_f32_e32 v128, v128
	v_sub_f32_e32 v129, v129, v190
	v_exp_f32_e32 v129, v129
	v_sub_f32_e32 v130, v130, v190
	v_add_f32_e32 v254, 0, v128
	v_exp_f32_e32 v130, v130
	v_sub_f32_e32 v131, v131, v190
	s_waitcnt lgkmcnt(6)
	v_mfma_f32_32x32x16_bf16 v[222:237], v[238:241], v[156:159], v[222:237]
	ds_read_b64_tr_b16 v[238:239], v218
	ds_read_b64_tr_b16 v[240:241], v218 offset:4096
	v_add_f32_e32 v254, v129, v254
	v_exp_f32_e32 v131, v131
	v_sub_f32_e32 v132, v132, v190
	v_add_f32_e32 v254, v130, v254
	v_exp_f32_e32 v132, v132
	v_sub_f32_e32 v133, v133, v190
	v_add_f32_e32 v254, v131, v254
	v_exp_f32_e32 v133, v133
	s_waitcnt lgkmcnt(7)
	v_mfma_f32_32x32x16_bf16 v[222:237], v[242:245], v[160:163], v[222:237]
	v_sub_f32_e32 v134, v134, v190
	v_add_f32_e32 v254, v132, v254
	v_exp_f32_e32 v134, v134
	v_sub_f32_e32 v135, v135, v190
	v_add_f32_e32 v254, v133, v254
	v_exp_f32_e32 v135, v135
	v_sub_f32_e32 v136, v136, v190
	v_add_f32_e32 v254, v134, v254
	s_waitcnt lgkmcnt(6)
	v_mfma_f32_32x32x16_bf16 v[222:237], v[250:253], v[164:167], v[222:237]
	v_exp_f32_e32 v136, v136
	v_sub_f32_e32 v137, v137, v190
	v_add_f32_e32 v254, v135, v254
	v_exp_f32_e32 v137, v137
	v_sub_f32_e32 v138, v138, v190
	v_add_f32_e32 v254, v136, v254
	v_exp_f32_e32 v138, v138
	v_sub_f32_e32 v139, v139, v190
	s_waitcnt lgkmcnt(5)
	v_mfma_f32_32x32x16_bf16 v[222:237], v[206:209], v[168:171], v[222:237]
	ds_read_b64_tr_b16 v[206:207], v219
	ds_read_b64_tr_b16 v[208:209], v219 offset:4096
	v_add_f32_e32 v254, v137, v254
	v_exp_f32_e32 v139, v139
	v_sub_f32_e32 v140, v140, v190
	v_add_f32_e32 v254, v138, v254
	v_exp_f32_e32 v140, v140
	v_sub_f32_e32 v141, v141, v190
	v_add_f32_e32 v254, v139, v254
	v_exp_f32_e32 v141, v141
	s_waitcnt lgkmcnt(6)
	v_mfma_f32_32x32x16_bf16 v[222:237], v[210:213], v[172:175], v[222:237]
	ds_read_b64_tr_b16 v[210:211], v221
	ds_read_b64_tr_b16 v[212:213], v221 offset:4096
	v_sub_f32_e32 v142, v142, v190
	v_add_f32_e32 v254, v140, v254
	v_exp_f32_e32 v142, v142
	v_sub_f32_e32 v143, v143, v190
	v_add_f32_e32 v254, v141, v254
	v_exp_f32_e32 v143, v143
	v_add_f32_e32 v254, v142, v254
	v_add_f32_e32 v254, v143, v254
	v_cvt_pk_bf16_f32 v242, v128, v129
	v_cvt_pk_bf16_f32 v243, v130, v131
	v_cvt_pk_bf16_f32 v244, v132, v133
	v_cvt_pk_bf16_f32 v245, v134, v135
	v_cvt_pk_bf16_f32 v250, v136, v137
	v_cvt_pk_bf16_f32 v251, v138, v139
	v_cvt_pk_bf16_f32 v252, v140, v141
	v_cvt_pk_bf16_f32 v253, v142, v143
	v_add_f32_e32 v195, v195, v254
	s_nop 1
	ds_read_b64_tr_b16 v[128:129], v205 offset:256
	ds_read_b64_tr_b16 v[130:131], v205 offset:4352
	s_waitcnt lgkmcnt(8)
	v_mfma_f32_32x32x16_bf16 v[112:127], v[214:217], v[242:245], v[112:127]
	ds_read_b64_tr_b16 v[214:215], v218 offset:256
	ds_read_b64_tr_b16 v[216:217], v218 offset:4352
	v_and_or_b32 v246, v204, 31, s83
	v_bfe_u32 v247, v204, 5, 1
	s_add_i32 s100, s4, 32
	v_lshl_add_u32 v247, v247, 2, s100
	v_add_u32_e32 v249, 0, v247
	v_cmp_le_i32_e32 vcc, v249, v246
	v_add_u32_e32 v254, 1, v247
	s_nop 0
	v_cndmask_b32_e32 v222, v192, v222, vcc
	v_cmp_le_i32_e32 vcc, v254, v246
	v_add_u32_e32 v249, 2, v247
	s_nop 0
	v_cndmask_b32_e32 v223, v192, v223, vcc
	v_cmp_le_i32_e32 vcc, v249, v246
	v_add_u32_e32 v254, 3, v247
	s_nop 0
	v_cndmask_b32_e32 v224, v192, v224, vcc
	v_cmp_le_i32_e32 vcc, v254, v246
	v_add_u32_e32 v249, 8, v247
	s_nop 0
	v_cndmask_b32_e32 v225, v192, v225, vcc
	v_cmp_le_i32_e32 vcc, v249, v246
	v_add_u32_e32 v254, 9, v247
	s_nop 0
	v_cndmask_b32_e32 v226, v192, v226, vcc
	v_cmp_le_i32_e32 vcc, v254, v246
	v_add_u32_e32 v249, 10, v247
	s_nop 0
	v_cndmask_b32_e32 v227, v192, v227, vcc
	v_cmp_le_i32_e32 vcc, v249, v246
	v_add_u32_e32 v254, 11, v247
	s_nop 0
	v_cndmask_b32_e32 v228, v192, v228, vcc
	v_cmp_le_i32_e32 vcc, v254, v246
	s_waitcnt lgkmcnt(8)
	v_mfma_f32_32x32x16_bf16 v[96:111], v[238:241], v[242:245], v[96:111]
	ds_read_b64_tr_b16 v[238:239], v219 offset:256
	ds_read_b64_tr_b16 v[240:241], v219 offset:4352
	v_add_u32_e32 v249, 16, v247
	s_nop 0
	v_cndmask_b32_e32 v229, v192, v229, vcc
	v_cmp_le_i32_e32 vcc, v249, v246
	v_add_u32_e32 v254, 17, v247
	s_nop 0
	v_cndmask_b32_e32 v230, v192, v230, vcc
	v_cmp_le_i32_e32 vcc, v254, v246
	v_add_u32_e32 v249, 18, v247
	s_nop 0
	v_cndmask_b32_e32 v231, v192, v231, vcc
	v_cmp_le_i32_e32 vcc, v249, v246
	v_add_u32_e32 v254, 19, v247
	s_nop 0
	v_cndmask_b32_e32 v232, v192, v232, vcc
	v_cmp_le_i32_e32 vcc, v254, v246
	v_add_u32_e32 v249, 24, v247
	s_nop 0
	v_cndmask_b32_e32 v233, v192, v233, vcc
	v_cmp_le_i32_e32 vcc, v249, v246
	v_add_u32_e32 v254, 25, v247
	s_nop 0
	v_cndmask_b32_e32 v234, v192, v234, vcc
	v_cmp_le_i32_e32 vcc, v254, v246
	v_add_u32_e32 v249, 26, v247
	s_nop 0
	v_cndmask_b32_e32 v235, v192, v235, vcc
	v_cmp_le_i32_e32 vcc, v249, v246
	v_add_u32_e32 v254, 27, v247
	s_nop 0
	v_cndmask_b32_e32 v236, v192, v236, vcc
	v_cmp_le_i32_e32 vcc, v254, v246
	s_nop 1
	v_cndmask_b32_e32 v237, v192, v237, vcc
	s_waitcnt lgkmcnt(8)
	v_mfma_f32_32x32x16_bf16 v[80:95], v[206:209], v[242:245], v[80:95]
	ds_read_b64_tr_b16 v[206:207], v221 offset:256
	ds_read_b64_tr_b16 v[208:209], v221 offset:4352
	v_max3_f32 v246, v222, v223, v224
	v_max3_f32 v247, v225, v226, v227
	v_max3_f32 v246, v246, v228, v229
	v_max3_f32 v247, v247, v230, v231
	v_max3_f32 v246, v246, v232, v233
	v_max3_f32 v247, v247, v234, v235
	s_waitcnt lgkmcnt(8)
	v_mfma_f32_32x32x16_bf16 v[64:79], v[210:213], v[242:245], v[64:79]
	ds_read_b64_tr_b16 v[210:211], v205 offset:8192
	ds_read_b64_tr_b16 v[212:213], v205 offset:12288
	v_max3_f32 v246, v246, v236, v237
	v_max_f32_e32 v246, v246, v247
	v_mov_b32_e32 v247, v246
	v_add_f32_e32 v249, 0x41000000, v190
	s_nop 1
	s_waitcnt lgkmcnt(8)
	v_mfma_f32_32x32x16_bf16 v[48:63], v[128:131], v[242:245], v[48:63]
	ds_read_b64_tr_b16 v[128:129], v218 offset:8192
	ds_read_b64_tr_b16 v[130:131], v218 offset:12288
	v_permlane32_swap_b32_e32 v246, v247
	v_max_f32_e32 v246, v246, v247
	v_cmp_gt_f32_e32 vcc, v246, v249
	s_cbranch_vccnz .Latt_rs1_1A
	s_waitcnt lgkmcnt(8)
	v_mfma_f32_32x32x16_bf16 v[32:47], v[214:217], v[242:245], v[32:47]
	ds_read_b64_tr_b16 v[214:215], v219 offset:8192
	ds_read_b64_tr_b16 v[216:217], v219 offset:12288
	v_sub_f32_e32 v222, v222, v190
	v_exp_f32_e32 v222, v222
	v_sub_f32_e32 v223, v223, v190
	v_exp_f32_e32 v223, v223
	v_sub_f32_e32 v224, v224, v190
	s_waitcnt lgkmcnt(8)
	v_mfma_f32_32x32x16_bf16 v[16:31], v[238:241], v[242:245], v[16:31]
	ds_read_b64_tr_b16 v[238:239], v221 offset:8192
	ds_read_b64_tr_b16 v[240:241], v221 offset:12288
	v_add_f32_e32 v254, 0, v222
	v_exp_f32_e32 v224, v224
	v_sub_f32_e32 v225, v225, v190
	v_add_f32_e32 v254, v223, v254
	v_exp_f32_e32 v225, v225
	s_waitcnt lgkmcnt(8)
	v_mfma_f32_32x32x16_bf16 v[0:15], v[206:209], v[242:245], v[0:15]
	ds_read_b64_tr_b16 v[206:207], v205 offset:8448
	ds_read_b64_tr_b16 v[208:209], v205 offset:12544
	v_sub_f32_e32 v226, v226, v190
	v_add_f32_e32 v254, v224, v254
	v_exp_f32_e32 v226, v226
	v_sub_f32_e32 v227, v227, v190
	v_add_f32_e32 v254, v225, v254
	s_waitcnt lgkmcnt(8)
	v_mfma_f32_32x32x16_bf16 v[112:127], v[210:213], v[250:253], v[112:127]
	ds_read_b64_tr_b16 v[210:211], v218 offset:8448
	ds_read_b64_tr_b16 v[212:213], v218 offset:12544
	v_exp_f32_e32 v227, v227
	v_sub_f32_e32 v228, v228, v190
	v_add_f32_e32 v254, v226, v254
	v_exp_f32_e32 v228, v228
	v_sub_f32_e32 v229, v229, v190
	s_waitcnt lgkmcnt(8)
	v_mfma_f32_32x32x16_bf16 v[96:111], v[128:131], v[250:253], v[96:111]
	ds_read_b64_tr_b16 v[128:129], v219 offset:8448
	ds_read_b64_tr_b16 v[130:131], v219 offset:12544
	v_add_f32_e32 v254, v227, v254
	v_exp_f32_e32 v229, v229
	v_sub_f32_e32 v230, v230, v190
	v_add_f32_e32 v254, v228, v254
	s_waitcnt lgkmcnt(8)
	v_mfma_f32_32x32x16_bf16 v[80:95], v[214:217], v[250:253], v[80:95]
	ds_read_b64_tr_b16 v[214:215], v221 offset:8448
	ds_read_b64_tr_b16 v[216:217], v221 offset:12544
	v_exp_f32_e32 v230, v230
	v_sub_f32_e32 v231, v231, v190
	v_add_f32_e32 v254, v229, v254
	v_exp_f32_e32 v231, v231
	s_waitcnt lgkmcnt(8)
	v_mfma_f32_32x32x16_bf16 v[64:79], v[238:241], v[250:253], v[64:79]
	ds_read_b64_tr_b16 v[238:239], v205 offset:16384
	ds_read_b64_tr_b16 v[240:241], v205 offset:20480
	v_sub_f32_e32 v232, v232, v190
	v_add_f32_e32 v254, v230, v254
	v_exp_f32_e32 v232, v232
	v_sub_f32_e32 v233, v233, v190
	s_waitcnt lgkmcnt(8)
	v_mfma_f32_32x32x16_bf16 v[48:63], v[206:209], v[250:253], v[48:63]
	ds_read_b64_tr_b16 v[206:207], v218 offset:16384
	ds_read_b64_tr_b16 v[208:209], v218 offset:20480
	v_add_f32_e32 v254, v231, v254
	v_exp_f32_e32 v233, v233
	v_sub_f32_e32 v234, v234, v190
	v_add_f32_e32 v254, v232, v254
	s_waitcnt lgkmcnt(8)
	v_mfma_f32_32x32x16_bf16 v[32:47], v[210:213], v[250:253], v[32:47]
	ds_read_b64_tr_b16 v[210:211], v219 offset:16384
	ds_read_b64_tr_b16 v[212:213], v219 offset:20480
	v_exp_f32_e32 v234, v234
	v_sub_f32_e32 v235, v235, v190
	v_add_f32_e32 v254, v233, v254
	v_exp_f32_e32 v235, v235
	s_waitcnt lgkmcnt(8)
	v_mfma_f32_32x32x16_bf16 v[16:31], v[128:131], v[250:253], v[16:31]
	ds_read_b64_tr_b16 v[128:129], v221 offset:16384
	ds_read_b64_tr_b16 v[130:131], v221 offset:20480
	v_sub_f32_e32 v236, v236, v190
	v_add_f32_e32 v254, v234, v254
	v_exp_f32_e32 v236, v236
	v_sub_f32_e32 v237, v237, v190
	s_waitcnt lgkmcnt(8)
	v_mfma_f32_32x32x16_bf16 v[0:15], v[214:217], v[250:253], v[0:15]
	ds_read_b64_tr_b16 v[214:215], v205 offset:16640
	ds_read_b64_tr_b16 v[216:217], v205 offset:20736
	v_add_f32_e32 v254, v235, v254
	v_exp_f32_e32 v237, v237
	v_add_f32_e32 v254, v236, v254
	v_add_f32_e32 v254, v237, v254
	v_cvt_pk_bf16_f32 v242, v222, v223
	v_cvt_pk_bf16_f32 v243, v224, v225
	v_cvt_pk_bf16_f32 v244, v226, v227
	v_cvt_pk_bf16_f32 v245, v228, v229
	v_cvt_pk_bf16_f32 v250, v230, v231
	v_cvt_pk_bf16_f32 v251, v232, v233
	v_cvt_pk_bf16_f32 v252, v234, v235
	v_cvt_pk_bf16_f32 v253, v236, v237
	v_add_f32_e32 v195, v195, v254
	s_nop 1

.Latt_rs1_1F:
	s_waitcnt lgkmcnt(8)
	v_mfma_f32_32x32x16_bf16 v[32:47], v[214:217], v[242:245], v[32:47]
	ds_read_b64_tr_b16 v[214:215], v219 offset:8192
	ds_read_b64_tr_b16 v[216:217], v219 offset:12288
	s_waitcnt lgkmcnt(8)
	v_mfma_f32_32x32x16_bf16 v[16:31], v[238:241], v[242:245], v[16:31]
	ds_read_b64_tr_b16 v[238:239], v221 offset:8192
	ds_read_b64_tr_b16 v[240:241], v221 offset:12288
	s_waitcnt lgkmcnt(8)
	v_mfma_f32_32x32x16_bf16 v[0:15], v[206:209], v[242:245], v[0:15]
	ds_read_b64_tr_b16 v[206:207], v205 offset:8448
	ds_read_b64_tr_b16 v[208:209], v205 offset:12544
	s_waitcnt lgkmcnt(8)
	v_mfma_f32_32x32x16_bf16 v[112:127], v[210:213], v[250:253], v[112:127]
	ds_read_b64_tr_b16 v[210:211], v218 offset:8448
	ds_read_b64_tr_b16 v[212:213], v218 offset:12544
	s_waitcnt lgkmcnt(8)
	v_mfma_f32_32x32x16_bf16 v[96:111], v[128:131], v[250:253], v[96:111]
	ds_read_b64_tr_b16 v[128:129], v219 offset:8448
	ds_read_b64_tr_b16 v[130:131], v219 offset:12544
	s_waitcnt lgkmcnt(8)
	v_mfma_f32_32x32x16_bf16 v[80:95], v[214:217], v[250:253], v[80:95]
	ds_read_b64_tr_b16 v[214:215], v221 offset:8448
	ds_read_b64_tr_b16 v[216:217], v221 offset:12544
	s_waitcnt lgkmcnt(8)
	v_mfma_f32_32x32x16_bf16 v[64:79], v[238:241], v[250:253], v[64:79]
	ds_read_b64_tr_b16 v[238:239], v205 offset:16384
	ds_read_b64_tr_b16 v[240:241], v205 offset:20480
	s_waitcnt lgkmcnt(8)
	v_mfma_f32_32x32x16_bf16 v[48:63], v[206:209], v[250:253], v[48:63]
	ds_read_b64_tr_b16 v[206:207], v218 offset:16384
	ds_read_b64_tr_b16 v[208:209], v218 offset:20480
	s_waitcnt lgkmcnt(8)
	v_mfma_f32_32x32x16_bf16 v[32:47], v[210:213], v[250:253], v[32:47]
	ds_read_b64_tr_b16 v[210:211], v219 offset:16384
	ds_read_b64_tr_b16 v[212:213], v219 offset:20480
	s_waitcnt lgkmcnt(8)
	v_mfma_f32_32x32x16_bf16 v[16:31], v[128:131], v[250:253], v[16:31]
	ds_read_b64_tr_b16 v[128:129], v221 offset:16384
	ds_read_b64_tr_b16 v[130:131], v221 offset:20480
	s_waitcnt lgkmcnt(8)
	v_mfma_f32_32x32x16_bf16 v[0:15], v[214:217], v[250:253], v[0:15]
	ds_read_b64_tr_b16 v[214:215], v205 offset:16640
	ds_read_b64_tr_b16 v[216:217], v205 offset:20736
	s_nop 11
	v_max_f32_e32 v246, v190, v246
	v_sub_f32_e32 v190, v190, v246
	v_exp_f32_e32 v190, v190
	s_nop 0
	v_pk_mul_f32 v[126:127], v[126:127], v[190:191] op_sel_hi:[1,0]
	v_pk_mul_f32 v[124:125], v[124:125], v[190:191] op_sel_hi:[1,0]
	v_pk_mul_f32 v[122:123], v[122:123], v[190:191] op_sel_hi:[1,0]
	v_pk_mul_f32 v[120:121], v[120:121], v[190:191] op_sel_hi:[1,0]
	v_pk_mul_f32 v[118:119], v[118:119], v[190:191] op_sel_hi:[1,0]
	v_pk_mul_f32 v[116:117], v[116:117], v[190:191] op_sel_hi:[1,0]
	v_pk_mul_f32 v[114:115], v[114:115], v[190:191] op_sel_hi:[1,0]
	v_pk_mul_f32 v[112:113], v[112:113], v[190:191] op_sel_hi:[1,0]
	v_pk_mul_f32 v[110:111], v[110:111], v[190:191] op_sel_hi:[1,0]
	v_pk_mul_f32 v[108:109], v[108:109], v[190:191] op_sel_hi:[1,0]
	v_pk_mul_f32 v[106:107], v[106:107], v[190:191] op_sel_hi:[1,0]
	v_pk_mul_f32 v[104:105], v[104:105], v[190:191] op_sel_hi:[1,0]
	v_pk_mul_f32 v[102:103], v[102:103], v[190:191] op_sel_hi:[1,0]
	v_pk_mul_f32 v[100:101], v[100:101], v[190:191] op_sel_hi:[1,0]
	v_pk_mul_f32 v[98:99], v[98:99], v[190:191] op_sel_hi:[1,0]
	v_pk_mul_f32 v[96:97], v[96:97], v[190:191] op_sel_hi:[1,0]
	v_pk_mul_f32 v[94:95], v[94:95], v[190:191] op_sel_hi:[1,0]
	v_pk_mul_f32 v[92:93], v[92:93], v[190:191] op_sel_hi:[1,0]
	v_pk_mul_f32 v[90:91], v[90:91], v[190:191] op_sel_hi:[1,0]
	v_pk_mul_f32 v[88:89], v[88:89], v[190:191] op_sel_hi:[1,0]
	v_pk_mul_f32 v[86:87], v[86:87], v[190:191] op_sel_hi:[1,0]
	v_pk_mul_f32 v[84:85], v[84:85], v[190:191] op_sel_hi:[1,0]
	v_pk_mul_f32 v[82:83], v[82:83], v[190:191] op_sel_hi:[1,0]
	v_pk_mul_f32 v[80:81], v[80:81], v[190:191] op_sel_hi:[1,0]
	v_pk_mul_f32 v[78:79], v[78:79], v[190:191] op_sel_hi:[1,0]
	v_pk_mul_f32 v[76:77], v[76:77], v[190:191] op_sel_hi:[1,0]
	v_pk_mul_f32 v[74:75], v[74:75], v[190:191] op_sel_hi:[1,0]
	v_pk_mul_f32 v[72:73], v[72:73], v[190:191] op_sel_hi:[1,0]
	v_pk_mul_f32 v[70:71], v[70:71], v[190:191] op_sel_hi:[1,0]
	v_pk_mul_f32 v[68:69], v[68:69], v[190:191] op_sel_hi:[1,0]
	v_pk_mul_f32 v[66:67], v[66:67], v[190:191] op_sel_hi:[1,0]
	v_pk_mul_f32 v[64:65], v[64:65], v[190:191] op_sel_hi:[1,0]
	v_pk_mul_f32 v[62:63], v[62:63], v[190:191] op_sel_hi:[1,0]
	v_pk_mul_f32 v[60:61], v[60:61], v[190:191] op_sel_hi:[1,0]
	v_pk_mul_f32 v[58:59], v[58:59], v[190:191] op_sel_hi:[1,0]
	v_pk_mul_f32 v[56:57], v[56:57], v[190:191] op_sel_hi:[1,0]
	v_pk_mul_f32 v[54:55], v[54:55], v[190:191] op_sel_hi:[1,0]
	v_pk_mul_f32 v[52:53], v[52:53], v[190:191] op_sel_hi:[1,0]
	v_pk_mul_f32 v[50:51], v[50:51], v[190:191] op_sel_hi:[1,0]
	v_pk_mul_f32 v[48:49], v[48:49], v[190:191] op_sel_hi:[1,0]
	v_pk_mul_f32 v[46:47], v[46:47], v[190:191] op_sel_hi:[1,0]
	v_pk_mul_f32 v[44:45], v[44:45], v[190:191] op_sel_hi:[1,0]
	v_pk_mul_f32 v[42:43], v[42:43], v[190:191] op_sel_hi:[1,0]
	v_pk_mul_f32 v[40:41], v[40:41], v[190:191] op_sel_hi:[1,0]
	v_pk_mul_f32 v[38:39], v[38:39], v[190:191] op_sel_hi:[1,0]
	v_pk_mul_f32 v[36:37], v[36:37], v[190:191] op_sel_hi:[1,0]
	v_pk_mul_f32 v[34:35], v[34:35], v[190:191] op_sel_hi:[1,0]
	v_pk_mul_f32 v[32:33], v[32:33], v[190:191] op_sel_hi:[1,0]
	v_pk_mul_f32 v[30:31], v[30:31], v[190:191] op_sel_hi:[1,0]
	v_pk_mul_f32 v[28:29], v[28:29], v[190:191] op_sel_hi:[1,0]
	v_pk_mul_f32 v[26:27], v[26:27], v[190:191] op_sel_hi:[1,0]
	v_pk_mul_f32 v[24:25], v[24:25], v[190:191] op_sel_hi:[1,0]
	v_pk_mul_f32 v[22:23], v[22:23], v[190:191] op_sel_hi:[1,0]
	v_pk_mul_f32 v[20:21], v[20:21], v[190:191] op_sel_hi:[1,0]
	v_pk_mul_f32 v[18:19], v[18:19], v[190:191] op_sel_hi:[1,0]
	v_pk_mul_f32 v[16:17], v[16:17], v[190:191] op_sel_hi:[1,0]
	v_pk_mul_f32 v[14:15], v[14:15], v[190:191] op_sel_hi:[1,0]
	v_pk_mul_f32 v[12:13], v[12:13], v[190:191] op_sel_hi:[1,0]
	v_pk_mul_f32 v[10:11], v[10:11], v[190:191] op_sel_hi:[1,0]
	v_pk_mul_f32 v[8:9], v[8:9], v[190:191] op_sel_hi:[1,0]
	v_pk_mul_f32 v[6:7], v[6:7], v[190:191] op_sel_hi:[1,0]
	v_pk_mul_f32 v[4:5], v[4:5], v[190:191] op_sel_hi:[1,0]
	v_pk_mul_f32 v[2:3], v[2:3], v[190:191] op_sel_hi:[1,0]
	v_pk_mul_f32 v[0:1], v[0:1], v[190:191] op_sel_hi:[1,0]
	v_mul_f32_e32 v195, v195, v190
	v_mov_b32_e32 v190, v246
	v_sub_f32_e32 v222, v222, v190
	v_exp_f32_e32 v222, v222
	v_sub_f32_e32 v223, v223, v190
	v_exp_f32_e32 v223, v223
	v_sub_f32_e32 v224, v224, v190
	v_add_f32_e32 v254, 0, v222
	v_exp_f32_e32 v224, v224
	v_sub_f32_e32 v225, v225, v190
	v_add_f32_e32 v254, v223, v254
	v_exp_f32_e32 v225, v225
	v_sub_f32_e32 v226, v226, v190
	v_add_f32_e32 v254, v224, v254
	v_exp_f32_e32 v226, v226
	v_sub_f32_e32 v227, v227, v190
	v_add_f32_e32 v254, v225, v254
	v_exp_f32_e32 v227, v227
	v_sub_f32_e32 v228, v228, v190
	v_add_f32_e32 v254, v226, v254
	v_exp_f32_e32 v228, v228
	v_sub_f32_e32 v229, v229, v190
	v_add_f32_e32 v254, v227, v254
	v_exp_f32_e32 v229, v229
	v_sub_f32_e32 v230, v230, v190
	v_add_f32_e32 v254, v228, v254
	v_exp_f32_e32 v230, v230
	v_sub_f32_e32 v231, v231, v190
	v_add_f32_e32 v254, v229, v254
	v_exp_f32_e32 v231, v231
	v_sub_f32_e32 v232, v232, v190
	v_add_f32_e32 v254, v230, v254
	v_exp_f32_e32 v232, v232
	v_sub_f32_e32 v233, v233, v190
	v_add_f32_e32 v254, v231, v254
	v_exp_f32_e32 v233, v233
	v_sub_f32_e32 v234, v234, v190
	v_add_f32_e32 v254, v232, v254
	v_exp_f32_e32 v234, v234
	v_sub_f32_e32 v235, v235, v190
	v_add_f32_e32 v254, v233, v254
	v_exp_f32_e32 v235, v235
	v_sub_f32_e32 v236, v236, v190
	v_add_f32_e32 v254, v234, v254
	v_exp_f32_e32 v236, v236
	v_sub_f32_e32 v237, v237, v190
	v_add_f32_e32 v254, v235, v254
	v_exp_f32_e32 v237, v237
	v_add_f32_e32 v254, v236, v254
	v_add_f32_e32 v254, v237, v254
	v_cvt_pk_bf16_f32 v242, v222, v223
	v_cvt_pk_bf16_f32 v243, v224, v225
	v_cvt_pk_bf16_f32 v244, v226, v227
	v_cvt_pk_bf16_f32 v245, v228, v229
	v_cvt_pk_bf16_f32 v250, v230, v231
	v_cvt_pk_bf16_f32 v251, v232, v233
	v_cvt_pk_bf16_f32 v252, v234, v235
	v_cvt_pk_bf16_f32 v253, v236, v237
	v_add_f32_e32 v195, v195, v254
	s_nop 1
	s_branch .Latt_pv1_1F
	s_lshl_b32 s89, s33, 14
	s_add_i32 s90, s89, 0
	v_add_u32_e32 v207, s90, v196
	ds_read_b128 v[128:131], v207
	v_add_u32_e32 v208, s90, v197
	ds_read_b128 v[210:213], v208
	v_add_u32_e32 v209, s90, v198
	v_lshrrev_b32_e32 v205, 3, v204
	s_add_i32 s91, s4, 31
	v_and_or_b32 v206, v204, 31, s83
	s_cmp_le_i32 s91, s83
	s_waitcnt lgkmcnt(1)
	v_mfma_f32_32x32x16_bf16 v[128:143], v[128:131], v[144:147], 0
	s_waitcnt lgkmcnt(0)
	v_mfma_f32_32x32x16_bf16 v[128:143], v[210:213], v[148:151], v[128:143]
	ds_read_b128 v[212:215], v209
	v_add_u32_e32 v210, s90, v199
	v_add_u32_e32 v211, s90, v200
	s_waitcnt lgkmcnt(0)
	v_mfma_f32_32x32x16_bf16 v[128:143], v[212:215], v[152:155], v[128:143]
	ds_read_b128 v[212:215], v210
	s_waitcnt lgkmcnt(0)
	v_mfma_f32_32x32x16_bf16 v[128:143], v[212:215], v[156:159], v[128:143]
	ds_read_b128 v[214:217], v211
	v_add_u32_e32 v212, s90, v201
	v_add_u32_e32 v213, s90, v202
	s_waitcnt lgkmcnt(0)
	v_mfma_f32_32x32x16_bf16 v[128:143], v[214:217], v[160:163], v[128:143]
	ds_read_b128 v[214:217], v212
	s_waitcnt lgkmcnt(0)
	v_mfma_f32_32x32x16_bf16 v[128:143], v[214:217], v[164:167], v[128:143]
	ds_read_b128 v[216:219], v213
	v_add_u32_e32 v215, s90, v203
	v_and_b32_e32 v214, 4, v205
	s_waitcnt lgkmcnt(0)
	v_mfma_f32_32x32x16_bf16 v[128:143], v[216:219], v[168:171], v[128:143]
	ds_read_b128 v[216:219], v215
	s_waitcnt lgkmcnt(0)
	v_mfma_f32_32x32x16_bf16 v[128:143], v[216:219], v[172:175], v[128:143]
	s_cbranch_scc1 .LBB0_869
	v_add_u32_e32 v205, s4, v214
	v_cmp_lt_i32_e32 vcc, v205, v206
	v_add_u32_e32 v216, 2, v205
	s_nop 7
	v_cndmask_b32_e32 v129, v192, v129, vcc
	v_cmp_le_i32_e32 vcc, v205, v206
	s_nop 1
	v_cndmask_b32_e32 v128, v192, v128, vcc
	v_cmp_le_i32_e32 vcc, v216, v206
	v_add_u32_e32 v216, 3, v205
	s_nop 0
	v_cndmask_b32_e32 v130, v192, v130, vcc
	v_cmp_le_i32_e32 vcc, v216, v206
	v_add_u32_e32 v216, 8, v205
	s_nop 0
	v_cndmask_b32_e32 v131, v192, v131, vcc
	v_cmp_le_i32_e32 vcc, v216, v206
	v_add_u32_e32 v216, 9, v205
	s_nop 0
	v_cndmask_b32_e32 v132, v192, v132, vcc
	v_cmp_le_i32_e32 vcc, v216, v206
	v_add_u32_e32 v216, 10, v205
	s_nop 0
	v_cndmask_b32_e32 v133, v192, v133, vcc
	v_cmp_le_i32_e32 vcc, v216, v206
	v_add_u32_e32 v216, 11, v205
	s_nop 0
	v_cndmask_b32_e32 v134, v192, v134, vcc
	v_cmp_le_i32_e32 vcc, v216, v206
	v_add_u32_e32 v216, 16, v205
	s_nop 0
	v_cndmask_b32_e32 v135, v192, v135, vcc
	v_cmp_le_i32_e32 vcc, v216, v206
	v_add_u32_e32 v216, 17, v205
	s_nop 0
	v_cndmask_b32_e32 v136, v192, v136, vcc
	v_cmp_le_i32_e32 vcc, v216, v206
	v_add_u32_e32 v216, 18, v205
	s_nop 0
	v_cndmask_b32_e32 v137, v192, v137, vcc
	v_cmp_le_i32_e32 vcc, v216, v206
	v_add_u32_e32 v216, 19, v205
	s_nop 0
	v_cndmask_b32_e32 v138, v192, v138, vcc
	v_cmp_le_i32_e32 vcc, v216, v206
	v_add_u32_e32 v216, 24, v205
	s_nop 0
	v_cndmask_b32_e32 v139, v192, v139, vcc
	v_cmp_le_i32_e32 vcc, v216, v206
	v_add_u32_e32 v216, 25, v205
	s_nop 0
	v_cndmask_b32_e32 v140, v192, v140, vcc
	v_cmp_le_i32_e32 vcc, v216, v206
	v_add_u32_e32 v216, 26, v205
	v_add_u32_e32 v205, 27, v205
	v_cndmask_b32_e32 v141, v192, v141, vcc
	v_cmp_le_i32_e32 vcc, v216, v206
	s_nop 1
	v_cndmask_b32_e32 v142, v192, v142, vcc
	v_cmp_le_i32_e32 vcc, v205, v206
	s_nop 1
	v_cndmask_b32_e32 v143, v192, v143, vcc

.LBB0_883:
	s_cmp_ge_u32 s85, s78
	s_cselect_b64 s[12:13], -1, 0
	v_mov_b32_e32 v204, v176
	s_and_b64 vcc, exec, s[12:13]
	s_cbranch_vccnz .LBB0_885
	s_cmp_le_i32 s84, s81
	s_cbranch_scc1 .LBB0_885
	v_sub_co_u32_e64 v128, s[14:15], s38, 1
	s_nop 1
	v_cndmask_b32_e64 v130, v128, 2, s[14:15]
	v_lshlrev_b32_e32 v128, 14, v130
	v_add_u32_e32 v131, s40, v128
	v_lshl_add_u64 v[128:129], s[22:23], 0, v[178:179]
	s_add_u32 s14, s22, 0x1000
	v_readfirstlane_b32 s39, v131
	s_mov_b32 s52, m0
	s_mov_b32 m0, s39
	s_nop 0
	global_load_lds_dwordx4 v[128:129], off
	s_mov_b32 m0, s52
	v_lshl_add_u64 v[128:129], s[22:23], 0, v[180:181]
	s_addc_u32 s15, s23, 0
	s_addk_i32 s39, 0x400
	s_mov_b32 s52, m0
	s_mov_b32 m0, s39
	s_nop 0
	global_load_lds_dwordx4 v[128:129], off
	s_mov_b32 m0, s52
	v_lshlrev_b32_e32 v128, 15, v130
	v_add_u32_e32 v130, s41, v128
	v_lshl_add_u64 v[128:129], s[14:15], 0, v[182:183]
	v_readfirstlane_b32 s39, v130
	s_mov_b32 s52, m0
	s_mov_b32 m0, s39
	s_nop 0
	global_load_lds_dwordx4 v[128:129], off
	s_mov_b32 m0, s52
	v_lshl_add_u64 v[128:129], s[14:15], 0, v[184:185]
	s_add_i32 s52, s39, 0x400
	s_mov_b32 s53, m0
	s_mov_b32 m0, s52
	s_nop 0
	global_load_lds_dwordx4 v[128:129], off
	s_mov_b32 m0, s53
	v_lshl_add_u64 v[128:129], s[14:15], 0, v[186:187]
	s_add_i32 s52, s39, 0x800
	s_mov_b32 s53, m0
	s_mov_b32 m0, s52
	s_nop 0
	global_load_lds_dwordx4 v[128:129], off
	s_mov_b32 m0, s53
	v_lshl_add_u64 v[128:129], s[14:15], 0, v[188:189]
	s_add_i32 s14, s39, 0xc00
	s_mov_b32 s15, m0
	s_mov_b32 m0, s14
	s_nop 0
	global_load_lds_dwordx4 v[128:129], off
	s_mov_b32 m0, s15
.LBB0_885:
	s_cmp_gt_i32 s84, s81
	s_cbranch_scc1 .LBB0_896
	s_add_i32 s100, s84, 63
	s_cmp_le_i32 s100, s80
	s_cbranch_scc1 .Latt_full_2
	s_add_i32 s100, s84, 32
	s_cmp_le_i32 s100, s81
	s_cbranch_scc1 .Latt_diagA_2
	s_lshl_b32 s98, s38, 14
	s_lshl_b32 s99, s38, 15
	s_add_i32 s99, s99, 0xc000
	v_add_u32_e32 v206, s98, v195
	ds_read_b128 v[206:209], v206
	v_add_u32_e32 v210, s98, v196
	ds_read_b128 v[210:213], v210
	v_add_u32_e32 v214, s98, v197
	ds_read_b128 v[214:217], v214
	v_add_u32_e32 v238, s98, v198
	ds_read_b128 v[238:241], v238
	v_add_u32_e32 v242, s98, v199
	ds_read_b128 v[242:245], v242
	v_add_u32_e32 v250, s98, v200
	ds_read_b128 v[250:253], v250
	v_add_u32_e32 v222, s98, v201
	ds_read_b128 v[222:225], v222
	v_add_u32_e32 v226, s98, v202
	ds_read_b128 v[226:229], v226
	v_bfe_u32 v246, v204, 2, 2
	v_bfe_u32 v247, v204, 5, 1
	v_lshl_or_b32 v247, v247, 2, v246
	v_and_b32_e32 v249, 3, v204
	v_and_b32_e32 v254, 16, v204
	v_lshl_or_b32 v249, v249, 2, v254
	v_lshlrev_b32_e32 v249, 1, v249
	v_lshl_add_u32 v247, v247, 9, v249
	v_add_u32_e32 v247, s99, v247
	v_lshlrev_b32_e32 v246, 6, v246
	v_add_u32_e32 v205, v247, v246
	v_xor_b32_e32 v249, 64, v246
	v_add_u32_e32 v218, v247, v249
	v_xor_b32_e32 v249, 0x80, v246
	v_add_u32_e32 v219, v247, v249
	v_xor_b32_e32 v249, 0xc0, v246
	v_add_u32_e32 v221, v247, v249
	s_waitcnt lgkmcnt(7)
	v_mfma_f32_32x32x16_bf16 v[128:143], v[206:209], v[144:147], 0
	ds_read_b64_tr_b16 v[206:207], v205
	ds_read_b64_tr_b16 v[208:209], v205 offset:4096
	s_waitcnt lgkmcnt(8)
	v_mfma_f32_32x32x16_bf16 v[128:143], v[210:213], v[148:151], v[128:143]
	ds_read_b64_tr_b16 v[210:211], v218
	ds_read_b64_tr_b16 v[212:213], v218 offset:4096
	s_waitcnt lgkmcnt(9)
	v_mfma_f32_32x32x16_bf16 v[128:143], v[214:217], v[152:155], v[128:143]
	s_waitcnt lgkmcnt(8)
	v_mfma_f32_32x32x16_bf16 v[128:143], v[238:241], v[156:159], v[128:143]
	ds_read_b64_tr_b16 v[214:215], v219
	ds_read_b64_tr_b16 v[216:217], v219 offset:4096
	s_waitcnt lgkmcnt(9)
	v_mfma_f32_32x32x16_bf16 v[128:143], v[242:245], v[160:163], v[128:143]
	s_waitcnt lgkmcnt(8)
	v_mfma_f32_32x32x16_bf16 v[128:143], v[250:253], v[164:167], v[128:143]
	ds_read_b64_tr_b16 v[238:239], v221
	ds_read_b64_tr_b16 v[240:241], v221 offset:4096
	s_waitcnt lgkmcnt(9)
	v_mfma_f32_32x32x16_bf16 v[128:143], v[222:225], v[168:171], v[128:143]
	s_waitcnt lgkmcnt(8)
	v_mfma_f32_32x32x16_bf16 v[128:143], v[226:229], v[172:175], v[128:143]
	s_nop 11
	v_and_or_b32 v246, v204, 31, s80
	v_bfe_u32 v247, v204, 5, 1
	s_add_i32 s100, s84, 0
	v_lshl_add_u32 v247, v247, 2, s100
	v_add_u32_e32 v249, 0, v247
	v_cmp_le_i32_e32 vcc, v249, v246
	v_add_u32_e32 v254, 1, v247
	s_nop 0
	v_cndmask_b32_e32 v128, v192, v128, vcc
	v_cmp_le_i32_e32 vcc, v254, v246
	v_add_u32_e32 v249, 2, v247
	s_nop 0
	v_cndmask_b32_e32 v129, v192, v129, vcc
	v_cmp_le_i32_e32 vcc, v249, v246
	v_add_u32_e32 v254, 3, v247
	s_nop 0
	v_cndmask_b32_e32 v130, v192, v130, vcc
	v_cmp_le_i32_e32 vcc, v254, v246
	v_add_u32_e32 v249, 8, v247
	s_nop 0
	v_cndmask_b32_e32 v131, v192, v131, vcc
	v_cmp_le_i32_e32 vcc, v249, v246
	v_add_u32_e32 v254, 9, v247
	s_nop 0
	v_cndmask_b32_e32 v132, v192, v132, vcc
	v_cmp_le_i32_e32 vcc, v254, v246
	v_add_u32_e32 v249, 10, v247
	s_nop 0
	v_cndmask_b32_e32 v133, v192, v133, vcc
	v_cmp_le_i32_e32 vcc, v249, v246
	v_add_u32_e32 v254, 11, v247
	s_nop 0
	v_cndmask_b32_e32 v134, v192, v134, vcc
	v_cmp_le_i32_e32 vcc, v254, v246
	v_add_u32_e32 v249, 16, v247
	s_nop 0
	v_cndmask_b32_e32 v135, v192, v135, vcc
	v_cmp_le_i32_e32 vcc, v249, v246
	v_add_u32_e32 v254, 17, v247
	s_nop 0
	v_cndmask_b32_e32 v136, v192, v136, vcc
	v_cmp_le_i32_e32 vcc, v254, v246
	v_add_u32_e32 v249, 18, v247
	s_nop 0
	v_cndmask_b32_e32 v137, v192, v137, vcc
	v_cmp_le_i32_e32 vcc, v249, v246
	v_add_u32_e32 v254, 19, v247
	s_nop 0
	v_cndmask_b32_e32 v138, v192, v138, vcc
	v_cmp_le_i32_e32 vcc, v254, v246
	v_add_u32_e32 v249, 24, v247
	s_nop 0
	v_cndmask_b32_e32 v139, v192, v139, vcc
	v_cmp_le_i32_e32 vcc, v249, v246
	v_add_u32_e32 v254, 25, v247
	s_nop 0
	v_cndmask_b32_e32 v140, v192, v140, vcc
	v_cmp_le_i32_e32 vcc, v254, v246
	v_add_u32_e32 v249, 26, v247
	s_nop 0
	v_cndmask_b32_e32 v141, v192, v141, vcc
	v_cmp_le_i32_e32 vcc, v249, v246
	v_add_u32_e32 v254, 27, v247
	s_nop 0
	v_cndmask_b32_e32 v142, v192, v142, vcc
	v_cmp_le_i32_e32 vcc, v254, v246
	s_nop 1
	v_cndmask_b32_e32 v143, v192, v143, vcc
	v_max3_f32 v246, v128, v129, v130
	v_max3_f32 v247, v131, v132, v133
	v_max3_f32 v246, v246, v134, v135
	v_max3_f32 v247, v247, v136, v137
	v_max3_f32 v246, v246, v138, v139
	v_max3_f32 v247, v247, v140, v141
	v_max3_f32 v246, v246, v142, v143
	v_max_f32_e32 v246, v246, v247
	v_mov_b32_e32 v247, v246
	v_add_f32_e32 v249, 0x41000000, v190
	s_nop 1
	v_permlane32_swap_b32_e32 v246, v247
	v_max_f32_e32 v246, v246, v247
	v_cmp_gt_f32_e32 vcc, v246, v249
	s_cbranch_vccz .Latt_nr0_2B
	v_max_f32_e32 v246, v190, v246
	v_sub_f32_e32 v190, v190, v246
	v_exp_f32_e32 v190, v190
	s_nop 0
	v_pk_mul_f32 v[126:127], v[126:127], v[190:191] op_sel_hi:[1,0]
	v_pk_mul_f32 v[124:125], v[124:125], v[190:191] op_sel_hi:[1,0]
	v_pk_mul_f32 v[122:123], v[122:123], v[190:191] op_sel_hi:[1,0]
	v_pk_mul_f32 v[120:121], v[120:121], v[190:191] op_sel_hi:[1,0]
	v_pk_mul_f32 v[118:119], v[118:119], v[190:191] op_sel_hi:[1,0]
	v_pk_mul_f32 v[116:117], v[116:117], v[190:191] op_sel_hi:[1,0]
	v_pk_mul_f32 v[114:115], v[114:115], v[190:191] op_sel_hi:[1,0]
	v_pk_mul_f32 v[112:113], v[112:113], v[190:191] op_sel_hi:[1,0]
	v_pk_mul_f32 v[110:111], v[110:111], v[190:191] op_sel_hi:[1,0]
	v_pk_mul_f32 v[108:109], v[108:109], v[190:191] op_sel_hi:[1,0]
	v_pk_mul_f32 v[106:107], v[106:107], v[190:191] op_sel_hi:[1,0]
	v_pk_mul_f32 v[104:105], v[104:105], v[190:191] op_sel_hi:[1,0]
	v_pk_mul_f32 v[102:103], v[102:103], v[190:191] op_sel_hi:[1,0]
	v_pk_mul_f32 v[100:101], v[100:101], v[190:191] op_sel_hi:[1,0]
	v_pk_mul_f32 v[98:99], v[98:99], v[190:191] op_sel_hi:[1,0]
	v_pk_mul_f32 v[96:97], v[96:97], v[190:191] op_sel_hi:[1,0]
	v_pk_mul_f32 v[94:95], v[94:95], v[190:191] op_sel_hi:[1,0]
	v_pk_mul_f32 v[92:93], v[92:93], v[190:191] op_sel_hi:[1,0]
	v_pk_mul_f32 v[90:91], v[90:91], v[190:191] op_sel_hi:[1,0]
	v_pk_mul_f32 v[88:89], v[88:89], v[190:191] op_sel_hi:[1,0]
	v_pk_mul_f32 v[86:87], v[86:87], v[190:191] op_sel_hi:[1,0]
	v_pk_mul_f32 v[84:85], v[84:85], v[190:191] op_sel_hi:[1,0]
	v_pk_mul_f32 v[82:83], v[82:83], v[190:191] op_sel_hi:[1,0]
	v_pk_mul_f32 v[80:81], v[80:81], v[190:191] op_sel_hi:[1,0]
	v_pk_mul_f32 v[78:79], v[78:79], v[190:191] op_sel_hi:[1,0]
	v_pk_mul_f32 v[76:77], v[76:77], v[190:191] op_sel_hi:[1,0]
	v_pk_mul_f32 v[74:75], v[74:75], v[190:191] op_sel_hi:[1,0]
	v_pk_mul_f32 v[72:73], v[72:73], v[190:191] op_sel_hi:[1,0]
	v_pk_mul_f32 v[70:71], v[70:71], v[190:191] op_sel_hi:[1,0]
	v_pk_mul_f32 v[68:69], v[68:69], v[190:191] op_sel_hi:[1,0]
	v_pk_mul_f32 v[66:67], v[66:67], v[190:191] op_sel_hi:[1,0]
	v_pk_mul_f32 v[64:65], v[64:65], v[190:191] op_sel_hi:[1,0]
	v_pk_mul_f32 v[62:63], v[62:63], v[190:191] op_sel_hi:[1,0]
	v_pk_mul_f32 v[60:61], v[60:61], v[190:191] op_sel_hi:[1,0]
	v_pk_mul_f32 v[58:59], v[58:59], v[190:191] op_sel_hi:[1,0]
	v_pk_mul_f32 v[56:57], v[56:57], v[190:191] op_sel_hi:[1,0]
	v_pk_mul_f32 v[54:55], v[54:55], v[190:191] op_sel_hi:[1,0]
	v_pk_mul_f32 v[52:53], v[52:53], v[190:191] op_sel_hi:[1,0]
	v_pk_mul_f32 v[50:51], v[50:51], v[190:191] op_sel_hi:[1,0]
	v_pk_mul_f32 v[48:49], v[48:49], v[190:191] op_sel_hi:[1,0]
	v_pk_mul_f32 v[46:47], v[46:47], v[190:191] op_sel_hi:[1,0]
	v_pk_mul_f32 v[44:45], v[44:45], v[190:191] op_sel_hi:[1,0]
	v_pk_mul_f32 v[42:43], v[42:43], v[190:191] op_sel_hi:[1,0]
	v_pk_mul_f32 v[40:41], v[40:41], v[190:191] op_sel_hi:[1,0]
	v_pk_mul_f32 v[38:39], v[38:39], v[190:191] op_sel_hi:[1,0]
	v_pk_mul_f32 v[36:37], v[36:37], v[190:191] op_sel_hi:[1,0]
	v_pk_mul_f32 v[34:35], v[34:35], v[190:191] op_sel_hi:[1,0]
	v_pk_mul_f32 v[32:33], v[32:33], v[190:191] op_sel_hi:[1,0]
	v_pk_mul_f32 v[30:31], v[30:31], v[190:191] op_sel_hi:[1,0]
	v_pk_mul_f32 v[28:29], v[28:29], v[190:191] op_sel_hi:[1,0]
	v_pk_mul_f32 v[26:27], v[26:27], v[190:191] op_sel_hi:[1,0]
	v_pk_mul_f32 v[24:25], v[24:25], v[190:191] op_sel_hi:[1,0]
	v_pk_mul_f32 v[22:23], v[22:23], v[190:191] op_sel_hi:[1,0]
	v_pk_mul_f32 v[20:21], v[20:21], v[190:191] op_sel_hi:[1,0]
	v_pk_mul_f32 v[18:19], v[18:19], v[190:191] op_sel_hi:[1,0]
	v_pk_mul_f32 v[16:17], v[16:17], v[190:191] op_sel_hi:[1,0]
	v_pk_mul_f32 v[14:15], v[14:15], v[190:191] op_sel_hi:[1,0]
	v_pk_mul_f32 v[12:13], v[12:13], v[190:191] op_sel_hi:[1,0]
	v_pk_mul_f32 v[10:11], v[10:11], v[190:191] op_sel_hi:[1,0]
	v_pk_mul_f32 v[8:9], v[8:9], v[190:191] op_sel_hi:[1,0]
	v_pk_mul_f32 v[6:7], v[6:7], v[190:191] op_sel_hi:[1,0]
	v_pk_mul_f32 v[4:5], v[4:5], v[190:191] op_sel_hi:[1,0]
	v_pk_mul_f32 v[2:3], v[2:3], v[190:191] op_sel_hi:[1,0]
	v_pk_mul_f32 v[0:1], v[0:1], v[190:191] op_sel_hi:[1,0]
	v_mul_f32_e32 v203, v203, v190
	v_mov_b32_e32 v190, v246
.Latt_nr0_2B:
	v_sub_f32_e32 v128, v128, v190
	v_exp_f32_e32 v128, v128
	v_sub_f32_e32 v129, v129, v190
	v_exp_f32_e32 v129, v129
	v_sub_f32_e32 v130, v130, v190
	v_add_f32_e32 v254, 0, v128
	v_exp_f32_e32 v130, v130
	v_sub_f32_e32 v131, v131, v190
	v_add_f32_e32 v254, v129, v254
	v_exp_f32_e32 v131, v131
	v_sub_f32_e32 v132, v132, v190
	v_add_f32_e32 v254, v130, v254
	v_exp_f32_e32 v132, v132
	v_sub_f32_e32 v133, v133, v190
	v_add_f32_e32 v254, v131, v254
	v_exp_f32_e32 v133, v133
	v_sub_f32_e32 v134, v134, v190
	v_add_f32_e32 v254, v132, v254
	v_exp_f32_e32 v134, v134
	v_sub_f32_e32 v135, v135, v190
	v_add_f32_e32 v254, v133, v254
	v_exp_f32_e32 v135, v135
	v_sub_f32_e32 v136, v136, v190
	v_add_f32_e32 v254, v134, v254
	v_exp_f32_e32 v136, v136
	v_sub_f32_e32 v137, v137, v190
	v_add_f32_e32 v254, v135, v254
	v_exp_f32_e32 v137, v137
	v_sub_f32_e32 v138, v138, v190
	v_add_f32_e32 v254, v136, v254
	v_exp_f32_e32 v138, v138
	v_sub_f32_e32 v139, v139, v190
	v_add_f32_e32 v254, v137, v254
	v_exp_f32_e32 v139, v139
	v_sub_f32_e32 v140, v140, v190
	v_add_f32_e32 v254, v138, v254
	v_exp_f32_e32 v140, v140
	v_sub_f32_e32 v141, v141, v190
	v_add_f32_e32 v254, v139, v254
	v_exp_f32_e32 v141, v141
	v_sub_f32_e32 v142, v142, v190
	v_add_f32_e32 v254, v140, v254
	v_exp_f32_e32 v142, v142
	v_sub_f32_e32 v143, v143, v190
	v_add_f32_e32 v254, v141, v254
	v_exp_f32_e32 v143, v143
	v_add_f32_e32 v254, v142, v254
	v_add_f32_e32 v254, v143, v254
	v_cvt_pk_bf16_f32 v242, v128, v129
	v_cvt_pk_bf16_f32 v243, v130, v131
	v_cvt_pk_bf16_f32 v244, v132, v133
	v_cvt_pk_bf16_f32 v245, v134, v135
	v_cvt_pk_bf16_f32 v250, v136, v137
	v_cvt_pk_bf16_f32 v251, v138, v139
	v_cvt_pk_bf16_f32 v252, v140, v141
	v_cvt_pk_bf16_f32 v253, v142, v143
	v_add_f32_e32 v203, v203, v254
	s_nop 1
	ds_read_b64_tr_b16 v[128:129], v205 offset:256
	ds_read_b64_tr_b16 v[130:131], v205 offset:4352
	s_waitcnt lgkmcnt(8)
	v_mfma_f32_32x32x16_bf16 v[112:127], v[206:209], v[242:245], v[112:127]
	ds_read_b64_tr_b16 v[206:207], v218 offset:256
	ds_read_b64_tr_b16 v[208:209], v218 offset:4352
	s_waitcnt lgkmcnt(8)
	v_mfma_f32_32x32x16_bf16 v[96:111], v[210:213], v[242:245], v[96:111]
	ds_read_b64_tr_b16 v[210:211], v219 offset:256
	ds_read_b64_tr_b16 v[212:213], v219 offset:4352
	s_cmp_lg_u64 s[12:13], 0
	s_cbranch_scc1 .Latt_nd0_2B
	s_sub_i32 s100, s38, 1
	s_cmp_eq_u32 s38, 0
	s_cselect_b32 s100, 2, s100
	s_lshl_b32 s101, s100, 14
	s_add_i32 m0, s40, s101
	s_nop 0
	global_load_lds_dwordx4 v178, s[22:23]
.Latt_nd0_2B:
	s_waitcnt lgkmcnt(8)
	v_mfma_f32_32x32x16_bf16 v[80:95], v[214:217], v[242:245], v[80:95]
	ds_read_b64_tr_b16 v[214:215], v221 offset:256
	ds_read_b64_tr_b16 v[216:217], v221 offset:4352
	s_waitcnt lgkmcnt(8)
	v_mfma_f32_32x32x16_bf16 v[64:79], v[238:241], v[242:245], v[64:79]
	ds_read_b64_tr_b16 v[238:239], v205 offset:8192
	ds_read_b64_tr_b16 v[240:241], v205 offset:12288
	s_cmp_lg_u64 s[12:13], 0
	s_cbranch_scc1 .Latt_nd1_2B
	s_add_i32 m0, m0, 0x400
	s_nop 0
	global_load_lds_dwordx4 v180, s[22:23]
.Latt_nd1_2B:
	s_waitcnt lgkmcnt(8)
	v_mfma_f32_32x32x16_bf16 v[48:63], v[128:131], v[242:245], v[48:63]
	ds_read_b64_tr_b16 v[128:129], v218 offset:8192
	ds_read_b64_tr_b16 v[130:131], v218 offset:12288
	s_waitcnt lgkmcnt(8)
	v_mfma_f32_32x32x16_bf16 v[32:47], v[206:209], v[242:245], v[32:47]
	ds_read_b64_tr_b16 v[206:207], v219 offset:8192
	ds_read_b64_tr_b16 v[208:209], v219 offset:12288
	s_cmp_lg_u64 s[12:13], 0
	s_cbranch_scc1 .Latt_nd2_2B
	s_lshl_b32 s101, s100, 15
	s_add_i32 m0, s41, s101
	s_add_u32 s100, s22, 0x1000
	s_addc_u32 s101, s23, 0
	global_load_lds_dwordx4 v182, s[100:101]
.Latt_nd2_2B:
	s_waitcnt lgkmcnt(8)
	v_mfma_f32_32x32x16_bf16 v[16:31], v[210:213], v[242:245], v[16:31]
	ds_read_b64_tr_b16 v[210:211], v221 offset:8192
	ds_read_b64_tr_b16 v[212:213], v221 offset:12288
	s_waitcnt lgkmcnt(8)
	v_mfma_f32_32x32x16_bf16 v[0:15], v[214:217], v[242:245], v[0:15]
	ds_read_b64_tr_b16 v[214:215], v205 offset:8448
	ds_read_b64_tr_b16 v[216:217], v205 offset:12544
	s_cmp_lg_u64 s[12:13], 0
	s_cbranch_scc1 .Latt_nd3_2B
	s_add_i32 m0, m0, 0x400
	s_nop 0
	global_load_lds_dwordx4 v184, s[100:101]
.Latt_nd3_2B:
	s_waitcnt lgkmcnt(8)
	v_mfma_f32_32x32x16_bf16 v[112:127], v[238:241], v[250:253], v[112:127]
	ds_read_b64_tr_b16 v[238:239], v218 offset:8448
	ds_read_b64_tr_b16 v[240:241], v218 offset:12544
	s_waitcnt lgkmcnt(8)
	v_mfma_f32_32x32x16_bf16 v[96:111], v[128:131], v[250:253], v[96:111]
	ds_read_b64_tr_b16 v[128:129], v219 offset:8448
	ds_read_b64_tr_b16 v[130:131], v219 offset:12544
	s_cmp_lg_u64 s[12:13], 0
	s_cbranch_scc1 .Latt_nd4_2B
	s_add_i32 m0, m0, 0x400
	s_nop 0
	global_load_lds_dwordx4 v186, s[100:101]
.Latt_nd4_2B:
	s_waitcnt lgkmcnt(8)
	v_mfma_f32_32x32x16_bf16 v[80:95], v[206:209], v[250:253], v[80:95]
	ds_read_b64_tr_b16 v[206:207], v221 offset:8448
	ds_read_b64_tr_b16 v[208:209], v221 offset:12544
	s_waitcnt lgkmcnt(8)
	v_mfma_f32_32x32x16_bf16 v[64:79], v[210:213], v[250:253], v[64:79]
	s_cmp_lg_u64 s[12:13], 0
	s_cbranch_scc1 .Latt_nd5_2B
	s_add_i32 m0, m0, 0x400
	s_nop 0
	global_load_lds_dwordx4 v188, s[100:101]

.Latt_diagA_2:
	s_lshl_b32 s98, s38, 14
	s_lshl_b32 s99, s38, 15
	s_add_i32 s99, s99, 0xc000
	v_add_u32_e32 v206, s98, v195
	ds_read_b128 v[206:209], v206
	v_add_u32_e32 v210, s98, v196
	ds_read_b128 v[210:213], v210
	v_add_u32_e32 v214, s98, v197
	ds_read_b128 v[214:217], v214
	v_add_u32_e32 v238, s98, v198
	ds_read_b128 v[238:241], v238
	v_add_u32_e32 v242, s98, v199
	ds_read_b128 v[242:245], v242
	v_add_u32_e32 v250, s98, v200
	ds_read_b128 v[250:253], v250
	v_add_u32_e32 v222, s98, v201
	ds_read_b128 v[222:225], v222
	v_add_u32_e32 v226, s98, v202
	ds_read_b128 v[226:229], v226
	v_bfe_u32 v246, v204, 2, 2
	v_bfe_u32 v247, v204, 5, 1
	v_lshl_or_b32 v247, v247, 2, v246
	v_and_b32_e32 v249, 3, v204
	v_and_b32_e32 v254, 16, v204
	v_lshl_or_b32 v249, v249, 2, v254
	v_lshlrev_b32_e32 v249, 1, v249
	v_lshl_add_u32 v247, v247, 9, v249
	v_add_u32_e32 v247, s99, v247
	v_lshlrev_b32_e32 v246, 6, v246
	v_add_u32_e32 v205, v247, v246
	v_xor_b32_e32 v249, 64, v246
	v_add_u32_e32 v218, v247, v249
	v_xor_b32_e32 v249, 0x80, v246
	v_add_u32_e32 v219, v247, v249
	v_xor_b32_e32 v249, 0xc0, v246
	v_add_u32_e32 v221, v247, v249
	s_waitcnt lgkmcnt(7)
	v_mfma_f32_32x32x16_bf16 v[128:143], v[206:209], v[144:147], 0
	v_add_u32_e32 v206, s98, v195
	ds_read_b128 v[206:209], v206 offset:8192
	s_waitcnt lgkmcnt(7)
	v_mfma_f32_32x32x16_bf16 v[128:143], v[210:213], v[148:151], v[128:143]
	v_add_u32_e32 v210, s98, v196
	ds_read_b128 v[210:213], v210 offset:8192
	s_waitcnt lgkmcnt(7)
	v_mfma_f32_32x32x16_bf16 v[128:143], v[214:217], v[152:155], v[128:143]
	v_add_u32_e32 v214, s98, v197
	ds_read_b128 v[214:217], v214 offset:8192
	s_waitcnt lgkmcnt(7)
	v_mfma_f32_32x32x16_bf16 v[128:143], v[238:241], v[156:159], v[128:143]
	v_add_u32_e32 v238, s98, v198
	ds_read_b128 v[238:241], v238 offset:8192
	s_waitcnt lgkmcnt(7)
	v_mfma_f32_32x32x16_bf16 v[128:143], v[242:245], v[160:163], v[128:143]
	v_add_u32_e32 v242, s98, v199
	ds_read_b128 v[242:245], v242 offset:8192
	s_waitcnt lgkmcnt(7)
	v_mfma_f32_32x32x16_bf16 v[128:143], v[250:253], v[164:167], v[128:143]
	v_add_u32_e32 v250, s98, v200
	ds_read_b128 v[250:253], v250 offset:8192
	s_waitcnt lgkmcnt(7)
	v_mfma_f32_32x32x16_bf16 v[128:143], v[222:225], v[168:171], v[128:143]
	s_waitcnt lgkmcnt(6)
	v_mfma_f32_32x32x16_bf16 v[128:143], v[226:229], v[172:175], v[128:143]
	s_waitcnt lgkmcnt(5)
	v_mfma_f32_32x32x16_bf16 v[222:237], v[206:209], v[144:147], 0
	v_add_u32_e32 v206, s98, v201
	ds_read_b128 v[206:209], v206 offset:8192
	s_nop 7
	v_max3_f32 v246, v128, v129, v130
	v_max3_f32 v247, v131, v132, v133
	v_max3_f32 v246, v246, v134, v135
	v_max3_f32 v247, v247, v136, v137
	v_max3_f32 v246, v246, v138, v139
	v_max3_f32 v247, v247, v140, v141
	v_max3_f32 v246, v246, v142, v143
	s_waitcnt lgkmcnt(5)
	v_mfma_f32_32x32x16_bf16 v[222:237], v[210:213], v[148:151], v[222:237]
	v_add_u32_e32 v210, s98, v202
	ds_read_b128 v[210:213], v210 offset:8192
	v_max_f32_e32 v246, v246, v247
	v_mov_b32_e32 v247, v246
	v_add_f32_e32 v249, 0x41000000, v190
	s_nop 1
	v_permlane32_swap_b32_e32 v246, v247
	v_max_f32_e32 v246, v246, v247
	v_cmp_gt_f32_e32 vcc, v246, v249
	s_cbranch_vccz .Latt_nr0_2A
	v_max_f32_e32 v246, v190, v246
	v_sub_f32_e32 v190, v190, v246
	v_exp_f32_e32 v190, v190
	s_nop 0
	v_pk_mul_f32 v[126:127], v[126:127], v[190:191] op_sel_hi:[1,0]
	v_pk_mul_f32 v[124:125], v[124:125], v[190:191] op_sel_hi:[1,0]
	v_pk_mul_f32 v[122:123], v[122:123], v[190:191] op_sel_hi:[1,0]
	v_pk_mul_f32 v[120:121], v[120:121], v[190:191] op_sel_hi:[1,0]
	v_pk_mul_f32 v[118:119], v[118:119], v[190:191] op_sel_hi:[1,0]
	v_pk_mul_f32 v[116:117], v[116:117], v[190:191] op_sel_hi:[1,0]
	v_pk_mul_f32 v[114:115], v[114:115], v[190:191] op_sel_hi:[1,0]
	v_pk_mul_f32 v[112:113], v[112:113], v[190:191] op_sel_hi:[1,0]
	v_pk_mul_f32 v[110:111], v[110:111], v[190:191] op_sel_hi:[1,0]
	v_pk_mul_f32 v[108:109], v[108:109], v[190:191] op_sel_hi:[1,0]
	v_pk_mul_f32 v[106:107], v[106:107], v[190:191] op_sel_hi:[1,0]
	v_pk_mul_f32 v[104:105], v[104:105], v[190:191] op_sel_hi:[1,0]
	v_pk_mul_f32 v[102:103], v[102:103], v[190:191] op_sel_hi:[1,0]
	v_pk_mul_f32 v[100:101], v[100:101], v[190:191] op_sel_hi:[1,0]
	v_pk_mul_f32 v[98:99], v[98:99], v[190:191] op_sel_hi:[1,0]
	v_pk_mul_f32 v[96:97], v[96:97], v[190:191] op_sel_hi:[1,0]
	v_pk_mul_f32 v[94:95], v[94:95], v[190:191] op_sel_hi:[1,0]
	v_pk_mul_f32 v[92:93], v[92:93], v[190:191] op_sel_hi:[1,0]
	v_pk_mul_f32 v[90:91], v[90:91], v[190:191] op_sel_hi:[1,0]
	v_pk_mul_f32 v[88:89], v[88:89], v[190:191] op_sel_hi:[1,0]
	v_pk_mul_f32 v[86:87], v[86:87], v[190:191] op_sel_hi:[1,0]
	v_pk_mul_f32 v[84:85], v[84:85], v[190:191] op_sel_hi:[1,0]
	v_pk_mul_f32 v[82:83], v[82:83], v[190:191] op_sel_hi:[1,0]
	v_pk_mul_f32 v[80:81], v[80:81], v[190:191] op_sel_hi:[1,0]
	v_pk_mul_f32 v[78:79], v[78:79], v[190:191] op_sel_hi:[1,0]
	v_pk_mul_f32 v[76:77], v[76:77], v[190:191] op_sel_hi:[1,0]
	v_pk_mul_f32 v[74:75], v[74:75], v[190:191] op_sel_hi:[1,0]
	v_pk_mul_f32 v[72:73], v[72:73], v[190:191] op_sel_hi:[1,0]
	v_pk_mul_f32 v[70:71], v[70:71], v[190:191] op_sel_hi:[1,0]
	v_pk_mul_f32 v[68:69], v[68:69], v[190:191] op_sel_hi:[1,0]
	v_pk_mul_f32 v[66:67], v[66:67], v[190:191] op_sel_hi:[1,0]
	v_pk_mul_f32 v[64:65], v[64:65], v[190:191] op_sel_hi:[1,0]
	v_pk_mul_f32 v[62:63], v[62:63], v[190:191] op_sel_hi:[1,0]
	v_pk_mul_f32 v[60:61], v[60:61], v[190:191] op_sel_hi:[1,0]
	v_pk_mul_f32 v[58:59], v[58:59], v[190:191] op_sel_hi:[1,0]
	v_pk_mul_f32 v[56:57], v[56:57], v[190:191] op_sel_hi:[1,0]
	v_pk_mul_f32 v[54:55], v[54:55], v[190:191] op_sel_hi:[1,0]
	v_pk_mul_f32 v[52:53], v[52:53], v[190:191] op_sel_hi:[1,0]
	v_pk_mul_f32 v[50:51], v[50:51], v[190:191] op_sel_hi:[1,0]
	v_pk_mul_f32 v[48:49], v[48:49], v[190:191] op_sel_hi:[1,0]
	v_pk_mul_f32 v[46:47], v[46:47], v[190:191] op_sel_hi:[1,0]
	v_pk_mul_f32 v[44:45], v[44:45], v[190:191] op_sel_hi:[1,0]
	v_pk_mul_f32 v[42:43], v[42:43], v[190:191] op_sel_hi:[1,0]
	v_pk_mul_f32 v[40:41], v[40:41], v[190:191] op_sel_hi:[1,0]
	v_pk_mul_f32 v[38:39], v[38:39], v[190:191] op_sel_hi:[1,0]
	v_pk_mul_f32 v[36:37], v[36:37], v[190:191] op_sel_hi:[1,0]
	v_pk_mul_f32 v[34:35], v[34:35], v[190:191] op_sel_hi:[1,0]
	v_pk_mul_f32 v[32:33], v[32:33], v[190:191] op_sel_hi:[1,0]
	v_pk_mul_f32 v[30:31], v[30:31], v[190:191] op_sel_hi:[1,0]
	v_pk_mul_f32 v[28:29], v[28:29], v[190:191] op_sel_hi:[1,0]
	v_pk_mul_f32 v[26:27], v[26:27], v[190:191] op_sel_hi:[1,0]
	v_pk_mul_f32 v[24:25], v[24:25], v[190:191] op_sel_hi:[1,0]
	v_pk_mul_f32 v[22:23], v[22:23], v[190:191] op_sel_hi:[1,0]
	v_pk_mul_f32 v[20:21], v[20:21], v[190:191] op_sel_hi:[1,0]
	v_pk_mul_f32 v[18:19], v[18:19], v[190:191] op_sel_hi:[1,0]
	v_pk_mul_f32 v[16:17], v[16:17], v[190:191] op_sel_hi:[1,0]
	v_pk_mul_f32 v[14:15], v[14:15], v[190:191] op_sel_hi:[1,0]
	v_pk_mul_f32 v[12:13], v[12:13], v[190:191] op_sel_hi:[1,0]
	v_pk_mul_f32 v[10:11], v[10:11], v[190:191] op_sel_hi:[1,0]
	v_pk_mul_f32 v[8:9], v[8:9], v[190:191] op_sel_hi:[1,0]
	v_pk_mul_f32 v[6:7], v[6:7], v[190:191] op_sel_hi:[1,0]
	v_pk_mul_f32 v[4:5], v[4:5], v[190:191] op_sel_hi:[1,0]
	v_pk_mul_f32 v[2:3], v[2:3], v[190:191] op_sel_hi:[1,0]
	v_pk_mul_f32 v[0:1], v[0:1], v[190:191] op_sel_hi:[1,0]
	v_mul_f32_e32 v203, v203, v190
	v_mov_b32_e32 v190, v246
.Latt_nr0_2A:
	s_waitcnt lgkmcnt(5)
	v_mfma_f32_32x32x16_bf16 v[222:237], v[214:217], v[152:155], v[222:237]
	ds_read_b64_tr_b16 v[214:215], v205
	ds_read_b64_tr_b16 v[216:217], v205 offset:4096
	v_sub_f32_e32 v128, v128, v190
	v_exp_f32_e32 v128, v128
	v_sub_f32_e32 v129, v129, v190
	v_exp_f32_e32 v129, v129
	v_sub_f32_e32 v130, v130, v190
	v_add_f32_e32 v254, 0, v128
	v_exp_f32_e32 v130, v130
	v_sub_f32_e32 v131, v131, v190
	s_waitcnt lgkmcnt(6)
	v_mfma_f32_32x32x16_bf16 v[222:237], v[238:241], v[156:159], v[222:237]
	ds_read_b64_tr_b16 v[238:239], v218
	ds_read_b64_tr_b16 v[240:241], v218 offset:4096
	v_add_f32_e32 v254, v129, v254
	v_exp_f32_e32 v131, v131
	v_sub_f32_e32 v132, v132, v190
	v_add_f32_e32 v254, v130, v254
	v_exp_f32_e32 v132, v132
	v_sub_f32_e32 v133, v133, v190
	v_add_f32_e32 v254, v131, v254
	v_exp_f32_e32 v133, v133
	s_waitcnt lgkmcnt(7)
	v_mfma_f32_32x32x16_bf16 v[222:237], v[242:245], v[160:163], v[222:237]
	v_sub_f32_e32 v134, v134, v190
	v_add_f32_e32 v254, v132, v254
	v_exp_f32_e32 v134, v134
	v_sub_f32_e32 v135, v135, v190
	v_add_f32_e32 v254, v133, v254
	v_exp_f32_e32 v135, v135
	v_sub_f32_e32 v136, v136, v190
	v_add_f32_e32 v254, v134, v254
	s_waitcnt lgkmcnt(6)
	v_mfma_f32_32x32x16_bf16 v[222:237], v[250:253], v[164:167], v[222:237]
	v_exp_f32_e32 v136, v136
	v_sub_f32_e32 v137, v137, v190
	v_add_f32_e32 v254, v135, v254
	v_exp_f32_e32 v137, v137
	v_sub_f32_e32 v138, v138, v190
	v_add_f32_e32 v254, v136, v254
	v_exp_f32_e32 v138, v138
	v_sub_f32_e32 v139, v139, v190
	s_waitcnt lgkmcnt(5)
	v_mfma_f32_32x32x16_bf16 v[222:237], v[206:209], v[168:171], v[222:237]
	ds_read_b64_tr_b16 v[206:207], v219
	ds_read_b64_tr_b16 v[208:209], v219 offset:4096
	v_add_f32_e32 v254, v137, v254
	v_exp_f32_e32 v139, v139
	v_sub_f32_e32 v140, v140, v190
	v_add_f32_e32 v254, v138, v254
	v_exp_f32_e32 v140, v140
	v_sub_f32_e32 v141, v141, v190
	v_add_f32_e32 v254, v139, v254
	v_exp_f32_e32 v141, v141
	s_waitcnt lgkmcnt(6)
	v_mfma_f32_32x32x16_bf16 v[222:237], v[210:213], v[172:175], v[222:237]
	ds_read_b64_tr_b16 v[210:211], v221
	ds_read_b64_tr_b16 v[212:213], v221 offset:4096
	v_sub_f32_e32 v142, v142, v190
	v_add_f32_e32 v254, v140, v254
	v_exp_f32_e32 v142, v142
	v_sub_f32_e32 v143, v143, v190
	v_add_f32_e32 v254, v141, v254
	v_exp_f32_e32 v143, v143
	v_add_f32_e32 v254, v142, v254
	v_add_f32_e32 v254, v143, v254
	v_cvt_pk_bf16_f32 v242, v128, v129
	v_cvt_pk_bf16_f32 v243, v130, v131
	v_cvt_pk_bf16_f32 v244, v132, v133
	v_cvt_pk_bf16_f32 v245, v134, v135
	v_cvt_pk_bf16_f32 v250, v136, v137
	v_cvt_pk_bf16_f32 v251, v138, v139
	v_cvt_pk_bf16_f32 v252, v140, v141
	v_cvt_pk_bf16_f32 v253, v142, v143
	v_add_f32_e32 v203, v203, v254
	s_nop 1
	ds_read_b64_tr_b16 v[128:129], v205 offset:256
	ds_read_b64_tr_b16 v[130:131], v205 offset:4352
	s_waitcnt lgkmcnt(8)
	v_mfma_f32_32x32x16_bf16 v[112:127], v[214:217], v[242:245], v[112:127]
	ds_read_b64_tr_b16 v[214:215], v218 offset:256
	ds_read_b64_tr_b16 v[216:217], v218 offset:4352
	v_and_or_b32 v246, v204, 31, s80
	v_bfe_u32 v247, v204, 5, 1
	s_add_i32 s100, s84, 32
	v_lshl_add_u32 v247, v247, 2, s100
	v_add_u32_e32 v249, 0, v247
	v_cmp_le_i32_e32 vcc, v249, v246
	v_add_u32_e32 v254, 1, v247
	s_nop 0
	v_cndmask_b32_e32 v222, v192, v222, vcc
	v_cmp_le_i32_e32 vcc, v254, v246
	v_add_u32_e32 v249, 2, v247
	s_nop 0
	v_cndmask_b32_e32 v223, v192, v223, vcc
	v_cmp_le_i32_e32 vcc, v249, v246
	v_add_u32_e32 v254, 3, v247
	s_nop 0
	v_cndmask_b32_e32 v224, v192, v224, vcc
	v_cmp_le_i32_e32 vcc, v254, v246
	v_add_u32_e32 v249, 8, v247
	s_nop 0
	v_cndmask_b32_e32 v225, v192, v225, vcc
	v_cmp_le_i32_e32 vcc, v249, v246
	v_add_u32_e32 v254, 9, v247
	s_nop 0
	v_cndmask_b32_e32 v226, v192, v226, vcc
	v_cmp_le_i32_e32 vcc, v254, v246
	v_add_u32_e32 v249, 10, v247
	s_nop 0
	v_cndmask_b32_e32 v227, v192, v227, vcc
	v_cmp_le_i32_e32 vcc, v249, v246
	v_add_u32_e32 v254, 11, v247
	s_nop 0
	v_cndmask_b32_e32 v228, v192, v228, vcc
	v_cmp_le_i32_e32 vcc, v254, v246
	s_waitcnt lgkmcnt(8)
	v_mfma_f32_32x32x16_bf16 v[96:111], v[238:241], v[242:245], v[96:111]
	ds_read_b64_tr_b16 v[238:239], v219 offset:256
	ds_read_b64_tr_b16 v[240:241], v219 offset:4352
	v_add_u32_e32 v249, 16, v247
	s_nop 0
	v_cndmask_b32_e32 v229, v192, v229, vcc
	v_cmp_le_i32_e32 vcc, v249, v246
	v_add_u32_e32 v254, 17, v247
	s_nop 0
	v_cndmask_b32_e32 v230, v192, v230, vcc
	v_cmp_le_i32_e32 vcc, v254, v246
	v_add_u32_e32 v249, 18, v247
	s_nop 0
	v_cndmask_b32_e32 v231, v192, v231, vcc
	v_cmp_le_i32_e32 vcc, v249, v246
	v_add_u32_e32 v254, 19, v247
	s_nop 0
	v_cndmask_b32_e32 v232, v192, v232, vcc
	v_cmp_le_i32_e32 vcc, v254, v246
	v_add_u32_e32 v249, 24, v247
	s_nop 0
	v_cndmask_b32_e32 v233, v192, v233, vcc
	v_cmp_le_i32_e32 vcc, v249, v246
	v_add_u32_e32 v254, 25, v247
	s_nop 0
	v_cndmask_b32_e32 v234, v192, v234, vcc
	v_cmp_le_i32_e32 vcc, v254, v246
	v_add_u32_e32 v249, 26, v247
	s_nop 0
	v_cndmask_b32_e32 v235, v192, v235, vcc
	v_cmp_le_i32_e32 vcc, v249, v246
	v_add_u32_e32 v254, 27, v247
	s_nop 0
	v_cndmask_b32_e32 v236, v192, v236, vcc
	v_cmp_le_i32_e32 vcc, v254, v246
	s_nop 1
	v_cndmask_b32_e32 v237, v192, v237, vcc
	s_waitcnt lgkmcnt(8)
	v_mfma_f32_32x32x16_bf16 v[80:95], v[206:209], v[242:245], v[80:95]
	ds_read_b64_tr_b16 v[206:207], v221 offset:256
	ds_read_b64_tr_b16 v[208:209], v221 offset:4352
	v_max3_f32 v246, v222, v223, v224
	v_max3_f32 v247, v225, v226, v227
	v_max3_f32 v246, v246, v228, v229
	v_max3_f32 v247, v247, v230, v231
	v_max3_f32 v246, v246, v232, v233
	v_max3_f32 v247, v247, v234, v235
	s_waitcnt lgkmcnt(8)
	v_mfma_f32_32x32x16_bf16 v[64:79], v[210:213], v[242:245], v[64:79]
	ds_read_b64_tr_b16 v[210:211], v205 offset:8192
	ds_read_b64_tr_b16 v[212:213], v205 offset:12288
	v_max3_f32 v246, v246, v236, v237
	v_max_f32_e32 v246, v246, v247
	v_mov_b32_e32 v247, v246
	v_add_f32_e32 v249, 0x41000000, v190
	s_nop 1
	s_waitcnt lgkmcnt(8)
	v_mfma_f32_32x32x16_bf16 v[48:63], v[128:131], v[242:245], v[48:63]
	ds_read_b64_tr_b16 v[128:129], v218 offset:8192
	ds_read_b64_tr_b16 v[130:131], v218 offset:12288
	v_permlane32_swap_b32_e32 v246, v247
	v_max_f32_e32 v246, v246, v247
	v_cmp_gt_f32_e32 vcc, v246, v249
	s_cbranch_vccnz .Latt_rs1_2A
	s_waitcnt lgkmcnt(8)
	v_mfma_f32_32x32x16_bf16 v[32:47], v[214:217], v[242:245], v[32:47]
	ds_read_b64_tr_b16 v[214:215], v219 offset:8192
	ds_read_b64_tr_b16 v[216:217], v219 offset:12288
	v_sub_f32_e32 v222, v222, v190
	v_exp_f32_e32 v222, v222
	v_sub_f32_e32 v223, v223, v190
	v_exp_f32_e32 v223, v223
	v_sub_f32_e32 v224, v224, v190
	s_waitcnt lgkmcnt(8)
	v_mfma_f32_32x32x16_bf16 v[16:31], v[238:241], v[242:245], v[16:31]
	ds_read_b64_tr_b16 v[238:239], v221 offset:8192
	ds_read_b64_tr_b16 v[240:241], v221 offset:12288
	v_add_f32_e32 v254, 0, v222
	v_exp_f32_e32 v224, v224
	v_sub_f32_e32 v225, v225, v190
	v_add_f32_e32 v254, v223, v254
	v_exp_f32_e32 v225, v225
	s_waitcnt lgkmcnt(8)
	v_mfma_f32_32x32x16_bf16 v[0:15], v[206:209], v[242:245], v[0:15]
	ds_read_b64_tr_b16 v[206:207], v205 offset:8448
	ds_read_b64_tr_b16 v[208:209], v205 offset:12544
	v_sub_f32_e32 v226, v226, v190
	v_add_f32_e32 v254, v224, v254
	v_exp_f32_e32 v226, v226
	v_sub_f32_e32 v227, v227, v190
	v_add_f32_e32 v254, v225, v254
	s_waitcnt lgkmcnt(8)
	v_mfma_f32_32x32x16_bf16 v[112:127], v[210:213], v[250:253], v[112:127]
	ds_read_b64_tr_b16 v[210:211], v218 offset:8448
	ds_read_b64_tr_b16 v[212:213], v218 offset:12544
	v_exp_f32_e32 v227, v227
	v_sub_f32_e32 v228, v228, v190
	v_add_f32_e32 v254, v226, v254
	v_exp_f32_e32 v228, v228
	v_sub_f32_e32 v229, v229, v190
	s_waitcnt lgkmcnt(8)
	v_mfma_f32_32x32x16_bf16 v[96:111], v[128:131], v[250:253], v[96:111]
	ds_read_b64_tr_b16 v[128:129], v219 offset:8448
	ds_read_b64_tr_b16 v[130:131], v219 offset:12544
	v_add_f32_e32 v254, v227, v254
	v_exp_f32_e32 v229, v229
	v_sub_f32_e32 v230, v230, v190
	v_add_f32_e32 v254, v228, v254
	s_waitcnt lgkmcnt(8)
	v_mfma_f32_32x32x16_bf16 v[80:95], v[214:217], v[250:253], v[80:95]
	ds_read_b64_tr_b16 v[214:215], v221 offset:8448
	ds_read_b64_tr_b16 v[216:217], v221 offset:12544
	v_exp_f32_e32 v230, v230
	v_sub_f32_e32 v231, v231, v190
	v_add_f32_e32 v254, v229, v254
	v_exp_f32_e32 v231, v231
	s_waitcnt lgkmcnt(8)
	v_mfma_f32_32x32x16_bf16 v[64:79], v[238:241], v[250:253], v[64:79]
	ds_read_b64_tr_b16 v[238:239], v205 offset:16384
	ds_read_b64_tr_b16 v[240:241], v205 offset:20480
	v_sub_f32_e32 v232, v232, v190
	v_add_f32_e32 v254, v230, v254
	v_exp_f32_e32 v232, v232
	v_sub_f32_e32 v233, v233, v190
	s_waitcnt lgkmcnt(8)
	v_mfma_f32_32x32x16_bf16 v[48:63], v[206:209], v[250:253], v[48:63]
	ds_read_b64_tr_b16 v[206:207], v218 offset:16384
	ds_read_b64_tr_b16 v[208:209], v218 offset:20480
	v_add_f32_e32 v254, v231, v254
	v_exp_f32_e32 v233, v233
	v_sub_f32_e32 v234, v234, v190
	v_add_f32_e32 v254, v232, v254
	s_waitcnt lgkmcnt(8)
	v_mfma_f32_32x32x16_bf16 v[32:47], v[210:213], v[250:253], v[32:47]
	ds_read_b64_tr_b16 v[210:211], v219 offset:16384
	ds_read_b64_tr_b16 v[212:213], v219 offset:20480
	v_exp_f32_e32 v234, v234
	v_sub_f32_e32 v235, v235, v190
	v_add_f32_e32 v254, v233, v254
	v_exp_f32_e32 v235, v235
	s_waitcnt lgkmcnt(8)
	v_mfma_f32_32x32x16_bf16 v[16:31], v[128:131], v[250:253], v[16:31]
	ds_read_b64_tr_b16 v[128:129], v221 offset:16384
	ds_read_b64_tr_b16 v[130:131], v221 offset:20480
	v_sub_f32_e32 v236, v236, v190
	v_add_f32_e32 v254, v234, v254
	v_exp_f32_e32 v236, v236
	v_sub_f32_e32 v237, v237, v190
	s_waitcnt lgkmcnt(8)
	v_mfma_f32_32x32x16_bf16 v[0:15], v[214:217], v[250:253], v[0:15]
	ds_read_b64_tr_b16 v[214:215], v205 offset:16640
	ds_read_b64_tr_b16 v[216:217], v205 offset:20736
	v_add_f32_e32 v254, v235, v254
	v_exp_f32_e32 v237, v237
	v_add_f32_e32 v254, v236, v254
	v_add_f32_e32 v254, v237, v254
	v_cvt_pk_bf16_f32 v242, v222, v223
	v_cvt_pk_bf16_f32 v243, v224, v225
	v_cvt_pk_bf16_f32 v244, v226, v227
	v_cvt_pk_bf16_f32 v245, v228, v229
	v_cvt_pk_bf16_f32 v250, v230, v231
	v_cvt_pk_bf16_f32 v251, v232, v233
	v_cvt_pk_bf16_f32 v252, v234, v235
	v_cvt_pk_bf16_f32 v253, v236, v237
	v_add_f32_e32 v203, v203, v254
	s_nop 1

.Latt_rs1_2F:
	s_waitcnt lgkmcnt(8)
	v_mfma_f32_32x32x16_bf16 v[32:47], v[214:217], v[242:245], v[32:47]
	ds_read_b64_tr_b16 v[214:215], v219 offset:8192
	ds_read_b64_tr_b16 v[216:217], v219 offset:12288
	s_waitcnt lgkmcnt(8)
	v_mfma_f32_32x32x16_bf16 v[16:31], v[238:241], v[242:245], v[16:31]
	ds_read_b64_tr_b16 v[238:239], v221 offset:8192
	ds_read_b64_tr_b16 v[240:241], v221 offset:12288
	s_waitcnt lgkmcnt(8)
	v_mfma_f32_32x32x16_bf16 v[0:15], v[206:209], v[242:245], v[0:15]
	ds_read_b64_tr_b16 v[206:207], v205 offset:8448
	ds_read_b64_tr_b16 v[208:209], v205 offset:12544
	s_waitcnt lgkmcnt(8)
	v_mfma_f32_32x32x16_bf16 v[112:127], v[210:213], v[250:253], v[112:127]
	ds_read_b64_tr_b16 v[210:211], v218 offset:8448
	ds_read_b64_tr_b16 v[212:213], v218 offset:12544
	s_waitcnt lgkmcnt(8)
	v_mfma_f32_32x32x16_bf16 v[96:111], v[128:131], v[250:253], v[96:111]
	ds_read_b64_tr_b16 v[128:129], v219 offset:8448
	ds_read_b64_tr_b16 v[130:131], v219 offset:12544
	s_waitcnt lgkmcnt(8)
	v_mfma_f32_32x32x16_bf16 v[80:95], v[214:217], v[250:253], v[80:95]
	ds_read_b64_tr_b16 v[214:215], v221 offset:8448
	ds_read_b64_tr_b16 v[216:217], v221 offset:12544
	s_waitcnt lgkmcnt(8)
	v_mfma_f32_32x32x16_bf16 v[64:79], v[238:241], v[250:253], v[64:79]
	ds_read_b64_tr_b16 v[238:239], v205 offset:16384
	ds_read_b64_tr_b16 v[240:241], v205 offset:20480
	s_waitcnt lgkmcnt(8)
	v_mfma_f32_32x32x16_bf16 v[48:63], v[206:209], v[250:253], v[48:63]
	ds_read_b64_tr_b16 v[206:207], v218 offset:16384
	ds_read_b64_tr_b16 v[208:209], v218 offset:20480
	s_waitcnt lgkmcnt(8)
	v_mfma_f32_32x32x16_bf16 v[32:47], v[210:213], v[250:253], v[32:47]
	ds_read_b64_tr_b16 v[210:211], v219 offset:16384
	ds_read_b64_tr_b16 v[212:213], v219 offset:20480
	s_waitcnt lgkmcnt(8)
	v_mfma_f32_32x32x16_bf16 v[16:31], v[128:131], v[250:253], v[16:31]
	ds_read_b64_tr_b16 v[128:129], v221 offset:16384
	ds_read_b64_tr_b16 v[130:131], v221 offset:20480
	s_waitcnt lgkmcnt(8)
	v_mfma_f32_32x32x16_bf16 v[0:15], v[214:217], v[250:253], v[0:15]
	ds_read_b64_tr_b16 v[214:215], v205 offset:16640
	ds_read_b64_tr_b16 v[216:217], v205 offset:20736
	s_nop 11
	v_max_f32_e32 v246, v190, v246
	v_sub_f32_e32 v190, v190, v246
	v_exp_f32_e32 v190, v190
	s_nop 0
	v_pk_mul_f32 v[126:127], v[126:127], v[190:191] op_sel_hi:[1,0]
	v_pk_mul_f32 v[124:125], v[124:125], v[190:191] op_sel_hi:[1,0]
	v_pk_mul_f32 v[122:123], v[122:123], v[190:191] op_sel_hi:[1,0]
	v_pk_mul_f32 v[120:121], v[120:121], v[190:191] op_sel_hi:[1,0]
	v_pk_mul_f32 v[118:119], v[118:119], v[190:191] op_sel_hi:[1,0]
	v_pk_mul_f32 v[116:117], v[116:117], v[190:191] op_sel_hi:[1,0]
	v_pk_mul_f32 v[114:115], v[114:115], v[190:191] op_sel_hi:[1,0]
	v_pk_mul_f32 v[112:113], v[112:113], v[190:191] op_sel_hi:[1,0]
	v_pk_mul_f32 v[110:111], v[110:111], v[190:191] op_sel_hi:[1,0]
	v_pk_mul_f32 v[108:109], v[108:109], v[190:191] op_sel_hi:[1,0]
	v_pk_mul_f32 v[106:107], v[106:107], v[190:191] op_sel_hi:[1,0]
	v_pk_mul_f32 v[104:105], v[104:105], v[190:191] op_sel_hi:[1,0]
	v_pk_mul_f32 v[102:103], v[102:103], v[190:191] op_sel_hi:[1,0]
	v_pk_mul_f32 v[100:101], v[100:101], v[190:191] op_sel_hi:[1,0]
	v_pk_mul_f32 v[98:99], v[98:99], v[190:191] op_sel_hi:[1,0]
	v_pk_mul_f32 v[96:97], v[96:97], v[190:191] op_sel_hi:[1,0]
	v_pk_mul_f32 v[94:95], v[94:95], v[190:191] op_sel_hi:[1,0]
	v_pk_mul_f32 v[92:93], v[92:93], v[190:191] op_sel_hi:[1,0]
	v_pk_mul_f32 v[90:91], v[90:91], v[190:191] op_sel_hi:[1,0]
	v_pk_mul_f32 v[88:89], v[88:89], v[190:191] op_sel_hi:[1,0]
	v_pk_mul_f32 v[86:87], v[86:87], v[190:191] op_sel_hi:[1,0]
	v_pk_mul_f32 v[84:85], v[84:85], v[190:191] op_sel_hi:[1,0]
	v_pk_mul_f32 v[82:83], v[82:83], v[190:191] op_sel_hi:[1,0]
	v_pk_mul_f32 v[80:81], v[80:81], v[190:191] op_sel_hi:[1,0]
	v_pk_mul_f32 v[78:79], v[78:79], v[190:191] op_sel_hi:[1,0]
	v_pk_mul_f32 v[76:77], v[76:77], v[190:191] op_sel_hi:[1,0]
	v_pk_mul_f32 v[74:75], v[74:75], v[190:191] op_sel_hi:[1,0]
	v_pk_mul_f32 v[72:73], v[72:73], v[190:191] op_sel_hi:[1,0]
	v_pk_mul_f32 v[70:71], v[70:71], v[190:191] op_sel_hi:[1,0]
	v_pk_mul_f32 v[68:69], v[68:69], v[190:191] op_sel_hi:[1,0]
	v_pk_mul_f32 v[66:67], v[66:67], v[190:191] op_sel_hi:[1,0]
	v_pk_mul_f32 v[64:65], v[64:65], v[190:191] op_sel_hi:[1,0]
	v_pk_mul_f32 v[62:63], v[62:63], v[190:191] op_sel_hi:[1,0]
	v_pk_mul_f32 v[60:61], v[60:61], v[190:191] op_sel_hi:[1,0]
	v_pk_mul_f32 v[58:59], v[58:59], v[190:191] op_sel_hi:[1,0]
	v_pk_mul_f32 v[56:57], v[56:57], v[190:191] op_sel_hi:[1,0]
	v_pk_mul_f32 v[54:55], v[54:55], v[190:191] op_sel_hi:[1,0]
	v_pk_mul_f32 v[52:53], v[52:53], v[190:191] op_sel_hi:[1,0]
	v_pk_mul_f32 v[50:51], v[50:51], v[190:191] op_sel_hi:[1,0]
	v_pk_mul_f32 v[48:49], v[48:49], v[190:191] op_sel_hi:[1,0]
	v_pk_mul_f32 v[46:47], v[46:47], v[190:191] op_sel_hi:[1,0]
	v_pk_mul_f32 v[44:45], v[44:45], v[190:191] op_sel_hi:[1,0]
	v_pk_mul_f32 v[42:43], v[42:43], v[190:191] op_sel_hi:[1,0]
	v_pk_mul_f32 v[40:41], v[40:41], v[190:191] op_sel_hi:[1,0]
	v_pk_mul_f32 v[38:39], v[38:39], v[190:191] op_sel_hi:[1,0]
	v_pk_mul_f32 v[36:37], v[36:37], v[190:191] op_sel_hi:[1,0]
	v_pk_mul_f32 v[34:35], v[34:35], v[190:191] op_sel_hi:[1,0]
	v_pk_mul_f32 v[32:33], v[32:33], v[190:191] op_sel_hi:[1,0]
	v_pk_mul_f32 v[30:31], v[30:31], v[190:191] op_sel_hi:[1,0]
	v_pk_mul_f32 v[28:29], v[28:29], v[190:191] op_sel_hi:[1,0]
	v_pk_mul_f32 v[26:27], v[26:27], v[190:191] op_sel_hi:[1,0]
	v_pk_mul_f32 v[24:25], v[24:25], v[190:191] op_sel_hi:[1,0]
	v_pk_mul_f32 v[22:23], v[22:23], v[190:191] op_sel_hi:[1,0]
	v_pk_mul_f32 v[20:21], v[20:21], v[190:191] op_sel_hi:[1,0]
	v_pk_mul_f32 v[18:19], v[18:19], v[190:191] op_sel_hi:[1,0]
	v_pk_mul_f32 v[16:17], v[16:17], v[190:191] op_sel_hi:[1,0]
	v_pk_mul_f32 v[14:15], v[14:15], v[190:191] op_sel_hi:[1,0]
	v_pk_mul_f32 v[12:13], v[12:13], v[190:191] op_sel_hi:[1,0]
	v_pk_mul_f32 v[10:11], v[10:11], v[190:191] op_sel_hi:[1,0]
	v_pk_mul_f32 v[8:9], v[8:9], v[190:191] op_sel_hi:[1,0]
	v_pk_mul_f32 v[6:7], v[6:7], v[190:191] op_sel_hi:[1,0]
	v_pk_mul_f32 v[4:5], v[4:5], v[190:191] op_sel_hi:[1,0]
	v_pk_mul_f32 v[2:3], v[2:3], v[190:191] op_sel_hi:[1,0]
	v_pk_mul_f32 v[0:1], v[0:1], v[190:191] op_sel_hi:[1,0]
	v_mul_f32_e32 v203, v203, v190
	v_mov_b32_e32 v190, v246
	v_sub_f32_e32 v222, v222, v190
	v_exp_f32_e32 v222, v222
	v_sub_f32_e32 v223, v223, v190
	v_exp_f32_e32 v223, v223
	v_sub_f32_e32 v224, v224, v190
	v_add_f32_e32 v254, 0, v222
	v_exp_f32_e32 v224, v224
	v_sub_f32_e32 v225, v225, v190
	v_add_f32_e32 v254, v223, v254
	v_exp_f32_e32 v225, v225
	v_sub_f32_e32 v226, v226, v190
	v_add_f32_e32 v254, v224, v254
	v_exp_f32_e32 v226, v226
	v_sub_f32_e32 v227, v227, v190
	v_add_f32_e32 v254, v225, v254
	v_exp_f32_e32 v227, v227
	v_sub_f32_e32 v228, v228, v190
	v_add_f32_e32 v254, v226, v254
	v_exp_f32_e32 v228, v228
	v_sub_f32_e32 v229, v229, v190
	v_add_f32_e32 v254, v227, v254
	v_exp_f32_e32 v229, v229
	v_sub_f32_e32 v230, v230, v190
	v_add_f32_e32 v254, v228, v254
	v_exp_f32_e32 v230, v230
	v_sub_f32_e32 v231, v231, v190
	v_add_f32_e32 v254, v229, v254
	v_exp_f32_e32 v231, v231
	v_sub_f32_e32 v232, v232, v190
	v_add_f32_e32 v254, v230, v254
	v_exp_f32_e32 v232, v232
	v_sub_f32_e32 v233, v233, v190
	v_add_f32_e32 v254, v231, v254
	v_exp_f32_e32 v233, v233
	v_sub_f32_e32 v234, v234, v190
	v_add_f32_e32 v254, v232, v254
	v_exp_f32_e32 v234, v234
	v_sub_f32_e32 v235, v235, v190
	v_add_f32_e32 v254, v233, v254
	v_exp_f32_e32 v235, v235
	v_sub_f32_e32 v236, v236, v190
	v_add_f32_e32 v254, v234, v254
	v_exp_f32_e32 v236, v236
	v_sub_f32_e32 v237, v237, v190
	v_add_f32_e32 v254, v235, v254
	v_exp_f32_e32 v237, v237
	v_add_f32_e32 v254, v236, v254
	v_add_f32_e32 v254, v237, v254
	v_cvt_pk_bf16_f32 v242, v222, v223
	v_cvt_pk_bf16_f32 v243, v224, v225
	v_cvt_pk_bf16_f32 v244, v226, v227
	v_cvt_pk_bf16_f32 v245, v228, v229
	v_cvt_pk_bf16_f32 v250, v230, v231
	v_cvt_pk_bf16_f32 v251, v232, v233
	v_cvt_pk_bf16_f32 v252, v234, v235
	v_cvt_pk_bf16_f32 v253, v236, v237
	v_add_f32_e32 v203, v203, v254
	s_nop 1
	s_branch .Latt_pv1_2F
	s_lshl_b32 s14, s38, 14
	s_add_i32 s15, s14, 0
	v_add_u32_e32 v207, s15, v195
	ds_read_b128 v[128:131], v207
	v_add_u32_e32 v208, s15, v196
	ds_read_b128 v[210:213], v208
	v_add_u32_e32 v209, s15, v197
	v_lshrrev_b32_e32 v205, 3, v204
	s_add_i32 s39, s84, 31
	v_and_or_b32 v206, v204, 31, s80
	s_cmp_le_i32 s39, s80
	s_waitcnt lgkmcnt(1)
	v_mfma_f32_32x32x16_bf16 v[128:143], v[128:131], v[144:147], 0
	s_waitcnt lgkmcnt(0)
	v_mfma_f32_32x32x16_bf16 v[128:143], v[210:213], v[148:151], v[128:143]
	ds_read_b128 v[212:215], v209
	v_add_u32_e32 v210, s15, v198
	ds_read_b128 v[216:219], v210
	v_add_u32_e32 v211, s15, v199
	s_waitcnt lgkmcnt(1)
	v_mfma_f32_32x32x16_bf16 v[128:143], v[212:215], v[152:155], v[128:143]
	v_add_u32_e32 v213, s15, v200
	v_and_b32_e32 v212, 4, v205
	ds_read_b128 v[222:225], v213
	s_waitcnt lgkmcnt(1)
	v_mfma_f32_32x32x16_bf16 v[128:143], v[216:219], v[156:159], v[128:143]
	ds_read_b128 v[214:217], v211
	s_waitcnt lgkmcnt(0)
	v_mfma_f32_32x32x16_bf16 v[128:143], v[214:217], v[160:163], v[128:143]
	v_add_u32_e32 v214, s15, v201
	ds_read_b128 v[216:219], v214
	v_add_u32_e32 v215, s15, v202
	v_mfma_f32_32x32x16_bf16 v[128:143], v[222:225], v[164:167], v[128:143]
	ds_read_b128 v[222:225], v215
	s_waitcnt lgkmcnt(1)
	v_mfma_f32_32x32x16_bf16 v[128:143], v[216:219], v[168:171], v[128:143]
	s_waitcnt lgkmcnt(0)
	v_mfma_f32_32x32x16_bf16 v[128:143], v[222:225], v[172:175], v[128:143]
	s_cbranch_scc1 .LBB0_888
	v_add_u32_e32 v205, s84, v212
	v_cmp_lt_i32_e32 vcc, v205, v206
	v_add_u32_e32 v216, 2, v205
	s_nop 7
	v_cndmask_b32_e32 v129, v192, v129, vcc
	v_cmp_le_i32_e32 vcc, v205, v206
	s_nop 1
	v_cndmask_b32_e32 v128, v192, v128, vcc
	v_cmp_le_i32_e32 vcc, v216, v206
	v_add_u32_e32 v216, 3, v205
	s_nop 0
	v_cndmask_b32_e32 v130, v192, v130, vcc
	v_cmp_le_i32_e32 vcc, v216, v206
	v_add_u32_e32 v216, 8, v205
	s_nop 0
	v_cndmask_b32_e32 v131, v192, v131, vcc
	v_cmp_le_i32_e32 vcc, v216, v206
	v_add_u32_e32 v216, 9, v205
	s_nop 0
	v_cndmask_b32_e32 v132, v192, v132, vcc
	v_cmp_le_i32_e32 vcc, v216, v206
	v_add_u32_e32 v216, 10, v205
	s_nop 0
	v_cndmask_b32_e32 v133, v192, v133, vcc
	v_cmp_le_i32_e32 vcc, v216, v206
	v_add_u32_e32 v216, 11, v205
	s_nop 0
	v_cndmask_b32_e32 v134, v192, v134, vcc
	v_cmp_le_i32_e32 vcc, v216, v206
	v_add_u32_e32 v216, 16, v205
	s_nop 0
	v_cndmask_b32_e32 v135, v192, v135, vcc
	v_cmp_le_i32_e32 vcc, v216, v206
	v_add_u32_e32 v216, 17, v205
	s_nop 0
	v_cndmask_b32_e32 v136, v192, v136, vcc
	v_cmp_le_i32_e32 vcc, v216, v206
	v_add_u32_e32 v216, 18, v205
	s_nop 0
	v_cndmask_b32_e32 v137, v192, v137, vcc
	v_cmp_le_i32_e32 vcc, v216, v206
	v_add_u32_e32 v216, 19, v205
	s_nop 0
	v_cndmask_b32_e32 v138, v192, v138, vcc
	v_cmp_le_i32_e32 vcc, v216, v206
	v_add_u32_e32 v216, 24, v205
	s_nop 0
	v_cndmask_b32_e32 v139, v192, v139, vcc
	v_cmp_le_i32_e32 vcc, v216, v206
	v_add_u32_e32 v216, 25, v205
	s_nop 0
	v_cndmask_b32_e32 v140, v192, v140, vcc
	v_cmp_le_i32_e32 vcc, v216, v206
	v_add_u32_e32 v216, 26, v205
	v_add_u32_e32 v205, 27, v205
	v_cndmask_b32_e32 v141, v192, v141, vcc
	v_cmp_le_i32_e32 vcc, v216, v206
	s_nop 1
	v_cndmask_b32_e32 v142, v192, v142, vcc
	v_cmp_le_i32_e32 vcc, v205, v206
	s_nop 1
	v_cndmask_b32_e32 v143, v192, v143, vcc

.LBB0_902:
	s_cmp_ge_u32 s10, s78
	s_cselect_b64 s[8:9], -1, 0
	v_mov_b32_e32 v204, v176
	s_and_b64 vcc, exec, s[8:9]
	s_cbranch_vccnz .LBB0_904
	s_cmp_le_i32 s14, s81
	s_cbranch_scc1 .LBB0_904
	v_sub_co_u32_e64 v128, s[16:17], s11, 1
	s_nop 1
	v_cndmask_b32_e64 v130, v128, 2, s[16:17]
	v_lshlrev_b32_e32 v128, 14, v130
	v_add_u32_e32 v131, s40, v128
	v_lshl_add_u64 v[128:129], s[34:35], 0, v[178:179]
	s_add_u32 s16, s34, 0xf00
	v_readfirstlane_b32 s15, v131
	s_mov_b32 s22, m0
	s_mov_b32 m0, s15
	s_nop 0
	global_load_lds_dwordx4 v[128:129], off
	s_mov_b32 m0, s22
	v_lshl_add_u64 v[128:129], s[34:35], 0, v[180:181]
	s_addc_u32 s17, s35, 0
	s_addk_i32 s15, 0x400
	s_mov_b32 s22, m0
	s_mov_b32 m0, s15
	s_nop 0
	global_load_lds_dwordx4 v[128:129], off
	s_mov_b32 m0, s22
	v_lshlrev_b32_e32 v128, 15, v130
	v_add_u32_e32 v130, s41, v128
	v_lshl_add_u64 v[128:129], s[16:17], 0, v[182:183]
	v_readfirstlane_b32 s15, v130
	s_mov_b32 s22, m0
	s_mov_b32 m0, s15
	s_nop 0
	global_load_lds_dwordx4 v[128:129], off
	s_mov_b32 m0, s22
	v_lshl_add_u64 v[128:129], s[16:17], 0, v[184:185]
	s_add_i32 s22, s15, 0x400
	s_mov_b32 s23, m0
	s_mov_b32 m0, s22
	s_nop 0
	global_load_lds_dwordx4 v[128:129], off
	s_mov_b32 m0, s23
	v_lshl_add_u64 v[128:129], s[16:17], 0, v[186:187]
	s_add_i32 s22, s15, 0x800
	s_mov_b32 s23, m0
	s_mov_b32 m0, s22
	s_nop 0
	global_load_lds_dwordx4 v[128:129], off
	s_mov_b32 m0, s23
	v_lshl_add_u64 v[128:129], s[16:17], 0, v[188:189]
	s_addk_i32 s15, 0xc00
	s_mov_b32 s16, m0
	s_mov_b32 m0, s15
	s_nop 0
	global_load_lds_dwordx4 v[128:129], off
	s_mov_b32 m0, s16
.LBB0_904:
	s_cmp_gt_i32 s14, s81
	s_cbranch_scc1 .LBB0_915
	s_add_i32 s100, s14, 63
	s_cmp_le_i32 s100, s80
	s_cbranch_scc1 .Latt_full_3
	s_add_i32 s100, s14, 32
	s_cmp_le_i32 s100, s81
	s_cbranch_scc1 .Latt_diagA_3
	s_lshl_b32 s98, s11, 14
	s_lshl_b32 s99, s11, 15
	s_add_i32 s99, s99, 0xc000
	v_add_u32_e32 v206, s98, v196
	ds_read_b128 v[206:209], v206
	v_add_u32_e32 v210, s98, v197
	ds_read_b128 v[210:213], v210
	v_add_u32_e32 v214, s98, v198
	ds_read_b128 v[214:217], v214
	v_add_u32_e32 v238, s98, v199
	ds_read_b128 v[238:241], v238
	v_add_u32_e32 v242, s98, v200
	ds_read_b128 v[242:245], v242
	v_add_u32_e32 v250, s98, v201
	ds_read_b128 v[250:253], v250
	v_add_u32_e32 v222, s98, v202
	ds_read_b128 v[222:225], v222
	v_add_u32_e32 v226, s98, v203
	ds_read_b128 v[226:229], v226
	v_bfe_u32 v246, v204, 2, 2
	v_bfe_u32 v247, v204, 5, 1
	v_lshl_or_b32 v247, v247, 2, v246
	v_and_b32_e32 v249, 3, v204
	v_and_b32_e32 v254, 16, v204
	v_lshl_or_b32 v249, v249, 2, v254
	v_lshlrev_b32_e32 v249, 1, v249
	v_lshl_add_u32 v247, v247, 9, v249
	v_add_u32_e32 v247, s99, v247
	v_lshlrev_b32_e32 v246, 6, v246
	v_add_u32_e32 v205, v247, v246
	v_xor_b32_e32 v249, 64, v246
	v_add_u32_e32 v218, v247, v249
	v_xor_b32_e32 v249, 0x80, v246
	v_add_u32_e32 v219, v247, v249
	v_xor_b32_e32 v249, 0xc0, v246
	v_add_u32_e32 v221, v247, v249
	s_waitcnt lgkmcnt(7)
	v_mfma_f32_32x32x16_bf16 v[128:143], v[206:209], v[144:147], 0
	ds_read_b64_tr_b16 v[206:207], v205
	ds_read_b64_tr_b16 v[208:209], v205 offset:4096
	s_waitcnt lgkmcnt(8)
	v_mfma_f32_32x32x16_bf16 v[128:143], v[210:213], v[148:151], v[128:143]
	ds_read_b64_tr_b16 v[210:211], v218
	ds_read_b64_tr_b16 v[212:213], v218 offset:4096
	s_waitcnt lgkmcnt(9)
	v_mfma_f32_32x32x16_bf16 v[128:143], v[214:217], v[152:155], v[128:143]
	s_waitcnt lgkmcnt(8)
	v_mfma_f32_32x32x16_bf16 v[128:143], v[238:241], v[156:159], v[128:143]
	ds_read_b64_tr_b16 v[214:215], v219
	ds_read_b64_tr_b16 v[216:217], v219 offset:4096
	s_waitcnt lgkmcnt(9)
	v_mfma_f32_32x32x16_bf16 v[128:143], v[242:245], v[160:163], v[128:143]
	s_waitcnt lgkmcnt(8)
	v_mfma_f32_32x32x16_bf16 v[128:143], v[250:253], v[164:167], v[128:143]
	ds_read_b64_tr_b16 v[238:239], v221
	ds_read_b64_tr_b16 v[240:241], v221 offset:4096
	s_waitcnt lgkmcnt(9)
	v_mfma_f32_32x32x16_bf16 v[128:143], v[222:225], v[168:171], v[128:143]
	s_waitcnt lgkmcnt(8)
	v_mfma_f32_32x32x16_bf16 v[128:143], v[226:229], v[172:175], v[128:143]
	s_nop 11
	v_and_or_b32 v246, v204, 31, s80
	v_bfe_u32 v247, v204, 5, 1
	s_add_i32 s100, s14, 0
	v_lshl_add_u32 v247, v247, 2, s100
	v_add_u32_e32 v249, 0, v247
	v_cmp_le_i32_e32 vcc, v249, v246
	v_add_u32_e32 v254, 1, v247
	s_nop 0
	v_cndmask_b32_e32 v128, v192, v128, vcc
	v_cmp_le_i32_e32 vcc, v254, v246
	v_add_u32_e32 v249, 2, v247
	s_nop 0
	v_cndmask_b32_e32 v129, v192, v129, vcc
	v_cmp_le_i32_e32 vcc, v249, v246
	v_add_u32_e32 v254, 3, v247
	s_nop 0
	v_cndmask_b32_e32 v130, v192, v130, vcc
	v_cmp_le_i32_e32 vcc, v254, v246
	v_add_u32_e32 v249, 8, v247
	s_nop 0
	v_cndmask_b32_e32 v131, v192, v131, vcc
	v_cmp_le_i32_e32 vcc, v249, v246
	v_add_u32_e32 v254, 9, v247
	s_nop 0
	v_cndmask_b32_e32 v132, v192, v132, vcc
	v_cmp_le_i32_e32 vcc, v254, v246
	v_add_u32_e32 v249, 10, v247
	s_nop 0
	v_cndmask_b32_e32 v133, v192, v133, vcc
	v_cmp_le_i32_e32 vcc, v249, v246
	v_add_u32_e32 v254, 11, v247
	s_nop 0
	v_cndmask_b32_e32 v134, v192, v134, vcc
	v_cmp_le_i32_e32 vcc, v254, v246
	v_add_u32_e32 v249, 16, v247
	s_nop 0
	v_cndmask_b32_e32 v135, v192, v135, vcc
	v_cmp_le_i32_e32 vcc, v249, v246
	v_add_u32_e32 v254, 17, v247
	s_nop 0
	v_cndmask_b32_e32 v136, v192, v136, vcc
	v_cmp_le_i32_e32 vcc, v254, v246
	v_add_u32_e32 v249, 18, v247
	s_nop 0
	v_cndmask_b32_e32 v137, v192, v137, vcc
	v_cmp_le_i32_e32 vcc, v249, v246
	v_add_u32_e32 v254, 19, v247
	s_nop 0
	v_cndmask_b32_e32 v138, v192, v138, vcc
	v_cmp_le_i32_e32 vcc, v254, v246
	v_add_u32_e32 v249, 24, v247
	s_nop 0
	v_cndmask_b32_e32 v139, v192, v139, vcc
	v_cmp_le_i32_e32 vcc, v249, v246
	v_add_u32_e32 v254, 25, v247
	s_nop 0
	v_cndmask_b32_e32 v140, v192, v140, vcc
	v_cmp_le_i32_e32 vcc, v254, v246
	v_add_u32_e32 v249, 26, v247
	s_nop 0
	v_cndmask_b32_e32 v141, v192, v141, vcc
	v_cmp_le_i32_e32 vcc, v249, v246
	v_add_u32_e32 v254, 27, v247
	s_nop 0
	v_cndmask_b32_e32 v142, v192, v142, vcc
	v_cmp_le_i32_e32 vcc, v254, v246
	s_nop 1
	v_cndmask_b32_e32 v143, v192, v143, vcc
	v_max3_f32 v246, v128, v129, v130
	v_max3_f32 v247, v131, v132, v133
	v_max3_f32 v246, v246, v134, v135
	v_max3_f32 v247, v247, v136, v137
	v_max3_f32 v246, v246, v138, v139
	v_max3_f32 v247, v247, v140, v141
	v_max3_f32 v246, v246, v142, v143
	v_max_f32_e32 v246, v246, v247
	v_mov_b32_e32 v247, v246
	v_add_f32_e32 v249, 0x41000000, v190
	s_nop 1
	v_permlane32_swap_b32_e32 v246, v247
	v_max_f32_e32 v246, v246, v247
	v_cmp_gt_f32_e32 vcc, v246, v249
	s_cbranch_vccz .Latt_nr0_3B
	v_max_f32_e32 v246, v190, v246
	v_sub_f32_e32 v190, v190, v246
	v_exp_f32_e32 v190, v190
	s_nop 0
	v_pk_mul_f32 v[126:127], v[126:127], v[190:191] op_sel_hi:[1,0]
	v_pk_mul_f32 v[124:125], v[124:125], v[190:191] op_sel_hi:[1,0]
	v_pk_mul_f32 v[122:123], v[122:123], v[190:191] op_sel_hi:[1,0]
	v_pk_mul_f32 v[120:121], v[120:121], v[190:191] op_sel_hi:[1,0]
	v_pk_mul_f32 v[118:119], v[118:119], v[190:191] op_sel_hi:[1,0]
	v_pk_mul_f32 v[116:117], v[116:117], v[190:191] op_sel_hi:[1,0]
	v_pk_mul_f32 v[114:115], v[114:115], v[190:191] op_sel_hi:[1,0]
	v_pk_mul_f32 v[112:113], v[112:113], v[190:191] op_sel_hi:[1,0]
	v_pk_mul_f32 v[110:111], v[110:111], v[190:191] op_sel_hi:[1,0]
	v_pk_mul_f32 v[108:109], v[108:109], v[190:191] op_sel_hi:[1,0]
	v_pk_mul_f32 v[106:107], v[106:107], v[190:191] op_sel_hi:[1,0]
	v_pk_mul_f32 v[104:105], v[104:105], v[190:191] op_sel_hi:[1,0]
	v_pk_mul_f32 v[102:103], v[102:103], v[190:191] op_sel_hi:[1,0]
	v_pk_mul_f32 v[100:101], v[100:101], v[190:191] op_sel_hi:[1,0]
	v_pk_mul_f32 v[98:99], v[98:99], v[190:191] op_sel_hi:[1,0]
	v_pk_mul_f32 v[96:97], v[96:97], v[190:191] op_sel_hi:[1,0]
	v_pk_mul_f32 v[94:95], v[94:95], v[190:191] op_sel_hi:[1,0]
	v_pk_mul_f32 v[92:93], v[92:93], v[190:191] op_sel_hi:[1,0]
	v_pk_mul_f32 v[90:91], v[90:91], v[190:191] op_sel_hi:[1,0]
	v_pk_mul_f32 v[88:89], v[88:89], v[190:191] op_sel_hi:[1,0]
	v_pk_mul_f32 v[86:87], v[86:87], v[190:191] op_sel_hi:[1,0]
	v_pk_mul_f32 v[84:85], v[84:85], v[190:191] op_sel_hi:[1,0]
	v_pk_mul_f32 v[82:83], v[82:83], v[190:191] op_sel_hi:[1,0]
	v_pk_mul_f32 v[80:81], v[80:81], v[190:191] op_sel_hi:[1,0]
	v_pk_mul_f32 v[78:79], v[78:79], v[190:191] op_sel_hi:[1,0]
	v_pk_mul_f32 v[76:77], v[76:77], v[190:191] op_sel_hi:[1,0]
	v_pk_mul_f32 v[74:75], v[74:75], v[190:191] op_sel_hi:[1,0]
	v_pk_mul_f32 v[72:73], v[72:73], v[190:191] op_sel_hi:[1,0]
	v_pk_mul_f32 v[70:71], v[70:71], v[190:191] op_sel_hi:[1,0]
	v_pk_mul_f32 v[68:69], v[68:69], v[190:191] op_sel_hi:[1,0]
	v_pk_mul_f32 v[66:67], v[66:67], v[190:191] op_sel_hi:[1,0]
	v_pk_mul_f32 v[64:65], v[64:65], v[190:191] op_sel_hi:[1,0]
	v_pk_mul_f32 v[62:63], v[62:63], v[190:191] op_sel_hi:[1,0]
	v_pk_mul_f32 v[60:61], v[60:61], v[190:191] op_sel_hi:[1,0]
	v_pk_mul_f32 v[58:59], v[58:59], v[190:191] op_sel_hi:[1,0]
	v_pk_mul_f32 v[56:57], v[56:57], v[190:191] op_sel_hi:[1,0]
	v_pk_mul_f32 v[54:55], v[54:55], v[190:191] op_sel_hi:[1,0]
	v_pk_mul_f32 v[52:53], v[52:53], v[190:191] op_sel_hi:[1,0]
	v_pk_mul_f32 v[50:51], v[50:51], v[190:191] op_sel_hi:[1,0]
	v_pk_mul_f32 v[48:49], v[48:49], v[190:191] op_sel_hi:[1,0]
	v_pk_mul_f32 v[46:47], v[46:47], v[190:191] op_sel_hi:[1,0]
	v_pk_mul_f32 v[44:45], v[44:45], v[190:191] op_sel_hi:[1,0]
	v_pk_mul_f32 v[42:43], v[42:43], v[190:191] op_sel_hi:[1,0]
	v_pk_mul_f32 v[40:41], v[40:41], v[190:191] op_sel_hi:[1,0]
	v_pk_mul_f32 v[38:39], v[38:39], v[190:191] op_sel_hi:[1,0]
	v_pk_mul_f32 v[36:37], v[36:37], v[190:191] op_sel_hi:[1,0]
	v_pk_mul_f32 v[34:35], v[34:35], v[190:191] op_sel_hi:[1,0]
	v_pk_mul_f32 v[32:33], v[32:33], v[190:191] op_sel_hi:[1,0]
	v_pk_mul_f32 v[30:31], v[30:31], v[190:191] op_sel_hi:[1,0]
	v_pk_mul_f32 v[28:29], v[28:29], v[190:191] op_sel_hi:[1,0]
	v_pk_mul_f32 v[26:27], v[26:27], v[190:191] op_sel_hi:[1,0]
	v_pk_mul_f32 v[24:25], v[24:25], v[190:191] op_sel_hi:[1,0]
	v_pk_mul_f32 v[22:23], v[22:23], v[190:191] op_sel_hi:[1,0]
	v_pk_mul_f32 v[20:21], v[20:21], v[190:191] op_sel_hi:[1,0]
	v_pk_mul_f32 v[18:19], v[18:19], v[190:191] op_sel_hi:[1,0]
	v_pk_mul_f32 v[16:17], v[16:17], v[190:191] op_sel_hi:[1,0]
	v_pk_mul_f32 v[14:15], v[14:15], v[190:191] op_sel_hi:[1,0]
	v_pk_mul_f32 v[12:13], v[12:13], v[190:191] op_sel_hi:[1,0]
	v_pk_mul_f32 v[10:11], v[10:11], v[190:191] op_sel_hi:[1,0]
	v_pk_mul_f32 v[8:9], v[8:9], v[190:191] op_sel_hi:[1,0]
	v_pk_mul_f32 v[6:7], v[6:7], v[190:191] op_sel_hi:[1,0]
	v_pk_mul_f32 v[4:5], v[4:5], v[190:191] op_sel_hi:[1,0]
	v_pk_mul_f32 v[2:3], v[2:3], v[190:191] op_sel_hi:[1,0]
	v_pk_mul_f32 v[0:1], v[0:1], v[190:191] op_sel_hi:[1,0]
	v_mul_f32_e32 v195, v195, v190
	v_mov_b32_e32 v190, v246
.Latt_nr0_3B:
	v_sub_f32_e32 v128, v128, v190
	v_exp_f32_e32 v128, v128
	v_sub_f32_e32 v129, v129, v190
	v_exp_f32_e32 v129, v129
	v_sub_f32_e32 v130, v130, v190
	v_add_f32_e32 v254, 0, v128
	v_exp_f32_e32 v130, v130
	v_sub_f32_e32 v131, v131, v190
	v_add_f32_e32 v254, v129, v254
	v_exp_f32_e32 v131, v131
	v_sub_f32_e32 v132, v132, v190
	v_add_f32_e32 v254, v130, v254
	v_exp_f32_e32 v132, v132
	v_sub_f32_e32 v133, v133, v190
	v_add_f32_e32 v254, v131, v254
	v_exp_f32_e32 v133, v133
	v_sub_f32_e32 v134, v134, v190
	v_add_f32_e32 v254, v132, v254
	v_exp_f32_e32 v134, v134
	v_sub_f32_e32 v135, v135, v190
	v_add_f32_e32 v254, v133, v254
	v_exp_f32_e32 v135, v135
	v_sub_f32_e32 v136, v136, v190
	v_add_f32_e32 v254, v134, v254
	v_exp_f32_e32 v136, v136
	v_sub_f32_e32 v137, v137, v190
	v_add_f32_e32 v254, v135, v254
	v_exp_f32_e32 v137, v137
	v_sub_f32_e32 v138, v138, v190
	v_add_f32_e32 v254, v136, v254
	v_exp_f32_e32 v138, v138
	v_sub_f32_e32 v139, v139, v190
	v_add_f32_e32 v254, v137, v254
	v_exp_f32_e32 v139, v139
	v_sub_f32_e32 v140, v140, v190
	v_add_f32_e32 v254, v138, v254
	v_exp_f32_e32 v140, v140
	v_sub_f32_e32 v141, v141, v190
	v_add_f32_e32 v254, v139, v254
	v_exp_f32_e32 v141, v141
	v_sub_f32_e32 v142, v142, v190
	v_add_f32_e32 v254, v140, v254
	v_exp_f32_e32 v142, v142
	v_sub_f32_e32 v143, v143, v190
	v_add_f32_e32 v254, v141, v254
	v_exp_f32_e32 v143, v143
	v_add_f32_e32 v254, v142, v254
	v_add_f32_e32 v254, v143, v254
	v_cvt_pk_bf16_f32 v242, v128, v129
	v_cvt_pk_bf16_f32 v243, v130, v131
	v_cvt_pk_bf16_f32 v244, v132, v133
	v_cvt_pk_bf16_f32 v245, v134, v135
	v_cvt_pk_bf16_f32 v250, v136, v137
	v_cvt_pk_bf16_f32 v251, v138, v139
	v_cvt_pk_bf16_f32 v252, v140, v141
	v_cvt_pk_bf16_f32 v253, v142, v143
	v_add_f32_e32 v195, v195, v254
	s_nop 1
	ds_read_b64_tr_b16 v[128:129], v205 offset:256
	ds_read_b64_tr_b16 v[130:131], v205 offset:4352
	s_waitcnt lgkmcnt(8)
	v_mfma_f32_32x32x16_bf16 v[112:127], v[206:209], v[242:245], v[112:127]
	ds_read_b64_tr_b16 v[206:207], v218 offset:256
	ds_read_b64_tr_b16 v[208:209], v218 offset:4352
	s_waitcnt lgkmcnt(8)
	v_mfma_f32_32x32x16_bf16 v[96:111], v[210:213], v[242:245], v[96:111]
	ds_read_b64_tr_b16 v[210:211], v219 offset:256
	ds_read_b64_tr_b16 v[212:213], v219 offset:4352
	s_cmp_lg_u64 s[8:9], 0
	s_cbranch_scc1 .Latt_nd0_3B
	s_sub_i32 s100, s11, 1
	s_cmp_eq_u32 s11, 0
	s_cselect_b32 s100, 2, s100
	s_lshl_b32 s101, s100, 14
	s_add_i32 m0, s40, s101
	s_nop 0
	global_load_lds_dwordx4 v178, s[34:35]
.Latt_nd0_3B:
	s_waitcnt lgkmcnt(8)
	v_mfma_f32_32x32x16_bf16 v[80:95], v[214:217], v[242:245], v[80:95]
	ds_read_b64_tr_b16 v[214:215], v221 offset:256
	ds_read_b64_tr_b16 v[216:217], v221 offset:4352
	s_waitcnt lgkmcnt(8)
	v_mfma_f32_32x32x16_bf16 v[64:79], v[238:241], v[242:245], v[64:79]
	ds_read_b64_tr_b16 v[238:239], v205 offset:8192
	ds_read_b64_tr_b16 v[240:241], v205 offset:12288
	s_cmp_lg_u64 s[8:9], 0
	s_cbranch_scc1 .Latt_nd1_3B
	s_add_i32 m0, m0, 0x400
	s_nop 0
	global_load_lds_dwordx4 v180, s[34:35]
.Latt_nd1_3B:
	s_waitcnt lgkmcnt(8)
	v_mfma_f32_32x32x16_bf16 v[48:63], v[128:131], v[242:245], v[48:63]
	ds_read_b64_tr_b16 v[128:129], v218 offset:8192
	ds_read_b64_tr_b16 v[130:131], v218 offset:12288
	s_waitcnt lgkmcnt(8)
	v_mfma_f32_32x32x16_bf16 v[32:47], v[206:209], v[242:245], v[32:47]
	ds_read_b64_tr_b16 v[206:207], v219 offset:8192
	ds_read_b64_tr_b16 v[208:209], v219 offset:12288
	s_cmp_lg_u64 s[8:9], 0
	s_cbranch_scc1 .Latt_nd2_3B
	s_lshl_b32 s101, s100, 15
	s_add_i32 m0, s41, s101
	s_add_u32 s100, s34, 0xf00
	s_addc_u32 s101, s35, 0
	global_load_lds_dwordx4 v182, s[100:101]
.Latt_nd2_3B:
	s_waitcnt lgkmcnt(8)
	v_mfma_f32_32x32x16_bf16 v[16:31], v[210:213], v[242:245], v[16:31]
	ds_read_b64_tr_b16 v[210:211], v221 offset:8192
	ds_read_b64_tr_b16 v[212:213], v221 offset:12288
	s_waitcnt lgkmcnt(8)
	v_mfma_f32_32x32x16_bf16 v[0:15], v[214:217], v[242:245], v[0:15]
	ds_read_b64_tr_b16 v[214:215], v205 offset:8448
	ds_read_b64_tr_b16 v[216:217], v205 offset:12544
	s_cmp_lg_u64 s[8:9], 0
	s_cbranch_scc1 .Latt_nd3_3B
	s_add_i32 m0, m0, 0x400
	s_nop 0
	global_load_lds_dwordx4 v184, s[100:101]
.Latt_nd3_3B:
	s_waitcnt lgkmcnt(8)
	v_mfma_f32_32x32x16_bf16 v[112:127], v[238:241], v[250:253], v[112:127]
	ds_read_b64_tr_b16 v[238:239], v218 offset:8448
	ds_read_b64_tr_b16 v[240:241], v218 offset:12544
	s_waitcnt lgkmcnt(8)
	v_mfma_f32_32x32x16_bf16 v[96:111], v[128:131], v[250:253], v[96:111]
	ds_read_b64_tr_b16 v[128:129], v219 offset:8448
	ds_read_b64_tr_b16 v[130:131], v219 offset:12544
	s_cmp_lg_u64 s[8:9], 0
	s_cbranch_scc1 .Latt_nd4_3B
	s_add_i32 m0, m0, 0x400
	s_nop 0
	global_load_lds_dwordx4 v186, s[100:101]
.Latt_nd4_3B:
	s_waitcnt lgkmcnt(8)
	v_mfma_f32_32x32x16_bf16 v[80:95], v[206:209], v[250:253], v[80:95]
	ds_read_b64_tr_b16 v[206:207], v221 offset:8448
	ds_read_b64_tr_b16 v[208:209], v221 offset:12544
	s_waitcnt lgkmcnt(8)
	v_mfma_f32_32x32x16_bf16 v[64:79], v[210:213], v[250:253], v[64:79]
	s_cmp_lg_u64 s[8:9], 0
	s_cbranch_scc1 .Latt_nd5_3B
	s_add_i32 m0, m0, 0x400
	s_nop 0
	global_load_lds_dwordx4 v188, s[100:101]

.Latt_diagA_3:
	s_lshl_b32 s98, s11, 14
	s_lshl_b32 s99, s11, 15
	s_add_i32 s99, s99, 0xc000
	v_add_u32_e32 v206, s98, v196
	ds_read_b128 v[206:209], v206
	v_add_u32_e32 v210, s98, v197
	ds_read_b128 v[210:213], v210
	v_add_u32_e32 v214, s98, v198
	ds_read_b128 v[214:217], v214
	v_add_u32_e32 v238, s98, v199
	ds_read_b128 v[238:241], v238
	v_add_u32_e32 v242, s98, v200
	ds_read_b128 v[242:245], v242
	v_add_u32_e32 v250, s98, v201
	ds_read_b128 v[250:253], v250
	v_add_u32_e32 v222, s98, v202
	ds_read_b128 v[222:225], v222
	v_add_u32_e32 v226, s98, v203
	ds_read_b128 v[226:229], v226
	v_bfe_u32 v246, v204, 2, 2
	v_bfe_u32 v247, v204, 5, 1
	v_lshl_or_b32 v247, v247, 2, v246
	v_and_b32_e32 v249, 3, v204
	v_and_b32_e32 v254, 16, v204
	v_lshl_or_b32 v249, v249, 2, v254
	v_lshlrev_b32_e32 v249, 1, v249
	v_lshl_add_u32 v247, v247, 9, v249
	v_add_u32_e32 v247, s99, v247
	v_lshlrev_b32_e32 v246, 6, v246
	v_add_u32_e32 v205, v247, v246
	v_xor_b32_e32 v249, 64, v246
	v_add_u32_e32 v218, v247, v249
	v_xor_b32_e32 v249, 0x80, v246
	v_add_u32_e32 v219, v247, v249
	v_xor_b32_e32 v249, 0xc0, v246
	v_add_u32_e32 v221, v247, v249
	s_waitcnt lgkmcnt(7)
	v_mfma_f32_32x32x16_bf16 v[128:143], v[206:209], v[144:147], 0
	v_add_u32_e32 v206, s98, v196
	ds_read_b128 v[206:209], v206 offset:8192
	s_waitcnt lgkmcnt(7)
	v_mfma_f32_32x32x16_bf16 v[128:143], v[210:213], v[148:151], v[128:143]
	v_add_u32_e32 v210, s98, v197
	ds_read_b128 v[210:213], v210 offset:8192
	s_waitcnt lgkmcnt(7)
	v_mfma_f32_32x32x16_bf16 v[128:143], v[214:217], v[152:155], v[128:143]
	v_add_u32_e32 v214, s98, v198
	ds_read_b128 v[214:217], v214 offset:8192
	s_waitcnt lgkmcnt(7)
	v_mfma_f32_32x32x16_bf16 v[128:143], v[238:241], v[156:159], v[128:143]
	v_add_u32_e32 v238, s98, v199
	ds_read_b128 v[238:241], v238 offset:8192
	s_waitcnt lgkmcnt(7)
	v_mfma_f32_32x32x16_bf16 v[128:143], v[242:245], v[160:163], v[128:143]
	v_add_u32_e32 v242, s98, v200
	ds_read_b128 v[242:245], v242 offset:8192
	s_waitcnt lgkmcnt(7)
	v_mfma_f32_32x32x16_bf16 v[128:143], v[250:253], v[164:167], v[128:143]
	v_add_u32_e32 v250, s98, v201
	ds_read_b128 v[250:253], v250 offset:8192
	s_waitcnt lgkmcnt(7)
	v_mfma_f32_32x32x16_bf16 v[128:143], v[222:225], v[168:171], v[128:143]
	s_waitcnt lgkmcnt(6)
	v_mfma_f32_32x32x16_bf16 v[128:143], v[226:229], v[172:175], v[128:143]
	s_waitcnt lgkmcnt(5)
	v_mfma_f32_32x32x16_bf16 v[222:237], v[206:209], v[144:147], 0
	v_add_u32_e32 v206, s98, v202
	ds_read_b128 v[206:209], v206 offset:8192
	s_nop 7
	v_max3_f32 v246, v128, v129, v130
	v_max3_f32 v247, v131, v132, v133
	v_max3_f32 v246, v246, v134, v135
	v_max3_f32 v247, v247, v136, v137
	v_max3_f32 v246, v246, v138, v139
	v_max3_f32 v247, v247, v140, v141
	v_max3_f32 v246, v246, v142, v143
	s_waitcnt lgkmcnt(5)
	v_mfma_f32_32x32x16_bf16 v[222:237], v[210:213], v[148:151], v[222:237]
	v_add_u32_e32 v210, s98, v203
	ds_read_b128 v[210:213], v210 offset:8192
	v_max_f32_e32 v246, v246, v247
	v_mov_b32_e32 v247, v246
	v_add_f32_e32 v249, 0x41000000, v190
	s_nop 1
	v_permlane32_swap_b32_e32 v246, v247
	v_max_f32_e32 v246, v246, v247
	v_cmp_gt_f32_e32 vcc, v246, v249
	s_cbranch_vccz .Latt_nr0_3A
	v_max_f32_e32 v246, v190, v246
	v_sub_f32_e32 v190, v190, v246
	v_exp_f32_e32 v190, v190
	s_nop 0
	v_pk_mul_f32 v[126:127], v[126:127], v[190:191] op_sel_hi:[1,0]
	v_pk_mul_f32 v[124:125], v[124:125], v[190:191] op_sel_hi:[1,0]
	v_pk_mul_f32 v[122:123], v[122:123], v[190:191] op_sel_hi:[1,0]
	v_pk_mul_f32 v[120:121], v[120:121], v[190:191] op_sel_hi:[1,0]
	v_pk_mul_f32 v[118:119], v[118:119], v[190:191] op_sel_hi:[1,0]
	v_pk_mul_f32 v[116:117], v[116:117], v[190:191] op_sel_hi:[1,0]
	v_pk_mul_f32 v[114:115], v[114:115], v[190:191] op_sel_hi:[1,0]
	v_pk_mul_f32 v[112:113], v[112:113], v[190:191] op_sel_hi:[1,0]
	v_pk_mul_f32 v[110:111], v[110:111], v[190:191] op_sel_hi:[1,0]
	v_pk_mul_f32 v[108:109], v[108:109], v[190:191] op_sel_hi:[1,0]
	v_pk_mul_f32 v[106:107], v[106:107], v[190:191] op_sel_hi:[1,0]
	v_pk_mul_f32 v[104:105], v[104:105], v[190:191] op_sel_hi:[1,0]
	v_pk_mul_f32 v[102:103], v[102:103], v[190:191] op_sel_hi:[1,0]
	v_pk_mul_f32 v[100:101], v[100:101], v[190:191] op_sel_hi:[1,0]
	v_pk_mul_f32 v[98:99], v[98:99], v[190:191] op_sel_hi:[1,0]
	v_pk_mul_f32 v[96:97], v[96:97], v[190:191] op_sel_hi:[1,0]
	v_pk_mul_f32 v[94:95], v[94:95], v[190:191] op_sel_hi:[1,0]
	v_pk_mul_f32 v[92:93], v[92:93], v[190:191] op_sel_hi:[1,0]
	v_pk_mul_f32 v[90:91], v[90:91], v[190:191] op_sel_hi:[1,0]
	v_pk_mul_f32 v[88:89], v[88:89], v[190:191] op_sel_hi:[1,0]
	v_pk_mul_f32 v[86:87], v[86:87], v[190:191] op_sel_hi:[1,0]
	v_pk_mul_f32 v[84:85], v[84:85], v[190:191] op_sel_hi:[1,0]
	v_pk_mul_f32 v[82:83], v[82:83], v[190:191] op_sel_hi:[1,0]
	v_pk_mul_f32 v[80:81], v[80:81], v[190:191] op_sel_hi:[1,0]
	v_pk_mul_f32 v[78:79], v[78:79], v[190:191] op_sel_hi:[1,0]
	v_pk_mul_f32 v[76:77], v[76:77], v[190:191] op_sel_hi:[1,0]
	v_pk_mul_f32 v[74:75], v[74:75], v[190:191] op_sel_hi:[1,0]
	v_pk_mul_f32 v[72:73], v[72:73], v[190:191] op_sel_hi:[1,0]
	v_pk_mul_f32 v[70:71], v[70:71], v[190:191] op_sel_hi:[1,0]
	v_pk_mul_f32 v[68:69], v[68:69], v[190:191] op_sel_hi:[1,0]
	v_pk_mul_f32 v[66:67], v[66:67], v[190:191] op_sel_hi:[1,0]
	v_pk_mul_f32 v[64:65], v[64:65], v[190:191] op_sel_hi:[1,0]
	v_pk_mul_f32 v[62:63], v[62:63], v[190:191] op_sel_hi:[1,0]
	v_pk_mul_f32 v[60:61], v[60:61], v[190:191] op_sel_hi:[1,0]
	v_pk_mul_f32 v[58:59], v[58:59], v[190:191] op_sel_hi:[1,0]
	v_pk_mul_f32 v[56:57], v[56:57], v[190:191] op_sel_hi:[1,0]
	v_pk_mul_f32 v[54:55], v[54:55], v[190:191] op_sel_hi:[1,0]
	v_pk_mul_f32 v[52:53], v[52:53], v[190:191] op_sel_hi:[1,0]
	v_pk_mul_f32 v[50:51], v[50:51], v[190:191] op_sel_hi:[1,0]
	v_pk_mul_f32 v[48:49], v[48:49], v[190:191] op_sel_hi:[1,0]
	v_pk_mul_f32 v[46:47], v[46:47], v[190:191] op_sel_hi:[1,0]
	v_pk_mul_f32 v[44:45], v[44:45], v[190:191] op_sel_hi:[1,0]
	v_pk_mul_f32 v[42:43], v[42:43], v[190:191] op_sel_hi:[1,0]
	v_pk_mul_f32 v[40:41], v[40:41], v[190:191] op_sel_hi:[1,0]
	v_pk_mul_f32 v[38:39], v[38:39], v[190:191] op_sel_hi:[1,0]
	v_pk_mul_f32 v[36:37], v[36:37], v[190:191] op_sel_hi:[1,0]
	v_pk_mul_f32 v[34:35], v[34:35], v[190:191] op_sel_hi:[1,0]
	v_pk_mul_f32 v[32:33], v[32:33], v[190:191] op_sel_hi:[1,0]
	v_pk_mul_f32 v[30:31], v[30:31], v[190:191] op_sel_hi:[1,0]
	v_pk_mul_f32 v[28:29], v[28:29], v[190:191] op_sel_hi:[1,0]
	v_pk_mul_f32 v[26:27], v[26:27], v[190:191] op_sel_hi:[1,0]
	v_pk_mul_f32 v[24:25], v[24:25], v[190:191] op_sel_hi:[1,0]
	v_pk_mul_f32 v[22:23], v[22:23], v[190:191] op_sel_hi:[1,0]
	v_pk_mul_f32 v[20:21], v[20:21], v[190:191] op_sel_hi:[1,0]
	v_pk_mul_f32 v[18:19], v[18:19], v[190:191] op_sel_hi:[1,0]
	v_pk_mul_f32 v[16:17], v[16:17], v[190:191] op_sel_hi:[1,0]
	v_pk_mul_f32 v[14:15], v[14:15], v[190:191] op_sel_hi:[1,0]
	v_pk_mul_f32 v[12:13], v[12:13], v[190:191] op_sel_hi:[1,0]
	v_pk_mul_f32 v[10:11], v[10:11], v[190:191] op_sel_hi:[1,0]
	v_pk_mul_f32 v[8:9], v[8:9], v[190:191] op_sel_hi:[1,0]
	v_pk_mul_f32 v[6:7], v[6:7], v[190:191] op_sel_hi:[1,0]
	v_pk_mul_f32 v[4:5], v[4:5], v[190:191] op_sel_hi:[1,0]
	v_pk_mul_f32 v[2:3], v[2:3], v[190:191] op_sel_hi:[1,0]
	v_pk_mul_f32 v[0:1], v[0:1], v[190:191] op_sel_hi:[1,0]
	v_mul_f32_e32 v195, v195, v190
	v_mov_b32_e32 v190, v246
.Latt_nr0_3A:
	s_waitcnt lgkmcnt(5)
	v_mfma_f32_32x32x16_bf16 v[222:237], v[214:217], v[152:155], v[222:237]
	ds_read_b64_tr_b16 v[214:215], v205
	ds_read_b64_tr_b16 v[216:217], v205 offset:4096
	v_sub_f32_e32 v128, v128, v190
	v_exp_f32_e32 v128, v128
	v_sub_f32_e32 v129, v129, v190
	v_exp_f32_e32 v129, v129
	v_sub_f32_e32 v130, v130, v190
	v_add_f32_e32 v254, 0, v128
	v_exp_f32_e32 v130, v130
	v_sub_f32_e32 v131, v131, v190
	s_waitcnt lgkmcnt(6)
	v_mfma_f32_32x32x16_bf16 v[222:237], v[238:241], v[156:159], v[222:237]
	ds_read_b64_tr_b16 v[238:239], v218
	ds_read_b64_tr_b16 v[240:241], v218 offset:4096
	v_add_f32_e32 v254, v129, v254
	v_exp_f32_e32 v131, v131
	v_sub_f32_e32 v132, v132, v190
	v_add_f32_e32 v254, v130, v254
	v_exp_f32_e32 v132, v132
	v_sub_f32_e32 v133, v133, v190
	v_add_f32_e32 v254, v131, v254
	v_exp_f32_e32 v133, v133
	s_waitcnt lgkmcnt(7)
	v_mfma_f32_32x32x16_bf16 v[222:237], v[242:245], v[160:163], v[222:237]
	v_sub_f32_e32 v134, v134, v190
	v_add_f32_e32 v254, v132, v254
	v_exp_f32_e32 v134, v134
	v_sub_f32_e32 v135, v135, v190
	v_add_f32_e32 v254, v133, v254
	v_exp_f32_e32 v135, v135
	v_sub_f32_e32 v136, v136, v190
	v_add_f32_e32 v254, v134, v254
	s_waitcnt lgkmcnt(6)
	v_mfma_f32_32x32x16_bf16 v[222:237], v[250:253], v[164:167], v[222:237]
	v_exp_f32_e32 v136, v136
	v_sub_f32_e32 v137, v137, v190
	v_add_f32_e32 v254, v135, v254
	v_exp_f32_e32 v137, v137
	v_sub_f32_e32 v138, v138, v190
	v_add_f32_e32 v254, v136, v254
	v_exp_f32_e32 v138, v138
	v_sub_f32_e32 v139, v139, v190
	s_waitcnt lgkmcnt(5)
	v_mfma_f32_32x32x16_bf16 v[222:237], v[206:209], v[168:171], v[222:237]
	ds_read_b64_tr_b16 v[206:207], v219
	ds_read_b64_tr_b16 v[208:209], v219 offset:4096
	v_add_f32_e32 v254, v137, v254
	v_exp_f32_e32 v139, v139
	v_sub_f32_e32 v140, v140, v190
	v_add_f32_e32 v254, v138, v254
	v_exp_f32_e32 v140, v140
	v_sub_f32_e32 v141, v141, v190
	v_add_f32_e32 v254, v139, v254
	v_exp_f32_e32 v141, v141
	s_waitcnt lgkmcnt(6)
	v_mfma_f32_32x32x16_bf16 v[222:237], v[210:213], v[172:175], v[222:237]
	ds_read_b64_tr_b16 v[210:211], v221
	ds_read_b64_tr_b16 v[212:213], v221 offset:4096
	v_sub_f32_e32 v142, v142, v190
	v_add_f32_e32 v254, v140, v254
	v_exp_f32_e32 v142, v142
	v_sub_f32_e32 v143, v143, v190
	v_add_f32_e32 v254, v141, v254
	v_exp_f32_e32 v143, v143
	v_add_f32_e32 v254, v142, v254
	v_add_f32_e32 v254, v143, v254
	v_cvt_pk_bf16_f32 v242, v128, v129
	v_cvt_pk_bf16_f32 v243, v130, v131
	v_cvt_pk_bf16_f32 v244, v132, v133
	v_cvt_pk_bf16_f32 v245, v134, v135
	v_cvt_pk_bf16_f32 v250, v136, v137
	v_cvt_pk_bf16_f32 v251, v138, v139
	v_cvt_pk_bf16_f32 v252, v140, v141
	v_cvt_pk_bf16_f32 v253, v142, v143
	v_add_f32_e32 v195, v195, v254
	s_nop 1
	ds_read_b64_tr_b16 v[128:129], v205 offset:256
	ds_read_b64_tr_b16 v[130:131], v205 offset:4352
	s_waitcnt lgkmcnt(8)
	v_mfma_f32_32x32x16_bf16 v[112:127], v[214:217], v[242:245], v[112:127]
	ds_read_b64_tr_b16 v[214:215], v218 offset:256
	ds_read_b64_tr_b16 v[216:217], v218 offset:4352
	v_and_or_b32 v246, v204, 31, s80
	v_bfe_u32 v247, v204, 5, 1
	s_add_i32 s100, s14, 32
	v_lshl_add_u32 v247, v247, 2, s100
	v_add_u32_e32 v249, 0, v247
	v_cmp_le_i32_e32 vcc, v249, v246
	v_add_u32_e32 v254, 1, v247
	s_nop 0
	v_cndmask_b32_e32 v222, v192, v222, vcc
	v_cmp_le_i32_e32 vcc, v254, v246
	v_add_u32_e32 v249, 2, v247
	s_nop 0
	v_cndmask_b32_e32 v223, v192, v223, vcc
	v_cmp_le_i32_e32 vcc, v249, v246
	v_add_u32_e32 v254, 3, v247
	s_nop 0
	v_cndmask_b32_e32 v224, v192, v224, vcc
	v_cmp_le_i32_e32 vcc, v254, v246
	v_add_u32_e32 v249, 8, v247
	s_nop 0
	v_cndmask_b32_e32 v225, v192, v225, vcc
	v_cmp_le_i32_e32 vcc, v249, v246
	v_add_u32_e32 v254, 9, v247
	s_nop 0
	v_cndmask_b32_e32 v226, v192, v226, vcc
	v_cmp_le_i32_e32 vcc, v254, v246
	v_add_u32_e32 v249, 10, v247
	s_nop 0
	v_cndmask_b32_e32 v227, v192, v227, vcc
	v_cmp_le_i32_e32 vcc, v249, v246
	v_add_u32_e32 v254, 11, v247
	s_nop 0
	v_cndmask_b32_e32 v228, v192, v228, vcc
	v_cmp_le_i32_e32 vcc, v254, v246
	s_waitcnt lgkmcnt(8)
	v_mfma_f32_32x32x16_bf16 v[96:111], v[238:241], v[242:245], v[96:111]
	ds_read_b64_tr_b16 v[238:239], v219 offset:256
	ds_read_b64_tr_b16 v[240:241], v219 offset:4352
	v_add_u32_e32 v249, 16, v247
	s_nop 0
	v_cndmask_b32_e32 v229, v192, v229, vcc
	v_cmp_le_i32_e32 vcc, v249, v246
	v_add_u32_e32 v254, 17, v247
	s_nop 0
	v_cndmask_b32_e32 v230, v192, v230, vcc
	v_cmp_le_i32_e32 vcc, v254, v246
	v_add_u32_e32 v249, 18, v247
	s_nop 0
	v_cndmask_b32_e32 v231, v192, v231, vcc
	v_cmp_le_i32_e32 vcc, v249, v246
	v_add_u32_e32 v254, 19, v247
	s_nop 0
	v_cndmask_b32_e32 v232, v192, v232, vcc
	v_cmp_le_i32_e32 vcc, v254, v246
	v_add_u32_e32 v249, 24, v247
	s_nop 0
	v_cndmask_b32_e32 v233, v192, v233, vcc
	v_cmp_le_i32_e32 vcc, v249, v246
	v_add_u32_e32 v254, 25, v247
	s_nop 0
	v_cndmask_b32_e32 v234, v192, v234, vcc
	v_cmp_le_i32_e32 vcc, v254, v246
	v_add_u32_e32 v249, 26, v247
	s_nop 0
	v_cndmask_b32_e32 v235, v192, v235, vcc
	v_cmp_le_i32_e32 vcc, v249, v246
	v_add_u32_e32 v254, 27, v247
	s_nop 0
	v_cndmask_b32_e32 v236, v192, v236, vcc
	v_cmp_le_i32_e32 vcc, v254, v246
	s_nop 1
	v_cndmask_b32_e32 v237, v192, v237, vcc
	s_waitcnt lgkmcnt(8)
	v_mfma_f32_32x32x16_bf16 v[80:95], v[206:209], v[242:245], v[80:95]
	ds_read_b64_tr_b16 v[206:207], v221 offset:256
	ds_read_b64_tr_b16 v[208:209], v221 offset:4352
	v_max3_f32 v246, v222, v223, v224
	v_max3_f32 v247, v225, v226, v227
	v_max3_f32 v246, v246, v228, v229
	v_max3_f32 v247, v247, v230, v231
	v_max3_f32 v246, v246, v232, v233
	v_max3_f32 v247, v247, v234, v235
	s_waitcnt lgkmcnt(8)
	v_mfma_f32_32x32x16_bf16 v[64:79], v[210:213], v[242:245], v[64:79]
	ds_read_b64_tr_b16 v[210:211], v205 offset:8192
	ds_read_b64_tr_b16 v[212:213], v205 offset:12288
	v_max3_f32 v246, v246, v236, v237
	v_max_f32_e32 v246, v246, v247
	v_mov_b32_e32 v247, v246
	v_add_f32_e32 v249, 0x41000000, v190
	s_nop 1
	s_waitcnt lgkmcnt(8)
	v_mfma_f32_32x32x16_bf16 v[48:63], v[128:131], v[242:245], v[48:63]
	ds_read_b64_tr_b16 v[128:129], v218 offset:8192
	ds_read_b64_tr_b16 v[130:131], v218 offset:12288
	v_permlane32_swap_b32_e32 v246, v247
	v_max_f32_e32 v246, v246, v247
	v_cmp_gt_f32_e32 vcc, v246, v249
	s_cbranch_vccnz .Latt_rs1_3A
	s_waitcnt lgkmcnt(8)
	v_mfma_f32_32x32x16_bf16 v[32:47], v[214:217], v[242:245], v[32:47]
	ds_read_b64_tr_b16 v[214:215], v219 offset:8192
	ds_read_b64_tr_b16 v[216:217], v219 offset:12288
	v_sub_f32_e32 v222, v222, v190
	v_exp_f32_e32 v222, v222
	v_sub_f32_e32 v223, v223, v190
	v_exp_f32_e32 v223, v223
	v_sub_f32_e32 v224, v224, v190
	s_waitcnt lgkmcnt(8)
	v_mfma_f32_32x32x16_bf16 v[16:31], v[238:241], v[242:245], v[16:31]
	ds_read_b64_tr_b16 v[238:239], v221 offset:8192
	ds_read_b64_tr_b16 v[240:241], v221 offset:12288
	v_add_f32_e32 v254, 0, v222
	v_exp_f32_e32 v224, v224
	v_sub_f32_e32 v225, v225, v190
	v_add_f32_e32 v254, v223, v254
	v_exp_f32_e32 v225, v225
	s_waitcnt lgkmcnt(8)
	v_mfma_f32_32x32x16_bf16 v[0:15], v[206:209], v[242:245], v[0:15]
	ds_read_b64_tr_b16 v[206:207], v205 offset:8448
	ds_read_b64_tr_b16 v[208:209], v205 offset:12544
	v_sub_f32_e32 v226, v226, v190
	v_add_f32_e32 v254, v224, v254
	v_exp_f32_e32 v226, v226
	v_sub_f32_e32 v227, v227, v190
	v_add_f32_e32 v254, v225, v254
	s_waitcnt lgkmcnt(8)
	v_mfma_f32_32x32x16_bf16 v[112:127], v[210:213], v[250:253], v[112:127]
	ds_read_b64_tr_b16 v[210:211], v218 offset:8448
	ds_read_b64_tr_b16 v[212:213], v218 offset:12544
	v_exp_f32_e32 v227, v227
	v_sub_f32_e32 v228, v228, v190
	v_add_f32_e32 v254, v226, v254
	v_exp_f32_e32 v228, v228
	v_sub_f32_e32 v229, v229, v190
	s_waitcnt lgkmcnt(8)
	v_mfma_f32_32x32x16_bf16 v[96:111], v[128:131], v[250:253], v[96:111]
	ds_read_b64_tr_b16 v[128:129], v219 offset:8448
	ds_read_b64_tr_b16 v[130:131], v219 offset:12544
	v_add_f32_e32 v254, v227, v254
	v_exp_f32_e32 v229, v229
	v_sub_f32_e32 v230, v230, v190
	v_add_f32_e32 v254, v228, v254
	s_waitcnt lgkmcnt(8)
	v_mfma_f32_32x32x16_bf16 v[80:95], v[214:217], v[250:253], v[80:95]
	ds_read_b64_tr_b16 v[214:215], v221 offset:8448
	ds_read_b64_tr_b16 v[216:217], v221 offset:12544
	v_exp_f32_e32 v230, v230
	v_sub_f32_e32 v231, v231, v190
	v_add_f32_e32 v254, v229, v254
	v_exp_f32_e32 v231, v231
	s_waitcnt lgkmcnt(8)
	v_mfma_f32_32x32x16_bf16 v[64:79], v[238:241], v[250:253], v[64:79]
	ds_read_b64_tr_b16 v[238:239], v205 offset:16384
	ds_read_b64_tr_b16 v[240:241], v205 offset:20480
	v_sub_f32_e32 v232, v232, v190
	v_add_f32_e32 v254, v230, v254
	v_exp_f32_e32 v232, v232
	v_sub_f32_e32 v233, v233, v190
	s_waitcnt lgkmcnt(8)
	v_mfma_f32_32x32x16_bf16 v[48:63], v[206:209], v[250:253], v[48:63]
	ds_read_b64_tr_b16 v[206:207], v218 offset:16384
	ds_read_b64_tr_b16 v[208:209], v218 offset:20480
	v_add_f32_e32 v254, v231, v254
	v_exp_f32_e32 v233, v233
	v_sub_f32_e32 v234, v234, v190
	v_add_f32_e32 v254, v232, v254
	s_waitcnt lgkmcnt(8)
	v_mfma_f32_32x32x16_bf16 v[32:47], v[210:213], v[250:253], v[32:47]
	ds_read_b64_tr_b16 v[210:211], v219 offset:16384
	ds_read_b64_tr_b16 v[212:213], v219 offset:20480
	v_exp_f32_e32 v234, v234
	v_sub_f32_e32 v235, v235, v190
	v_add_f32_e32 v254, v233, v254
	v_exp_f32_e32 v235, v235
	s_waitcnt lgkmcnt(8)
	v_mfma_f32_32x32x16_bf16 v[16:31], v[128:131], v[250:253], v[16:31]
	ds_read_b64_tr_b16 v[128:129], v221 offset:16384
	ds_read_b64_tr_b16 v[130:131], v221 offset:20480
	v_sub_f32_e32 v236, v236, v190
	v_add_f32_e32 v254, v234, v254
	v_exp_f32_e32 v236, v236
	v_sub_f32_e32 v237, v237, v190
	s_waitcnt lgkmcnt(8)
	v_mfma_f32_32x32x16_bf16 v[0:15], v[214:217], v[250:253], v[0:15]
	ds_read_b64_tr_b16 v[214:215], v205 offset:16640
	ds_read_b64_tr_b16 v[216:217], v205 offset:20736
	v_add_f32_e32 v254, v235, v254
	v_exp_f32_e32 v237, v237
	v_add_f32_e32 v254, v236, v254
	v_add_f32_e32 v254, v237, v254
	v_cvt_pk_bf16_f32 v242, v222, v223
	v_cvt_pk_bf16_f32 v243, v224, v225
	v_cvt_pk_bf16_f32 v244, v226, v227
	v_cvt_pk_bf16_f32 v245, v228, v229
	v_cvt_pk_bf16_f32 v250, v230, v231
	v_cvt_pk_bf16_f32 v251, v232, v233
	v_cvt_pk_bf16_f32 v252, v234, v235
	v_cvt_pk_bf16_f32 v253, v236, v237
	v_add_f32_e32 v195, v195, v254
	s_nop 1

.Latt_rs1_3F:
	s_waitcnt lgkmcnt(8)
	v_mfma_f32_32x32x16_bf16 v[32:47], v[214:217], v[242:245], v[32:47]
	ds_read_b64_tr_b16 v[214:215], v219 offset:8192
	ds_read_b64_tr_b16 v[216:217], v219 offset:12288
	s_waitcnt lgkmcnt(8)
	v_mfma_f32_32x32x16_bf16 v[16:31], v[238:241], v[242:245], v[16:31]
	ds_read_b64_tr_b16 v[238:239], v221 offset:8192
	ds_read_b64_tr_b16 v[240:241], v221 offset:12288
	s_waitcnt lgkmcnt(8)
	v_mfma_f32_32x32x16_bf16 v[0:15], v[206:209], v[242:245], v[0:15]
	ds_read_b64_tr_b16 v[206:207], v205 offset:8448
	ds_read_b64_tr_b16 v[208:209], v205 offset:12544
	s_waitcnt lgkmcnt(8)
	v_mfma_f32_32x32x16_bf16 v[112:127], v[210:213], v[250:253], v[112:127]
	ds_read_b64_tr_b16 v[210:211], v218 offset:8448
	ds_read_b64_tr_b16 v[212:213], v218 offset:12544
	s_waitcnt lgkmcnt(8)
	v_mfma_f32_32x32x16_bf16 v[96:111], v[128:131], v[250:253], v[96:111]
	ds_read_b64_tr_b16 v[128:129], v219 offset:8448
	ds_read_b64_tr_b16 v[130:131], v219 offset:12544
	s_waitcnt lgkmcnt(8)
	v_mfma_f32_32x32x16_bf16 v[80:95], v[214:217], v[250:253], v[80:95]
	ds_read_b64_tr_b16 v[214:215], v221 offset:8448
	ds_read_b64_tr_b16 v[216:217], v221 offset:12544
	s_waitcnt lgkmcnt(8)
	v_mfma_f32_32x32x16_bf16 v[64:79], v[238:241], v[250:253], v[64:79]
	ds_read_b64_tr_b16 v[238:239], v205 offset:16384
	ds_read_b64_tr_b16 v[240:241], v205 offset:20480
	s_waitcnt lgkmcnt(8)
	v_mfma_f32_32x32x16_bf16 v[48:63], v[206:209], v[250:253], v[48:63]
	ds_read_b64_tr_b16 v[206:207], v218 offset:16384
	ds_read_b64_tr_b16 v[208:209], v218 offset:20480
	s_waitcnt lgkmcnt(8)
	v_mfma_f32_32x32x16_bf16 v[32:47], v[210:213], v[250:253], v[32:47]
	ds_read_b64_tr_b16 v[210:211], v219 offset:16384
	ds_read_b64_tr_b16 v[212:213], v219 offset:20480
	s_waitcnt lgkmcnt(8)
	v_mfma_f32_32x32x16_bf16 v[16:31], v[128:131], v[250:253], v[16:31]
	ds_read_b64_tr_b16 v[128:129], v221 offset:16384
	ds_read_b64_tr_b16 v[130:131], v221 offset:20480
	s_waitcnt lgkmcnt(8)
	v_mfma_f32_32x32x16_bf16 v[0:15], v[214:217], v[250:253], v[0:15]
	ds_read_b64_tr_b16 v[214:215], v205 offset:16640
	ds_read_b64_tr_b16 v[216:217], v205 offset:20736
	s_nop 11
	v_max_f32_e32 v246, v190, v246
	v_sub_f32_e32 v190, v190, v246
	v_exp_f32_e32 v190, v190
	s_nop 0
	v_pk_mul_f32 v[126:127], v[126:127], v[190:191] op_sel_hi:[1,0]
	v_pk_mul_f32 v[124:125], v[124:125], v[190:191] op_sel_hi:[1,0]
	v_pk_mul_f32 v[122:123], v[122:123], v[190:191] op_sel_hi:[1,0]
	v_pk_mul_f32 v[120:121], v[120:121], v[190:191] op_sel_hi:[1,0]
	v_pk_mul_f32 v[118:119], v[118:119], v[190:191] op_sel_hi:[1,0]
	v_pk_mul_f32 v[116:117], v[116:117], v[190:191] op_sel_hi:[1,0]
	v_pk_mul_f32 v[114:115], v[114:115], v[190:191] op_sel_hi:[1,0]
	v_pk_mul_f32 v[112:113], v[112:113], v[190:191] op_sel_hi:[1,0]
	v_pk_mul_f32 v[110:111], v[110:111], v[190:191] op_sel_hi:[1,0]
	v_pk_mul_f32 v[108:109], v[108:109], v[190:191] op_sel_hi:[1,0]
	v_pk_mul_f32 v[106:107], v[106:107], v[190:191] op_sel_hi:[1,0]
	v_pk_mul_f32 v[104:105], v[104:105], v[190:191] op_sel_hi:[1,0]
	v_pk_mul_f32 v[102:103], v[102:103], v[190:191] op_sel_hi:[1,0]
	v_pk_mul_f32 v[100:101], v[100:101], v[190:191] op_sel_hi:[1,0]
	v_pk_mul_f32 v[98:99], v[98:99], v[190:191] op_sel_hi:[1,0]
	v_pk_mul_f32 v[96:97], v[96:97], v[190:191] op_sel_hi:[1,0]
	v_pk_mul_f32 v[94:95], v[94:95], v[190:191] op_sel_hi:[1,0]
	v_pk_mul_f32 v[92:93], v[92:93], v[190:191] op_sel_hi:[1,0]
	v_pk_mul_f32 v[90:91], v[90:91], v[190:191] op_sel_hi:[1,0]
	v_pk_mul_f32 v[88:89], v[88:89], v[190:191] op_sel_hi:[1,0]
	v_pk_mul_f32 v[86:87], v[86:87], v[190:191] op_sel_hi:[1,0]
	v_pk_mul_f32 v[84:85], v[84:85], v[190:191] op_sel_hi:[1,0]
	v_pk_mul_f32 v[82:83], v[82:83], v[190:191] op_sel_hi:[1,0]
	v_pk_mul_f32 v[80:81], v[80:81], v[190:191] op_sel_hi:[1,0]
	v_pk_mul_f32 v[78:79], v[78:79], v[190:191] op_sel_hi:[1,0]
	v_pk_mul_f32 v[76:77], v[76:77], v[190:191] op_sel_hi:[1,0]
	v_pk_mul_f32 v[74:75], v[74:75], v[190:191] op_sel_hi:[1,0]
	v_pk_mul_f32 v[72:73], v[72:73], v[190:191] op_sel_hi:[1,0]
	v_pk_mul_f32 v[70:71], v[70:71], v[190:191] op_sel_hi:[1,0]
	v_pk_mul_f32 v[68:69], v[68:69], v[190:191] op_sel_hi:[1,0]
	v_pk_mul_f32 v[66:67], v[66:67], v[190:191] op_sel_hi:[1,0]
	v_pk_mul_f32 v[64:65], v[64:65], v[190:191] op_sel_hi:[1,0]
	v_pk_mul_f32 v[62:63], v[62:63], v[190:191] op_sel_hi:[1,0]
	v_pk_mul_f32 v[60:61], v[60:61], v[190:191] op_sel_hi:[1,0]
	v_pk_mul_f32 v[58:59], v[58:59], v[190:191] op_sel_hi:[1,0]
	v_pk_mul_f32 v[56:57], v[56:57], v[190:191] op_sel_hi:[1,0]
	v_pk_mul_f32 v[54:55], v[54:55], v[190:191] op_sel_hi:[1,0]
	v_pk_mul_f32 v[52:53], v[52:53], v[190:191] op_sel_hi:[1,0]
	v_pk_mul_f32 v[50:51], v[50:51], v[190:191] op_sel_hi:[1,0]
	v_pk_mul_f32 v[48:49], v[48:49], v[190:191] op_sel_hi:[1,0]
	v_pk_mul_f32 v[46:47], v[46:47], v[190:191] op_sel_hi:[1,0]
	v_pk_mul_f32 v[44:45], v[44:45], v[190:191] op_sel_hi:[1,0]
	v_pk_mul_f32 v[42:43], v[42:43], v[190:191] op_sel_hi:[1,0]
	v_pk_mul_f32 v[40:41], v[40:41], v[190:191] op_sel_hi:[1,0]
	v_pk_mul_f32 v[38:39], v[38:39], v[190:191] op_sel_hi:[1,0]
	v_pk_mul_f32 v[36:37], v[36:37], v[190:191] op_sel_hi:[1,0]
	v_pk_mul_f32 v[34:35], v[34:35], v[190:191] op_sel_hi:[1,0]
	v_pk_mul_f32 v[32:33], v[32:33], v[190:191] op_sel_hi:[1,0]
	v_pk_mul_f32 v[30:31], v[30:31], v[190:191] op_sel_hi:[1,0]
	v_pk_mul_f32 v[28:29], v[28:29], v[190:191] op_sel_hi:[1,0]
	v_pk_mul_f32 v[26:27], v[26:27], v[190:191] op_sel_hi:[1,0]
	v_pk_mul_f32 v[24:25], v[24:25], v[190:191] op_sel_hi:[1,0]
	v_pk_mul_f32 v[22:23], v[22:23], v[190:191] op_sel_hi:[1,0]
	v_pk_mul_f32 v[20:21], v[20:21], v[190:191] op_sel_hi:[1,0]
	v_pk_mul_f32 v[18:19], v[18:19], v[190:191] op_sel_hi:[1,0]
	v_pk_mul_f32 v[16:17], v[16:17], v[190:191] op_sel_hi:[1,0]
	v_pk_mul_f32 v[14:15], v[14:15], v[190:191] op_sel_hi:[1,0]
	v_pk_mul_f32 v[12:13], v[12:13], v[190:191] op_sel_hi:[1,0]
	v_pk_mul_f32 v[10:11], v[10:11], v[190:191] op_sel_hi:[1,0]
	v_pk_mul_f32 v[8:9], v[8:9], v[190:191] op_sel_hi:[1,0]
	v_pk_mul_f32 v[6:7], v[6:7], v[190:191] op_sel_hi:[1,0]
	v_pk_mul_f32 v[4:5], v[4:5], v[190:191] op_sel_hi:[1,0]
	v_pk_mul_f32 v[2:3], v[2:3], v[190:191] op_sel_hi:[1,0]
	v_pk_mul_f32 v[0:1], v[0:1], v[190:191] op_sel_hi:[1,0]
	v_mul_f32_e32 v195, v195, v190
	v_mov_b32_e32 v190, v246
	v_sub_f32_e32 v222, v222, v190
	v_exp_f32_e32 v222, v222
	v_sub_f32_e32 v223, v223, v190
	v_exp_f32_e32 v223, v223
	v_sub_f32_e32 v224, v224, v190
	v_add_f32_e32 v254, 0, v222
	v_exp_f32_e32 v224, v224
	v_sub_f32_e32 v225, v225, v190
	v_add_f32_e32 v254, v223, v254
	v_exp_f32_e32 v225, v225
	v_sub_f32_e32 v226, v226, v190
	v_add_f32_e32 v254, v224, v254
	v_exp_f32_e32 v226, v226
	v_sub_f32_e32 v227, v227, v190
	v_add_f32_e32 v254, v225, v254
	v_exp_f32_e32 v227, v227
	v_sub_f32_e32 v228, v228, v190
	v_add_f32_e32 v254, v226, v254
	v_exp_f32_e32 v228, v228
	v_sub_f32_e32 v229, v229, v190
	v_add_f32_e32 v254, v227, v254
	v_exp_f32_e32 v229, v229
	v_sub_f32_e32 v230, v230, v190
	v_add_f32_e32 v254, v228, v254
	v_exp_f32_e32 v230, v230
	v_sub_f32_e32 v231, v231, v190
	v_add_f32_e32 v254, v229, v254
	v_exp_f32_e32 v231, v231
	v_sub_f32_e32 v232, v232, v190
	v_add_f32_e32 v254, v230, v254
	v_exp_f32_e32 v232, v232
	v_sub_f32_e32 v233, v233, v190
	v_add_f32_e32 v254, v231, v254
	v_exp_f32_e32 v233, v233
	v_sub_f32_e32 v234, v234, v190
	v_add_f32_e32 v254, v232, v254
	v_exp_f32_e32 v234, v234
	v_sub_f32_e32 v235, v235, v190
	v_add_f32_e32 v254, v233, v254
	v_exp_f32_e32 v235, v235
	v_sub_f32_e32 v236, v236, v190
	v_add_f32_e32 v254, v234, v254
	v_exp_f32_e32 v236, v236
	v_sub_f32_e32 v237, v237, v190
	v_add_f32_e32 v254, v235, v254
	v_exp_f32_e32 v237, v237
	v_add_f32_e32 v254, v236, v254
	v_add_f32_e32 v254, v237, v254
	v_cvt_pk_bf16_f32 v242, v222, v223
	v_cvt_pk_bf16_f32 v243, v224, v225
	v_cvt_pk_bf16_f32 v244, v226, v227
	v_cvt_pk_bf16_f32 v245, v228, v229
	v_cvt_pk_bf16_f32 v250, v230, v231
	v_cvt_pk_bf16_f32 v251, v232, v233
	v_cvt_pk_bf16_f32 v252, v234, v235
	v_cvt_pk_bf16_f32 v253, v236, v237
	v_add_f32_e32 v195, v195, v254
	s_nop 1
	s_branch .Latt_pv1_3F
	s_lshl_b32 s15, s11, 14
	s_add_i32 s16, s15, 0
	v_add_u32_e32 v207, s16, v196
	ds_read_b128 v[128:131], v207
	v_add_u32_e32 v208, s16, v197
	ds_read_b128 v[210:213], v208
	v_add_u32_e32 v209, s16, v198
	v_lshrrev_b32_e32 v205, 3, v204
	s_add_i32 s17, s14, 31
	v_and_or_b32 v206, v204, 31, s80
	s_cmp_le_i32 s17, s80
	s_waitcnt lgkmcnt(1)
	v_mfma_f32_32x32x16_bf16 v[128:143], v[128:131], v[144:147], 0
	s_waitcnt lgkmcnt(0)
	v_mfma_f32_32x32x16_bf16 v[128:143], v[210:213], v[148:151], v[128:143]
	ds_read_b128 v[212:215], v209
	v_add_u32_e32 v210, s16, v199
	ds_read_b128 v[216:219], v210
	v_add_u32_e32 v211, s16, v200
	s_waitcnt lgkmcnt(1)
	v_mfma_f32_32x32x16_bf16 v[128:143], v[212:215], v[152:155], v[128:143]
	v_add_u32_e32 v213, s16, v201
	v_and_b32_e32 v212, 4, v205
	ds_read_b128 v[222:225], v213
	s_waitcnt lgkmcnt(1)
	v_mfma_f32_32x32x16_bf16 v[128:143], v[216:219], v[156:159], v[128:143]
	ds_read_b128 v[214:217], v211
	s_waitcnt lgkmcnt(0)
	v_mfma_f32_32x32x16_bf16 v[128:143], v[214:217], v[160:163], v[128:143]
	v_add_u32_e32 v214, s16, v202
	ds_read_b128 v[216:219], v214
	v_add_u32_e32 v215, s16, v203
	v_mfma_f32_32x32x16_bf16 v[128:143], v[222:225], v[164:167], v[128:143]
	ds_read_b128 v[222:225], v215
	s_waitcnt lgkmcnt(1)
	v_mfma_f32_32x32x16_bf16 v[128:143], v[216:219], v[168:171], v[128:143]
	s_waitcnt lgkmcnt(0)
	v_mfma_f32_32x32x16_bf16 v[128:143], v[222:225], v[172:175], v[128:143]
	s_cbranch_scc1 .LBB0_907
	v_add_u32_e32 v205, s14, v212
	v_cmp_lt_i32_e32 vcc, v205, v206
	v_add_u32_e32 v216, 2, v205
	s_nop 7
	v_cndmask_b32_e32 v129, v192, v129, vcc
	v_cmp_le_i32_e32 vcc, v205, v206
	s_nop 1
	v_cndmask_b32_e32 v128, v192, v128, vcc
	v_cmp_le_i32_e32 vcc, v216, v206
	v_add_u32_e32 v216, 3, v205
	s_nop 0
	v_cndmask_b32_e32 v130, v192, v130, vcc
	v_cmp_le_i32_e32 vcc, v216, v206
	v_add_u32_e32 v216, 8, v205
	s_nop 0
	v_cndmask_b32_e32 v131, v192, v131, vcc
	v_cmp_le_i32_e32 vcc, v216, v206
	v_add_u32_e32 v216, 9, v205
	s_nop 0
	v_cndmask_b32_e32 v132, v192, v132, vcc
	v_cmp_le_i32_e32 vcc, v216, v206
	v_add_u32_e32 v216, 10, v205
	s_nop 0
	v_cndmask_b32_e32 v133, v192, v133, vcc
	v_cmp_le_i32_e32 vcc, v216, v206
	v_add_u32_e32 v216, 11, v205
	s_nop 0
	v_cndmask_b32_e32 v134, v192, v134, vcc
	v_cmp_le_i32_e32 vcc, v216, v206
	v_add_u32_e32 v216, 16, v205
	s_nop 0
	v_cndmask_b32_e32 v135, v192, v135, vcc
	v_cmp_le_i32_e32 vcc, v216, v206
	v_add_u32_e32 v216, 17, v205
	s_nop 0
	v_cndmask_b32_e32 v136, v192, v136, vcc
	v_cmp_le_i32_e32 vcc, v216, v206
	v_add_u32_e32 v216, 18, v205
	s_nop 0
	v_cndmask_b32_e32 v137, v192, v137, vcc
	v_cmp_le_i32_e32 vcc, v216, v206
	v_add_u32_e32 v216, 19, v205
	s_nop 0
	v_cndmask_b32_e32 v138, v192, v138, vcc
	v_cmp_le_i32_e32 vcc, v216, v206
	v_add_u32_e32 v216, 24, v205
	s_nop 0
	v_cndmask_b32_e32 v139, v192, v139, vcc
	v_cmp_le_i32_e32 vcc, v216, v206
	v_add_u32_e32 v216, 25, v205
	s_nop 0
	v_cndmask_b32_e32 v140, v192, v140, vcc
	v_cmp_le_i32_e32 vcc, v216, v206
	v_add_u32_e32 v216, 26, v205
	v_add_u32_e32 v205, 27, v205
	v_cndmask_b32_e32 v141, v192, v141, vcc
	v_cmp_le_i32_e32 vcc, v216, v206
	s_nop 1
	v_cndmask_b32_e32 v142, v192, v142, vcc
	v_cmp_le_i32_e32 vcc, v205, v206
	s_nop 1
	v_cndmask_b32_e32 v143, v192, v143, vcc

.LBB0_1799:
	s_cmp_ge_u32 s38, s70
	s_cselect_b64 s[18:19], -1, 0
	v_mov_b32_e32 v203, v176
	s_and_b64 vcc, exec, s[18:19]
	s_cbranch_vccnz .LBB0_1801
	s_cmp_le_i32 s39, s72
	s_cbranch_scc1 .LBB0_1801
	v_sub_co_u32_e64 v128, s[22:23], s76, 1
	s_nop 1
	v_cndmask_b32_e64 v130, v128, 2, s[22:23]
	v_lshlrev_b32_e32 v128, 14, v130
	v_add_u32_e32 v131, s73, v128
	v_lshl_add_u64 v[128:129], s[14:15], 0, v[178:179]
	s_add_u32 s22, s14, 0x1000
	v_readfirstlane_b32 s77, v131
	s_mov_b32 s78, m0
	s_mov_b32 m0, s77
	s_nop 0
	global_load_lds_dwordx4 v[128:129], off
	s_mov_b32 m0, s78
	v_lshl_add_u64 v[128:129], s[14:15], 0, v[180:181]
	s_addc_u32 s23, s15, 0
	s_addk_i32 s77, 0x400
	s_mov_b32 s78, m0
	s_mov_b32 m0, s77
	s_nop 0
	global_load_lds_dwordx4 v[128:129], off
	s_mov_b32 m0, s78
	v_lshlrev_b32_e32 v128, 15, v130
	v_add_u32_e32 v130, s74, v128
	v_lshl_add_u64 v[128:129], s[22:23], 0, v[182:183]
	v_readfirstlane_b32 s77, v130
	s_mov_b32 s78, m0
	s_mov_b32 m0, s77
	s_nop 0
	global_load_lds_dwordx4 v[128:129], off
	s_mov_b32 m0, s78
	v_lshl_add_u64 v[128:129], s[22:23], 0, v[184:185]
	s_add_i32 s78, s77, 0x400
	s_mov_b32 s79, m0
	s_mov_b32 m0, s78
	s_nop 0
	global_load_lds_dwordx4 v[128:129], off
	s_mov_b32 m0, s79
	v_lshl_add_u64 v[128:129], s[22:23], 0, v[186:187]
	s_add_i32 s78, s77, 0x800
	s_mov_b32 s79, m0
	s_mov_b32 m0, s78
	s_nop 0
	global_load_lds_dwordx4 v[128:129], off
	s_mov_b32 m0, s79
	v_lshl_add_u64 v[128:129], s[22:23], 0, v[188:189]
	s_add_i32 s22, s77, 0xc00
	s_mov_b32 s23, m0
	s_mov_b32 m0, s22
	s_nop 0
	global_load_lds_dwordx4 v[128:129], off
	s_mov_b32 m0, s23
.LBB0_1801:
	s_cmp_gt_i32 s39, s72
	s_cbranch_scc1 .LBB0_1812
	s_add_i32 s100, s39, 63
	s_cmp_le_i32 s100, s71
	s_cbranch_scc1 .Latt_full_4
	s_add_i32 s100, s39, 32
	s_cmp_le_i32 s100, s72
	s_cbranch_scc1 .Latt_diagA_4
	s_lshl_b32 s98, s76, 14
	s_lshl_b32 s99, s76, 15
	s_add_i32 s99, s99, 0xc000
	v_add_u32_e32 v206, s98, v194
	ds_read_b128 v[206:209], v206
	v_add_u32_e32 v210, s98, v195
	ds_read_b128 v[210:213], v210
	v_add_u32_e32 v214, s98, v196
	ds_read_b128 v[214:217], v214
	v_add_u32_e32 v238, s98, v197
	ds_read_b128 v[238:241], v238
	v_add_u32_e32 v242, s98, v198
	ds_read_b128 v[242:245], v242
	v_add_u32_e32 v250, s98, v199
	ds_read_b128 v[250:253], v250
	v_add_u32_e32 v222, s98, v200
	ds_read_b128 v[222:225], v222
	v_add_u32_e32 v226, s98, v201
	ds_read_b128 v[226:229], v226
	v_bfe_u32 v246, v203, 2, 2
	v_bfe_u32 v247, v203, 5, 1
	v_lshl_or_b32 v247, v247, 2, v246
	v_and_b32_e32 v249, 3, v203
	v_and_b32_e32 v254, 16, v203
	v_lshl_or_b32 v249, v249, 2, v254
	v_lshlrev_b32_e32 v249, 1, v249
	v_lshl_add_u32 v247, v247, 9, v249
	v_add_u32_e32 v247, s99, v247
	v_lshlrev_b32_e32 v246, 6, v246
	v_add_u32_e32 v205, v247, v246
	v_xor_b32_e32 v249, 64, v246
	v_add_u32_e32 v218, v247, v249
	v_xor_b32_e32 v249, 0x80, v246
	v_add_u32_e32 v219, v247, v249
	v_xor_b32_e32 v249, 0xc0, v246
	v_add_u32_e32 v221, v247, v249
	s_waitcnt lgkmcnt(7)
	v_mfma_f32_32x32x16_bf16 v[128:143], v[206:209], v[144:147], 0
	ds_read_b64_tr_b16 v[206:207], v205
	ds_read_b64_tr_b16 v[208:209], v205 offset:4096
	s_waitcnt lgkmcnt(8)
	v_mfma_f32_32x32x16_bf16 v[128:143], v[210:213], v[148:151], v[128:143]
	ds_read_b64_tr_b16 v[210:211], v218
	ds_read_b64_tr_b16 v[212:213], v218 offset:4096
	s_waitcnt lgkmcnt(9)
	v_mfma_f32_32x32x16_bf16 v[128:143], v[214:217], v[152:155], v[128:143]
	s_waitcnt lgkmcnt(8)
	v_mfma_f32_32x32x16_bf16 v[128:143], v[238:241], v[156:159], v[128:143]
	ds_read_b64_tr_b16 v[214:215], v219
	ds_read_b64_tr_b16 v[216:217], v219 offset:4096
	s_waitcnt lgkmcnt(9)
	v_mfma_f32_32x32x16_bf16 v[128:143], v[242:245], v[160:163], v[128:143]
	s_waitcnt lgkmcnt(8)
	v_mfma_f32_32x32x16_bf16 v[128:143], v[250:253], v[164:167], v[128:143]
	ds_read_b64_tr_b16 v[238:239], v221
	ds_read_b64_tr_b16 v[240:241], v221 offset:4096
	s_waitcnt lgkmcnt(9)
	v_mfma_f32_32x32x16_bf16 v[128:143], v[222:225], v[168:171], v[128:143]
	s_waitcnt lgkmcnt(8)
	v_mfma_f32_32x32x16_bf16 v[128:143], v[226:229], v[172:175], v[128:143]
	s_nop 11
	v_and_or_b32 v246, v203, 31, s71
	v_bfe_u32 v247, v203, 5, 1
	s_add_i32 s100, s39, 0
	v_lshl_add_u32 v247, v247, 2, s100
	v_add_u32_e32 v249, 0, v247
	v_cmp_le_i32_e32 vcc, v249, v246
	v_add_u32_e32 v254, 1, v247
	s_nop 0
	v_cndmask_b32_e32 v128, v192, v128, vcc
	v_cmp_le_i32_e32 vcc, v254, v246
	v_add_u32_e32 v249, 2, v247
	s_nop 0
	v_cndmask_b32_e32 v129, v192, v129, vcc
	v_cmp_le_i32_e32 vcc, v249, v246
	v_add_u32_e32 v254, 3, v247
	s_nop 0
	v_cndmask_b32_e32 v130, v192, v130, vcc
	v_cmp_le_i32_e32 vcc, v254, v246
	v_add_u32_e32 v249, 8, v247
	s_nop 0
	v_cndmask_b32_e32 v131, v192, v131, vcc
	v_cmp_le_i32_e32 vcc, v249, v246
	v_add_u32_e32 v254, 9, v247
	s_nop 0
	v_cndmask_b32_e32 v132, v192, v132, vcc
	v_cmp_le_i32_e32 vcc, v254, v246
	v_add_u32_e32 v249, 10, v247
	s_nop 0
	v_cndmask_b32_e32 v133, v192, v133, vcc
	v_cmp_le_i32_e32 vcc, v249, v246
	v_add_u32_e32 v254, 11, v247
	s_nop 0
	v_cndmask_b32_e32 v134, v192, v134, vcc
	v_cmp_le_i32_e32 vcc, v254, v246
	v_add_u32_e32 v249, 16, v247
	s_nop 0
	v_cndmask_b32_e32 v135, v192, v135, vcc
	v_cmp_le_i32_e32 vcc, v249, v246
	v_add_u32_e32 v254, 17, v247
	s_nop 0
	v_cndmask_b32_e32 v136, v192, v136, vcc
	v_cmp_le_i32_e32 vcc, v254, v246
	v_add_u32_e32 v249, 18, v247
	s_nop 0
	v_cndmask_b32_e32 v137, v192, v137, vcc
	v_cmp_le_i32_e32 vcc, v249, v246
	v_add_u32_e32 v254, 19, v247
	s_nop 0
	v_cndmask_b32_e32 v138, v192, v138, vcc
	v_cmp_le_i32_e32 vcc, v254, v246
	v_add_u32_e32 v249, 24, v247
	s_nop 0
	v_cndmask_b32_e32 v139, v192, v139, vcc
	v_cmp_le_i32_e32 vcc, v249, v246
	v_add_u32_e32 v254, 25, v247
	s_nop 0
	v_cndmask_b32_e32 v140, v192, v140, vcc
	v_cmp_le_i32_e32 vcc, v254, v246
	v_add_u32_e32 v249, 26, v247
	s_nop 0
	v_cndmask_b32_e32 v141, v192, v141, vcc
	v_cmp_le_i32_e32 vcc, v249, v246
	v_add_u32_e32 v254, 27, v247
	s_nop 0
	v_cndmask_b32_e32 v142, v192, v142, vcc
	v_cmp_le_i32_e32 vcc, v254, v246
	s_nop 1
	v_cndmask_b32_e32 v143, v192, v143, vcc
	v_max3_f32 v246, v128, v129, v130
	v_max3_f32 v247, v131, v132, v133
	v_max3_f32 v246, v246, v134, v135
	v_max3_f32 v247, v247, v136, v137
	v_max3_f32 v246, v246, v138, v139
	v_max3_f32 v247, v247, v140, v141
	v_max3_f32 v246, v246, v142, v143
	v_max_f32_e32 v246, v246, v247
	v_mov_b32_e32 v247, v246
	v_add_f32_e32 v249, 0x41000000, v190
	s_nop 1
	v_permlane32_swap_b32_e32 v246, v247
	v_max_f32_e32 v246, v246, v247
	v_cmp_gt_f32_e32 vcc, v246, v249
	s_cbranch_vccz .Latt_nr0_4B
	v_max_f32_e32 v246, v190, v246
	v_sub_f32_e32 v190, v190, v246
	v_exp_f32_e32 v190, v190
	s_nop 0
	v_pk_mul_f32 v[126:127], v[126:127], v[190:191] op_sel_hi:[1,0]
	v_pk_mul_f32 v[124:125], v[124:125], v[190:191] op_sel_hi:[1,0]
	v_pk_mul_f32 v[122:123], v[122:123], v[190:191] op_sel_hi:[1,0]
	v_pk_mul_f32 v[120:121], v[120:121], v[190:191] op_sel_hi:[1,0]
	v_pk_mul_f32 v[118:119], v[118:119], v[190:191] op_sel_hi:[1,0]
	v_pk_mul_f32 v[116:117], v[116:117], v[190:191] op_sel_hi:[1,0]
	v_pk_mul_f32 v[114:115], v[114:115], v[190:191] op_sel_hi:[1,0]
	v_pk_mul_f32 v[112:113], v[112:113], v[190:191] op_sel_hi:[1,0]
	v_pk_mul_f32 v[110:111], v[110:111], v[190:191] op_sel_hi:[1,0]
	v_pk_mul_f32 v[108:109], v[108:109], v[190:191] op_sel_hi:[1,0]
	v_pk_mul_f32 v[106:107], v[106:107], v[190:191] op_sel_hi:[1,0]
	v_pk_mul_f32 v[104:105], v[104:105], v[190:191] op_sel_hi:[1,0]
	v_pk_mul_f32 v[102:103], v[102:103], v[190:191] op_sel_hi:[1,0]
	v_pk_mul_f32 v[100:101], v[100:101], v[190:191] op_sel_hi:[1,0]
	v_pk_mul_f32 v[98:99], v[98:99], v[190:191] op_sel_hi:[1,0]
	v_pk_mul_f32 v[96:97], v[96:97], v[190:191] op_sel_hi:[1,0]
	v_pk_mul_f32 v[94:95], v[94:95], v[190:191] op_sel_hi:[1,0]
	v_pk_mul_f32 v[92:93], v[92:93], v[190:191] op_sel_hi:[1,0]
	v_pk_mul_f32 v[90:91], v[90:91], v[190:191] op_sel_hi:[1,0]
	v_pk_mul_f32 v[88:89], v[88:89], v[190:191] op_sel_hi:[1,0]
	v_pk_mul_f32 v[86:87], v[86:87], v[190:191] op_sel_hi:[1,0]
	v_pk_mul_f32 v[84:85], v[84:85], v[190:191] op_sel_hi:[1,0]
	v_pk_mul_f32 v[82:83], v[82:83], v[190:191] op_sel_hi:[1,0]
	v_pk_mul_f32 v[80:81], v[80:81], v[190:191] op_sel_hi:[1,0]
	v_pk_mul_f32 v[78:79], v[78:79], v[190:191] op_sel_hi:[1,0]
	v_pk_mul_f32 v[76:77], v[76:77], v[190:191] op_sel_hi:[1,0]
	v_pk_mul_f32 v[74:75], v[74:75], v[190:191] op_sel_hi:[1,0]
	v_pk_mul_f32 v[72:73], v[72:73], v[190:191] op_sel_hi:[1,0]
	v_pk_mul_f32 v[70:71], v[70:71], v[190:191] op_sel_hi:[1,0]
	v_pk_mul_f32 v[68:69], v[68:69], v[190:191] op_sel_hi:[1,0]
	v_pk_mul_f32 v[66:67], v[66:67], v[190:191] op_sel_hi:[1,0]
	v_pk_mul_f32 v[64:65], v[64:65], v[190:191] op_sel_hi:[1,0]
	v_pk_mul_f32 v[62:63], v[62:63], v[190:191] op_sel_hi:[1,0]
	v_pk_mul_f32 v[60:61], v[60:61], v[190:191] op_sel_hi:[1,0]
	v_pk_mul_f32 v[58:59], v[58:59], v[190:191] op_sel_hi:[1,0]
	v_pk_mul_f32 v[56:57], v[56:57], v[190:191] op_sel_hi:[1,0]
	v_pk_mul_f32 v[54:55], v[54:55], v[190:191] op_sel_hi:[1,0]
	v_pk_mul_f32 v[52:53], v[52:53], v[190:191] op_sel_hi:[1,0]
	v_pk_mul_f32 v[50:51], v[50:51], v[190:191] op_sel_hi:[1,0]
	v_pk_mul_f32 v[48:49], v[48:49], v[190:191] op_sel_hi:[1,0]
	v_pk_mul_f32 v[46:47], v[46:47], v[190:191] op_sel_hi:[1,0]
	v_pk_mul_f32 v[44:45], v[44:45], v[190:191] op_sel_hi:[1,0]
	v_pk_mul_f32 v[42:43], v[42:43], v[190:191] op_sel_hi:[1,0]
	v_pk_mul_f32 v[40:41], v[40:41], v[190:191] op_sel_hi:[1,0]
	v_pk_mul_f32 v[38:39], v[38:39], v[190:191] op_sel_hi:[1,0]
	v_pk_mul_f32 v[36:37], v[36:37], v[190:191] op_sel_hi:[1,0]
	v_pk_mul_f32 v[34:35], v[34:35], v[190:191] op_sel_hi:[1,0]
	v_pk_mul_f32 v[32:33], v[32:33], v[190:191] op_sel_hi:[1,0]
	v_pk_mul_f32 v[30:31], v[30:31], v[190:191] op_sel_hi:[1,0]
	v_pk_mul_f32 v[28:29], v[28:29], v[190:191] op_sel_hi:[1,0]
	v_pk_mul_f32 v[26:27], v[26:27], v[190:191] op_sel_hi:[1,0]
	v_pk_mul_f32 v[24:25], v[24:25], v[190:191] op_sel_hi:[1,0]
	v_pk_mul_f32 v[22:23], v[22:23], v[190:191] op_sel_hi:[1,0]
	v_pk_mul_f32 v[20:21], v[20:21], v[190:191] op_sel_hi:[1,0]
	v_pk_mul_f32 v[18:19], v[18:19], v[190:191] op_sel_hi:[1,0]
	v_pk_mul_f32 v[16:17], v[16:17], v[190:191] op_sel_hi:[1,0]
	v_pk_mul_f32 v[14:15], v[14:15], v[190:191] op_sel_hi:[1,0]
	v_pk_mul_f32 v[12:13], v[12:13], v[190:191] op_sel_hi:[1,0]
	v_pk_mul_f32 v[10:11], v[10:11], v[190:191] op_sel_hi:[1,0]
	v_pk_mul_f32 v[8:9], v[8:9], v[190:191] op_sel_hi:[1,0]
	v_pk_mul_f32 v[6:7], v[6:7], v[190:191] op_sel_hi:[1,0]
	v_pk_mul_f32 v[4:5], v[4:5], v[190:191] op_sel_hi:[1,0]
	v_pk_mul_f32 v[2:3], v[2:3], v[190:191] op_sel_hi:[1,0]
	v_pk_mul_f32 v[0:1], v[0:1], v[190:191] op_sel_hi:[1,0]
	v_mul_f32_e32 v202, v202, v190
	v_mov_b32_e32 v190, v246
.Latt_nr0_4B:
	v_sub_f32_e32 v128, v128, v190
	v_exp_f32_e32 v128, v128
	v_sub_f32_e32 v129, v129, v190
	v_exp_f32_e32 v129, v129
	v_sub_f32_e32 v130, v130, v190
	v_add_f32_e32 v254, 0, v128
	v_exp_f32_e32 v130, v130
	v_sub_f32_e32 v131, v131, v190
	v_add_f32_e32 v254, v129, v254
	v_exp_f32_e32 v131, v131
	v_sub_f32_e32 v132, v132, v190
	v_add_f32_e32 v254, v130, v254
	v_exp_f32_e32 v132, v132
	v_sub_f32_e32 v133, v133, v190
	v_add_f32_e32 v254, v131, v254
	v_exp_f32_e32 v133, v133
	v_sub_f32_e32 v134, v134, v190
	v_add_f32_e32 v254, v132, v254
	v_exp_f32_e32 v134, v134
	v_sub_f32_e32 v135, v135, v190
	v_add_f32_e32 v254, v133, v254
	v_exp_f32_e32 v135, v135
	v_sub_f32_e32 v136, v136, v190
	v_add_f32_e32 v254, v134, v254
	v_exp_f32_e32 v136, v136
	v_sub_f32_e32 v137, v137, v190
	v_add_f32_e32 v254, v135, v254
	v_exp_f32_e32 v137, v137
	v_sub_f32_e32 v138, v138, v190
	v_add_f32_e32 v254, v136, v254
	v_exp_f32_e32 v138, v138
	v_sub_f32_e32 v139, v139, v190
	v_add_f32_e32 v254, v137, v254
	v_exp_f32_e32 v139, v139
	v_sub_f32_e32 v140, v140, v190
	v_add_f32_e32 v254, v138, v254
	v_exp_f32_e32 v140, v140
	v_sub_f32_e32 v141, v141, v190
	v_add_f32_e32 v254, v139, v254
	v_exp_f32_e32 v141, v141
	v_sub_f32_e32 v142, v142, v190
	v_add_f32_e32 v254, v140, v254
	v_exp_f32_e32 v142, v142
	v_sub_f32_e32 v143, v143, v190
	v_add_f32_e32 v254, v141, v254
	v_exp_f32_e32 v143, v143
	v_add_f32_e32 v254, v142, v254
	v_add_f32_e32 v254, v143, v254
	v_cvt_pk_bf16_f32 v242, v128, v129
	v_cvt_pk_bf16_f32 v243, v130, v131
	v_cvt_pk_bf16_f32 v244, v132, v133
	v_cvt_pk_bf16_f32 v245, v134, v135
	v_cvt_pk_bf16_f32 v250, v136, v137
	v_cvt_pk_bf16_f32 v251, v138, v139
	v_cvt_pk_bf16_f32 v252, v140, v141
	v_cvt_pk_bf16_f32 v253, v142, v143
	v_add_f32_e32 v202, v202, v254
	s_nop 1
	ds_read_b64_tr_b16 v[128:129], v205 offset:256
	ds_read_b64_tr_b16 v[130:131], v205 offset:4352
	s_waitcnt lgkmcnt(8)
	v_mfma_f32_32x32x16_bf16 v[112:127], v[206:209], v[242:245], v[112:127]
	ds_read_b64_tr_b16 v[206:207], v218 offset:256
	ds_read_b64_tr_b16 v[208:209], v218 offset:4352
	s_waitcnt lgkmcnt(8)
	v_mfma_f32_32x32x16_bf16 v[96:111], v[210:213], v[242:245], v[96:111]
	ds_read_b64_tr_b16 v[210:211], v219 offset:256
	ds_read_b64_tr_b16 v[212:213], v219 offset:4352
	s_cmp_lg_u64 s[18:19], 0
	s_cbranch_scc1 .Latt_nd0_4B
	s_sub_i32 s100, s76, 1
	s_cmp_eq_u32 s76, 0
	s_cselect_b32 s100, 2, s100
	s_lshl_b32 s101, s100, 14
	s_add_i32 m0, s73, s101
	s_nop 0
	global_load_lds_dwordx4 v178, s[14:15]

.Latt_nd1_4B:
	s_waitcnt lgkmcnt(8)
	v_mfma_f32_32x32x16_bf16 v[48:63], v[128:131], v[242:245], v[48:63]
	ds_read_b64_tr_b16 v[128:129], v218 offset:8192
	ds_read_b64_tr_b16 v[130:131], v218 offset:12288
	s_waitcnt lgkmcnt(8)
	v_mfma_f32_32x32x16_bf16 v[32:47], v[206:209], v[242:245], v[32:47]
	ds_read_b64_tr_b16 v[206:207], v219 offset:8192
	ds_read_b64_tr_b16 v[208:209], v219 offset:12288
	s_cmp_lg_u64 s[18:19], 0
	s_cbranch_scc1 .Latt_nd2_4B
	s_lshl_b32 s101, s100, 15
	s_add_i32 m0, s74, s101
	s_add_u32 s100, s14, 0x1000
	s_addc_u32 s101, s15, 0
	global_load_lds_dwordx4 v182, s[100:101]

.Latt_diagA_4:
	s_lshl_b32 s98, s76, 14
	s_lshl_b32 s99, s76, 15
	s_add_i32 s99, s99, 0xc000
	v_add_u32_e32 v206, s98, v194
	ds_read_b128 v[206:209], v206
	v_add_u32_e32 v210, s98, v195
	ds_read_b128 v[210:213], v210
	v_add_u32_e32 v214, s98, v196
	ds_read_b128 v[214:217], v214
	v_add_u32_e32 v238, s98, v197
	ds_read_b128 v[238:241], v238
	v_add_u32_e32 v242, s98, v198
	ds_read_b128 v[242:245], v242
	v_add_u32_e32 v250, s98, v199
	ds_read_b128 v[250:253], v250
	v_add_u32_e32 v222, s98, v200
	ds_read_b128 v[222:225], v222
	v_add_u32_e32 v226, s98, v201
	ds_read_b128 v[226:229], v226
	v_bfe_u32 v246, v203, 2, 2
	v_bfe_u32 v247, v203, 5, 1
	v_lshl_or_b32 v247, v247, 2, v246
	v_and_b32_e32 v249, 3, v203
	v_and_b32_e32 v254, 16, v203
	v_lshl_or_b32 v249, v249, 2, v254
	v_lshlrev_b32_e32 v249, 1, v249
	v_lshl_add_u32 v247, v247, 9, v249
	v_add_u32_e32 v247, s99, v247
	v_lshlrev_b32_e32 v246, 6, v246
	v_add_u32_e32 v205, v247, v246
	v_xor_b32_e32 v249, 64, v246
	v_add_u32_e32 v218, v247, v249
	v_xor_b32_e32 v249, 0x80, v246
	v_add_u32_e32 v219, v247, v249
	v_xor_b32_e32 v249, 0xc0, v246
	v_add_u32_e32 v221, v247, v249
	s_waitcnt lgkmcnt(7)
	v_mfma_f32_32x32x16_bf16 v[128:143], v[206:209], v[144:147], 0
	v_add_u32_e32 v206, s98, v194
	ds_read_b128 v[206:209], v206 offset:8192
	s_waitcnt lgkmcnt(7)
	v_mfma_f32_32x32x16_bf16 v[128:143], v[210:213], v[148:151], v[128:143]
	v_add_u32_e32 v210, s98, v195
	ds_read_b128 v[210:213], v210 offset:8192
	s_waitcnt lgkmcnt(7)
	v_mfma_f32_32x32x16_bf16 v[128:143], v[214:217], v[152:155], v[128:143]
	v_add_u32_e32 v214, s98, v196
	ds_read_b128 v[214:217], v214 offset:8192
	s_waitcnt lgkmcnt(7)
	v_mfma_f32_32x32x16_bf16 v[128:143], v[238:241], v[156:159], v[128:143]
	v_add_u32_e32 v238, s98, v197
	ds_read_b128 v[238:241], v238 offset:8192
	s_waitcnt lgkmcnt(7)
	v_mfma_f32_32x32x16_bf16 v[128:143], v[242:245], v[160:163], v[128:143]
	v_add_u32_e32 v242, s98, v198
	ds_read_b128 v[242:245], v242 offset:8192
	s_waitcnt lgkmcnt(7)
	v_mfma_f32_32x32x16_bf16 v[128:143], v[250:253], v[164:167], v[128:143]
	v_add_u32_e32 v250, s98, v199
	ds_read_b128 v[250:253], v250 offset:8192
	s_waitcnt lgkmcnt(7)
	v_mfma_f32_32x32x16_bf16 v[128:143], v[222:225], v[168:171], v[128:143]
	s_waitcnt lgkmcnt(6)
	v_mfma_f32_32x32x16_bf16 v[128:143], v[226:229], v[172:175], v[128:143]
	s_waitcnt lgkmcnt(5)
	v_mfma_f32_32x32x16_bf16 v[222:237], v[206:209], v[144:147], 0
	v_add_u32_e32 v206, s98, v200
	ds_read_b128 v[206:209], v206 offset:8192
	s_nop 7
	v_max3_f32 v246, v128, v129, v130
	v_max3_f32 v247, v131, v132, v133
	v_max3_f32 v246, v246, v134, v135
	v_max3_f32 v247, v247, v136, v137
	v_max3_f32 v246, v246, v138, v139
	v_max3_f32 v247, v247, v140, v141
	v_max3_f32 v246, v246, v142, v143
	s_waitcnt lgkmcnt(5)
	v_mfma_f32_32x32x16_bf16 v[222:237], v[210:213], v[148:151], v[222:237]
	v_add_u32_e32 v210, s98, v201
	ds_read_b128 v[210:213], v210 offset:8192
	v_max_f32_e32 v246, v246, v247
	v_mov_b32_e32 v247, v246
	v_add_f32_e32 v249, 0x41000000, v190
	s_nop 1
	v_permlane32_swap_b32_e32 v246, v247
	v_max_f32_e32 v246, v246, v247
	v_cmp_gt_f32_e32 vcc, v246, v249
	s_cbranch_vccz .Latt_nr0_4A
	v_max_f32_e32 v246, v190, v246
	v_sub_f32_e32 v190, v190, v246
	v_exp_f32_e32 v190, v190
	s_nop 0
	v_pk_mul_f32 v[126:127], v[126:127], v[190:191] op_sel_hi:[1,0]
	v_pk_mul_f32 v[124:125], v[124:125], v[190:191] op_sel_hi:[1,0]
	v_pk_mul_f32 v[122:123], v[122:123], v[190:191] op_sel_hi:[1,0]
	v_pk_mul_f32 v[120:121], v[120:121], v[190:191] op_sel_hi:[1,0]
	v_pk_mul_f32 v[118:119], v[118:119], v[190:191] op_sel_hi:[1,0]
	v_pk_mul_f32 v[116:117], v[116:117], v[190:191] op_sel_hi:[1,0]
	v_pk_mul_f32 v[114:115], v[114:115], v[190:191] op_sel_hi:[1,0]
	v_pk_mul_f32 v[112:113], v[112:113], v[190:191] op_sel_hi:[1,0]
	v_pk_mul_f32 v[110:111], v[110:111], v[190:191] op_sel_hi:[1,0]
	v_pk_mul_f32 v[108:109], v[108:109], v[190:191] op_sel_hi:[1,0]
	v_pk_mul_f32 v[106:107], v[106:107], v[190:191] op_sel_hi:[1,0]
	v_pk_mul_f32 v[104:105], v[104:105], v[190:191] op_sel_hi:[1,0]
	v_pk_mul_f32 v[102:103], v[102:103], v[190:191] op_sel_hi:[1,0]
	v_pk_mul_f32 v[100:101], v[100:101], v[190:191] op_sel_hi:[1,0]
	v_pk_mul_f32 v[98:99], v[98:99], v[190:191] op_sel_hi:[1,0]
	v_pk_mul_f32 v[96:97], v[96:97], v[190:191] op_sel_hi:[1,0]
	v_pk_mul_f32 v[94:95], v[94:95], v[190:191] op_sel_hi:[1,0]
	v_pk_mul_f32 v[92:93], v[92:93], v[190:191] op_sel_hi:[1,0]
	v_pk_mul_f32 v[90:91], v[90:91], v[190:191] op_sel_hi:[1,0]
	v_pk_mul_f32 v[88:89], v[88:89], v[190:191] op_sel_hi:[1,0]
	v_pk_mul_f32 v[86:87], v[86:87], v[190:191] op_sel_hi:[1,0]
	v_pk_mul_f32 v[84:85], v[84:85], v[190:191] op_sel_hi:[1,0]
	v_pk_mul_f32 v[82:83], v[82:83], v[190:191] op_sel_hi:[1,0]
	v_pk_mul_f32 v[80:81], v[80:81], v[190:191] op_sel_hi:[1,0]
	v_pk_mul_f32 v[78:79], v[78:79], v[190:191] op_sel_hi:[1,0]
	v_pk_mul_f32 v[76:77], v[76:77], v[190:191] op_sel_hi:[1,0]
	v_pk_mul_f32 v[74:75], v[74:75], v[190:191] op_sel_hi:[1,0]
	v_pk_mul_f32 v[72:73], v[72:73], v[190:191] op_sel_hi:[1,0]
	v_pk_mul_f32 v[70:71], v[70:71], v[190:191] op_sel_hi:[1,0]
	v_pk_mul_f32 v[68:69], v[68:69], v[190:191] op_sel_hi:[1,0]
	v_pk_mul_f32 v[66:67], v[66:67], v[190:191] op_sel_hi:[1,0]
	v_pk_mul_f32 v[64:65], v[64:65], v[190:191] op_sel_hi:[1,0]
	v_pk_mul_f32 v[62:63], v[62:63], v[190:191] op_sel_hi:[1,0]
	v_pk_mul_f32 v[60:61], v[60:61], v[190:191] op_sel_hi:[1,0]
	v_pk_mul_f32 v[58:59], v[58:59], v[190:191] op_sel_hi:[1,0]
	v_pk_mul_f32 v[56:57], v[56:57], v[190:191] op_sel_hi:[1,0]
	v_pk_mul_f32 v[54:55], v[54:55], v[190:191] op_sel_hi:[1,0]
	v_pk_mul_f32 v[52:53], v[52:53], v[190:191] op_sel_hi:[1,0]
	v_pk_mul_f32 v[50:51], v[50:51], v[190:191] op_sel_hi:[1,0]
	v_pk_mul_f32 v[48:49], v[48:49], v[190:191] op_sel_hi:[1,0]
	v_pk_mul_f32 v[46:47], v[46:47], v[190:191] op_sel_hi:[1,0]
	v_pk_mul_f32 v[44:45], v[44:45], v[190:191] op_sel_hi:[1,0]
	v_pk_mul_f32 v[42:43], v[42:43], v[190:191] op_sel_hi:[1,0]
	v_pk_mul_f32 v[40:41], v[40:41], v[190:191] op_sel_hi:[1,0]
	v_pk_mul_f32 v[38:39], v[38:39], v[190:191] op_sel_hi:[1,0]
	v_pk_mul_f32 v[36:37], v[36:37], v[190:191] op_sel_hi:[1,0]
	v_pk_mul_f32 v[34:35], v[34:35], v[190:191] op_sel_hi:[1,0]
	v_pk_mul_f32 v[32:33], v[32:33], v[190:191] op_sel_hi:[1,0]
	v_pk_mul_f32 v[30:31], v[30:31], v[190:191] op_sel_hi:[1,0]
	v_pk_mul_f32 v[28:29], v[28:29], v[190:191] op_sel_hi:[1,0]
	v_pk_mul_f32 v[26:27], v[26:27], v[190:191] op_sel_hi:[1,0]
	v_pk_mul_f32 v[24:25], v[24:25], v[190:191] op_sel_hi:[1,0]
	v_pk_mul_f32 v[22:23], v[22:23], v[190:191] op_sel_hi:[1,0]
	v_pk_mul_f32 v[20:21], v[20:21], v[190:191] op_sel_hi:[1,0]
	v_pk_mul_f32 v[18:19], v[18:19], v[190:191] op_sel_hi:[1,0]
	v_pk_mul_f32 v[16:17], v[16:17], v[190:191] op_sel_hi:[1,0]
	v_pk_mul_f32 v[14:15], v[14:15], v[190:191] op_sel_hi:[1,0]
	v_pk_mul_f32 v[12:13], v[12:13], v[190:191] op_sel_hi:[1,0]
	v_pk_mul_f32 v[10:11], v[10:11], v[190:191] op_sel_hi:[1,0]
	v_pk_mul_f32 v[8:9], v[8:9], v[190:191] op_sel_hi:[1,0]
	v_pk_mul_f32 v[6:7], v[6:7], v[190:191] op_sel_hi:[1,0]
	v_pk_mul_f32 v[4:5], v[4:5], v[190:191] op_sel_hi:[1,0]
	v_pk_mul_f32 v[2:3], v[2:3], v[190:191] op_sel_hi:[1,0]
	v_pk_mul_f32 v[0:1], v[0:1], v[190:191] op_sel_hi:[1,0]
	v_mul_f32_e32 v202, v202, v190
	v_mov_b32_e32 v190, v246
.Latt_nr0_4A:
	s_waitcnt lgkmcnt(5)
	v_mfma_f32_32x32x16_bf16 v[222:237], v[214:217], v[152:155], v[222:237]
	ds_read_b64_tr_b16 v[214:215], v205
	ds_read_b64_tr_b16 v[216:217], v205 offset:4096
	v_sub_f32_e32 v128, v128, v190
	v_exp_f32_e32 v128, v128
	v_sub_f32_e32 v129, v129, v190
	v_exp_f32_e32 v129, v129
	v_sub_f32_e32 v130, v130, v190
	v_add_f32_e32 v254, 0, v128
	v_exp_f32_e32 v130, v130
	v_sub_f32_e32 v131, v131, v190
	s_waitcnt lgkmcnt(6)
	v_mfma_f32_32x32x16_bf16 v[222:237], v[238:241], v[156:159], v[222:237]
	ds_read_b64_tr_b16 v[238:239], v218
	ds_read_b64_tr_b16 v[240:241], v218 offset:4096
	v_add_f32_e32 v254, v129, v254
	v_exp_f32_e32 v131, v131
	v_sub_f32_e32 v132, v132, v190
	v_add_f32_e32 v254, v130, v254
	v_exp_f32_e32 v132, v132
	v_sub_f32_e32 v133, v133, v190
	v_add_f32_e32 v254, v131, v254
	v_exp_f32_e32 v133, v133
	s_waitcnt lgkmcnt(7)
	v_mfma_f32_32x32x16_bf16 v[222:237], v[242:245], v[160:163], v[222:237]
	v_sub_f32_e32 v134, v134, v190
	v_add_f32_e32 v254, v132, v254
	v_exp_f32_e32 v134, v134
	v_sub_f32_e32 v135, v135, v190
	v_add_f32_e32 v254, v133, v254
	v_exp_f32_e32 v135, v135
	v_sub_f32_e32 v136, v136, v190
	v_add_f32_e32 v254, v134, v254
	s_waitcnt lgkmcnt(6)
	v_mfma_f32_32x32x16_bf16 v[222:237], v[250:253], v[164:167], v[222:237]
	v_exp_f32_e32 v136, v136
	v_sub_f32_e32 v137, v137, v190
	v_add_f32_e32 v254, v135, v254
	v_exp_f32_e32 v137, v137
	v_sub_f32_e32 v138, v138, v190
	v_add_f32_e32 v254, v136, v254
	v_exp_f32_e32 v138, v138
	v_sub_f32_e32 v139, v139, v190
	s_waitcnt lgkmcnt(5)
	v_mfma_f32_32x32x16_bf16 v[222:237], v[206:209], v[168:171], v[222:237]
	ds_read_b64_tr_b16 v[206:207], v219
	ds_read_b64_tr_b16 v[208:209], v219 offset:4096
	v_add_f32_e32 v254, v137, v254
	v_exp_f32_e32 v139, v139
	v_sub_f32_e32 v140, v140, v190
	v_add_f32_e32 v254, v138, v254
	v_exp_f32_e32 v140, v140
	v_sub_f32_e32 v141, v141, v190
	v_add_f32_e32 v254, v139, v254
	v_exp_f32_e32 v141, v141
	s_waitcnt lgkmcnt(6)
	v_mfma_f32_32x32x16_bf16 v[222:237], v[210:213], v[172:175], v[222:237]
	ds_read_b64_tr_b16 v[210:211], v221
	ds_read_b64_tr_b16 v[212:213], v221 offset:4096
	v_sub_f32_e32 v142, v142, v190
	v_add_f32_e32 v254, v140, v254
	v_exp_f32_e32 v142, v142
	v_sub_f32_e32 v143, v143, v190
	v_add_f32_e32 v254, v141, v254
	v_exp_f32_e32 v143, v143
	v_add_f32_e32 v254, v142, v254
	v_add_f32_e32 v254, v143, v254
	v_cvt_pk_bf16_f32 v242, v128, v129
	v_cvt_pk_bf16_f32 v243, v130, v131
	v_cvt_pk_bf16_f32 v244, v132, v133
	v_cvt_pk_bf16_f32 v245, v134, v135
	v_cvt_pk_bf16_f32 v250, v136, v137
	v_cvt_pk_bf16_f32 v251, v138, v139
	v_cvt_pk_bf16_f32 v252, v140, v141
	v_cvt_pk_bf16_f32 v253, v142, v143
	v_add_f32_e32 v202, v202, v254
	s_nop 1
	ds_read_b64_tr_b16 v[128:129], v205 offset:256
	ds_read_b64_tr_b16 v[130:131], v205 offset:4352
	s_waitcnt lgkmcnt(8)
	v_mfma_f32_32x32x16_bf16 v[112:127], v[214:217], v[242:245], v[112:127]
	ds_read_b64_tr_b16 v[214:215], v218 offset:256
	ds_read_b64_tr_b16 v[216:217], v218 offset:4352
	v_and_or_b32 v246, v203, 31, s71
	v_bfe_u32 v247, v203, 5, 1
	s_add_i32 s100, s39, 32
	v_lshl_add_u32 v247, v247, 2, s100
	v_add_u32_e32 v249, 0, v247
	v_cmp_le_i32_e32 vcc, v249, v246
	v_add_u32_e32 v254, 1, v247
	s_nop 0
	v_cndmask_b32_e32 v222, v192, v222, vcc
	v_cmp_le_i32_e32 vcc, v254, v246
	v_add_u32_e32 v249, 2, v247
	s_nop 0
	v_cndmask_b32_e32 v223, v192, v223, vcc
	v_cmp_le_i32_e32 vcc, v249, v246
	v_add_u32_e32 v254, 3, v247
	s_nop 0
	v_cndmask_b32_e32 v224, v192, v224, vcc
	v_cmp_le_i32_e32 vcc, v254, v246
	v_add_u32_e32 v249, 8, v247
	s_nop 0
	v_cndmask_b32_e32 v225, v192, v225, vcc
	v_cmp_le_i32_e32 vcc, v249, v246
	v_add_u32_e32 v254, 9, v247
	s_nop 0
	v_cndmask_b32_e32 v226, v192, v226, vcc
	v_cmp_le_i32_e32 vcc, v254, v246
	v_add_u32_e32 v249, 10, v247
	s_nop 0
	v_cndmask_b32_e32 v227, v192, v227, vcc
	v_cmp_le_i32_e32 vcc, v249, v246
	v_add_u32_e32 v254, 11, v247
	s_nop 0
	v_cndmask_b32_e32 v228, v192, v228, vcc
	v_cmp_le_i32_e32 vcc, v254, v246
	s_waitcnt lgkmcnt(8)
	v_mfma_f32_32x32x16_bf16 v[96:111], v[238:241], v[242:245], v[96:111]
	ds_read_b64_tr_b16 v[238:239], v219 offset:256
	ds_read_b64_tr_b16 v[240:241], v219 offset:4352
	v_add_u32_e32 v249, 16, v247
	s_nop 0
	v_cndmask_b32_e32 v229, v192, v229, vcc
	v_cmp_le_i32_e32 vcc, v249, v246
	v_add_u32_e32 v254, 17, v247
	s_nop 0
	v_cndmask_b32_e32 v230, v192, v230, vcc
	v_cmp_le_i32_e32 vcc, v254, v246
	v_add_u32_e32 v249, 18, v247
	s_nop 0
	v_cndmask_b32_e32 v231, v192, v231, vcc
	v_cmp_le_i32_e32 vcc, v249, v246
	v_add_u32_e32 v254, 19, v247
	s_nop 0
	v_cndmask_b32_e32 v232, v192, v232, vcc
	v_cmp_le_i32_e32 vcc, v254, v246
	v_add_u32_e32 v249, 24, v247
	s_nop 0
	v_cndmask_b32_e32 v233, v192, v233, vcc
	v_cmp_le_i32_e32 vcc, v249, v246
	v_add_u32_e32 v254, 25, v247
	s_nop 0
	v_cndmask_b32_e32 v234, v192, v234, vcc
	v_cmp_le_i32_e32 vcc, v254, v246
	v_add_u32_e32 v249, 26, v247
	s_nop 0
	v_cndmask_b32_e32 v235, v192, v235, vcc
	v_cmp_le_i32_e32 vcc, v249, v246
	v_add_u32_e32 v254, 27, v247
	s_nop 0
	v_cndmask_b32_e32 v236, v192, v236, vcc
	v_cmp_le_i32_e32 vcc, v254, v246
	s_nop 1
	v_cndmask_b32_e32 v237, v192, v237, vcc
	s_waitcnt lgkmcnt(8)
	v_mfma_f32_32x32x16_bf16 v[80:95], v[206:209], v[242:245], v[80:95]
	ds_read_b64_tr_b16 v[206:207], v221 offset:256
	ds_read_b64_tr_b16 v[208:209], v221 offset:4352
	v_max3_f32 v246, v222, v223, v224
	v_max3_f32 v247, v225, v226, v227
	v_max3_f32 v246, v246, v228, v229
	v_max3_f32 v247, v247, v230, v231
	v_max3_f32 v246, v246, v232, v233
	v_max3_f32 v247, v247, v234, v235
	s_waitcnt lgkmcnt(8)
	v_mfma_f32_32x32x16_bf16 v[64:79], v[210:213], v[242:245], v[64:79]
	ds_read_b64_tr_b16 v[210:211], v205 offset:8192
	ds_read_b64_tr_b16 v[212:213], v205 offset:12288
	v_max3_f32 v246, v246, v236, v237
	v_max_f32_e32 v246, v246, v247
	v_mov_b32_e32 v247, v246
	v_add_f32_e32 v249, 0x41000000, v190
	s_nop 1
	s_waitcnt lgkmcnt(8)
	v_mfma_f32_32x32x16_bf16 v[48:63], v[128:131], v[242:245], v[48:63]
	ds_read_b64_tr_b16 v[128:129], v218 offset:8192
	ds_read_b64_tr_b16 v[130:131], v218 offset:12288
	v_permlane32_swap_b32_e32 v246, v247
	v_max_f32_e32 v246, v246, v247
	v_cmp_gt_f32_e32 vcc, v246, v249
	s_cbranch_vccnz .Latt_rs1_4A
	s_waitcnt lgkmcnt(8)
	v_mfma_f32_32x32x16_bf16 v[32:47], v[214:217], v[242:245], v[32:47]
	ds_read_b64_tr_b16 v[214:215], v219 offset:8192
	ds_read_b64_tr_b16 v[216:217], v219 offset:12288
	v_sub_f32_e32 v222, v222, v190
	v_exp_f32_e32 v222, v222
	v_sub_f32_e32 v223, v223, v190
	v_exp_f32_e32 v223, v223
	v_sub_f32_e32 v224, v224, v190
	s_waitcnt lgkmcnt(8)
	v_mfma_f32_32x32x16_bf16 v[16:31], v[238:241], v[242:245], v[16:31]
	ds_read_b64_tr_b16 v[238:239], v221 offset:8192
	ds_read_b64_tr_b16 v[240:241], v221 offset:12288
	v_add_f32_e32 v254, 0, v222
	v_exp_f32_e32 v224, v224
	v_sub_f32_e32 v225, v225, v190
	v_add_f32_e32 v254, v223, v254
	v_exp_f32_e32 v225, v225
	s_waitcnt lgkmcnt(8)
	v_mfma_f32_32x32x16_bf16 v[0:15], v[206:209], v[242:245], v[0:15]
	ds_read_b64_tr_b16 v[206:207], v205 offset:8448
	ds_read_b64_tr_b16 v[208:209], v205 offset:12544
	v_sub_f32_e32 v226, v226, v190
	v_add_f32_e32 v254, v224, v254
	v_exp_f32_e32 v226, v226
	v_sub_f32_e32 v227, v227, v190
	v_add_f32_e32 v254, v225, v254
	s_waitcnt lgkmcnt(8)
	v_mfma_f32_32x32x16_bf16 v[112:127], v[210:213], v[250:253], v[112:127]
	ds_read_b64_tr_b16 v[210:211], v218 offset:8448
	ds_read_b64_tr_b16 v[212:213], v218 offset:12544
	v_exp_f32_e32 v227, v227
	v_sub_f32_e32 v228, v228, v190
	v_add_f32_e32 v254, v226, v254
	v_exp_f32_e32 v228, v228
	v_sub_f32_e32 v229, v229, v190
	s_waitcnt lgkmcnt(8)
	v_mfma_f32_32x32x16_bf16 v[96:111], v[128:131], v[250:253], v[96:111]
	ds_read_b64_tr_b16 v[128:129], v219 offset:8448
	ds_read_b64_tr_b16 v[130:131], v219 offset:12544
	v_add_f32_e32 v254, v227, v254
	v_exp_f32_e32 v229, v229
	v_sub_f32_e32 v230, v230, v190
	v_add_f32_e32 v254, v228, v254
	s_waitcnt lgkmcnt(8)
	v_mfma_f32_32x32x16_bf16 v[80:95], v[214:217], v[250:253], v[80:95]
	ds_read_b64_tr_b16 v[214:215], v221 offset:8448
	ds_read_b64_tr_b16 v[216:217], v221 offset:12544
	v_exp_f32_e32 v230, v230
	v_sub_f32_e32 v231, v231, v190
	v_add_f32_e32 v254, v229, v254
	v_exp_f32_e32 v231, v231
	s_waitcnt lgkmcnt(8)
	v_mfma_f32_32x32x16_bf16 v[64:79], v[238:241], v[250:253], v[64:79]
	ds_read_b64_tr_b16 v[238:239], v205 offset:16384
	ds_read_b64_tr_b16 v[240:241], v205 offset:20480
	v_sub_f32_e32 v232, v232, v190
	v_add_f32_e32 v254, v230, v254
	v_exp_f32_e32 v232, v232
	v_sub_f32_e32 v233, v233, v190
	s_waitcnt lgkmcnt(8)
	v_mfma_f32_32x32x16_bf16 v[48:63], v[206:209], v[250:253], v[48:63]
	ds_read_b64_tr_b16 v[206:207], v218 offset:16384
	ds_read_b64_tr_b16 v[208:209], v218 offset:20480
	v_add_f32_e32 v254, v231, v254
	v_exp_f32_e32 v233, v233
	v_sub_f32_e32 v234, v234, v190
	v_add_f32_e32 v254, v232, v254
	s_waitcnt lgkmcnt(8)
	v_mfma_f32_32x32x16_bf16 v[32:47], v[210:213], v[250:253], v[32:47]
	ds_read_b64_tr_b16 v[210:211], v219 offset:16384
	ds_read_b64_tr_b16 v[212:213], v219 offset:20480
	v_exp_f32_e32 v234, v234
	v_sub_f32_e32 v235, v235, v190
	v_add_f32_e32 v254, v233, v254
	v_exp_f32_e32 v235, v235
	s_waitcnt lgkmcnt(8)
	v_mfma_f32_32x32x16_bf16 v[16:31], v[128:131], v[250:253], v[16:31]
	ds_read_b64_tr_b16 v[128:129], v221 offset:16384
	ds_read_b64_tr_b16 v[130:131], v221 offset:20480
	v_sub_f32_e32 v236, v236, v190
	v_add_f32_e32 v254, v234, v254
	v_exp_f32_e32 v236, v236
	v_sub_f32_e32 v237, v237, v190
	s_waitcnt lgkmcnt(8)
	v_mfma_f32_32x32x16_bf16 v[0:15], v[214:217], v[250:253], v[0:15]
	ds_read_b64_tr_b16 v[214:215], v205 offset:16640
	ds_read_b64_tr_b16 v[216:217], v205 offset:20736
	v_add_f32_e32 v254, v235, v254
	v_exp_f32_e32 v237, v237
	v_add_f32_e32 v254, v236, v254
	v_add_f32_e32 v254, v237, v254
	v_cvt_pk_bf16_f32 v242, v222, v223
	v_cvt_pk_bf16_f32 v243, v224, v225
	v_cvt_pk_bf16_f32 v244, v226, v227
	v_cvt_pk_bf16_f32 v245, v228, v229
	v_cvt_pk_bf16_f32 v250, v230, v231
	v_cvt_pk_bf16_f32 v251, v232, v233
	v_cvt_pk_bf16_f32 v252, v234, v235
	v_cvt_pk_bf16_f32 v253, v236, v237
	v_add_f32_e32 v202, v202, v254
	s_nop 1

.Latt_rs1_4F:
	s_waitcnt lgkmcnt(8)
	v_mfma_f32_32x32x16_bf16 v[32:47], v[214:217], v[242:245], v[32:47]
	ds_read_b64_tr_b16 v[214:215], v219 offset:8192
	ds_read_b64_tr_b16 v[216:217], v219 offset:12288
	s_waitcnt lgkmcnt(8)
	v_mfma_f32_32x32x16_bf16 v[16:31], v[238:241], v[242:245], v[16:31]
	ds_read_b64_tr_b16 v[238:239], v221 offset:8192
	ds_read_b64_tr_b16 v[240:241], v221 offset:12288
	s_waitcnt lgkmcnt(8)
	v_mfma_f32_32x32x16_bf16 v[0:15], v[206:209], v[242:245], v[0:15]
	ds_read_b64_tr_b16 v[206:207], v205 offset:8448
	ds_read_b64_tr_b16 v[208:209], v205 offset:12544
	s_waitcnt lgkmcnt(8)
	v_mfma_f32_32x32x16_bf16 v[112:127], v[210:213], v[250:253], v[112:127]
	ds_read_b64_tr_b16 v[210:211], v218 offset:8448
	ds_read_b64_tr_b16 v[212:213], v218 offset:12544
	s_waitcnt lgkmcnt(8)
	v_mfma_f32_32x32x16_bf16 v[96:111], v[128:131], v[250:253], v[96:111]
	ds_read_b64_tr_b16 v[128:129], v219 offset:8448
	ds_read_b64_tr_b16 v[130:131], v219 offset:12544
	s_waitcnt lgkmcnt(8)
	v_mfma_f32_32x32x16_bf16 v[80:95], v[214:217], v[250:253], v[80:95]
	ds_read_b64_tr_b16 v[214:215], v221 offset:8448
	ds_read_b64_tr_b16 v[216:217], v221 offset:12544
	s_waitcnt lgkmcnt(8)
	v_mfma_f32_32x32x16_bf16 v[64:79], v[238:241], v[250:253], v[64:79]
	ds_read_b64_tr_b16 v[238:239], v205 offset:16384
	ds_read_b64_tr_b16 v[240:241], v205 offset:20480
	s_waitcnt lgkmcnt(8)
	v_mfma_f32_32x32x16_bf16 v[48:63], v[206:209], v[250:253], v[48:63]
	ds_read_b64_tr_b16 v[206:207], v218 offset:16384
	ds_read_b64_tr_b16 v[208:209], v218 offset:20480
	s_waitcnt lgkmcnt(8)
	v_mfma_f32_32x32x16_bf16 v[32:47], v[210:213], v[250:253], v[32:47]
	ds_read_b64_tr_b16 v[210:211], v219 offset:16384
	ds_read_b64_tr_b16 v[212:213], v219 offset:20480
	s_waitcnt lgkmcnt(8)
	v_mfma_f32_32x32x16_bf16 v[16:31], v[128:131], v[250:253], v[16:31]
	ds_read_b64_tr_b16 v[128:129], v221 offset:16384
	ds_read_b64_tr_b16 v[130:131], v221 offset:20480
	s_waitcnt lgkmcnt(8)
	v_mfma_f32_32x32x16_bf16 v[0:15], v[214:217], v[250:253], v[0:15]
	ds_read_b64_tr_b16 v[214:215], v205 offset:16640
	ds_read_b64_tr_b16 v[216:217], v205 offset:20736
	s_nop 11
	v_max_f32_e32 v246, v190, v246
	v_sub_f32_e32 v190, v190, v246
	v_exp_f32_e32 v190, v190
	s_nop 0
	v_pk_mul_f32 v[126:127], v[126:127], v[190:191] op_sel_hi:[1,0]
	v_pk_mul_f32 v[124:125], v[124:125], v[190:191] op_sel_hi:[1,0]
	v_pk_mul_f32 v[122:123], v[122:123], v[190:191] op_sel_hi:[1,0]
	v_pk_mul_f32 v[120:121], v[120:121], v[190:191] op_sel_hi:[1,0]
	v_pk_mul_f32 v[118:119], v[118:119], v[190:191] op_sel_hi:[1,0]
	v_pk_mul_f32 v[116:117], v[116:117], v[190:191] op_sel_hi:[1,0]
	v_pk_mul_f32 v[114:115], v[114:115], v[190:191] op_sel_hi:[1,0]
	v_pk_mul_f32 v[112:113], v[112:113], v[190:191] op_sel_hi:[1,0]
	v_pk_mul_f32 v[110:111], v[110:111], v[190:191] op_sel_hi:[1,0]
	v_pk_mul_f32 v[108:109], v[108:109], v[190:191] op_sel_hi:[1,0]
	v_pk_mul_f32 v[106:107], v[106:107], v[190:191] op_sel_hi:[1,0]
	v_pk_mul_f32 v[104:105], v[104:105], v[190:191] op_sel_hi:[1,0]
	v_pk_mul_f32 v[102:103], v[102:103], v[190:191] op_sel_hi:[1,0]
	v_pk_mul_f32 v[100:101], v[100:101], v[190:191] op_sel_hi:[1,0]
	v_pk_mul_f32 v[98:99], v[98:99], v[190:191] op_sel_hi:[1,0]
	v_pk_mul_f32 v[96:97], v[96:97], v[190:191] op_sel_hi:[1,0]
	v_pk_mul_f32 v[94:95], v[94:95], v[190:191] op_sel_hi:[1,0]
	v_pk_mul_f32 v[92:93], v[92:93], v[190:191] op_sel_hi:[1,0]
	v_pk_mul_f32 v[90:91], v[90:91], v[190:191] op_sel_hi:[1,0]
	v_pk_mul_f32 v[88:89], v[88:89], v[190:191] op_sel_hi:[1,0]
	v_pk_mul_f32 v[86:87], v[86:87], v[190:191] op_sel_hi:[1,0]
	v_pk_mul_f32 v[84:85], v[84:85], v[190:191] op_sel_hi:[1,0]
	v_pk_mul_f32 v[82:83], v[82:83], v[190:191] op_sel_hi:[1,0]
	v_pk_mul_f32 v[80:81], v[80:81], v[190:191] op_sel_hi:[1,0]
	v_pk_mul_f32 v[78:79], v[78:79], v[190:191] op_sel_hi:[1,0]
	v_pk_mul_f32 v[76:77], v[76:77], v[190:191] op_sel_hi:[1,0]
	v_pk_mul_f32 v[74:75], v[74:75], v[190:191] op_sel_hi:[1,0]
	v_pk_mul_f32 v[72:73], v[72:73], v[190:191] op_sel_hi:[1,0]
	v_pk_mul_f32 v[70:71], v[70:71], v[190:191] op_sel_hi:[1,0]
	v_pk_mul_f32 v[68:69], v[68:69], v[190:191] op_sel_hi:[1,0]
	v_pk_mul_f32 v[66:67], v[66:67], v[190:191] op_sel_hi:[1,0]
	v_pk_mul_f32 v[64:65], v[64:65], v[190:191] op_sel_hi:[1,0]
	v_pk_mul_f32 v[62:63], v[62:63], v[190:191] op_sel_hi:[1,0]
	v_pk_mul_f32 v[60:61], v[60:61], v[190:191] op_sel_hi:[1,0]
	v_pk_mul_f32 v[58:59], v[58:59], v[190:191] op_sel_hi:[1,0]
	v_pk_mul_f32 v[56:57], v[56:57], v[190:191] op_sel_hi:[1,0]
	v_pk_mul_f32 v[54:55], v[54:55], v[190:191] op_sel_hi:[1,0]
	v_pk_mul_f32 v[52:53], v[52:53], v[190:191] op_sel_hi:[1,0]
	v_pk_mul_f32 v[50:51], v[50:51], v[190:191] op_sel_hi:[1,0]
	v_pk_mul_f32 v[48:49], v[48:49], v[190:191] op_sel_hi:[1,0]
	v_pk_mul_f32 v[46:47], v[46:47], v[190:191] op_sel_hi:[1,0]
	v_pk_mul_f32 v[44:45], v[44:45], v[190:191] op_sel_hi:[1,0]
	v_pk_mul_f32 v[42:43], v[42:43], v[190:191] op_sel_hi:[1,0]
	v_pk_mul_f32 v[40:41], v[40:41], v[190:191] op_sel_hi:[1,0]
	v_pk_mul_f32 v[38:39], v[38:39], v[190:191] op_sel_hi:[1,0]
	v_pk_mul_f32 v[36:37], v[36:37], v[190:191] op_sel_hi:[1,0]
	v_pk_mul_f32 v[34:35], v[34:35], v[190:191] op_sel_hi:[1,0]
	v_pk_mul_f32 v[32:33], v[32:33], v[190:191] op_sel_hi:[1,0]
	v_pk_mul_f32 v[30:31], v[30:31], v[190:191] op_sel_hi:[1,0]
	v_pk_mul_f32 v[28:29], v[28:29], v[190:191] op_sel_hi:[1,0]
	v_pk_mul_f32 v[26:27], v[26:27], v[190:191] op_sel_hi:[1,0]
	v_pk_mul_f32 v[24:25], v[24:25], v[190:191] op_sel_hi:[1,0]
	v_pk_mul_f32 v[22:23], v[22:23], v[190:191] op_sel_hi:[1,0]
	v_pk_mul_f32 v[20:21], v[20:21], v[190:191] op_sel_hi:[1,0]
	v_pk_mul_f32 v[18:19], v[18:19], v[190:191] op_sel_hi:[1,0]
	v_pk_mul_f32 v[16:17], v[16:17], v[190:191] op_sel_hi:[1,0]
	v_pk_mul_f32 v[14:15], v[14:15], v[190:191] op_sel_hi:[1,0]
	v_pk_mul_f32 v[12:13], v[12:13], v[190:191] op_sel_hi:[1,0]
	v_pk_mul_f32 v[10:11], v[10:11], v[190:191] op_sel_hi:[1,0]
	v_pk_mul_f32 v[8:9], v[8:9], v[190:191] op_sel_hi:[1,0]
	v_pk_mul_f32 v[6:7], v[6:7], v[190:191] op_sel_hi:[1,0]
	v_pk_mul_f32 v[4:5], v[4:5], v[190:191] op_sel_hi:[1,0]
	v_pk_mul_f32 v[2:3], v[2:3], v[190:191] op_sel_hi:[1,0]
	v_pk_mul_f32 v[0:1], v[0:1], v[190:191] op_sel_hi:[1,0]
	v_mul_f32_e32 v202, v202, v190
	v_mov_b32_e32 v190, v246
	v_sub_f32_e32 v222, v222, v190
	v_exp_f32_e32 v222, v222
	v_sub_f32_e32 v223, v223, v190
	v_exp_f32_e32 v223, v223
	v_sub_f32_e32 v224, v224, v190
	v_add_f32_e32 v254, 0, v222
	v_exp_f32_e32 v224, v224
	v_sub_f32_e32 v225, v225, v190
	v_add_f32_e32 v254, v223, v254
	v_exp_f32_e32 v225, v225
	v_sub_f32_e32 v226, v226, v190
	v_add_f32_e32 v254, v224, v254
	v_exp_f32_e32 v226, v226
	v_sub_f32_e32 v227, v227, v190
	v_add_f32_e32 v254, v225, v254
	v_exp_f32_e32 v227, v227
	v_sub_f32_e32 v228, v228, v190
	v_add_f32_e32 v254, v226, v254
	v_exp_f32_e32 v228, v228
	v_sub_f32_e32 v229, v229, v190
	v_add_f32_e32 v254, v227, v254
	v_exp_f32_e32 v229, v229
	v_sub_f32_e32 v230, v230, v190
	v_add_f32_e32 v254, v228, v254
	v_exp_f32_e32 v230, v230
	v_sub_f32_e32 v231, v231, v190
	v_add_f32_e32 v254, v229, v254
	v_exp_f32_e32 v231, v231
	v_sub_f32_e32 v232, v232, v190
	v_add_f32_e32 v254, v230, v254
	v_exp_f32_e32 v232, v232
	v_sub_f32_e32 v233, v233, v190
	v_add_f32_e32 v254, v231, v254
	v_exp_f32_e32 v233, v233
	v_sub_f32_e32 v234, v234, v190
	v_add_f32_e32 v254, v232, v254
	v_exp_f32_e32 v234, v234
	v_sub_f32_e32 v235, v235, v190
	v_add_f32_e32 v254, v233, v254
	v_exp_f32_e32 v235, v235
	v_sub_f32_e32 v236, v236, v190
	v_add_f32_e32 v254, v234, v254
	v_exp_f32_e32 v236, v236
	v_sub_f32_e32 v237, v237, v190
	v_add_f32_e32 v254, v235, v254
	v_exp_f32_e32 v237, v237
	v_add_f32_e32 v254, v236, v254
	v_add_f32_e32 v254, v237, v254
	v_cvt_pk_bf16_f32 v242, v222, v223
	v_cvt_pk_bf16_f32 v243, v224, v225
	v_cvt_pk_bf16_f32 v244, v226, v227
	v_cvt_pk_bf16_f32 v245, v228, v229
	v_cvt_pk_bf16_f32 v250, v230, v231
	v_cvt_pk_bf16_f32 v251, v232, v233
	v_cvt_pk_bf16_f32 v252, v234, v235
	v_cvt_pk_bf16_f32 v253, v236, v237
	v_add_f32_e32 v202, v202, v254
	s_nop 1
	s_branch .Latt_pv1_4F
	s_lshl_b32 s22, s76, 14
	s_add_i32 s23, s22, 0
	v_add_u32_e32 v206, s23, v194
	ds_read_b128 v[128:131], v206
	v_add_u32_e32 v207, s23, v195
	ds_read_b128 v[210:213], v207
	v_add_u32_e32 v208, s23, v196
	v_add_u32_e32 v209, s23, v197
	v_lshrrev_b32_e32 v204, 3, v203
	s_add_i32 s77, s39, 31
	v_and_or_b32 v205, v203, 31, s71
	s_cmp_le_i32 s77, s71
	s_waitcnt lgkmcnt(1)
	v_mfma_f32_32x32x16_bf16 v[128:143], v[128:131], v[144:147], 0
	ds_read_b128 v[214:217], v209
	s_waitcnt lgkmcnt(1)
	v_mfma_f32_32x32x16_bf16 v[128:143], v[210:213], v[148:151], v[128:143]
	ds_read_b128 v[210:213], v208
	s_waitcnt lgkmcnt(0)
	v_mfma_f32_32x32x16_bf16 v[128:143], v[210:213], v[152:155], v[128:143]
	v_add_u32_e32 v210, s23, v198
	v_add_u32_e32 v212, s23, v199
	v_add_u32_e32 v213, s23, v200
	v_and_b32_e32 v211, 4, v204
	ds_read_b128 v[222:225], v212
	v_mfma_f32_32x32x16_bf16 v[128:143], v[214:217], v[156:159], v[128:143]
	ds_read_b128 v[214:217], v210
	s_waitcnt lgkmcnt(0)
	v_mfma_f32_32x32x16_bf16 v[128:143], v[214:217], v[160:163], v[128:143]
	ds_read_b128 v[216:219], v213
	v_add_u32_e32 v214, s23, v201
	v_mfma_f32_32x32x16_bf16 v[128:143], v[222:225], v[164:167], v[128:143]
	ds_read_b128 v[222:225], v214
	s_waitcnt lgkmcnt(1)
	v_mfma_f32_32x32x16_bf16 v[128:143], v[216:219], v[168:171], v[128:143]
	s_waitcnt lgkmcnt(0)
	v_mfma_f32_32x32x16_bf16 v[128:143], v[222:225], v[172:175], v[128:143]
	s_cbranch_scc1 .LBB0_1804
	v_add_u32_e32 v204, s39, v211
	v_cmp_lt_i32_e32 vcc, v204, v205
	v_add_u32_e32 v215, 2, v204
	s_nop 7
	v_cndmask_b32_e32 v129, v192, v129, vcc
	v_cmp_le_i32_e32 vcc, v204, v205
	s_nop 1
	v_cndmask_b32_e32 v128, v192, v128, vcc
	v_cmp_le_i32_e32 vcc, v215, v205
	v_add_u32_e32 v215, 3, v204
	s_nop 0
	v_cndmask_b32_e32 v130, v192, v130, vcc
	v_cmp_le_i32_e32 vcc, v215, v205
	v_add_u32_e32 v215, 8, v204
	s_nop 0
	v_cndmask_b32_e32 v131, v192, v131, vcc
	v_cmp_le_i32_e32 vcc, v215, v205
	v_add_u32_e32 v215, 9, v204
	s_nop 0
	v_cndmask_b32_e32 v132, v192, v132, vcc
	v_cmp_le_i32_e32 vcc, v215, v205
	v_add_u32_e32 v215, 10, v204
	s_nop 0
	v_cndmask_b32_e32 v133, v192, v133, vcc
	v_cmp_le_i32_e32 vcc, v215, v205
	v_add_u32_e32 v215, 11, v204
	s_nop 0
	v_cndmask_b32_e32 v134, v192, v134, vcc
	v_cmp_le_i32_e32 vcc, v215, v205
	v_add_u32_e32 v215, 16, v204
	s_nop 0
	v_cndmask_b32_e32 v135, v192, v135, vcc
	v_cmp_le_i32_e32 vcc, v215, v205
	v_add_u32_e32 v215, 17, v204
	s_nop 0
	v_cndmask_b32_e32 v136, v192, v136, vcc
	v_cmp_le_i32_e32 vcc, v215, v205
	v_add_u32_e32 v215, 18, v204
	s_nop 0
	v_cndmask_b32_e32 v137, v192, v137, vcc
	v_cmp_le_i32_e32 vcc, v215, v205
	v_add_u32_e32 v215, 19, v204
	s_nop 0
	v_cndmask_b32_e32 v138, v192, v138, vcc
	v_cmp_le_i32_e32 vcc, v215, v205
	v_add_u32_e32 v215, 24, v204
	s_nop 0
	v_cndmask_b32_e32 v139, v192, v139, vcc
	v_cmp_le_i32_e32 vcc, v215, v205
	v_add_u32_e32 v215, 25, v204
	s_nop 0
	v_cndmask_b32_e32 v140, v192, v140, vcc
	v_cmp_le_i32_e32 vcc, v215, v205
	v_add_u32_e32 v215, 26, v204
	v_add_u32_e32 v204, 27, v204
	v_cndmask_b32_e32 v141, v192, v141, vcc
	v_cmp_le_i32_e32 vcc, v215, v205
	s_nop 1
	v_cndmask_b32_e32 v142, v192, v142, vcc
	v_cmp_le_i32_e32 vcc, v204, v205
	s_nop 1
	v_cndmask_b32_e32 v143, v192, v143, vcc

.LBB0_1818:
	s_cmp_ge_u32 s76, s70
	s_cselect_b64 s[18:19], -1, 0
	v_mov_b32_e32 v204, v176
	s_and_b64 vcc, exec, s[18:19]
	s_cbranch_vccnz .LBB0_1820
	s_cmp_le_i32 s4, s72
	s_cbranch_scc1 .LBB0_1820
	v_sub_co_u32_e64 v128, s[78:79], s33, 1
	s_nop 1
	v_cndmask_b32_e64 v130, v128, 2, s[78:79]
	v_lshlrev_b32_e32 v128, 14, v130
	v_add_u32_e32 v131, s73, v128
	v_lshl_add_u64 v[128:129], s[12:13], 0, v[178:179]
	s_add_u32 s78, s12, 0xf00
	v_readfirstlane_b32 s77, v131
	s_mov_b32 s80, m0
	s_mov_b32 m0, s77
	s_nop 0
	global_load_lds_dwordx4 v[128:129], off
	s_mov_b32 m0, s80
	v_lshl_add_u64 v[128:129], s[12:13], 0, v[180:181]
	s_addc_u32 s79, s13, 0
	s_addk_i32 s77, 0x400
	s_mov_b32 s80, m0
	s_mov_b32 m0, s77
	s_nop 0
	global_load_lds_dwordx4 v[128:129], off
	s_mov_b32 m0, s80
	v_lshlrev_b32_e32 v128, 15, v130
	v_add_u32_e32 v130, s74, v128
	v_lshl_add_u64 v[128:129], s[78:79], 0, v[182:183]
	v_readfirstlane_b32 s77, v130
	s_mov_b32 s80, m0
	s_mov_b32 m0, s77
	s_nop 0
	global_load_lds_dwordx4 v[128:129], off
	s_mov_b32 m0, s80
	v_lshl_add_u64 v[128:129], s[78:79], 0, v[184:185]
	s_add_i32 s80, s77, 0x400
	s_mov_b32 s81, m0
	s_mov_b32 m0, s80
	s_nop 0
	global_load_lds_dwordx4 v[128:129], off
	s_mov_b32 m0, s81
	v_lshl_add_u64 v[128:129], s[78:79], 0, v[186:187]
	s_add_i32 s80, s77, 0x800
	s_mov_b32 s81, m0
	s_mov_b32 m0, s80
	s_nop 0
	global_load_lds_dwordx4 v[128:129], off
	s_mov_b32 m0, s81
	v_lshl_add_u64 v[128:129], s[78:79], 0, v[188:189]
	s_addk_i32 s77, 0xc00
	s_mov_b32 s78, m0
	s_mov_b32 m0, s77
	s_nop 0
	global_load_lds_dwordx4 v[128:129], off
	s_mov_b32 m0, s78
.LBB0_1820:
	s_cmp_gt_i32 s4, s72
	s_cbranch_scc1 .LBB0_1831
	s_add_i32 s100, s4, 63
	s_cmp_le_i32 s100, s71
	s_cbranch_scc1 .Latt_full_5
	s_add_i32 s100, s4, 32
	s_cmp_le_i32 s100, s72
	s_cbranch_scc1 .Latt_diagA_5
	s_lshl_b32 s98, s33, 14
	s_lshl_b32 s99, s33, 15
	s_add_i32 s99, s99, 0xc000
	v_add_u32_e32 v206, s98, v196
	ds_read_b128 v[206:209], v206
	v_add_u32_e32 v210, s98, v197
	ds_read_b128 v[210:213], v210
	v_add_u32_e32 v214, s98, v198
	ds_read_b128 v[214:217], v214
	v_add_u32_e32 v238, s98, v199
	ds_read_b128 v[238:241], v238
	v_add_u32_e32 v242, s98, v200
	ds_read_b128 v[242:245], v242
	v_add_u32_e32 v250, s98, v201
	ds_read_b128 v[250:253], v250
	v_add_u32_e32 v222, s98, v202
	ds_read_b128 v[222:225], v222
	v_add_u32_e32 v226, s98, v203
	ds_read_b128 v[226:229], v226
	v_bfe_u32 v246, v204, 2, 2
	v_bfe_u32 v247, v204, 5, 1
	v_lshl_or_b32 v247, v247, 2, v246
	v_and_b32_e32 v249, 3, v204
	v_and_b32_e32 v254, 16, v204
	v_lshl_or_b32 v249, v249, 2, v254
	v_lshlrev_b32_e32 v249, 1, v249
	v_lshl_add_u32 v247, v247, 9, v249
	v_add_u32_e32 v247, s99, v247
	v_lshlrev_b32_e32 v246, 6, v246
	v_add_u32_e32 v205, v247, v246
	v_xor_b32_e32 v249, 64, v246
	v_add_u32_e32 v218, v247, v249
	v_xor_b32_e32 v249, 0x80, v246
	v_add_u32_e32 v219, v247, v249
	v_xor_b32_e32 v249, 0xc0, v246
	v_add_u32_e32 v221, v247, v249
	s_waitcnt lgkmcnt(7)
	v_mfma_f32_32x32x16_bf16 v[128:143], v[206:209], v[144:147], 0
	ds_read_b64_tr_b16 v[206:207], v205
	ds_read_b64_tr_b16 v[208:209], v205 offset:4096
	s_waitcnt lgkmcnt(8)
	v_mfma_f32_32x32x16_bf16 v[128:143], v[210:213], v[148:151], v[128:143]
	ds_read_b64_tr_b16 v[210:211], v218
	ds_read_b64_tr_b16 v[212:213], v218 offset:4096
	s_waitcnt lgkmcnt(9)
	v_mfma_f32_32x32x16_bf16 v[128:143], v[214:217], v[152:155], v[128:143]
	s_waitcnt lgkmcnt(8)
	v_mfma_f32_32x32x16_bf16 v[128:143], v[238:241], v[156:159], v[128:143]
	ds_read_b64_tr_b16 v[214:215], v219
	ds_read_b64_tr_b16 v[216:217], v219 offset:4096
	s_waitcnt lgkmcnt(9)
	v_mfma_f32_32x32x16_bf16 v[128:143], v[242:245], v[160:163], v[128:143]
	s_waitcnt lgkmcnt(8)
	v_mfma_f32_32x32x16_bf16 v[128:143], v[250:253], v[164:167], v[128:143]
	ds_read_b64_tr_b16 v[238:239], v221
	ds_read_b64_tr_b16 v[240:241], v221 offset:4096
	s_waitcnt lgkmcnt(9)
	v_mfma_f32_32x32x16_bf16 v[128:143], v[222:225], v[168:171], v[128:143]
	s_waitcnt lgkmcnt(8)
	v_mfma_f32_32x32x16_bf16 v[128:143], v[226:229], v[172:175], v[128:143]
	s_nop 11
	v_and_or_b32 v246, v204, 31, s71
	v_bfe_u32 v247, v204, 5, 1
	s_add_i32 s100, s4, 0
	v_lshl_add_u32 v247, v247, 2, s100
	v_add_u32_e32 v249, 0, v247
	v_cmp_le_i32_e32 vcc, v249, v246
	v_add_u32_e32 v254, 1, v247
	s_nop 0
	v_cndmask_b32_e32 v128, v192, v128, vcc
	v_cmp_le_i32_e32 vcc, v254, v246
	v_add_u32_e32 v249, 2, v247
	s_nop 0
	v_cndmask_b32_e32 v129, v192, v129, vcc
	v_cmp_le_i32_e32 vcc, v249, v246
	v_add_u32_e32 v254, 3, v247
	s_nop 0
	v_cndmask_b32_e32 v130, v192, v130, vcc
	v_cmp_le_i32_e32 vcc, v254, v246
	v_add_u32_e32 v249, 8, v247
	s_nop 0
	v_cndmask_b32_e32 v131, v192, v131, vcc
	v_cmp_le_i32_e32 vcc, v249, v246
	v_add_u32_e32 v254, 9, v247
	s_nop 0
	v_cndmask_b32_e32 v132, v192, v132, vcc
	v_cmp_le_i32_e32 vcc, v254, v246
	v_add_u32_e32 v249, 10, v247
	s_nop 0
	v_cndmask_b32_e32 v133, v192, v133, vcc
	v_cmp_le_i32_e32 vcc, v249, v246
	v_add_u32_e32 v254, 11, v247
	s_nop 0
	v_cndmask_b32_e32 v134, v192, v134, vcc
	v_cmp_le_i32_e32 vcc, v254, v246
	v_add_u32_e32 v249, 16, v247
	s_nop 0
	v_cndmask_b32_e32 v135, v192, v135, vcc
	v_cmp_le_i32_e32 vcc, v249, v246
	v_add_u32_e32 v254, 17, v247
	s_nop 0
	v_cndmask_b32_e32 v136, v192, v136, vcc
	v_cmp_le_i32_e32 vcc, v254, v246
	v_add_u32_e32 v249, 18, v247
	s_nop 0
	v_cndmask_b32_e32 v137, v192, v137, vcc
	v_cmp_le_i32_e32 vcc, v249, v246
	v_add_u32_e32 v254, 19, v247
	s_nop 0
	v_cndmask_b32_e32 v138, v192, v138, vcc
	v_cmp_le_i32_e32 vcc, v254, v246
	v_add_u32_e32 v249, 24, v247
	s_nop 0
	v_cndmask_b32_e32 v139, v192, v139, vcc
	v_cmp_le_i32_e32 vcc, v249, v246
	v_add_u32_e32 v254, 25, v247
	s_nop 0
	v_cndmask_b32_e32 v140, v192, v140, vcc
	v_cmp_le_i32_e32 vcc, v254, v246
	v_add_u32_e32 v249, 26, v247
	s_nop 0
	v_cndmask_b32_e32 v141, v192, v141, vcc
	v_cmp_le_i32_e32 vcc, v249, v246
	v_add_u32_e32 v254, 27, v247
	s_nop 0
	v_cndmask_b32_e32 v142, v192, v142, vcc
	v_cmp_le_i32_e32 vcc, v254, v246
	s_nop 1
	v_cndmask_b32_e32 v143, v192, v143, vcc
	v_max3_f32 v246, v128, v129, v130
	v_max3_f32 v247, v131, v132, v133
	v_max3_f32 v246, v246, v134, v135
	v_max3_f32 v247, v247, v136, v137
	v_max3_f32 v246, v246, v138, v139
	v_max3_f32 v247, v247, v140, v141
	v_max3_f32 v246, v246, v142, v143
	v_max_f32_e32 v246, v246, v247
	v_mov_b32_e32 v247, v246
	v_add_f32_e32 v249, 0x41000000, v190
	s_nop 1
	v_permlane32_swap_b32_e32 v246, v247
	v_max_f32_e32 v246, v246, v247
	v_cmp_gt_f32_e32 vcc, v246, v249
	s_cbranch_vccz .Latt_nr0_5B
	v_max_f32_e32 v246, v190, v246
	v_sub_f32_e32 v190, v190, v246
	v_exp_f32_e32 v190, v190
	s_nop 0
	v_pk_mul_f32 v[126:127], v[126:127], v[190:191] op_sel_hi:[1,0]
	v_pk_mul_f32 v[124:125], v[124:125], v[190:191] op_sel_hi:[1,0]
	v_pk_mul_f32 v[122:123], v[122:123], v[190:191] op_sel_hi:[1,0]
	v_pk_mul_f32 v[120:121], v[120:121], v[190:191] op_sel_hi:[1,0]
	v_pk_mul_f32 v[118:119], v[118:119], v[190:191] op_sel_hi:[1,0]
	v_pk_mul_f32 v[116:117], v[116:117], v[190:191] op_sel_hi:[1,0]
	v_pk_mul_f32 v[114:115], v[114:115], v[190:191] op_sel_hi:[1,0]
	v_pk_mul_f32 v[112:113], v[112:113], v[190:191] op_sel_hi:[1,0]
	v_pk_mul_f32 v[110:111], v[110:111], v[190:191] op_sel_hi:[1,0]
	v_pk_mul_f32 v[108:109], v[108:109], v[190:191] op_sel_hi:[1,0]
	v_pk_mul_f32 v[106:107], v[106:107], v[190:191] op_sel_hi:[1,0]
	v_pk_mul_f32 v[104:105], v[104:105], v[190:191] op_sel_hi:[1,0]
	v_pk_mul_f32 v[102:103], v[102:103], v[190:191] op_sel_hi:[1,0]
	v_pk_mul_f32 v[100:101], v[100:101], v[190:191] op_sel_hi:[1,0]
	v_pk_mul_f32 v[98:99], v[98:99], v[190:191] op_sel_hi:[1,0]
	v_pk_mul_f32 v[96:97], v[96:97], v[190:191] op_sel_hi:[1,0]
	v_pk_mul_f32 v[94:95], v[94:95], v[190:191] op_sel_hi:[1,0]
	v_pk_mul_f32 v[92:93], v[92:93], v[190:191] op_sel_hi:[1,0]
	v_pk_mul_f32 v[90:91], v[90:91], v[190:191] op_sel_hi:[1,0]
	v_pk_mul_f32 v[88:89], v[88:89], v[190:191] op_sel_hi:[1,0]
	v_pk_mul_f32 v[86:87], v[86:87], v[190:191] op_sel_hi:[1,0]
	v_pk_mul_f32 v[84:85], v[84:85], v[190:191] op_sel_hi:[1,0]
	v_pk_mul_f32 v[82:83], v[82:83], v[190:191] op_sel_hi:[1,0]
	v_pk_mul_f32 v[80:81], v[80:81], v[190:191] op_sel_hi:[1,0]
	v_pk_mul_f32 v[78:79], v[78:79], v[190:191] op_sel_hi:[1,0]
	v_pk_mul_f32 v[76:77], v[76:77], v[190:191] op_sel_hi:[1,0]
	v_pk_mul_f32 v[74:75], v[74:75], v[190:191] op_sel_hi:[1,0]
	v_pk_mul_f32 v[72:73], v[72:73], v[190:191] op_sel_hi:[1,0]
	v_pk_mul_f32 v[70:71], v[70:71], v[190:191] op_sel_hi:[1,0]
	v_pk_mul_f32 v[68:69], v[68:69], v[190:191] op_sel_hi:[1,0]
	v_pk_mul_f32 v[66:67], v[66:67], v[190:191] op_sel_hi:[1,0]
	v_pk_mul_f32 v[64:65], v[64:65], v[190:191] op_sel_hi:[1,0]
	v_pk_mul_f32 v[62:63], v[62:63], v[190:191] op_sel_hi:[1,0]
	v_pk_mul_f32 v[60:61], v[60:61], v[190:191] op_sel_hi:[1,0]
	v_pk_mul_f32 v[58:59], v[58:59], v[190:191] op_sel_hi:[1,0]
	v_pk_mul_f32 v[56:57], v[56:57], v[190:191] op_sel_hi:[1,0]
	v_pk_mul_f32 v[54:55], v[54:55], v[190:191] op_sel_hi:[1,0]
	v_pk_mul_f32 v[52:53], v[52:53], v[190:191] op_sel_hi:[1,0]
	v_pk_mul_f32 v[50:51], v[50:51], v[190:191] op_sel_hi:[1,0]
	v_pk_mul_f32 v[48:49], v[48:49], v[190:191] op_sel_hi:[1,0]
	v_pk_mul_f32 v[46:47], v[46:47], v[190:191] op_sel_hi:[1,0]
	v_pk_mul_f32 v[44:45], v[44:45], v[190:191] op_sel_hi:[1,0]
	v_pk_mul_f32 v[42:43], v[42:43], v[190:191] op_sel_hi:[1,0]
	v_pk_mul_f32 v[40:41], v[40:41], v[190:191] op_sel_hi:[1,0]
	v_pk_mul_f32 v[38:39], v[38:39], v[190:191] op_sel_hi:[1,0]
	v_pk_mul_f32 v[36:37], v[36:37], v[190:191] op_sel_hi:[1,0]
	v_pk_mul_f32 v[34:35], v[34:35], v[190:191] op_sel_hi:[1,0]
	v_pk_mul_f32 v[32:33], v[32:33], v[190:191] op_sel_hi:[1,0]
	v_pk_mul_f32 v[30:31], v[30:31], v[190:191] op_sel_hi:[1,0]
	v_pk_mul_f32 v[28:29], v[28:29], v[190:191] op_sel_hi:[1,0]
	v_pk_mul_f32 v[26:27], v[26:27], v[190:191] op_sel_hi:[1,0]
	v_pk_mul_f32 v[24:25], v[24:25], v[190:191] op_sel_hi:[1,0]
	v_pk_mul_f32 v[22:23], v[22:23], v[190:191] op_sel_hi:[1,0]
	v_pk_mul_f32 v[20:21], v[20:21], v[190:191] op_sel_hi:[1,0]
	v_pk_mul_f32 v[18:19], v[18:19], v[190:191] op_sel_hi:[1,0]
	v_pk_mul_f32 v[16:17], v[16:17], v[190:191] op_sel_hi:[1,0]
	v_pk_mul_f32 v[14:15], v[14:15], v[190:191] op_sel_hi:[1,0]
	v_pk_mul_f32 v[12:13], v[12:13], v[190:191] op_sel_hi:[1,0]
	v_pk_mul_f32 v[10:11], v[10:11], v[190:191] op_sel_hi:[1,0]
	v_pk_mul_f32 v[8:9], v[8:9], v[190:191] op_sel_hi:[1,0]
	v_pk_mul_f32 v[6:7], v[6:7], v[190:191] op_sel_hi:[1,0]
	v_pk_mul_f32 v[4:5], v[4:5], v[190:191] op_sel_hi:[1,0]
	v_pk_mul_f32 v[2:3], v[2:3], v[190:191] op_sel_hi:[1,0]
	v_pk_mul_f32 v[0:1], v[0:1], v[190:191] op_sel_hi:[1,0]
	v_mul_f32_e32 v195, v195, v190
	v_mov_b32_e32 v190, v246
.Latt_nr0_5B:
	v_sub_f32_e32 v128, v128, v190
	v_exp_f32_e32 v128, v128
	v_sub_f32_e32 v129, v129, v190
	v_exp_f32_e32 v129, v129
	v_sub_f32_e32 v130, v130, v190
	v_add_f32_e32 v254, 0, v128
	v_exp_f32_e32 v130, v130
	v_sub_f32_e32 v131, v131, v190
	v_add_f32_e32 v254, v129, v254
	v_exp_f32_e32 v131, v131
	v_sub_f32_e32 v132, v132, v190
	v_add_f32_e32 v254, v130, v254
	v_exp_f32_e32 v132, v132
	v_sub_f32_e32 v133, v133, v190
	v_add_f32_e32 v254, v131, v254
	v_exp_f32_e32 v133, v133
	v_sub_f32_e32 v134, v134, v190
	v_add_f32_e32 v254, v132, v254
	v_exp_f32_e32 v134, v134
	v_sub_f32_e32 v135, v135, v190
	v_add_f32_e32 v254, v133, v254
	v_exp_f32_e32 v135, v135
	v_sub_f32_e32 v136, v136, v190
	v_add_f32_e32 v254, v134, v254
	v_exp_f32_e32 v136, v136
	v_sub_f32_e32 v137, v137, v190
	v_add_f32_e32 v254, v135, v254
	v_exp_f32_e32 v137, v137
	v_sub_f32_e32 v138, v138, v190
	v_add_f32_e32 v254, v136, v254
	v_exp_f32_e32 v138, v138
	v_sub_f32_e32 v139, v139, v190
	v_add_f32_e32 v254, v137, v254
	v_exp_f32_e32 v139, v139
	v_sub_f32_e32 v140, v140, v190
	v_add_f32_e32 v254, v138, v254
	v_exp_f32_e32 v140, v140
	v_sub_f32_e32 v141, v141, v190
	v_add_f32_e32 v254, v139, v254
	v_exp_f32_e32 v141, v141
	v_sub_f32_e32 v142, v142, v190
	v_add_f32_e32 v254, v140, v254
	v_exp_f32_e32 v142, v142
	v_sub_f32_e32 v143, v143, v190
	v_add_f32_e32 v254, v141, v254
	v_exp_f32_e32 v143, v143
	v_add_f32_e32 v254, v142, v254
	v_add_f32_e32 v254, v143, v254
	v_cvt_pk_bf16_f32 v242, v128, v129
	v_cvt_pk_bf16_f32 v243, v130, v131
	v_cvt_pk_bf16_f32 v244, v132, v133
	v_cvt_pk_bf16_f32 v245, v134, v135
	v_cvt_pk_bf16_f32 v250, v136, v137
	v_cvt_pk_bf16_f32 v251, v138, v139
	v_cvt_pk_bf16_f32 v252, v140, v141
	v_cvt_pk_bf16_f32 v253, v142, v143
	v_add_f32_e32 v195, v195, v254
	s_nop 1
	ds_read_b64_tr_b16 v[128:129], v205 offset:256
	ds_read_b64_tr_b16 v[130:131], v205 offset:4352
	s_waitcnt lgkmcnt(8)
	v_mfma_f32_32x32x16_bf16 v[112:127], v[206:209], v[242:245], v[112:127]
	ds_read_b64_tr_b16 v[206:207], v218 offset:256
	ds_read_b64_tr_b16 v[208:209], v218 offset:4352
	s_waitcnt lgkmcnt(8)
	v_mfma_f32_32x32x16_bf16 v[96:111], v[210:213], v[242:245], v[96:111]
	ds_read_b64_tr_b16 v[210:211], v219 offset:256
	ds_read_b64_tr_b16 v[212:213], v219 offset:4352
	s_cmp_lg_u64 s[18:19], 0
	s_cbranch_scc1 .Latt_nd0_5B
	s_sub_i32 s100, s33, 1
	s_cmp_eq_u32 s33, 0
	s_cselect_b32 s100, 2, s100
	s_lshl_b32 s101, s100, 14
	s_add_i32 m0, s73, s101
	s_nop 0
	global_load_lds_dwordx4 v178, s[12:13]

.Latt_nd1_5B:
	s_waitcnt lgkmcnt(8)
	v_mfma_f32_32x32x16_bf16 v[48:63], v[128:131], v[242:245], v[48:63]
	ds_read_b64_tr_b16 v[128:129], v218 offset:8192
	ds_read_b64_tr_b16 v[130:131], v218 offset:12288
	s_waitcnt lgkmcnt(8)
	v_mfma_f32_32x32x16_bf16 v[32:47], v[206:209], v[242:245], v[32:47]
	ds_read_b64_tr_b16 v[206:207], v219 offset:8192
	ds_read_b64_tr_b16 v[208:209], v219 offset:12288
	s_cmp_lg_u64 s[18:19], 0
	s_cbranch_scc1 .Latt_nd2_5B
	s_lshl_b32 s101, s100, 15
	s_add_i32 m0, s74, s101
	s_add_u32 s100, s12, 0xf00
	s_addc_u32 s101, s13, 0
	global_load_lds_dwordx4 v182, s[100:101]

.Latt_nr0_5A:
	s_waitcnt lgkmcnt(5)
	v_mfma_f32_32x32x16_bf16 v[222:237], v[214:217], v[152:155], v[222:237]
	ds_read_b64_tr_b16 v[214:215], v205
	ds_read_b64_tr_b16 v[216:217], v205 offset:4096
	v_sub_f32_e32 v128, v128, v190
	v_exp_f32_e32 v128, v128
	v_sub_f32_e32 v129, v129, v190
	v_exp_f32_e32 v129, v129
	v_sub_f32_e32 v130, v130, v190
	v_add_f32_e32 v254, 0, v128
	v_exp_f32_e32 v130, v130
	v_sub_f32_e32 v131, v131, v190
	s_waitcnt lgkmcnt(6)
	v_mfma_f32_32x32x16_bf16 v[222:237], v[238:241], v[156:159], v[222:237]
	ds_read_b64_tr_b16 v[238:239], v218
	ds_read_b64_tr_b16 v[240:241], v218 offset:4096
	v_add_f32_e32 v254, v129, v254
	v_exp_f32_e32 v131, v131
	v_sub_f32_e32 v132, v132, v190
	v_add_f32_e32 v254, v130, v254
	v_exp_f32_e32 v132, v132
	v_sub_f32_e32 v133, v133, v190
	v_add_f32_e32 v254, v131, v254
	v_exp_f32_e32 v133, v133
	s_waitcnt lgkmcnt(7)
	v_mfma_f32_32x32x16_bf16 v[222:237], v[242:245], v[160:163], v[222:237]
	v_sub_f32_e32 v134, v134, v190
	v_add_f32_e32 v254, v132, v254
	v_exp_f32_e32 v134, v134
	v_sub_f32_e32 v135, v135, v190
	v_add_f32_e32 v254, v133, v254
	v_exp_f32_e32 v135, v135
	v_sub_f32_e32 v136, v136, v190
	v_add_f32_e32 v254, v134, v254
	s_waitcnt lgkmcnt(6)
	v_mfma_f32_32x32x16_bf16 v[222:237], v[250:253], v[164:167], v[222:237]
	v_exp_f32_e32 v136, v136
	v_sub_f32_e32 v137, v137, v190
	v_add_f32_e32 v254, v135, v254
	v_exp_f32_e32 v137, v137
	v_sub_f32_e32 v138, v138, v190
	v_add_f32_e32 v254, v136, v254
	v_exp_f32_e32 v138, v138
	v_sub_f32_e32 v139, v139, v190
	s_waitcnt lgkmcnt(5)
	v_mfma_f32_32x32x16_bf16 v[222:237], v[206:209], v[168:171], v[222:237]
	ds_read_b64_tr_b16 v[206:207], v219
	ds_read_b64_tr_b16 v[208:209], v219 offset:4096
	v_add_f32_e32 v254, v137, v254
	v_exp_f32_e32 v139, v139
	v_sub_f32_e32 v140, v140, v190
	v_add_f32_e32 v254, v138, v254
	v_exp_f32_e32 v140, v140
	v_sub_f32_e32 v141, v141, v190
	v_add_f32_e32 v254, v139, v254
	v_exp_f32_e32 v141, v141
	s_waitcnt lgkmcnt(6)
	v_mfma_f32_32x32x16_bf16 v[222:237], v[210:213], v[172:175], v[222:237]
	ds_read_b64_tr_b16 v[210:211], v221
	ds_read_b64_tr_b16 v[212:213], v221 offset:4096
	v_sub_f32_e32 v142, v142, v190
	v_add_f32_e32 v254, v140, v254
	v_exp_f32_e32 v142, v142
	v_sub_f32_e32 v143, v143, v190
	v_add_f32_e32 v254, v141, v254
	v_exp_f32_e32 v143, v143
	v_add_f32_e32 v254, v142, v254
	v_add_f32_e32 v254, v143, v254
	v_cvt_pk_bf16_f32 v242, v128, v129
	v_cvt_pk_bf16_f32 v243, v130, v131
	v_cvt_pk_bf16_f32 v244, v132, v133
	v_cvt_pk_bf16_f32 v245, v134, v135
	v_cvt_pk_bf16_f32 v250, v136, v137
	v_cvt_pk_bf16_f32 v251, v138, v139
	v_cvt_pk_bf16_f32 v252, v140, v141
	v_cvt_pk_bf16_f32 v253, v142, v143
	v_add_f32_e32 v195, v195, v254
	s_nop 1
	ds_read_b64_tr_b16 v[128:129], v205 offset:256
	ds_read_b64_tr_b16 v[130:131], v205 offset:4352
	s_waitcnt lgkmcnt(8)
	v_mfma_f32_32x32x16_bf16 v[112:127], v[214:217], v[242:245], v[112:127]
	ds_read_b64_tr_b16 v[214:215], v218 offset:256
	ds_read_b64_tr_b16 v[216:217], v218 offset:4352
	v_and_or_b32 v246, v204, 31, s71
	v_bfe_u32 v247, v204, 5, 1
	s_add_i32 s100, s4, 32
	v_lshl_add_u32 v247, v247, 2, s100
	v_add_u32_e32 v249, 0, v247
	v_cmp_le_i32_e32 vcc, v249, v246
	v_add_u32_e32 v254, 1, v247
	s_nop 0
	v_cndmask_b32_e32 v222, v192, v222, vcc
	v_cmp_le_i32_e32 vcc, v254, v246
	v_add_u32_e32 v249, 2, v247
	s_nop 0
	v_cndmask_b32_e32 v223, v192, v223, vcc
	v_cmp_le_i32_e32 vcc, v249, v246
	v_add_u32_e32 v254, 3, v247
	s_nop 0
	v_cndmask_b32_e32 v224, v192, v224, vcc
	v_cmp_le_i32_e32 vcc, v254, v246
	v_add_u32_e32 v249, 8, v247
	s_nop 0
	v_cndmask_b32_e32 v225, v192, v225, vcc
	v_cmp_le_i32_e32 vcc, v249, v246
	v_add_u32_e32 v254, 9, v247
	s_nop 0
	v_cndmask_b32_e32 v226, v192, v226, vcc
	v_cmp_le_i32_e32 vcc, v254, v246
	v_add_u32_e32 v249, 10, v247
	s_nop 0
	v_cndmask_b32_e32 v227, v192, v227, vcc
	v_cmp_le_i32_e32 vcc, v249, v246
	v_add_u32_e32 v254, 11, v247
	s_nop 0
	v_cndmask_b32_e32 v228, v192, v228, vcc
	v_cmp_le_i32_e32 vcc, v254, v246
	s_waitcnt lgkmcnt(8)
	v_mfma_f32_32x32x16_bf16 v[96:111], v[238:241], v[242:245], v[96:111]
	ds_read_b64_tr_b16 v[238:239], v219 offset:256
	ds_read_b64_tr_b16 v[240:241], v219 offset:4352
	v_add_u32_e32 v249, 16, v247
	s_nop 0
	v_cndmask_b32_e32 v229, v192, v229, vcc
	v_cmp_le_i32_e32 vcc, v249, v246
	v_add_u32_e32 v254, 17, v247
	s_nop 0
	v_cndmask_b32_e32 v230, v192, v230, vcc
	v_cmp_le_i32_e32 vcc, v254, v246
	v_add_u32_e32 v249, 18, v247
	s_nop 0
	v_cndmask_b32_e32 v231, v192, v231, vcc
	v_cmp_le_i32_e32 vcc, v249, v246
	v_add_u32_e32 v254, 19, v247
	s_nop 0
	v_cndmask_b32_e32 v232, v192, v232, vcc
	v_cmp_le_i32_e32 vcc, v254, v246
	v_add_u32_e32 v249, 24, v247
	s_nop 0
	v_cndmask_b32_e32 v233, v192, v233, vcc
	v_cmp_le_i32_e32 vcc, v249, v246
	v_add_u32_e32 v254, 25, v247
	s_nop 0
	v_cndmask_b32_e32 v234, v192, v234, vcc
	v_cmp_le_i32_e32 vcc, v254, v246
	v_add_u32_e32 v249, 26, v247
	s_nop 0
	v_cndmask_b32_e32 v235, v192, v235, vcc
	v_cmp_le_i32_e32 vcc, v249, v246
	v_add_u32_e32 v254, 27, v247
	s_nop 0
	v_cndmask_b32_e32 v236, v192, v236, vcc
	v_cmp_le_i32_e32 vcc, v254, v246
	s_nop 1
	v_cndmask_b32_e32 v237, v192, v237, vcc
	s_waitcnt lgkmcnt(8)
	v_mfma_f32_32x32x16_bf16 v[80:95], v[206:209], v[242:245], v[80:95]
	ds_read_b64_tr_b16 v[206:207], v221 offset:256
	ds_read_b64_tr_b16 v[208:209], v221 offset:4352
	v_max3_f32 v246, v222, v223, v224
	v_max3_f32 v247, v225, v226, v227
	v_max3_f32 v246, v246, v228, v229
	v_max3_f32 v247, v247, v230, v231
	v_max3_f32 v246, v246, v232, v233
	v_max3_f32 v247, v247, v234, v235
	s_waitcnt lgkmcnt(8)
	v_mfma_f32_32x32x16_bf16 v[64:79], v[210:213], v[242:245], v[64:79]
	ds_read_b64_tr_b16 v[210:211], v205 offset:8192
	ds_read_b64_tr_b16 v[212:213], v205 offset:12288
	v_max3_f32 v246, v246, v236, v237
	v_max_f32_e32 v246, v246, v247
	v_mov_b32_e32 v247, v246
	v_add_f32_e32 v249, 0x41000000, v190
	s_nop 1
	s_waitcnt lgkmcnt(8)
	v_mfma_f32_32x32x16_bf16 v[48:63], v[128:131], v[242:245], v[48:63]
	ds_read_b64_tr_b16 v[128:129], v218 offset:8192
	ds_read_b64_tr_b16 v[130:131], v218 offset:12288
	v_permlane32_swap_b32_e32 v246, v247
	v_max_f32_e32 v246, v246, v247
	v_cmp_gt_f32_e32 vcc, v246, v249
	s_cbranch_vccnz .Latt_rs1_5A
	s_waitcnt lgkmcnt(8)
	v_mfma_f32_32x32x16_bf16 v[32:47], v[214:217], v[242:245], v[32:47]
	ds_read_b64_tr_b16 v[214:215], v219 offset:8192
	ds_read_b64_tr_b16 v[216:217], v219 offset:12288
	v_sub_f32_e32 v222, v222, v190
	v_exp_f32_e32 v222, v222
	v_sub_f32_e32 v223, v223, v190
	v_exp_f32_e32 v223, v223
	v_sub_f32_e32 v224, v224, v190
	s_waitcnt lgkmcnt(8)
	v_mfma_f32_32x32x16_bf16 v[16:31], v[238:241], v[242:245], v[16:31]
	ds_read_b64_tr_b16 v[238:239], v221 offset:8192
	ds_read_b64_tr_b16 v[240:241], v221 offset:12288
	v_add_f32_e32 v254, 0, v222
	v_exp_f32_e32 v224, v224
	v_sub_f32_e32 v225, v225, v190
	v_add_f32_e32 v254, v223, v254
	v_exp_f32_e32 v225, v225
	s_waitcnt lgkmcnt(8)
	v_mfma_f32_32x32x16_bf16 v[0:15], v[206:209], v[242:245], v[0:15]
	ds_read_b64_tr_b16 v[206:207], v205 offset:8448
	ds_read_b64_tr_b16 v[208:209], v205 offset:12544
	v_sub_f32_e32 v226, v226, v190
	v_add_f32_e32 v254, v224, v254
	v_exp_f32_e32 v226, v226
	v_sub_f32_e32 v227, v227, v190
	v_add_f32_e32 v254, v225, v254
	s_waitcnt lgkmcnt(8)
	v_mfma_f32_32x32x16_bf16 v[112:127], v[210:213], v[250:253], v[112:127]
	ds_read_b64_tr_b16 v[210:211], v218 offset:8448
	ds_read_b64_tr_b16 v[212:213], v218 offset:12544
	v_exp_f32_e32 v227, v227
	v_sub_f32_e32 v228, v228, v190
	v_add_f32_e32 v254, v226, v254
	v_exp_f32_e32 v228, v228
	v_sub_f32_e32 v229, v229, v190
	s_waitcnt lgkmcnt(8)
	v_mfma_f32_32x32x16_bf16 v[96:111], v[128:131], v[250:253], v[96:111]
	ds_read_b64_tr_b16 v[128:129], v219 offset:8448
	ds_read_b64_tr_b16 v[130:131], v219 offset:12544
	v_add_f32_e32 v254, v227, v254
	v_exp_f32_e32 v229, v229
	v_sub_f32_e32 v230, v230, v190
	v_add_f32_e32 v254, v228, v254
	s_waitcnt lgkmcnt(8)
	v_mfma_f32_32x32x16_bf16 v[80:95], v[214:217], v[250:253], v[80:95]
	ds_read_b64_tr_b16 v[214:215], v221 offset:8448
	ds_read_b64_tr_b16 v[216:217], v221 offset:12544
	v_exp_f32_e32 v230, v230
	v_sub_f32_e32 v231, v231, v190
	v_add_f32_e32 v254, v229, v254
	v_exp_f32_e32 v231, v231
	s_waitcnt lgkmcnt(8)
	v_mfma_f32_32x32x16_bf16 v[64:79], v[238:241], v[250:253], v[64:79]
	ds_read_b64_tr_b16 v[238:239], v205 offset:16384
	ds_read_b64_tr_b16 v[240:241], v205 offset:20480
	v_sub_f32_e32 v232, v232, v190
	v_add_f32_e32 v254, v230, v254
	v_exp_f32_e32 v232, v232
	v_sub_f32_e32 v233, v233, v190
	s_waitcnt lgkmcnt(8)
	v_mfma_f32_32x32x16_bf16 v[48:63], v[206:209], v[250:253], v[48:63]
	ds_read_b64_tr_b16 v[206:207], v218 offset:16384
	ds_read_b64_tr_b16 v[208:209], v218 offset:20480
	v_add_f32_e32 v254, v231, v254
	v_exp_f32_e32 v233, v233
	v_sub_f32_e32 v234, v234, v190
	v_add_f32_e32 v254, v232, v254
	s_waitcnt lgkmcnt(8)
	v_mfma_f32_32x32x16_bf16 v[32:47], v[210:213], v[250:253], v[32:47]
	ds_read_b64_tr_b16 v[210:211], v219 offset:16384
	ds_read_b64_tr_b16 v[212:213], v219 offset:20480
	v_exp_f32_e32 v234, v234
	v_sub_f32_e32 v235, v235, v190
	v_add_f32_e32 v254, v233, v254
	v_exp_f32_e32 v235, v235
	s_waitcnt lgkmcnt(8)
	v_mfma_f32_32x32x16_bf16 v[16:31], v[128:131], v[250:253], v[16:31]
	ds_read_b64_tr_b16 v[128:129], v221 offset:16384
	ds_read_b64_tr_b16 v[130:131], v221 offset:20480
	v_sub_f32_e32 v236, v236, v190
	v_add_f32_e32 v254, v234, v254
	v_exp_f32_e32 v236, v236
	v_sub_f32_e32 v237, v237, v190
	s_waitcnt lgkmcnt(8)
	v_mfma_f32_32x32x16_bf16 v[0:15], v[214:217], v[250:253], v[0:15]
	ds_read_b64_tr_b16 v[214:215], v205 offset:16640
	ds_read_b64_tr_b16 v[216:217], v205 offset:20736
	v_add_f32_e32 v254, v235, v254
	v_exp_f32_e32 v237, v237
	v_add_f32_e32 v254, v236, v254
	v_add_f32_e32 v254, v237, v254
	v_cvt_pk_bf16_f32 v242, v222, v223
	v_cvt_pk_bf16_f32 v243, v224, v225
	v_cvt_pk_bf16_f32 v244, v226, v227
	v_cvt_pk_bf16_f32 v245, v228, v229
	v_cvt_pk_bf16_f32 v250, v230, v231
	v_cvt_pk_bf16_f32 v251, v232, v233
	v_cvt_pk_bf16_f32 v252, v234, v235
	v_cvt_pk_bf16_f32 v253, v236, v237
	v_add_f32_e32 v195, v195, v254
	s_nop 1

.Latt_rs1_5F:
	s_waitcnt lgkmcnt(8)
	v_mfma_f32_32x32x16_bf16 v[32:47], v[214:217], v[242:245], v[32:47]
	ds_read_b64_tr_b16 v[214:215], v219 offset:8192
	ds_read_b64_tr_b16 v[216:217], v219 offset:12288
	s_waitcnt lgkmcnt(8)
	v_mfma_f32_32x32x16_bf16 v[16:31], v[238:241], v[242:245], v[16:31]
	ds_read_b64_tr_b16 v[238:239], v221 offset:8192
	ds_read_b64_tr_b16 v[240:241], v221 offset:12288
	s_waitcnt lgkmcnt(8)
	v_mfma_f32_32x32x16_bf16 v[0:15], v[206:209], v[242:245], v[0:15]
	ds_read_b64_tr_b16 v[206:207], v205 offset:8448
	ds_read_b64_tr_b16 v[208:209], v205 offset:12544
	s_waitcnt lgkmcnt(8)
	v_mfma_f32_32x32x16_bf16 v[112:127], v[210:213], v[250:253], v[112:127]
	ds_read_b64_tr_b16 v[210:211], v218 offset:8448
	ds_read_b64_tr_b16 v[212:213], v218 offset:12544
	s_waitcnt lgkmcnt(8)
	v_mfma_f32_32x32x16_bf16 v[96:111], v[128:131], v[250:253], v[96:111]
	ds_read_b64_tr_b16 v[128:129], v219 offset:8448
	ds_read_b64_tr_b16 v[130:131], v219 offset:12544
	s_waitcnt lgkmcnt(8)
	v_mfma_f32_32x32x16_bf16 v[80:95], v[214:217], v[250:253], v[80:95]
	ds_read_b64_tr_b16 v[214:215], v221 offset:8448
	ds_read_b64_tr_b16 v[216:217], v221 offset:12544
	s_waitcnt lgkmcnt(8)
	v_mfma_f32_32x32x16_bf16 v[64:79], v[238:241], v[250:253], v[64:79]
	ds_read_b64_tr_b16 v[238:239], v205 offset:16384
	ds_read_b64_tr_b16 v[240:241], v205 offset:20480
	s_waitcnt lgkmcnt(8)
	v_mfma_f32_32x32x16_bf16 v[48:63], v[206:209], v[250:253], v[48:63]
	ds_read_b64_tr_b16 v[206:207], v218 offset:16384
	ds_read_b64_tr_b16 v[208:209], v218 offset:20480
	s_waitcnt lgkmcnt(8)
	v_mfma_f32_32x32x16_bf16 v[32:47], v[210:213], v[250:253], v[32:47]
	ds_read_b64_tr_b16 v[210:211], v219 offset:16384
	ds_read_b64_tr_b16 v[212:213], v219 offset:20480
	s_waitcnt lgkmcnt(8)
	v_mfma_f32_32x32x16_bf16 v[16:31], v[128:131], v[250:253], v[16:31]
	ds_read_b64_tr_b16 v[128:129], v221 offset:16384
	ds_read_b64_tr_b16 v[130:131], v221 offset:20480
	s_waitcnt lgkmcnt(8)
	v_mfma_f32_32x32x16_bf16 v[0:15], v[214:217], v[250:253], v[0:15]
	ds_read_b64_tr_b16 v[214:215], v205 offset:16640
	ds_read_b64_tr_b16 v[216:217], v205 offset:20736
	s_nop 11
	v_max_f32_e32 v246, v190, v246
	v_sub_f32_e32 v190, v190, v246
	v_exp_f32_e32 v190, v190
	s_nop 0
	v_pk_mul_f32 v[126:127], v[126:127], v[190:191] op_sel_hi:[1,0]
	v_pk_mul_f32 v[124:125], v[124:125], v[190:191] op_sel_hi:[1,0]
	v_pk_mul_f32 v[122:123], v[122:123], v[190:191] op_sel_hi:[1,0]
	v_pk_mul_f32 v[120:121], v[120:121], v[190:191] op_sel_hi:[1,0]
	v_pk_mul_f32 v[118:119], v[118:119], v[190:191] op_sel_hi:[1,0]
	v_pk_mul_f32 v[116:117], v[116:117], v[190:191] op_sel_hi:[1,0]
	v_pk_mul_f32 v[114:115], v[114:115], v[190:191] op_sel_hi:[1,0]
	v_pk_mul_f32 v[112:113], v[112:113], v[190:191] op_sel_hi:[1,0]
	v_pk_mul_f32 v[110:111], v[110:111], v[190:191] op_sel_hi:[1,0]
	v_pk_mul_f32 v[108:109], v[108:109], v[190:191] op_sel_hi:[1,0]
	v_pk_mul_f32 v[106:107], v[106:107], v[190:191] op_sel_hi:[1,0]
	v_pk_mul_f32 v[104:105], v[104:105], v[190:191] op_sel_hi:[1,0]
	v_pk_mul_f32 v[102:103], v[102:103], v[190:191] op_sel_hi:[1,0]
	v_pk_mul_f32 v[100:101], v[100:101], v[190:191] op_sel_hi:[1,0]
	v_pk_mul_f32 v[98:99], v[98:99], v[190:191] op_sel_hi:[1,0]
	v_pk_mul_f32 v[96:97], v[96:97], v[190:191] op_sel_hi:[1,0]
	v_pk_mul_f32 v[94:95], v[94:95], v[190:191] op_sel_hi:[1,0]
	v_pk_mul_f32 v[92:93], v[92:93], v[190:191] op_sel_hi:[1,0]
	v_pk_mul_f32 v[90:91], v[90:91], v[190:191] op_sel_hi:[1,0]
	v_pk_mul_f32 v[88:89], v[88:89], v[190:191] op_sel_hi:[1,0]
	v_pk_mul_f32 v[86:87], v[86:87], v[190:191] op_sel_hi:[1,0]
	v_pk_mul_f32 v[84:85], v[84:85], v[190:191] op_sel_hi:[1,0]
	v_pk_mul_f32 v[82:83], v[82:83], v[190:191] op_sel_hi:[1,0]
	v_pk_mul_f32 v[80:81], v[80:81], v[190:191] op_sel_hi:[1,0]
	v_pk_mul_f32 v[78:79], v[78:79], v[190:191] op_sel_hi:[1,0]
	v_pk_mul_f32 v[76:77], v[76:77], v[190:191] op_sel_hi:[1,0]
	v_pk_mul_f32 v[74:75], v[74:75], v[190:191] op_sel_hi:[1,0]
	v_pk_mul_f32 v[72:73], v[72:73], v[190:191] op_sel_hi:[1,0]
	v_pk_mul_f32 v[70:71], v[70:71], v[190:191] op_sel_hi:[1,0]
	v_pk_mul_f32 v[68:69], v[68:69], v[190:191] op_sel_hi:[1,0]
	v_pk_mul_f32 v[66:67], v[66:67], v[190:191] op_sel_hi:[1,0]
	v_pk_mul_f32 v[64:65], v[64:65], v[190:191] op_sel_hi:[1,0]
	v_pk_mul_f32 v[62:63], v[62:63], v[190:191] op_sel_hi:[1,0]
	v_pk_mul_f32 v[60:61], v[60:61], v[190:191] op_sel_hi:[1,0]
	v_pk_mul_f32 v[58:59], v[58:59], v[190:191] op_sel_hi:[1,0]
	v_pk_mul_f32 v[56:57], v[56:57], v[190:191] op_sel_hi:[1,0]
	v_pk_mul_f32 v[54:55], v[54:55], v[190:191] op_sel_hi:[1,0]
	v_pk_mul_f32 v[52:53], v[52:53], v[190:191] op_sel_hi:[1,0]
	v_pk_mul_f32 v[50:51], v[50:51], v[190:191] op_sel_hi:[1,0]
	v_pk_mul_f32 v[48:49], v[48:49], v[190:191] op_sel_hi:[1,0]
	v_pk_mul_f32 v[46:47], v[46:47], v[190:191] op_sel_hi:[1,0]
	v_pk_mul_f32 v[44:45], v[44:45], v[190:191] op_sel_hi:[1,0]
	v_pk_mul_f32 v[42:43], v[42:43], v[190:191] op_sel_hi:[1,0]
	v_pk_mul_f32 v[40:41], v[40:41], v[190:191] op_sel_hi:[1,0]
	v_pk_mul_f32 v[38:39], v[38:39], v[190:191] op_sel_hi:[1,0]
	v_pk_mul_f32 v[36:37], v[36:37], v[190:191] op_sel_hi:[1,0]
	v_pk_mul_f32 v[34:35], v[34:35], v[190:191] op_sel_hi:[1,0]
	v_pk_mul_f32 v[32:33], v[32:33], v[190:191] op_sel_hi:[1,0]
	v_pk_mul_f32 v[30:31], v[30:31], v[190:191] op_sel_hi:[1,0]
	v_pk_mul_f32 v[28:29], v[28:29], v[190:191] op_sel_hi:[1,0]
	v_pk_mul_f32 v[26:27], v[26:27], v[190:191] op_sel_hi:[1,0]
	v_pk_mul_f32 v[24:25], v[24:25], v[190:191] op_sel_hi:[1,0]
	v_pk_mul_f32 v[22:23], v[22:23], v[190:191] op_sel_hi:[1,0]
	v_pk_mul_f32 v[20:21], v[20:21], v[190:191] op_sel_hi:[1,0]
	v_pk_mul_f32 v[18:19], v[18:19], v[190:191] op_sel_hi:[1,0]
	v_pk_mul_f32 v[16:17], v[16:17], v[190:191] op_sel_hi:[1,0]
	v_pk_mul_f32 v[14:15], v[14:15], v[190:191] op_sel_hi:[1,0]
	v_pk_mul_f32 v[12:13], v[12:13], v[190:191] op_sel_hi:[1,0]
	v_pk_mul_f32 v[10:11], v[10:11], v[190:191] op_sel_hi:[1,0]
	v_pk_mul_f32 v[8:9], v[8:9], v[190:191] op_sel_hi:[1,0]
	v_pk_mul_f32 v[6:7], v[6:7], v[190:191] op_sel_hi:[1,0]
	v_pk_mul_f32 v[4:5], v[4:5], v[190:191] op_sel_hi:[1,0]
	v_pk_mul_f32 v[2:3], v[2:3], v[190:191] op_sel_hi:[1,0]
	v_pk_mul_f32 v[0:1], v[0:1], v[190:191] op_sel_hi:[1,0]
	v_mul_f32_e32 v195, v195, v190
	v_mov_b32_e32 v190, v246
	v_sub_f32_e32 v222, v222, v190
	v_exp_f32_e32 v222, v222
	v_sub_f32_e32 v223, v223, v190
	v_exp_f32_e32 v223, v223
	v_sub_f32_e32 v224, v224, v190
	v_add_f32_e32 v254, 0, v222
	v_exp_f32_e32 v224, v224
	v_sub_f32_e32 v225, v225, v190
	v_add_f32_e32 v254, v223, v254
	v_exp_f32_e32 v225, v225
	v_sub_f32_e32 v226, v226, v190
	v_add_f32_e32 v254, v224, v254
	v_exp_f32_e32 v226, v226
	v_sub_f32_e32 v227, v227, v190
	v_add_f32_e32 v254, v225, v254
	v_exp_f32_e32 v227, v227
	v_sub_f32_e32 v228, v228, v190
	v_add_f32_e32 v254, v226, v254
	v_exp_f32_e32 v228, v228
	v_sub_f32_e32 v229, v229, v190
	v_add_f32_e32 v254, v227, v254
	v_exp_f32_e32 v229, v229
	v_sub_f32_e32 v230, v230, v190
	v_add_f32_e32 v254, v228, v254
	v_exp_f32_e32 v230, v230
	v_sub_f32_e32 v231, v231, v190
	v_add_f32_e32 v254, v229, v254
	v_exp_f32_e32 v231, v231
	v_sub_f32_e32 v232, v232, v190
	v_add_f32_e32 v254, v230, v254
	v_exp_f32_e32 v232, v232
	v_sub_f32_e32 v233, v233, v190
	v_add_f32_e32 v254, v231, v254
	v_exp_f32_e32 v233, v233
	v_sub_f32_e32 v234, v234, v190
	v_add_f32_e32 v254, v232, v254
	v_exp_f32_e32 v234, v234
	v_sub_f32_e32 v235, v235, v190
	v_add_f32_e32 v254, v233, v254
	v_exp_f32_e32 v235, v235
	v_sub_f32_e32 v236, v236, v190
	v_add_f32_e32 v254, v234, v254
	v_exp_f32_e32 v236, v236
	v_sub_f32_e32 v237, v237, v190
	v_add_f32_e32 v254, v235, v254
	v_exp_f32_e32 v237, v237
	v_add_f32_e32 v254, v236, v254
	v_add_f32_e32 v254, v237, v254
	v_cvt_pk_bf16_f32 v242, v222, v223
	v_cvt_pk_bf16_f32 v243, v224, v225
	v_cvt_pk_bf16_f32 v244, v226, v227
	v_cvt_pk_bf16_f32 v245, v228, v229
	v_cvt_pk_bf16_f32 v250, v230, v231
	v_cvt_pk_bf16_f32 v251, v232, v233
	v_cvt_pk_bf16_f32 v252, v234, v235
	v_cvt_pk_bf16_f32 v253, v236, v237
	v_add_f32_e32 v195, v195, v254
	s_nop 1
	s_branch .Latt_pv1_5F
	s_lshl_b32 s77, s33, 14
	s_add_i32 s78, s77, 0
	v_add_u32_e32 v207, s78, v196
	ds_read_b128 v[128:131], v207
	v_add_u32_e32 v208, s78, v197
	ds_read_b128 v[210:213], v208
	v_add_u32_e32 v209, s78, v198
	v_lshrrev_b32_e32 v205, 3, v204
	s_add_i32 s79, s4, 31
	v_and_or_b32 v206, v204, 31, s71
	s_cmp_le_i32 s79, s71
	s_waitcnt lgkmcnt(1)
	v_mfma_f32_32x32x16_bf16 v[128:143], v[128:131], v[144:147], 0
	s_waitcnt lgkmcnt(0)
	v_mfma_f32_32x32x16_bf16 v[128:143], v[210:213], v[148:151], v[128:143]
	ds_read_b128 v[212:215], v209
	v_add_u32_e32 v210, s78, v199
	ds_read_b128 v[216:219], v210
	v_add_u32_e32 v211, s78, v200
	s_waitcnt lgkmcnt(1)
	v_mfma_f32_32x32x16_bf16 v[128:143], v[212:215], v[152:155], v[128:143]
	v_add_u32_e32 v213, s78, v201
	v_and_b32_e32 v212, 4, v205
	ds_read_b128 v[222:225], v213
	s_waitcnt lgkmcnt(1)
	v_mfma_f32_32x32x16_bf16 v[128:143], v[216:219], v[156:159], v[128:143]
	ds_read_b128 v[214:217], v211
	s_waitcnt lgkmcnt(0)
	v_mfma_f32_32x32x16_bf16 v[128:143], v[214:217], v[160:163], v[128:143]
	v_add_u32_e32 v214, s78, v202
	ds_read_b128 v[216:219], v214
	v_add_u32_e32 v215, s78, v203
	v_mfma_f32_32x32x16_bf16 v[128:143], v[222:225], v[164:167], v[128:143]
	ds_read_b128 v[222:225], v215
	s_waitcnt lgkmcnt(1)
	v_mfma_f32_32x32x16_bf16 v[128:143], v[216:219], v[168:171], v[128:143]
	s_waitcnt lgkmcnt(0)
	v_mfma_f32_32x32x16_bf16 v[128:143], v[222:225], v[172:175], v[128:143]
	s_cbranch_scc1 .LBB0_1823
	v_add_u32_e32 v205, s4, v212
	v_cmp_lt_i32_e32 vcc, v205, v206
	v_add_u32_e32 v216, 2, v205
	s_nop 7
	v_cndmask_b32_e32 v129, v192, v129, vcc
	v_cmp_le_i32_e32 vcc, v205, v206
	s_nop 1
	v_cndmask_b32_e32 v128, v192, v128, vcc
	v_cmp_le_i32_e32 vcc, v216, v206
	v_add_u32_e32 v216, 3, v205
	s_nop 0
	v_cndmask_b32_e32 v130, v192, v130, vcc
	v_cmp_le_i32_e32 vcc, v216, v206
	v_add_u32_e32 v216, 8, v205
	s_nop 0
	v_cndmask_b32_e32 v131, v192, v131, vcc
	v_cmp_le_i32_e32 vcc, v216, v206
	v_add_u32_e32 v216, 9, v205
	s_nop 0
	v_cndmask_b32_e32 v132, v192, v132, vcc
	v_cmp_le_i32_e32 vcc, v216, v206
	v_add_u32_e32 v216, 10, v205
	s_nop 0
	v_cndmask_b32_e32 v133, v192, v133, vcc
	v_cmp_le_i32_e32 vcc, v216, v206
	v_add_u32_e32 v216, 11, v205
	s_nop 0
	v_cndmask_b32_e32 v134, v192, v134, vcc
	v_cmp_le_i32_e32 vcc, v216, v206
	v_add_u32_e32 v216, 16, v205
	s_nop 0
	v_cndmask_b32_e32 v135, v192, v135, vcc
	v_cmp_le_i32_e32 vcc, v216, v206
	v_add_u32_e32 v216, 17, v205
	s_nop 0
	v_cndmask_b32_e32 v136, v192, v136, vcc
	v_cmp_le_i32_e32 vcc, v216, v206
	v_add_u32_e32 v216, 18, v205
	s_nop 0
	v_cndmask_b32_e32 v137, v192, v137, vcc
	v_cmp_le_i32_e32 vcc, v216, v206
	v_add_u32_e32 v216, 19, v205
	s_nop 0
	v_cndmask_b32_e32 v138, v192, v138, vcc
	v_cmp_le_i32_e32 vcc, v216, v206
	v_add_u32_e32 v216, 24, v205
	s_nop 0
	v_cndmask_b32_e32 v139, v192, v139, vcc
	v_cmp_le_i32_e32 vcc, v216, v206
	v_add_u32_e32 v216, 25, v205
	s_nop 0
	v_cndmask_b32_e32 v140, v192, v140, vcc
	v_cmp_le_i32_e32 vcc, v216, v206
	v_add_u32_e32 v216, 26, v205
	v_add_u32_e32 v205, 27, v205
	v_cndmask_b32_e32 v141, v192, v141, vcc
	v_cmp_le_i32_e32 vcc, v216, v206
	s_nop 1
	v_cndmask_b32_e32 v142, v192, v142, vcc
	v_cmp_le_i32_e32 vcc, v205, v206
	s_nop 1
	v_cndmask_b32_e32 v143, v192, v143, vcc

.LBB0_1837:
	s_cmp_ge_u32 s73, s66
	s_cselect_b64 s[12:13], -1, 0
	v_mov_b32_e32 v204, v176
	s_and_b64 vcc, exec, s[12:13]
	s_cbranch_vccnz .LBB0_1839
	s_cmp_le_i32 s72, s69
	s_cbranch_scc1 .LBB0_1839
	v_sub_co_u32_e64 v128, s[14:15], s34, 1
	s_nop 1
	v_cndmask_b32_e64 v130, v128, 2, s[14:15]
	v_lshlrev_b32_e32 v128, 14, v130
	v_add_u32_e32 v131, s36, v128
	v_lshl_add_u64 v[128:129], s[20:21], 0, v[178:179]
	s_add_u32 s14, s20, 0x1000
	v_readfirstlane_b32 s35, v131
	s_mov_b32 s40, m0
	s_mov_b32 m0, s35
	s_nop 0
	global_load_lds_dwordx4 v[128:129], off
	s_mov_b32 m0, s40
	v_lshl_add_u64 v[128:129], s[20:21], 0, v[180:181]
	s_addc_u32 s15, s21, 0
	s_addk_i32 s35, 0x400
	s_mov_b32 s40, m0
	s_mov_b32 m0, s35
	s_nop 0
	global_load_lds_dwordx4 v[128:129], off
	s_mov_b32 m0, s40
	v_lshlrev_b32_e32 v128, 15, v130
	v_add_u32_e32 v130, s37, v128
	v_lshl_add_u64 v[128:129], s[14:15], 0, v[182:183]
	v_readfirstlane_b32 s35, v130
	s_mov_b32 s40, m0
	s_mov_b32 m0, s35
	s_nop 0
	global_load_lds_dwordx4 v[128:129], off
	s_mov_b32 m0, s40
	v_lshl_add_u64 v[128:129], s[14:15], 0, v[184:185]
	s_add_i32 s40, s35, 0x400
	s_mov_b32 s41, m0
	s_mov_b32 m0, s40
	s_nop 0
	global_load_lds_dwordx4 v[128:129], off
	s_mov_b32 m0, s41
	v_lshl_add_u64 v[128:129], s[14:15], 0, v[186:187]
	s_add_i32 s40, s35, 0x800
	s_mov_b32 s41, m0
	s_mov_b32 m0, s40
	s_nop 0
	global_load_lds_dwordx4 v[128:129], off
	s_mov_b32 m0, s41
	v_lshl_add_u64 v[128:129], s[14:15], 0, v[188:189]
	s_add_i32 s14, s35, 0xc00
	s_mov_b32 s15, m0
	s_mov_b32 m0, s14
	s_nop 0
	global_load_lds_dwordx4 v[128:129], off
	s_mov_b32 m0, s15
.LBB0_1839:
	s_cmp_gt_i32 s72, s69
	s_cbranch_scc1 .LBB0_1850
	s_add_i32 s100, s72, 63
	s_cmp_le_i32 s100, s68
	s_cbranch_scc1 .Latt_full_6
	s_add_i32 s100, s72, 32
	s_cmp_le_i32 s100, s69
	s_cbranch_scc1 .Latt_diagA_6
	s_lshl_b32 s98, s34, 14
	s_lshl_b32 s99, s34, 15
	s_add_i32 s99, s99, 0xc000
	v_add_u32_e32 v206, s98, v195
	ds_read_b128 v[206:209], v206
	v_add_u32_e32 v210, s98, v196
	ds_read_b128 v[210:213], v210
	v_add_u32_e32 v214, s98, v197
	ds_read_b128 v[214:217], v214
	v_add_u32_e32 v238, s98, v198
	ds_read_b128 v[238:241], v238
	v_add_u32_e32 v242, s98, v199
	ds_read_b128 v[242:245], v242
	v_add_u32_e32 v250, s98, v200
	ds_read_b128 v[250:253], v250
	v_add_u32_e32 v222, s98, v201
	ds_read_b128 v[222:225], v222
	v_add_u32_e32 v226, s98, v202
	ds_read_b128 v[226:229], v226
	v_bfe_u32 v246, v204, 2, 2
	v_bfe_u32 v247, v204, 5, 1
	v_lshl_or_b32 v247, v247, 2, v246
	v_and_b32_e32 v249, 3, v204
	v_and_b32_e32 v254, 16, v204
	v_lshl_or_b32 v249, v249, 2, v254
	v_lshlrev_b32_e32 v249, 1, v249
	v_lshl_add_u32 v247, v247, 9, v249
	v_add_u32_e32 v247, s99, v247
	v_lshlrev_b32_e32 v246, 6, v246
	v_add_u32_e32 v205, v247, v246
	v_xor_b32_e32 v249, 64, v246
	v_add_u32_e32 v218, v247, v249
	v_xor_b32_e32 v249, 0x80, v246
	v_add_u32_e32 v219, v247, v249
	v_xor_b32_e32 v249, 0xc0, v246
	v_add_u32_e32 v221, v247, v249
	s_waitcnt lgkmcnt(7)
	v_mfma_f32_32x32x16_bf16 v[128:143], v[206:209], v[144:147], 0
	ds_read_b64_tr_b16 v[206:207], v205
	ds_read_b64_tr_b16 v[208:209], v205 offset:4096
	s_waitcnt lgkmcnt(8)
	v_mfma_f32_32x32x16_bf16 v[128:143], v[210:213], v[148:151], v[128:143]
	ds_read_b64_tr_b16 v[210:211], v218
	ds_read_b64_tr_b16 v[212:213], v218 offset:4096
	s_waitcnt lgkmcnt(9)
	v_mfma_f32_32x32x16_bf16 v[128:143], v[214:217], v[152:155], v[128:143]
	s_waitcnt lgkmcnt(8)
	v_mfma_f32_32x32x16_bf16 v[128:143], v[238:241], v[156:159], v[128:143]
	ds_read_b64_tr_b16 v[214:215], v219
	ds_read_b64_tr_b16 v[216:217], v219 offset:4096
	s_waitcnt lgkmcnt(9)
	v_mfma_f32_32x32x16_bf16 v[128:143], v[242:245], v[160:163], v[128:143]
	s_waitcnt lgkmcnt(8)
	v_mfma_f32_32x32x16_bf16 v[128:143], v[250:253], v[164:167], v[128:143]
	ds_read_b64_tr_b16 v[238:239], v221
	ds_read_b64_tr_b16 v[240:241], v221 offset:4096
	s_waitcnt lgkmcnt(9)
	v_mfma_f32_32x32x16_bf16 v[128:143], v[222:225], v[168:171], v[128:143]
	s_waitcnt lgkmcnt(8)
	v_mfma_f32_32x32x16_bf16 v[128:143], v[226:229], v[172:175], v[128:143]
	s_nop 11
	v_and_or_b32 v246, v204, 31, s68
	v_bfe_u32 v247, v204, 5, 1
	s_add_i32 s100, s72, 0
	v_lshl_add_u32 v247, v247, 2, s100
	v_add_u32_e32 v249, 0, v247
	v_cmp_le_i32_e32 vcc, v249, v246
	v_add_u32_e32 v254, 1, v247
	s_nop 0
	v_cndmask_b32_e32 v128, v192, v128, vcc
	v_cmp_le_i32_e32 vcc, v254, v246
	v_add_u32_e32 v249, 2, v247
	s_nop 0
	v_cndmask_b32_e32 v129, v192, v129, vcc
	v_cmp_le_i32_e32 vcc, v249, v246
	v_add_u32_e32 v254, 3, v247
	s_nop 0
	v_cndmask_b32_e32 v130, v192, v130, vcc
	v_cmp_le_i32_e32 vcc, v254, v246
	v_add_u32_e32 v249, 8, v247
	s_nop 0
	v_cndmask_b32_e32 v131, v192, v131, vcc
	v_cmp_le_i32_e32 vcc, v249, v246
	v_add_u32_e32 v254, 9, v247
	s_nop 0
	v_cndmask_b32_e32 v132, v192, v132, vcc
	v_cmp_le_i32_e32 vcc, v254, v246
	v_add_u32_e32 v249, 10, v247
	s_nop 0
	v_cndmask_b32_e32 v133, v192, v133, vcc
	v_cmp_le_i32_e32 vcc, v249, v246
	v_add_u32_e32 v254, 11, v247
	s_nop 0
	v_cndmask_b32_e32 v134, v192, v134, vcc
	v_cmp_le_i32_e32 vcc, v254, v246
	v_add_u32_e32 v249, 16, v247
	s_nop 0
	v_cndmask_b32_e32 v135, v192, v135, vcc
	v_cmp_le_i32_e32 vcc, v249, v246
	v_add_u32_e32 v254, 17, v247
	s_nop 0
	v_cndmask_b32_e32 v136, v192, v136, vcc
	v_cmp_le_i32_e32 vcc, v254, v246
	v_add_u32_e32 v249, 18, v247
	s_nop 0
	v_cndmask_b32_e32 v137, v192, v137, vcc
	v_cmp_le_i32_e32 vcc, v249, v246
	v_add_u32_e32 v254, 19, v247
	s_nop 0
	v_cndmask_b32_e32 v138, v192, v138, vcc
	v_cmp_le_i32_e32 vcc, v254, v246
	v_add_u32_e32 v249, 24, v247
	s_nop 0
	v_cndmask_b32_e32 v139, v192, v139, vcc
	v_cmp_le_i32_e32 vcc, v249, v246
	v_add_u32_e32 v254, 25, v247
	s_nop 0
	v_cndmask_b32_e32 v140, v192, v140, vcc
	v_cmp_le_i32_e32 vcc, v254, v246
	v_add_u32_e32 v249, 26, v247
	s_nop 0
	v_cndmask_b32_e32 v141, v192, v141, vcc
	v_cmp_le_i32_e32 vcc, v249, v246
	v_add_u32_e32 v254, 27, v247
	s_nop 0
	v_cndmask_b32_e32 v142, v192, v142, vcc
	v_cmp_le_i32_e32 vcc, v254, v246
	s_nop 1
	v_cndmask_b32_e32 v143, v192, v143, vcc
	v_max3_f32 v246, v128, v129, v130
	v_max3_f32 v247, v131, v132, v133
	v_max3_f32 v246, v246, v134, v135
	v_max3_f32 v247, v247, v136, v137
	v_max3_f32 v246, v246, v138, v139
	v_max3_f32 v247, v247, v140, v141
	v_max3_f32 v246, v246, v142, v143
	v_max_f32_e32 v246, v246, v247
	v_mov_b32_e32 v247, v246
	v_add_f32_e32 v249, 0x41000000, v190
	s_nop 1
	v_permlane32_swap_b32_e32 v246, v247
	v_max_f32_e32 v246, v246, v247
	v_cmp_gt_f32_e32 vcc, v246, v249
	s_cbranch_vccz .Latt_nr0_6B
	v_max_f32_e32 v246, v190, v246
	v_sub_f32_e32 v190, v190, v246
	v_exp_f32_e32 v190, v190
	s_nop 0
	v_pk_mul_f32 v[126:127], v[126:127], v[190:191] op_sel_hi:[1,0]
	v_pk_mul_f32 v[124:125], v[124:125], v[190:191] op_sel_hi:[1,0]
	v_pk_mul_f32 v[122:123], v[122:123], v[190:191] op_sel_hi:[1,0]
	v_pk_mul_f32 v[120:121], v[120:121], v[190:191] op_sel_hi:[1,0]
	v_pk_mul_f32 v[118:119], v[118:119], v[190:191] op_sel_hi:[1,0]
	v_pk_mul_f32 v[116:117], v[116:117], v[190:191] op_sel_hi:[1,0]
	v_pk_mul_f32 v[114:115], v[114:115], v[190:191] op_sel_hi:[1,0]
	v_pk_mul_f32 v[112:113], v[112:113], v[190:191] op_sel_hi:[1,0]
	v_pk_mul_f32 v[110:111], v[110:111], v[190:191] op_sel_hi:[1,0]
	v_pk_mul_f32 v[108:109], v[108:109], v[190:191] op_sel_hi:[1,0]
	v_pk_mul_f32 v[106:107], v[106:107], v[190:191] op_sel_hi:[1,0]
	v_pk_mul_f32 v[104:105], v[104:105], v[190:191] op_sel_hi:[1,0]
	v_pk_mul_f32 v[102:103], v[102:103], v[190:191] op_sel_hi:[1,0]
	v_pk_mul_f32 v[100:101], v[100:101], v[190:191] op_sel_hi:[1,0]
	v_pk_mul_f32 v[98:99], v[98:99], v[190:191] op_sel_hi:[1,0]
	v_pk_mul_f32 v[96:97], v[96:97], v[190:191] op_sel_hi:[1,0]
	v_pk_mul_f32 v[94:95], v[94:95], v[190:191] op_sel_hi:[1,0]
	v_pk_mul_f32 v[92:93], v[92:93], v[190:191] op_sel_hi:[1,0]
	v_pk_mul_f32 v[90:91], v[90:91], v[190:191] op_sel_hi:[1,0]
	v_pk_mul_f32 v[88:89], v[88:89], v[190:191] op_sel_hi:[1,0]
	v_pk_mul_f32 v[86:87], v[86:87], v[190:191] op_sel_hi:[1,0]
	v_pk_mul_f32 v[84:85], v[84:85], v[190:191] op_sel_hi:[1,0]
	v_pk_mul_f32 v[82:83], v[82:83], v[190:191] op_sel_hi:[1,0]
	v_pk_mul_f32 v[80:81], v[80:81], v[190:191] op_sel_hi:[1,0]
	v_pk_mul_f32 v[78:79], v[78:79], v[190:191] op_sel_hi:[1,0]
	v_pk_mul_f32 v[76:77], v[76:77], v[190:191] op_sel_hi:[1,0]
	v_pk_mul_f32 v[74:75], v[74:75], v[190:191] op_sel_hi:[1,0]
	v_pk_mul_f32 v[72:73], v[72:73], v[190:191] op_sel_hi:[1,0]
	v_pk_mul_f32 v[70:71], v[70:71], v[190:191] op_sel_hi:[1,0]
	v_pk_mul_f32 v[68:69], v[68:69], v[190:191] op_sel_hi:[1,0]
	v_pk_mul_f32 v[66:67], v[66:67], v[190:191] op_sel_hi:[1,0]
	v_pk_mul_f32 v[64:65], v[64:65], v[190:191] op_sel_hi:[1,0]
	v_pk_mul_f32 v[62:63], v[62:63], v[190:191] op_sel_hi:[1,0]
	v_pk_mul_f32 v[60:61], v[60:61], v[190:191] op_sel_hi:[1,0]
	v_pk_mul_f32 v[58:59], v[58:59], v[190:191] op_sel_hi:[1,0]
	v_pk_mul_f32 v[56:57], v[56:57], v[190:191] op_sel_hi:[1,0]
	v_pk_mul_f32 v[54:55], v[54:55], v[190:191] op_sel_hi:[1,0]
	v_pk_mul_f32 v[52:53], v[52:53], v[190:191] op_sel_hi:[1,0]
	v_pk_mul_f32 v[50:51], v[50:51], v[190:191] op_sel_hi:[1,0]
	v_pk_mul_f32 v[48:49], v[48:49], v[190:191] op_sel_hi:[1,0]
	v_pk_mul_f32 v[46:47], v[46:47], v[190:191] op_sel_hi:[1,0]
	v_pk_mul_f32 v[44:45], v[44:45], v[190:191] op_sel_hi:[1,0]
	v_pk_mul_f32 v[42:43], v[42:43], v[190:191] op_sel_hi:[1,0]
	v_pk_mul_f32 v[40:41], v[40:41], v[190:191] op_sel_hi:[1,0]
	v_pk_mul_f32 v[38:39], v[38:39], v[190:191] op_sel_hi:[1,0]
	v_pk_mul_f32 v[36:37], v[36:37], v[190:191] op_sel_hi:[1,0]
	v_pk_mul_f32 v[34:35], v[34:35], v[190:191] op_sel_hi:[1,0]
	v_pk_mul_f32 v[32:33], v[32:33], v[190:191] op_sel_hi:[1,0]
	v_pk_mul_f32 v[30:31], v[30:31], v[190:191] op_sel_hi:[1,0]
	v_pk_mul_f32 v[28:29], v[28:29], v[190:191] op_sel_hi:[1,0]
	v_pk_mul_f32 v[26:27], v[26:27], v[190:191] op_sel_hi:[1,0]
	v_pk_mul_f32 v[24:25], v[24:25], v[190:191] op_sel_hi:[1,0]
	v_pk_mul_f32 v[22:23], v[22:23], v[190:191] op_sel_hi:[1,0]
	v_pk_mul_f32 v[20:21], v[20:21], v[190:191] op_sel_hi:[1,0]
	v_pk_mul_f32 v[18:19], v[18:19], v[190:191] op_sel_hi:[1,0]
	v_pk_mul_f32 v[16:17], v[16:17], v[190:191] op_sel_hi:[1,0]
	v_pk_mul_f32 v[14:15], v[14:15], v[190:191] op_sel_hi:[1,0]
	v_pk_mul_f32 v[12:13], v[12:13], v[190:191] op_sel_hi:[1,0]
	v_pk_mul_f32 v[10:11], v[10:11], v[190:191] op_sel_hi:[1,0]
	v_pk_mul_f32 v[8:9], v[8:9], v[190:191] op_sel_hi:[1,0]
	v_pk_mul_f32 v[6:7], v[6:7], v[190:191] op_sel_hi:[1,0]
	v_pk_mul_f32 v[4:5], v[4:5], v[190:191] op_sel_hi:[1,0]
	v_pk_mul_f32 v[2:3], v[2:3], v[190:191] op_sel_hi:[1,0]
	v_pk_mul_f32 v[0:1], v[0:1], v[190:191] op_sel_hi:[1,0]
	v_mul_f32_e32 v203, v203, v190
	v_mov_b32_e32 v190, v246
.Latt_nr0_6B:
	v_sub_f32_e32 v128, v128, v190
	v_exp_f32_e32 v128, v128
	v_sub_f32_e32 v129, v129, v190
	v_exp_f32_e32 v129, v129
	v_sub_f32_e32 v130, v130, v190
	v_add_f32_e32 v254, 0, v128
	v_exp_f32_e32 v130, v130
	v_sub_f32_e32 v131, v131, v190
	v_add_f32_e32 v254, v129, v254
	v_exp_f32_e32 v131, v131
	v_sub_f32_e32 v132, v132, v190
	v_add_f32_e32 v254, v130, v254
	v_exp_f32_e32 v132, v132
	v_sub_f32_e32 v133, v133, v190
	v_add_f32_e32 v254, v131, v254
	v_exp_f32_e32 v133, v133
	v_sub_f32_e32 v134, v134, v190
	v_add_f32_e32 v254, v132, v254
	v_exp_f32_e32 v134, v134
	v_sub_f32_e32 v135, v135, v190
	v_add_f32_e32 v254, v133, v254
	v_exp_f32_e32 v135, v135
	v_sub_f32_e32 v136, v136, v190
	v_add_f32_e32 v254, v134, v254
	v_exp_f32_e32 v136, v136
	v_sub_f32_e32 v137, v137, v190
	v_add_f32_e32 v254, v135, v254
	v_exp_f32_e32 v137, v137
	v_sub_f32_e32 v138, v138, v190
	v_add_f32_e32 v254, v136, v254
	v_exp_f32_e32 v138, v138
	v_sub_f32_e32 v139, v139, v190
	v_add_f32_e32 v254, v137, v254
	v_exp_f32_e32 v139, v139
	v_sub_f32_e32 v140, v140, v190
	v_add_f32_e32 v254, v138, v254
	v_exp_f32_e32 v140, v140
	v_sub_f32_e32 v141, v141, v190
	v_add_f32_e32 v254, v139, v254
	v_exp_f32_e32 v141, v141
	v_sub_f32_e32 v142, v142, v190
	v_add_f32_e32 v254, v140, v254
	v_exp_f32_e32 v142, v142
	v_sub_f32_e32 v143, v143, v190
	v_add_f32_e32 v254, v141, v254
	v_exp_f32_e32 v143, v143
	v_add_f32_e32 v254, v142, v254
	v_add_f32_e32 v254, v143, v254
	v_cvt_pk_bf16_f32 v242, v128, v129
	v_cvt_pk_bf16_f32 v243, v130, v131
	v_cvt_pk_bf16_f32 v244, v132, v133
	v_cvt_pk_bf16_f32 v245, v134, v135
	v_cvt_pk_bf16_f32 v250, v136, v137
	v_cvt_pk_bf16_f32 v251, v138, v139
	v_cvt_pk_bf16_f32 v252, v140, v141
	v_cvt_pk_bf16_f32 v253, v142, v143
	v_add_f32_e32 v203, v203, v254
	s_nop 1
	ds_read_b64_tr_b16 v[128:129], v205 offset:256
	ds_read_b64_tr_b16 v[130:131], v205 offset:4352
	s_waitcnt lgkmcnt(8)
	v_mfma_f32_32x32x16_bf16 v[112:127], v[206:209], v[242:245], v[112:127]
	ds_read_b64_tr_b16 v[206:207], v218 offset:256
	ds_read_b64_tr_b16 v[208:209], v218 offset:4352
	s_waitcnt lgkmcnt(8)
	v_mfma_f32_32x32x16_bf16 v[96:111], v[210:213], v[242:245], v[96:111]
	ds_read_b64_tr_b16 v[210:211], v219 offset:256
	ds_read_b64_tr_b16 v[212:213], v219 offset:4352
	s_cmp_lg_u64 s[12:13], 0
	s_cbranch_scc1 .Latt_nd0_6B
	s_sub_i32 s100, s34, 1
	s_cmp_eq_u32 s34, 0
	s_cselect_b32 s100, 2, s100
	s_lshl_b32 s101, s100, 14
	s_add_i32 m0, s36, s101
	s_nop 0
	global_load_lds_dwordx4 v178, s[20:21]
.Latt_nd0_6B:
	s_waitcnt lgkmcnt(8)
	v_mfma_f32_32x32x16_bf16 v[80:95], v[214:217], v[242:245], v[80:95]
	ds_read_b64_tr_b16 v[214:215], v221 offset:256
	ds_read_b64_tr_b16 v[216:217], v221 offset:4352
	s_waitcnt lgkmcnt(8)
	v_mfma_f32_32x32x16_bf16 v[64:79], v[238:241], v[242:245], v[64:79]
	ds_read_b64_tr_b16 v[238:239], v205 offset:8192
	ds_read_b64_tr_b16 v[240:241], v205 offset:12288
	s_cmp_lg_u64 s[12:13], 0
	s_cbranch_scc1 .Latt_nd1_6B
	s_add_i32 m0, m0, 0x400
	s_nop 0
	global_load_lds_dwordx4 v180, s[20:21]
.Latt_nd1_6B:
	s_waitcnt lgkmcnt(8)
	v_mfma_f32_32x32x16_bf16 v[48:63], v[128:131], v[242:245], v[48:63]
	ds_read_b64_tr_b16 v[128:129], v218 offset:8192
	ds_read_b64_tr_b16 v[130:131], v218 offset:12288
	s_waitcnt lgkmcnt(8)
	v_mfma_f32_32x32x16_bf16 v[32:47], v[206:209], v[242:245], v[32:47]
	ds_read_b64_tr_b16 v[206:207], v219 offset:8192
	ds_read_b64_tr_b16 v[208:209], v219 offset:12288
	s_cmp_lg_u64 s[12:13], 0
	s_cbranch_scc1 .Latt_nd2_6B
	s_lshl_b32 s101, s100, 15
	s_add_i32 m0, s37, s101
	s_add_u32 s100, s20, 0x1000
	s_addc_u32 s101, s21, 0
	global_load_lds_dwordx4 v182, s[100:101]

.Latt_diagA_6:
	s_lshl_b32 s98, s34, 14
	s_lshl_b32 s99, s34, 15
	s_add_i32 s99, s99, 0xc000
	v_add_u32_e32 v206, s98, v195
	ds_read_b128 v[206:209], v206
	v_add_u32_e32 v210, s98, v196
	ds_read_b128 v[210:213], v210
	v_add_u32_e32 v214, s98, v197
	ds_read_b128 v[214:217], v214
	v_add_u32_e32 v238, s98, v198
	ds_read_b128 v[238:241], v238
	v_add_u32_e32 v242, s98, v199
	ds_read_b128 v[242:245], v242
	v_add_u32_e32 v250, s98, v200
	ds_read_b128 v[250:253], v250
	v_add_u32_e32 v222, s98, v201
	ds_read_b128 v[222:225], v222
	v_add_u32_e32 v226, s98, v202
	ds_read_b128 v[226:229], v226
	v_bfe_u32 v246, v204, 2, 2
	v_bfe_u32 v247, v204, 5, 1
	v_lshl_or_b32 v247, v247, 2, v246
	v_and_b32_e32 v249, 3, v204
	v_and_b32_e32 v254, 16, v204
	v_lshl_or_b32 v249, v249, 2, v254
	v_lshlrev_b32_e32 v249, 1, v249
	v_lshl_add_u32 v247, v247, 9, v249
	v_add_u32_e32 v247, s99, v247
	v_lshlrev_b32_e32 v246, 6, v246
	v_add_u32_e32 v205, v247, v246
	v_xor_b32_e32 v249, 64, v246
	v_add_u32_e32 v218, v247, v249
	v_xor_b32_e32 v249, 0x80, v246
	v_add_u32_e32 v219, v247, v249
	v_xor_b32_e32 v249, 0xc0, v246
	v_add_u32_e32 v221, v247, v249
	s_waitcnt lgkmcnt(7)
	v_mfma_f32_32x32x16_bf16 v[128:143], v[206:209], v[144:147], 0
	v_add_u32_e32 v206, s98, v195
	ds_read_b128 v[206:209], v206 offset:8192
	s_waitcnt lgkmcnt(7)
	v_mfma_f32_32x32x16_bf16 v[128:143], v[210:213], v[148:151], v[128:143]
	v_add_u32_e32 v210, s98, v196
	ds_read_b128 v[210:213], v210 offset:8192
	s_waitcnt lgkmcnt(7)
	v_mfma_f32_32x32x16_bf16 v[128:143], v[214:217], v[152:155], v[128:143]
	v_add_u32_e32 v214, s98, v197
	ds_read_b128 v[214:217], v214 offset:8192
	s_waitcnt lgkmcnt(7)
	v_mfma_f32_32x32x16_bf16 v[128:143], v[238:241], v[156:159], v[128:143]
	v_add_u32_e32 v238, s98, v198
	ds_read_b128 v[238:241], v238 offset:8192
	s_waitcnt lgkmcnt(7)
	v_mfma_f32_32x32x16_bf16 v[128:143], v[242:245], v[160:163], v[128:143]
	v_add_u32_e32 v242, s98, v199
	ds_read_b128 v[242:245], v242 offset:8192
	s_waitcnt lgkmcnt(7)
	v_mfma_f32_32x32x16_bf16 v[128:143], v[250:253], v[164:167], v[128:143]
	v_add_u32_e32 v250, s98, v200
	ds_read_b128 v[250:253], v250 offset:8192
	s_waitcnt lgkmcnt(7)
	v_mfma_f32_32x32x16_bf16 v[128:143], v[222:225], v[168:171], v[128:143]
	s_waitcnt lgkmcnt(6)
	v_mfma_f32_32x32x16_bf16 v[128:143], v[226:229], v[172:175], v[128:143]
	s_waitcnt lgkmcnt(5)
	v_mfma_f32_32x32x16_bf16 v[222:237], v[206:209], v[144:147], 0
	v_add_u32_e32 v206, s98, v201
	ds_read_b128 v[206:209], v206 offset:8192
	s_nop 7
	v_max3_f32 v246, v128, v129, v130
	v_max3_f32 v247, v131, v132, v133
	v_max3_f32 v246, v246, v134, v135
	v_max3_f32 v247, v247, v136, v137
	v_max3_f32 v246, v246, v138, v139
	v_max3_f32 v247, v247, v140, v141
	v_max3_f32 v246, v246, v142, v143
	s_waitcnt lgkmcnt(5)
	v_mfma_f32_32x32x16_bf16 v[222:237], v[210:213], v[148:151], v[222:237]
	v_add_u32_e32 v210, s98, v202
	ds_read_b128 v[210:213], v210 offset:8192
	v_max_f32_e32 v246, v246, v247
	v_mov_b32_e32 v247, v246
	v_add_f32_e32 v249, 0x41000000, v190
	s_nop 1
	v_permlane32_swap_b32_e32 v246, v247
	v_max_f32_e32 v246, v246, v247
	v_cmp_gt_f32_e32 vcc, v246, v249
	s_cbranch_vccz .Latt_nr0_6A
	v_max_f32_e32 v246, v190, v246
	v_sub_f32_e32 v190, v190, v246
	v_exp_f32_e32 v190, v190
	s_nop 0
	v_pk_mul_f32 v[126:127], v[126:127], v[190:191] op_sel_hi:[1,0]
	v_pk_mul_f32 v[124:125], v[124:125], v[190:191] op_sel_hi:[1,0]
	v_pk_mul_f32 v[122:123], v[122:123], v[190:191] op_sel_hi:[1,0]
	v_pk_mul_f32 v[120:121], v[120:121], v[190:191] op_sel_hi:[1,0]
	v_pk_mul_f32 v[118:119], v[118:119], v[190:191] op_sel_hi:[1,0]
	v_pk_mul_f32 v[116:117], v[116:117], v[190:191] op_sel_hi:[1,0]
	v_pk_mul_f32 v[114:115], v[114:115], v[190:191] op_sel_hi:[1,0]
	v_pk_mul_f32 v[112:113], v[112:113], v[190:191] op_sel_hi:[1,0]
	v_pk_mul_f32 v[110:111], v[110:111], v[190:191] op_sel_hi:[1,0]
	v_pk_mul_f32 v[108:109], v[108:109], v[190:191] op_sel_hi:[1,0]
	v_pk_mul_f32 v[106:107], v[106:107], v[190:191] op_sel_hi:[1,0]
	v_pk_mul_f32 v[104:105], v[104:105], v[190:191] op_sel_hi:[1,0]
	v_pk_mul_f32 v[102:103], v[102:103], v[190:191] op_sel_hi:[1,0]
	v_pk_mul_f32 v[100:101], v[100:101], v[190:191] op_sel_hi:[1,0]
	v_pk_mul_f32 v[98:99], v[98:99], v[190:191] op_sel_hi:[1,0]
	v_pk_mul_f32 v[96:97], v[96:97], v[190:191] op_sel_hi:[1,0]
	v_pk_mul_f32 v[94:95], v[94:95], v[190:191] op_sel_hi:[1,0]
	v_pk_mul_f32 v[92:93], v[92:93], v[190:191] op_sel_hi:[1,0]
	v_pk_mul_f32 v[90:91], v[90:91], v[190:191] op_sel_hi:[1,0]
	v_pk_mul_f32 v[88:89], v[88:89], v[190:191] op_sel_hi:[1,0]
	v_pk_mul_f32 v[86:87], v[86:87], v[190:191] op_sel_hi:[1,0]
	v_pk_mul_f32 v[84:85], v[84:85], v[190:191] op_sel_hi:[1,0]
	v_pk_mul_f32 v[82:83], v[82:83], v[190:191] op_sel_hi:[1,0]
	v_pk_mul_f32 v[80:81], v[80:81], v[190:191] op_sel_hi:[1,0]
	v_pk_mul_f32 v[78:79], v[78:79], v[190:191] op_sel_hi:[1,0]
	v_pk_mul_f32 v[76:77], v[76:77], v[190:191] op_sel_hi:[1,0]
	v_pk_mul_f32 v[74:75], v[74:75], v[190:191] op_sel_hi:[1,0]
	v_pk_mul_f32 v[72:73], v[72:73], v[190:191] op_sel_hi:[1,0]
	v_pk_mul_f32 v[70:71], v[70:71], v[190:191] op_sel_hi:[1,0]
	v_pk_mul_f32 v[68:69], v[68:69], v[190:191] op_sel_hi:[1,0]
	v_pk_mul_f32 v[66:67], v[66:67], v[190:191] op_sel_hi:[1,0]
	v_pk_mul_f32 v[64:65], v[64:65], v[190:191] op_sel_hi:[1,0]
	v_pk_mul_f32 v[62:63], v[62:63], v[190:191] op_sel_hi:[1,0]
	v_pk_mul_f32 v[60:61], v[60:61], v[190:191] op_sel_hi:[1,0]
	v_pk_mul_f32 v[58:59], v[58:59], v[190:191] op_sel_hi:[1,0]
	v_pk_mul_f32 v[56:57], v[56:57], v[190:191] op_sel_hi:[1,0]
	v_pk_mul_f32 v[54:55], v[54:55], v[190:191] op_sel_hi:[1,0]
	v_pk_mul_f32 v[52:53], v[52:53], v[190:191] op_sel_hi:[1,0]
	v_pk_mul_f32 v[50:51], v[50:51], v[190:191] op_sel_hi:[1,0]
	v_pk_mul_f32 v[48:49], v[48:49], v[190:191] op_sel_hi:[1,0]
	v_pk_mul_f32 v[46:47], v[46:47], v[190:191] op_sel_hi:[1,0]
	v_pk_mul_f32 v[44:45], v[44:45], v[190:191] op_sel_hi:[1,0]
	v_pk_mul_f32 v[42:43], v[42:43], v[190:191] op_sel_hi:[1,0]
	v_pk_mul_f32 v[40:41], v[40:41], v[190:191] op_sel_hi:[1,0]
	v_pk_mul_f32 v[38:39], v[38:39], v[190:191] op_sel_hi:[1,0]
	v_pk_mul_f32 v[36:37], v[36:37], v[190:191] op_sel_hi:[1,0]
	v_pk_mul_f32 v[34:35], v[34:35], v[190:191] op_sel_hi:[1,0]
	v_pk_mul_f32 v[32:33], v[32:33], v[190:191] op_sel_hi:[1,0]
	v_pk_mul_f32 v[30:31], v[30:31], v[190:191] op_sel_hi:[1,0]
	v_pk_mul_f32 v[28:29], v[28:29], v[190:191] op_sel_hi:[1,0]
	v_pk_mul_f32 v[26:27], v[26:27], v[190:191] op_sel_hi:[1,0]
	v_pk_mul_f32 v[24:25], v[24:25], v[190:191] op_sel_hi:[1,0]
	v_pk_mul_f32 v[22:23], v[22:23], v[190:191] op_sel_hi:[1,0]
	v_pk_mul_f32 v[20:21], v[20:21], v[190:191] op_sel_hi:[1,0]
	v_pk_mul_f32 v[18:19], v[18:19], v[190:191] op_sel_hi:[1,0]
	v_pk_mul_f32 v[16:17], v[16:17], v[190:191] op_sel_hi:[1,0]
	v_pk_mul_f32 v[14:15], v[14:15], v[190:191] op_sel_hi:[1,0]
	v_pk_mul_f32 v[12:13], v[12:13], v[190:191] op_sel_hi:[1,0]
	v_pk_mul_f32 v[10:11], v[10:11], v[190:191] op_sel_hi:[1,0]
	v_pk_mul_f32 v[8:9], v[8:9], v[190:191] op_sel_hi:[1,0]
	v_pk_mul_f32 v[6:7], v[6:7], v[190:191] op_sel_hi:[1,0]
	v_pk_mul_f32 v[4:5], v[4:5], v[190:191] op_sel_hi:[1,0]
	v_pk_mul_f32 v[2:3], v[2:3], v[190:191] op_sel_hi:[1,0]
	v_pk_mul_f32 v[0:1], v[0:1], v[190:191] op_sel_hi:[1,0]
	v_mul_f32_e32 v203, v203, v190
	v_mov_b32_e32 v190, v246
.Latt_nr0_6A:
	s_waitcnt lgkmcnt(5)
	v_mfma_f32_32x32x16_bf16 v[222:237], v[214:217], v[152:155], v[222:237]
	ds_read_b64_tr_b16 v[214:215], v205
	ds_read_b64_tr_b16 v[216:217], v205 offset:4096
	v_sub_f32_e32 v128, v128, v190
	v_exp_f32_e32 v128, v128
	v_sub_f32_e32 v129, v129, v190
	v_exp_f32_e32 v129, v129
	v_sub_f32_e32 v130, v130, v190
	v_add_f32_e32 v254, 0, v128
	v_exp_f32_e32 v130, v130
	v_sub_f32_e32 v131, v131, v190
	s_waitcnt lgkmcnt(6)
	v_mfma_f32_32x32x16_bf16 v[222:237], v[238:241], v[156:159], v[222:237]
	ds_read_b64_tr_b16 v[238:239], v218
	ds_read_b64_tr_b16 v[240:241], v218 offset:4096
	v_add_f32_e32 v254, v129, v254
	v_exp_f32_e32 v131, v131
	v_sub_f32_e32 v132, v132, v190
	v_add_f32_e32 v254, v130, v254
	v_exp_f32_e32 v132, v132
	v_sub_f32_e32 v133, v133, v190
	v_add_f32_e32 v254, v131, v254
	v_exp_f32_e32 v133, v133
	s_waitcnt lgkmcnt(7)
	v_mfma_f32_32x32x16_bf16 v[222:237], v[242:245], v[160:163], v[222:237]
	v_sub_f32_e32 v134, v134, v190
	v_add_f32_e32 v254, v132, v254
	v_exp_f32_e32 v134, v134
	v_sub_f32_e32 v135, v135, v190
	v_add_f32_e32 v254, v133, v254
	v_exp_f32_e32 v135, v135
	v_sub_f32_e32 v136, v136, v190
	v_add_f32_e32 v254, v134, v254
	s_waitcnt lgkmcnt(6)
	v_mfma_f32_32x32x16_bf16 v[222:237], v[250:253], v[164:167], v[222:237]
	v_exp_f32_e32 v136, v136
	v_sub_f32_e32 v137, v137, v190
	v_add_f32_e32 v254, v135, v254
	v_exp_f32_e32 v137, v137
	v_sub_f32_e32 v138, v138, v190
	v_add_f32_e32 v254, v136, v254
	v_exp_f32_e32 v138, v138
	v_sub_f32_e32 v139, v139, v190
	s_waitcnt lgkmcnt(5)
	v_mfma_f32_32x32x16_bf16 v[222:237], v[206:209], v[168:171], v[222:237]
	ds_read_b64_tr_b16 v[206:207], v219
	ds_read_b64_tr_b16 v[208:209], v219 offset:4096
	v_add_f32_e32 v254, v137, v254
	v_exp_f32_e32 v139, v139
	v_sub_f32_e32 v140, v140, v190
	v_add_f32_e32 v254, v138, v254
	v_exp_f32_e32 v140, v140
	v_sub_f32_e32 v141, v141, v190
	v_add_f32_e32 v254, v139, v254
	v_exp_f32_e32 v141, v141
	s_waitcnt lgkmcnt(6)
	v_mfma_f32_32x32x16_bf16 v[222:237], v[210:213], v[172:175], v[222:237]
	ds_read_b64_tr_b16 v[210:211], v221
	ds_read_b64_tr_b16 v[212:213], v221 offset:4096
	v_sub_f32_e32 v142, v142, v190
	v_add_f32_e32 v254, v140, v254
	v_exp_f32_e32 v142, v142
	v_sub_f32_e32 v143, v143, v190
	v_add_f32_e32 v254, v141, v254
	v_exp_f32_e32 v143, v143
	v_add_f32_e32 v254, v142, v254
	v_add_f32_e32 v254, v143, v254
	v_cvt_pk_bf16_f32 v242, v128, v129
	v_cvt_pk_bf16_f32 v243, v130, v131
	v_cvt_pk_bf16_f32 v244, v132, v133
	v_cvt_pk_bf16_f32 v245, v134, v135
	v_cvt_pk_bf16_f32 v250, v136, v137
	v_cvt_pk_bf16_f32 v251, v138, v139
	v_cvt_pk_bf16_f32 v252, v140, v141
	v_cvt_pk_bf16_f32 v253, v142, v143
	v_add_f32_e32 v203, v203, v254
	s_nop 1
	ds_read_b64_tr_b16 v[128:129], v205 offset:256
	ds_read_b64_tr_b16 v[130:131], v205 offset:4352
	s_waitcnt lgkmcnt(8)
	v_mfma_f32_32x32x16_bf16 v[112:127], v[214:217], v[242:245], v[112:127]
	ds_read_b64_tr_b16 v[214:215], v218 offset:256
	ds_read_b64_tr_b16 v[216:217], v218 offset:4352
	v_and_or_b32 v246, v204, 31, s68
	v_bfe_u32 v247, v204, 5, 1
	s_add_i32 s100, s72, 32
	v_lshl_add_u32 v247, v247, 2, s100
	v_add_u32_e32 v249, 0, v247
	v_cmp_le_i32_e32 vcc, v249, v246
	v_add_u32_e32 v254, 1, v247
	s_nop 0
	v_cndmask_b32_e32 v222, v192, v222, vcc
	v_cmp_le_i32_e32 vcc, v254, v246
	v_add_u32_e32 v249, 2, v247
	s_nop 0
	v_cndmask_b32_e32 v223, v192, v223, vcc
	v_cmp_le_i32_e32 vcc, v249, v246
	v_add_u32_e32 v254, 3, v247
	s_nop 0
	v_cndmask_b32_e32 v224, v192, v224, vcc
	v_cmp_le_i32_e32 vcc, v254, v246
	v_add_u32_e32 v249, 8, v247
	s_nop 0
	v_cndmask_b32_e32 v225, v192, v225, vcc
	v_cmp_le_i32_e32 vcc, v249, v246
	v_add_u32_e32 v254, 9, v247
	s_nop 0
	v_cndmask_b32_e32 v226, v192, v226, vcc
	v_cmp_le_i32_e32 vcc, v254, v246
	v_add_u32_e32 v249, 10, v247
	s_nop 0
	v_cndmask_b32_e32 v227, v192, v227, vcc
	v_cmp_le_i32_e32 vcc, v249, v246
	v_add_u32_e32 v254, 11, v247
	s_nop 0
	v_cndmask_b32_e32 v228, v192, v228, vcc
	v_cmp_le_i32_e32 vcc, v254, v246
	s_waitcnt lgkmcnt(8)
	v_mfma_f32_32x32x16_bf16 v[96:111], v[238:241], v[242:245], v[96:111]
	ds_read_b64_tr_b16 v[238:239], v219 offset:256
	ds_read_b64_tr_b16 v[240:241], v219 offset:4352
	v_add_u32_e32 v249, 16, v247
	s_nop 0
	v_cndmask_b32_e32 v229, v192, v229, vcc
	v_cmp_le_i32_e32 vcc, v249, v246
	v_add_u32_e32 v254, 17, v247
	s_nop 0
	v_cndmask_b32_e32 v230, v192, v230, vcc
	v_cmp_le_i32_e32 vcc, v254, v246
	v_add_u32_e32 v249, 18, v247
	s_nop 0
	v_cndmask_b32_e32 v231, v192, v231, vcc
	v_cmp_le_i32_e32 vcc, v249, v246
	v_add_u32_e32 v254, 19, v247
	s_nop 0
	v_cndmask_b32_e32 v232, v192, v232, vcc
	v_cmp_le_i32_e32 vcc, v254, v246
	v_add_u32_e32 v249, 24, v247
	s_nop 0
	v_cndmask_b32_e32 v233, v192, v233, vcc
	v_cmp_le_i32_e32 vcc, v249, v246
	v_add_u32_e32 v254, 25, v247
	s_nop 0
	v_cndmask_b32_e32 v234, v192, v234, vcc
	v_cmp_le_i32_e32 vcc, v254, v246
	v_add_u32_e32 v249, 26, v247
	s_nop 0
	v_cndmask_b32_e32 v235, v192, v235, vcc
	v_cmp_le_i32_e32 vcc, v249, v246
	v_add_u32_e32 v254, 27, v247
	s_nop 0
	v_cndmask_b32_e32 v236, v192, v236, vcc
	v_cmp_le_i32_e32 vcc, v254, v246
	s_nop 1
	v_cndmask_b32_e32 v237, v192, v237, vcc
	s_waitcnt lgkmcnt(8)
	v_mfma_f32_32x32x16_bf16 v[80:95], v[206:209], v[242:245], v[80:95]
	ds_read_b64_tr_b16 v[206:207], v221 offset:256
	ds_read_b64_tr_b16 v[208:209], v221 offset:4352
	v_max3_f32 v246, v222, v223, v224
	v_max3_f32 v247, v225, v226, v227
	v_max3_f32 v246, v246, v228, v229
	v_max3_f32 v247, v247, v230, v231
	v_max3_f32 v246, v246, v232, v233
	v_max3_f32 v247, v247, v234, v235
	s_waitcnt lgkmcnt(8)
	v_mfma_f32_32x32x16_bf16 v[64:79], v[210:213], v[242:245], v[64:79]
	ds_read_b64_tr_b16 v[210:211], v205 offset:8192
	ds_read_b64_tr_b16 v[212:213], v205 offset:12288
	v_max3_f32 v246, v246, v236, v237
	v_max_f32_e32 v246, v246, v247
	v_mov_b32_e32 v247, v246
	v_add_f32_e32 v249, 0x41000000, v190
	s_nop 1
	s_waitcnt lgkmcnt(8)
	v_mfma_f32_32x32x16_bf16 v[48:63], v[128:131], v[242:245], v[48:63]
	ds_read_b64_tr_b16 v[128:129], v218 offset:8192
	ds_read_b64_tr_b16 v[130:131], v218 offset:12288
	v_permlane32_swap_b32_e32 v246, v247
	v_max_f32_e32 v246, v246, v247
	v_cmp_gt_f32_e32 vcc, v246, v249
	s_cbranch_vccnz .Latt_rs1_6A
	s_waitcnt lgkmcnt(8)
	v_mfma_f32_32x32x16_bf16 v[32:47], v[214:217], v[242:245], v[32:47]
	ds_read_b64_tr_b16 v[214:215], v219 offset:8192
	ds_read_b64_tr_b16 v[216:217], v219 offset:12288
	v_sub_f32_e32 v222, v222, v190
	v_exp_f32_e32 v222, v222
	v_sub_f32_e32 v223, v223, v190
	v_exp_f32_e32 v223, v223
	v_sub_f32_e32 v224, v224, v190
	s_waitcnt lgkmcnt(8)
	v_mfma_f32_32x32x16_bf16 v[16:31], v[238:241], v[242:245], v[16:31]
	ds_read_b64_tr_b16 v[238:239], v221 offset:8192
	ds_read_b64_tr_b16 v[240:241], v221 offset:12288
	v_add_f32_e32 v254, 0, v222
	v_exp_f32_e32 v224, v224
	v_sub_f32_e32 v225, v225, v190
	v_add_f32_e32 v254, v223, v254
	v_exp_f32_e32 v225, v225
	s_waitcnt lgkmcnt(8)
	v_mfma_f32_32x32x16_bf16 v[0:15], v[206:209], v[242:245], v[0:15]
	ds_read_b64_tr_b16 v[206:207], v205 offset:8448
	ds_read_b64_tr_b16 v[208:209], v205 offset:12544
	v_sub_f32_e32 v226, v226, v190
	v_add_f32_e32 v254, v224, v254
	v_exp_f32_e32 v226, v226
	v_sub_f32_e32 v227, v227, v190
	v_add_f32_e32 v254, v225, v254
	s_waitcnt lgkmcnt(8)
	v_mfma_f32_32x32x16_bf16 v[112:127], v[210:213], v[250:253], v[112:127]
	ds_read_b64_tr_b16 v[210:211], v218 offset:8448
	ds_read_b64_tr_b16 v[212:213], v218 offset:12544
	v_exp_f32_e32 v227, v227
	v_sub_f32_e32 v228, v228, v190
	v_add_f32_e32 v254, v226, v254
	v_exp_f32_e32 v228, v228
	v_sub_f32_e32 v229, v229, v190
	s_waitcnt lgkmcnt(8)
	v_mfma_f32_32x32x16_bf16 v[96:111], v[128:131], v[250:253], v[96:111]
	ds_read_b64_tr_b16 v[128:129], v219 offset:8448
	ds_read_b64_tr_b16 v[130:131], v219 offset:12544
	v_add_f32_e32 v254, v227, v254
	v_exp_f32_e32 v229, v229
	v_sub_f32_e32 v230, v230, v190
	v_add_f32_e32 v254, v228, v254
	s_waitcnt lgkmcnt(8)
	v_mfma_f32_32x32x16_bf16 v[80:95], v[214:217], v[250:253], v[80:95]
	ds_read_b64_tr_b16 v[214:215], v221 offset:8448
	ds_read_b64_tr_b16 v[216:217], v221 offset:12544
	v_exp_f32_e32 v230, v230
	v_sub_f32_e32 v231, v231, v190
	v_add_f32_e32 v254, v229, v254
	v_exp_f32_e32 v231, v231
	s_waitcnt lgkmcnt(8)
	v_mfma_f32_32x32x16_bf16 v[64:79], v[238:241], v[250:253], v[64:79]
	ds_read_b64_tr_b16 v[238:239], v205 offset:16384
	ds_read_b64_tr_b16 v[240:241], v205 offset:20480
	v_sub_f32_e32 v232, v232, v190
	v_add_f32_e32 v254, v230, v254
	v_exp_f32_e32 v232, v232
	v_sub_f32_e32 v233, v233, v190
	s_waitcnt lgkmcnt(8)
	v_mfma_f32_32x32x16_bf16 v[48:63], v[206:209], v[250:253], v[48:63]
	ds_read_b64_tr_b16 v[206:207], v218 offset:16384
	ds_read_b64_tr_b16 v[208:209], v218 offset:20480
	v_add_f32_e32 v254, v231, v254
	v_exp_f32_e32 v233, v233
	v_sub_f32_e32 v234, v234, v190
	v_add_f32_e32 v254, v232, v254
	s_waitcnt lgkmcnt(8)
	v_mfma_f32_32x32x16_bf16 v[32:47], v[210:213], v[250:253], v[32:47]
	ds_read_b64_tr_b16 v[210:211], v219 offset:16384
	ds_read_b64_tr_b16 v[212:213], v219 offset:20480
	v_exp_f32_e32 v234, v234
	v_sub_f32_e32 v235, v235, v190
	v_add_f32_e32 v254, v233, v254
	v_exp_f32_e32 v235, v235
	s_waitcnt lgkmcnt(8)
	v_mfma_f32_32x32x16_bf16 v[16:31], v[128:131], v[250:253], v[16:31]
	ds_read_b64_tr_b16 v[128:129], v221 offset:16384
	ds_read_b64_tr_b16 v[130:131], v221 offset:20480
	v_sub_f32_e32 v236, v236, v190
	v_add_f32_e32 v254, v234, v254
	v_exp_f32_e32 v236, v236
	v_sub_f32_e32 v237, v237, v190
	s_waitcnt lgkmcnt(8)
	v_mfma_f32_32x32x16_bf16 v[0:15], v[214:217], v[250:253], v[0:15]
	ds_read_b64_tr_b16 v[214:215], v205 offset:16640
	ds_read_b64_tr_b16 v[216:217], v205 offset:20736
	v_add_f32_e32 v254, v235, v254
	v_exp_f32_e32 v237, v237
	v_add_f32_e32 v254, v236, v254
	v_add_f32_e32 v254, v237, v254
	v_cvt_pk_bf16_f32 v242, v222, v223
	v_cvt_pk_bf16_f32 v243, v224, v225
	v_cvt_pk_bf16_f32 v244, v226, v227
	v_cvt_pk_bf16_f32 v245, v228, v229
	v_cvt_pk_bf16_f32 v250, v230, v231
	v_cvt_pk_bf16_f32 v251, v232, v233
	v_cvt_pk_bf16_f32 v252, v234, v235
	v_cvt_pk_bf16_f32 v253, v236, v237
	v_add_f32_e32 v203, v203, v254
	s_nop 1

.Latt_rs1_6F:
	s_waitcnt lgkmcnt(8)
	v_mfma_f32_32x32x16_bf16 v[32:47], v[214:217], v[242:245], v[32:47]
	ds_read_b64_tr_b16 v[214:215], v219 offset:8192
	ds_read_b64_tr_b16 v[216:217], v219 offset:12288
	s_waitcnt lgkmcnt(8)
	v_mfma_f32_32x32x16_bf16 v[16:31], v[238:241], v[242:245], v[16:31]
	ds_read_b64_tr_b16 v[238:239], v221 offset:8192
	ds_read_b64_tr_b16 v[240:241], v221 offset:12288
	s_waitcnt lgkmcnt(8)
	v_mfma_f32_32x32x16_bf16 v[0:15], v[206:209], v[242:245], v[0:15]
	ds_read_b64_tr_b16 v[206:207], v205 offset:8448
	ds_read_b64_tr_b16 v[208:209], v205 offset:12544
	s_waitcnt lgkmcnt(8)
	v_mfma_f32_32x32x16_bf16 v[112:127], v[210:213], v[250:253], v[112:127]
	ds_read_b64_tr_b16 v[210:211], v218 offset:8448
	ds_read_b64_tr_b16 v[212:213], v218 offset:12544
	s_waitcnt lgkmcnt(8)
	v_mfma_f32_32x32x16_bf16 v[96:111], v[128:131], v[250:253], v[96:111]
	ds_read_b64_tr_b16 v[128:129], v219 offset:8448
	ds_read_b64_tr_b16 v[130:131], v219 offset:12544
	s_waitcnt lgkmcnt(8)
	v_mfma_f32_32x32x16_bf16 v[80:95], v[214:217], v[250:253], v[80:95]
	ds_read_b64_tr_b16 v[214:215], v221 offset:8448
	ds_read_b64_tr_b16 v[216:217], v221 offset:12544
	s_waitcnt lgkmcnt(8)
	v_mfma_f32_32x32x16_bf16 v[64:79], v[238:241], v[250:253], v[64:79]
	ds_read_b64_tr_b16 v[238:239], v205 offset:16384
	ds_read_b64_tr_b16 v[240:241], v205 offset:20480
	s_waitcnt lgkmcnt(8)
	v_mfma_f32_32x32x16_bf16 v[48:63], v[206:209], v[250:253], v[48:63]
	ds_read_b64_tr_b16 v[206:207], v218 offset:16384
	ds_read_b64_tr_b16 v[208:209], v218 offset:20480
	s_waitcnt lgkmcnt(8)
	v_mfma_f32_32x32x16_bf16 v[32:47], v[210:213], v[250:253], v[32:47]
	ds_read_b64_tr_b16 v[210:211], v219 offset:16384
	ds_read_b64_tr_b16 v[212:213], v219 offset:20480
	s_waitcnt lgkmcnt(8)
	v_mfma_f32_32x32x16_bf16 v[16:31], v[128:131], v[250:253], v[16:31]
	ds_read_b64_tr_b16 v[128:129], v221 offset:16384
	ds_read_b64_tr_b16 v[130:131], v221 offset:20480
	s_waitcnt lgkmcnt(8)
	v_mfma_f32_32x32x16_bf16 v[0:15], v[214:217], v[250:253], v[0:15]
	ds_read_b64_tr_b16 v[214:215], v205 offset:16640
	ds_read_b64_tr_b16 v[216:217], v205 offset:20736
	s_nop 11
	v_max_f32_e32 v246, v190, v246
	v_sub_f32_e32 v190, v190, v246
	v_exp_f32_e32 v190, v190
	s_nop 0
	v_pk_mul_f32 v[126:127], v[126:127], v[190:191] op_sel_hi:[1,0]
	v_pk_mul_f32 v[124:125], v[124:125], v[190:191] op_sel_hi:[1,0]
	v_pk_mul_f32 v[122:123], v[122:123], v[190:191] op_sel_hi:[1,0]
	v_pk_mul_f32 v[120:121], v[120:121], v[190:191] op_sel_hi:[1,0]
	v_pk_mul_f32 v[118:119], v[118:119], v[190:191] op_sel_hi:[1,0]
	v_pk_mul_f32 v[116:117], v[116:117], v[190:191] op_sel_hi:[1,0]
	v_pk_mul_f32 v[114:115], v[114:115], v[190:191] op_sel_hi:[1,0]
	v_pk_mul_f32 v[112:113], v[112:113], v[190:191] op_sel_hi:[1,0]
	v_pk_mul_f32 v[110:111], v[110:111], v[190:191] op_sel_hi:[1,0]
	v_pk_mul_f32 v[108:109], v[108:109], v[190:191] op_sel_hi:[1,0]
	v_pk_mul_f32 v[106:107], v[106:107], v[190:191] op_sel_hi:[1,0]
	v_pk_mul_f32 v[104:105], v[104:105], v[190:191] op_sel_hi:[1,0]
	v_pk_mul_f32 v[102:103], v[102:103], v[190:191] op_sel_hi:[1,0]
	v_pk_mul_f32 v[100:101], v[100:101], v[190:191] op_sel_hi:[1,0]
	v_pk_mul_f32 v[98:99], v[98:99], v[190:191] op_sel_hi:[1,0]
	v_pk_mul_f32 v[96:97], v[96:97], v[190:191] op_sel_hi:[1,0]
	v_pk_mul_f32 v[94:95], v[94:95], v[190:191] op_sel_hi:[1,0]
	v_pk_mul_f32 v[92:93], v[92:93], v[190:191] op_sel_hi:[1,0]
	v_pk_mul_f32 v[90:91], v[90:91], v[190:191] op_sel_hi:[1,0]
	v_pk_mul_f32 v[88:89], v[88:89], v[190:191] op_sel_hi:[1,0]
	v_pk_mul_f32 v[86:87], v[86:87], v[190:191] op_sel_hi:[1,0]
	v_pk_mul_f32 v[84:85], v[84:85], v[190:191] op_sel_hi:[1,0]
	v_pk_mul_f32 v[82:83], v[82:83], v[190:191] op_sel_hi:[1,0]
	v_pk_mul_f32 v[80:81], v[80:81], v[190:191] op_sel_hi:[1,0]
	v_pk_mul_f32 v[78:79], v[78:79], v[190:191] op_sel_hi:[1,0]
	v_pk_mul_f32 v[76:77], v[76:77], v[190:191] op_sel_hi:[1,0]
	v_pk_mul_f32 v[74:75], v[74:75], v[190:191] op_sel_hi:[1,0]
	v_pk_mul_f32 v[72:73], v[72:73], v[190:191] op_sel_hi:[1,0]
	v_pk_mul_f32 v[70:71], v[70:71], v[190:191] op_sel_hi:[1,0]
	v_pk_mul_f32 v[68:69], v[68:69], v[190:191] op_sel_hi:[1,0]
	v_pk_mul_f32 v[66:67], v[66:67], v[190:191] op_sel_hi:[1,0]
	v_pk_mul_f32 v[64:65], v[64:65], v[190:191] op_sel_hi:[1,0]
	v_pk_mul_f32 v[62:63], v[62:63], v[190:191] op_sel_hi:[1,0]
	v_pk_mul_f32 v[60:61], v[60:61], v[190:191] op_sel_hi:[1,0]
	v_pk_mul_f32 v[58:59], v[58:59], v[190:191] op_sel_hi:[1,0]
	v_pk_mul_f32 v[56:57], v[56:57], v[190:191] op_sel_hi:[1,0]
	v_pk_mul_f32 v[54:55], v[54:55], v[190:191] op_sel_hi:[1,0]
	v_pk_mul_f32 v[52:53], v[52:53], v[190:191] op_sel_hi:[1,0]
	v_pk_mul_f32 v[50:51], v[50:51], v[190:191] op_sel_hi:[1,0]
	v_pk_mul_f32 v[48:49], v[48:49], v[190:191] op_sel_hi:[1,0]
	v_pk_mul_f32 v[46:47], v[46:47], v[190:191] op_sel_hi:[1,0]
	v_pk_mul_f32 v[44:45], v[44:45], v[190:191] op_sel_hi:[1,0]
	v_pk_mul_f32 v[42:43], v[42:43], v[190:191] op_sel_hi:[1,0]
	v_pk_mul_f32 v[40:41], v[40:41], v[190:191] op_sel_hi:[1,0]
	v_pk_mul_f32 v[38:39], v[38:39], v[190:191] op_sel_hi:[1,0]
	v_pk_mul_f32 v[36:37], v[36:37], v[190:191] op_sel_hi:[1,0]
	v_pk_mul_f32 v[34:35], v[34:35], v[190:191] op_sel_hi:[1,0]
	v_pk_mul_f32 v[32:33], v[32:33], v[190:191] op_sel_hi:[1,0]
	v_pk_mul_f32 v[30:31], v[30:31], v[190:191] op_sel_hi:[1,0]
	v_pk_mul_f32 v[28:29], v[28:29], v[190:191] op_sel_hi:[1,0]
	v_pk_mul_f32 v[26:27], v[26:27], v[190:191] op_sel_hi:[1,0]
	v_pk_mul_f32 v[24:25], v[24:25], v[190:191] op_sel_hi:[1,0]
	v_pk_mul_f32 v[22:23], v[22:23], v[190:191] op_sel_hi:[1,0]
	v_pk_mul_f32 v[20:21], v[20:21], v[190:191] op_sel_hi:[1,0]
	v_pk_mul_f32 v[18:19], v[18:19], v[190:191] op_sel_hi:[1,0]
	v_pk_mul_f32 v[16:17], v[16:17], v[190:191] op_sel_hi:[1,0]
	v_pk_mul_f32 v[14:15], v[14:15], v[190:191] op_sel_hi:[1,0]
	v_pk_mul_f32 v[12:13], v[12:13], v[190:191] op_sel_hi:[1,0]
	v_pk_mul_f32 v[10:11], v[10:11], v[190:191] op_sel_hi:[1,0]
	v_pk_mul_f32 v[8:9], v[8:9], v[190:191] op_sel_hi:[1,0]
	v_pk_mul_f32 v[6:7], v[6:7], v[190:191] op_sel_hi:[1,0]
	v_pk_mul_f32 v[4:5], v[4:5], v[190:191] op_sel_hi:[1,0]
	v_pk_mul_f32 v[2:3], v[2:3], v[190:191] op_sel_hi:[1,0]
	v_pk_mul_f32 v[0:1], v[0:1], v[190:191] op_sel_hi:[1,0]
	v_mul_f32_e32 v203, v203, v190
	v_mov_b32_e32 v190, v246
	v_sub_f32_e32 v222, v222, v190
	v_exp_f32_e32 v222, v222
	v_sub_f32_e32 v223, v223, v190
	v_exp_f32_e32 v223, v223
	v_sub_f32_e32 v224, v224, v190
	v_add_f32_e32 v254, 0, v222
	v_exp_f32_e32 v224, v224
	v_sub_f32_e32 v225, v225, v190
	v_add_f32_e32 v254, v223, v254
	v_exp_f32_e32 v225, v225
	v_sub_f32_e32 v226, v226, v190
	v_add_f32_e32 v254, v224, v254
	v_exp_f32_e32 v226, v226
	v_sub_f32_e32 v227, v227, v190
	v_add_f32_e32 v254, v225, v254
	v_exp_f32_e32 v227, v227
	v_sub_f32_e32 v228, v228, v190
	v_add_f32_e32 v254, v226, v254
	v_exp_f32_e32 v228, v228
	v_sub_f32_e32 v229, v229, v190
	v_add_f32_e32 v254, v227, v254
	v_exp_f32_e32 v229, v229
	v_sub_f32_e32 v230, v230, v190
	v_add_f32_e32 v254, v228, v254
	v_exp_f32_e32 v230, v230
	v_sub_f32_e32 v231, v231, v190
	v_add_f32_e32 v254, v229, v254
	v_exp_f32_e32 v231, v231
	v_sub_f32_e32 v232, v232, v190
	v_add_f32_e32 v254, v230, v254
	v_exp_f32_e32 v232, v232
	v_sub_f32_e32 v233, v233, v190
	v_add_f32_e32 v254, v231, v254
	v_exp_f32_e32 v233, v233
	v_sub_f32_e32 v234, v234, v190
	v_add_f32_e32 v254, v232, v254
	v_exp_f32_e32 v234, v234
	v_sub_f32_e32 v235, v235, v190
	v_add_f32_e32 v254, v233, v254
	v_exp_f32_e32 v235, v235
	v_sub_f32_e32 v236, v236, v190
	v_add_f32_e32 v254, v234, v254
	v_exp_f32_e32 v236, v236
	v_sub_f32_e32 v237, v237, v190
	v_add_f32_e32 v254, v235, v254
	v_exp_f32_e32 v237, v237
	v_add_f32_e32 v254, v236, v254
	v_add_f32_e32 v254, v237, v254
	v_cvt_pk_bf16_f32 v242, v222, v223
	v_cvt_pk_bf16_f32 v243, v224, v225
	v_cvt_pk_bf16_f32 v244, v226, v227
	v_cvt_pk_bf16_f32 v245, v228, v229
	v_cvt_pk_bf16_f32 v250, v230, v231
	v_cvt_pk_bf16_f32 v251, v232, v233
	v_cvt_pk_bf16_f32 v252, v234, v235
	v_cvt_pk_bf16_f32 v253, v236, v237
	v_add_f32_e32 v203, v203, v254
	s_nop 1
	s_branch .Latt_pv1_6F
	s_lshl_b32 s14, s34, 14
	s_add_i32 s15, s14, 0
	v_add_u32_e32 v207, s15, v195
	ds_read_b128 v[128:131], v207
	v_add_u32_e32 v208, s15, v196
	ds_read_b128 v[210:213], v208
	v_add_u32_e32 v209, s15, v197
	v_lshrrev_b32_e32 v205, 3, v204
	s_add_i32 s35, s72, 31
	v_and_or_b32 v206, v204, 31, s68
	s_cmp_le_i32 s35, s68
	s_waitcnt lgkmcnt(1)
	v_mfma_f32_32x32x16_bf16 v[128:143], v[128:131], v[144:147], 0
	s_waitcnt lgkmcnt(0)
	v_mfma_f32_32x32x16_bf16 v[128:143], v[210:213], v[148:151], v[128:143]
	ds_read_b128 v[212:215], v209
	v_add_u32_e32 v210, s15, v198
	ds_read_b128 v[216:219], v210
	v_add_u32_e32 v211, s15, v199
	s_waitcnt lgkmcnt(1)
	v_mfma_f32_32x32x16_bf16 v[128:143], v[212:215], v[152:155], v[128:143]
	v_add_u32_e32 v213, s15, v200
	v_and_b32_e32 v212, 4, v205
	ds_read_b128 v[222:225], v213
	s_waitcnt lgkmcnt(1)
	v_mfma_f32_32x32x16_bf16 v[128:143], v[216:219], v[156:159], v[128:143]
	ds_read_b128 v[214:217], v211
	s_waitcnt lgkmcnt(0)
	v_mfma_f32_32x32x16_bf16 v[128:143], v[214:217], v[160:163], v[128:143]
	v_add_u32_e32 v214, s15, v201
	ds_read_b128 v[216:219], v214
	v_add_u32_e32 v215, s15, v202
	v_mfma_f32_32x32x16_bf16 v[128:143], v[222:225], v[164:167], v[128:143]
	ds_read_b128 v[222:225], v215
	s_waitcnt lgkmcnt(1)
	v_mfma_f32_32x32x16_bf16 v[128:143], v[216:219], v[168:171], v[128:143]
	s_waitcnt lgkmcnt(0)
	v_mfma_f32_32x32x16_bf16 v[128:143], v[222:225], v[172:175], v[128:143]
	s_cbranch_scc1 .LBB0_1842
	v_add_u32_e32 v205, s72, v212
	v_cmp_lt_i32_e32 vcc, v205, v206
	v_add_u32_e32 v216, 2, v205
	s_nop 7
	v_cndmask_b32_e32 v129, v192, v129, vcc
	v_cmp_le_i32_e32 vcc, v205, v206
	s_nop 1
	v_cndmask_b32_e32 v128, v192, v128, vcc
	v_cmp_le_i32_e32 vcc, v216, v206
	v_add_u32_e32 v216, 3, v205
	s_nop 0
	v_cndmask_b32_e32 v130, v192, v130, vcc
	v_cmp_le_i32_e32 vcc, v216, v206
	v_add_u32_e32 v216, 8, v205
	s_nop 0
	v_cndmask_b32_e32 v131, v192, v131, vcc
	v_cmp_le_i32_e32 vcc, v216, v206
	v_add_u32_e32 v216, 9, v205
	s_nop 0
	v_cndmask_b32_e32 v132, v192, v132, vcc
	v_cmp_le_i32_e32 vcc, v216, v206
	v_add_u32_e32 v216, 10, v205
	s_nop 0
	v_cndmask_b32_e32 v133, v192, v133, vcc
	v_cmp_le_i32_e32 vcc, v216, v206
	v_add_u32_e32 v216, 11, v205
	s_nop 0
	v_cndmask_b32_e32 v134, v192, v134, vcc
	v_cmp_le_i32_e32 vcc, v216, v206
	v_add_u32_e32 v216, 16, v205
	s_nop 0
	v_cndmask_b32_e32 v135, v192, v135, vcc
	v_cmp_le_i32_e32 vcc, v216, v206
	v_add_u32_e32 v216, 17, v205
	s_nop 0
	v_cndmask_b32_e32 v136, v192, v136, vcc
	v_cmp_le_i32_e32 vcc, v216, v206
	v_add_u32_e32 v216, 18, v205
	s_nop 0
	v_cndmask_b32_e32 v137, v192, v137, vcc
	v_cmp_le_i32_e32 vcc, v216, v206
	v_add_u32_e32 v216, 19, v205
	s_nop 0
	v_cndmask_b32_e32 v138, v192, v138, vcc
	v_cmp_le_i32_e32 vcc, v216, v206
	v_add_u32_e32 v216, 24, v205
	s_nop 0
	v_cndmask_b32_e32 v139, v192, v139, vcc
	v_cmp_le_i32_e32 vcc, v216, v206
	v_add_u32_e32 v216, 25, v205
	s_nop 0
	v_cndmask_b32_e32 v140, v192, v140, vcc
	v_cmp_le_i32_e32 vcc, v216, v206
	v_add_u32_e32 v216, 26, v205
	v_add_u32_e32 v205, 27, v205
	v_cndmask_b32_e32 v141, v192, v141, vcc
	v_cmp_le_i32_e32 vcc, v216, v206
	s_nop 1
	v_cndmask_b32_e32 v142, v192, v142, vcc
	v_cmp_le_i32_e32 vcc, v205, v206
	s_nop 1
	v_cndmask_b32_e32 v143, v192, v143, vcc

.LBB0_1856:
	s_cmp_ge_u32 s10, s66
	s_cselect_b64 s[8:9], -1, 0
	v_mov_b32_e32 v204, v176
	s_and_b64 vcc, exec, s[8:9]
	s_cbranch_vccnz .LBB0_1858
	s_cmp_le_i32 s14, s69
	s_cbranch_scc1 .LBB0_1858
	v_sub_co_u32_e64 v128, s[16:17], s11, 1
	s_nop 1
	v_cndmask_b32_e64 v130, v128, 2, s[16:17]
	v_lshlrev_b32_e32 v128, 14, v130
	v_add_u32_e32 v131, s36, v128
	v_lshl_add_u64 v[128:129], s[22:23], 0, v[178:179]
	s_add_u32 s16, s22, 0xf00
	v_readfirstlane_b32 s15, v131
	s_mov_b32 s20, m0
	s_mov_b32 m0, s15
	s_nop 0
	global_load_lds_dwordx4 v[128:129], off
	s_mov_b32 m0, s20
	v_lshl_add_u64 v[128:129], s[22:23], 0, v[180:181]
	s_addc_u32 s17, s23, 0
	s_addk_i32 s15, 0x400
	s_mov_b32 s20, m0
	s_mov_b32 m0, s15
	s_nop 0
	global_load_lds_dwordx4 v[128:129], off
	s_mov_b32 m0, s20
	v_lshlrev_b32_e32 v128, 15, v130
	v_add_u32_e32 v130, s37, v128
	v_lshl_add_u64 v[128:129], s[16:17], 0, v[182:183]
	v_readfirstlane_b32 s15, v130
	s_mov_b32 s20, m0
	s_mov_b32 m0, s15
	s_nop 0
	global_load_lds_dwordx4 v[128:129], off
	s_mov_b32 m0, s20
	v_lshl_add_u64 v[128:129], s[16:17], 0, v[184:185]
	s_add_i32 s20, s15, 0x400
	s_mov_b32 s21, m0
	s_mov_b32 m0, s20
	s_nop 0
	global_load_lds_dwordx4 v[128:129], off
	s_mov_b32 m0, s21
	v_lshl_add_u64 v[128:129], s[16:17], 0, v[186:187]
	s_add_i32 s20, s15, 0x800
	s_mov_b32 s21, m0
	s_mov_b32 m0, s20
	s_nop 0
	global_load_lds_dwordx4 v[128:129], off
	s_mov_b32 m0, s21
	v_lshl_add_u64 v[128:129], s[16:17], 0, v[188:189]
	s_addk_i32 s15, 0xc00
	s_mov_b32 s16, m0
	s_mov_b32 m0, s15
	s_nop 0
	global_load_lds_dwordx4 v[128:129], off
	s_mov_b32 m0, s16
.LBB0_1858:
	s_cmp_gt_i32 s14, s69
	s_cbranch_scc1 .LBB0_1869
	s_add_i32 s100, s14, 63
	s_cmp_le_i32 s100, s68
	s_cbranch_scc1 .Latt_full_7
	s_add_i32 s100, s14, 32
	s_cmp_le_i32 s100, s69
	s_cbranch_scc1 .Latt_diagA_7
	s_lshl_b32 s98, s11, 14
	s_lshl_b32 s99, s11, 15
	s_add_i32 s99, s99, 0xc000
	v_add_u32_e32 v206, s98, v196
	ds_read_b128 v[206:209], v206
	v_add_u32_e32 v210, s98, v197
	ds_read_b128 v[210:213], v210
	v_add_u32_e32 v214, s98, v198
	ds_read_b128 v[214:217], v214
	v_add_u32_e32 v238, s98, v199
	ds_read_b128 v[238:241], v238
	v_add_u32_e32 v242, s98, v200
	ds_read_b128 v[242:245], v242
	v_add_u32_e32 v250, s98, v201
	ds_read_b128 v[250:253], v250
	v_add_u32_e32 v222, s98, v202
	ds_read_b128 v[222:225], v222
	v_add_u32_e32 v226, s98, v203
	ds_read_b128 v[226:229], v226
	v_bfe_u32 v246, v204, 2, 2
	v_bfe_u32 v247, v204, 5, 1
	v_lshl_or_b32 v247, v247, 2, v246
	v_and_b32_e32 v249, 3, v204
	v_and_b32_e32 v254, 16, v204
	v_lshl_or_b32 v249, v249, 2, v254
	v_lshlrev_b32_e32 v249, 1, v249
	v_lshl_add_u32 v247, v247, 9, v249
	v_add_u32_e32 v247, s99, v247
	v_lshlrev_b32_e32 v246, 6, v246
	v_add_u32_e32 v205, v247, v246
	v_xor_b32_e32 v249, 64, v246
	v_add_u32_e32 v218, v247, v249
	v_xor_b32_e32 v249, 0x80, v246
	v_add_u32_e32 v219, v247, v249
	v_xor_b32_e32 v249, 0xc0, v246
	v_add_u32_e32 v221, v247, v249
	s_waitcnt lgkmcnt(7)
	v_mfma_f32_32x32x16_bf16 v[128:143], v[206:209], v[144:147], 0
	ds_read_b64_tr_b16 v[206:207], v205
	ds_read_b64_tr_b16 v[208:209], v205 offset:4096
	s_waitcnt lgkmcnt(8)
	v_mfma_f32_32x32x16_bf16 v[128:143], v[210:213], v[148:151], v[128:143]
	ds_read_b64_tr_b16 v[210:211], v218
	ds_read_b64_tr_b16 v[212:213], v218 offset:4096
	s_waitcnt lgkmcnt(9)
	v_mfma_f32_32x32x16_bf16 v[128:143], v[214:217], v[152:155], v[128:143]
	s_waitcnt lgkmcnt(8)
	v_mfma_f32_32x32x16_bf16 v[128:143], v[238:241], v[156:159], v[128:143]
	ds_read_b64_tr_b16 v[214:215], v219
	ds_read_b64_tr_b16 v[216:217], v219 offset:4096
	s_waitcnt lgkmcnt(9)
	v_mfma_f32_32x32x16_bf16 v[128:143], v[242:245], v[160:163], v[128:143]
	s_waitcnt lgkmcnt(8)
	v_mfma_f32_32x32x16_bf16 v[128:143], v[250:253], v[164:167], v[128:143]
	ds_read_b64_tr_b16 v[238:239], v221
	ds_read_b64_tr_b16 v[240:241], v221 offset:4096
	s_waitcnt lgkmcnt(9)
	v_mfma_f32_32x32x16_bf16 v[128:143], v[222:225], v[168:171], v[128:143]
	s_waitcnt lgkmcnt(8)
	v_mfma_f32_32x32x16_bf16 v[128:143], v[226:229], v[172:175], v[128:143]
	s_nop 11
	v_and_or_b32 v246, v204, 31, s68
	v_bfe_u32 v247, v204, 5, 1
	s_add_i32 s100, s14, 0
	v_lshl_add_u32 v247, v247, 2, s100
	v_add_u32_e32 v249, 0, v247
	v_cmp_le_i32_e32 vcc, v249, v246
	v_add_u32_e32 v254, 1, v247
	s_nop 0
	v_cndmask_b32_e32 v128, v192, v128, vcc
	v_cmp_le_i32_e32 vcc, v254, v246
	v_add_u32_e32 v249, 2, v247
	s_nop 0
	v_cndmask_b32_e32 v129, v192, v129, vcc
	v_cmp_le_i32_e32 vcc, v249, v246
	v_add_u32_e32 v254, 3, v247
	s_nop 0
	v_cndmask_b32_e32 v130, v192, v130, vcc
	v_cmp_le_i32_e32 vcc, v254, v246
	v_add_u32_e32 v249, 8, v247
	s_nop 0
	v_cndmask_b32_e32 v131, v192, v131, vcc
	v_cmp_le_i32_e32 vcc, v249, v246
	v_add_u32_e32 v254, 9, v247
	s_nop 0
	v_cndmask_b32_e32 v132, v192, v132, vcc
	v_cmp_le_i32_e32 vcc, v254, v246
	v_add_u32_e32 v249, 10, v247
	s_nop 0
	v_cndmask_b32_e32 v133, v192, v133, vcc
	v_cmp_le_i32_e32 vcc, v249, v246
	v_add_u32_e32 v254, 11, v247
	s_nop 0
	v_cndmask_b32_e32 v134, v192, v134, vcc
	v_cmp_le_i32_e32 vcc, v254, v246
	v_add_u32_e32 v249, 16, v247
	s_nop 0
	v_cndmask_b32_e32 v135, v192, v135, vcc
	v_cmp_le_i32_e32 vcc, v249, v246
	v_add_u32_e32 v254, 17, v247
	s_nop 0
	v_cndmask_b32_e32 v136, v192, v136, vcc
	v_cmp_le_i32_e32 vcc, v254, v246
	v_add_u32_e32 v249, 18, v247
	s_nop 0
	v_cndmask_b32_e32 v137, v192, v137, vcc
	v_cmp_le_i32_e32 vcc, v249, v246
	v_add_u32_e32 v254, 19, v247
	s_nop 0
	v_cndmask_b32_e32 v138, v192, v138, vcc
	v_cmp_le_i32_e32 vcc, v254, v246
	v_add_u32_e32 v249, 24, v247
	s_nop 0
	v_cndmask_b32_e32 v139, v192, v139, vcc
	v_cmp_le_i32_e32 vcc, v249, v246
	v_add_u32_e32 v254, 25, v247
	s_nop 0
	v_cndmask_b32_e32 v140, v192, v140, vcc
	v_cmp_le_i32_e32 vcc, v254, v246
	v_add_u32_e32 v249, 26, v247
	s_nop 0
	v_cndmask_b32_e32 v141, v192, v141, vcc
	v_cmp_le_i32_e32 vcc, v249, v246
	v_add_u32_e32 v254, 27, v247
	s_nop 0
	v_cndmask_b32_e32 v142, v192, v142, vcc
	v_cmp_le_i32_e32 vcc, v254, v246
	s_nop 1
	v_cndmask_b32_e32 v143, v192, v143, vcc
	v_max3_f32 v246, v128, v129, v130
	v_max3_f32 v247, v131, v132, v133
	v_max3_f32 v246, v246, v134, v135
	v_max3_f32 v247, v247, v136, v137
	v_max3_f32 v246, v246, v138, v139
	v_max3_f32 v247, v247, v140, v141
	v_max3_f32 v246, v246, v142, v143
	v_max_f32_e32 v246, v246, v247
	v_mov_b32_e32 v247, v246
	v_add_f32_e32 v249, 0x41000000, v190
	s_nop 1
	v_permlane32_swap_b32_e32 v246, v247
	v_max_f32_e32 v246, v246, v247
	v_cmp_gt_f32_e32 vcc, v246, v249
	s_cbranch_vccz .Latt_nr0_7B
	v_max_f32_e32 v246, v190, v246
	v_sub_f32_e32 v190, v190, v246
	v_exp_f32_e32 v190, v190
	s_nop 0
	v_pk_mul_f32 v[126:127], v[126:127], v[190:191] op_sel_hi:[1,0]
	v_pk_mul_f32 v[124:125], v[124:125], v[190:191] op_sel_hi:[1,0]
	v_pk_mul_f32 v[122:123], v[122:123], v[190:191] op_sel_hi:[1,0]
	v_pk_mul_f32 v[120:121], v[120:121], v[190:191] op_sel_hi:[1,0]
	v_pk_mul_f32 v[118:119], v[118:119], v[190:191] op_sel_hi:[1,0]
	v_pk_mul_f32 v[116:117], v[116:117], v[190:191] op_sel_hi:[1,0]
	v_pk_mul_f32 v[114:115], v[114:115], v[190:191] op_sel_hi:[1,0]
	v_pk_mul_f32 v[112:113], v[112:113], v[190:191] op_sel_hi:[1,0]
	v_pk_mul_f32 v[110:111], v[110:111], v[190:191] op_sel_hi:[1,0]
	v_pk_mul_f32 v[108:109], v[108:109], v[190:191] op_sel_hi:[1,0]
	v_pk_mul_f32 v[106:107], v[106:107], v[190:191] op_sel_hi:[1,0]
	v_pk_mul_f32 v[104:105], v[104:105], v[190:191] op_sel_hi:[1,0]
	v_pk_mul_f32 v[102:103], v[102:103], v[190:191] op_sel_hi:[1,0]
	v_pk_mul_f32 v[100:101], v[100:101], v[190:191] op_sel_hi:[1,0]
	v_pk_mul_f32 v[98:99], v[98:99], v[190:191] op_sel_hi:[1,0]
	v_pk_mul_f32 v[96:97], v[96:97], v[190:191] op_sel_hi:[1,0]
	v_pk_mul_f32 v[94:95], v[94:95], v[190:191] op_sel_hi:[1,0]
	v_pk_mul_f32 v[92:93], v[92:93], v[190:191] op_sel_hi:[1,0]
	v_pk_mul_f32 v[90:91], v[90:91], v[190:191] op_sel_hi:[1,0]
	v_pk_mul_f32 v[88:89], v[88:89], v[190:191] op_sel_hi:[1,0]
	v_pk_mul_f32 v[86:87], v[86:87], v[190:191] op_sel_hi:[1,0]
	v_pk_mul_f32 v[84:85], v[84:85], v[190:191] op_sel_hi:[1,0]
	v_pk_mul_f32 v[82:83], v[82:83], v[190:191] op_sel_hi:[1,0]
	v_pk_mul_f32 v[80:81], v[80:81], v[190:191] op_sel_hi:[1,0]
	v_pk_mul_f32 v[78:79], v[78:79], v[190:191] op_sel_hi:[1,0]
	v_pk_mul_f32 v[76:77], v[76:77], v[190:191] op_sel_hi:[1,0]
	v_pk_mul_f32 v[74:75], v[74:75], v[190:191] op_sel_hi:[1,0]
	v_pk_mul_f32 v[72:73], v[72:73], v[190:191] op_sel_hi:[1,0]
	v_pk_mul_f32 v[70:71], v[70:71], v[190:191] op_sel_hi:[1,0]
	v_pk_mul_f32 v[68:69], v[68:69], v[190:191] op_sel_hi:[1,0]
	v_pk_mul_f32 v[66:67], v[66:67], v[190:191] op_sel_hi:[1,0]
	v_pk_mul_f32 v[64:65], v[64:65], v[190:191] op_sel_hi:[1,0]
	v_pk_mul_f32 v[62:63], v[62:63], v[190:191] op_sel_hi:[1,0]
	v_pk_mul_f32 v[60:61], v[60:61], v[190:191] op_sel_hi:[1,0]
	v_pk_mul_f32 v[58:59], v[58:59], v[190:191] op_sel_hi:[1,0]
	v_pk_mul_f32 v[56:57], v[56:57], v[190:191] op_sel_hi:[1,0]
	v_pk_mul_f32 v[54:55], v[54:55], v[190:191] op_sel_hi:[1,0]
	v_pk_mul_f32 v[52:53], v[52:53], v[190:191] op_sel_hi:[1,0]
	v_pk_mul_f32 v[50:51], v[50:51], v[190:191] op_sel_hi:[1,0]
	v_pk_mul_f32 v[48:49], v[48:49], v[190:191] op_sel_hi:[1,0]
	v_pk_mul_f32 v[46:47], v[46:47], v[190:191] op_sel_hi:[1,0]
	v_pk_mul_f32 v[44:45], v[44:45], v[190:191] op_sel_hi:[1,0]
	v_pk_mul_f32 v[42:43], v[42:43], v[190:191] op_sel_hi:[1,0]
	v_pk_mul_f32 v[40:41], v[40:41], v[190:191] op_sel_hi:[1,0]
	v_pk_mul_f32 v[38:39], v[38:39], v[190:191] op_sel_hi:[1,0]
	v_pk_mul_f32 v[36:37], v[36:37], v[190:191] op_sel_hi:[1,0]
	v_pk_mul_f32 v[34:35], v[34:35], v[190:191] op_sel_hi:[1,0]
	v_pk_mul_f32 v[32:33], v[32:33], v[190:191] op_sel_hi:[1,0]
	v_pk_mul_f32 v[30:31], v[30:31], v[190:191] op_sel_hi:[1,0]
	v_pk_mul_f32 v[28:29], v[28:29], v[190:191] op_sel_hi:[1,0]
	v_pk_mul_f32 v[26:27], v[26:27], v[190:191] op_sel_hi:[1,0]
	v_pk_mul_f32 v[24:25], v[24:25], v[190:191] op_sel_hi:[1,0]
	v_pk_mul_f32 v[22:23], v[22:23], v[190:191] op_sel_hi:[1,0]
	v_pk_mul_f32 v[20:21], v[20:21], v[190:191] op_sel_hi:[1,0]
	v_pk_mul_f32 v[18:19], v[18:19], v[190:191] op_sel_hi:[1,0]
	v_pk_mul_f32 v[16:17], v[16:17], v[190:191] op_sel_hi:[1,0]
	v_pk_mul_f32 v[14:15], v[14:15], v[190:191] op_sel_hi:[1,0]
	v_pk_mul_f32 v[12:13], v[12:13], v[190:191] op_sel_hi:[1,0]
	v_pk_mul_f32 v[10:11], v[10:11], v[190:191] op_sel_hi:[1,0]
	v_pk_mul_f32 v[8:9], v[8:9], v[190:191] op_sel_hi:[1,0]
	v_pk_mul_f32 v[6:7], v[6:7], v[190:191] op_sel_hi:[1,0]
	v_pk_mul_f32 v[4:5], v[4:5], v[190:191] op_sel_hi:[1,0]
	v_pk_mul_f32 v[2:3], v[2:3], v[190:191] op_sel_hi:[1,0]
	v_pk_mul_f32 v[0:1], v[0:1], v[190:191] op_sel_hi:[1,0]
	v_mul_f32_e32 v195, v195, v190
	v_mov_b32_e32 v190, v246
.Latt_nr0_7B:
	v_sub_f32_e32 v128, v128, v190
	v_exp_f32_e32 v128, v128
	v_sub_f32_e32 v129, v129, v190
	v_exp_f32_e32 v129, v129
	v_sub_f32_e32 v130, v130, v190
	v_add_f32_e32 v254, 0, v128
	v_exp_f32_e32 v130, v130
	v_sub_f32_e32 v131, v131, v190
	v_add_f32_e32 v254, v129, v254
	v_exp_f32_e32 v131, v131
	v_sub_f32_e32 v132, v132, v190
	v_add_f32_e32 v254, v130, v254
	v_exp_f32_e32 v132, v132
	v_sub_f32_e32 v133, v133, v190
	v_add_f32_e32 v254, v131, v254
	v_exp_f32_e32 v133, v133
	v_sub_f32_e32 v134, v134, v190
	v_add_f32_e32 v254, v132, v254
	v_exp_f32_e32 v134, v134
	v_sub_f32_e32 v135, v135, v190
	v_add_f32_e32 v254, v133, v254
	v_exp_f32_e32 v135, v135
	v_sub_f32_e32 v136, v136, v190
	v_add_f32_e32 v254, v134, v254
	v_exp_f32_e32 v136, v136
	v_sub_f32_e32 v137, v137, v190
	v_add_f32_e32 v254, v135, v254
	v_exp_f32_e32 v137, v137
	v_sub_f32_e32 v138, v138, v190
	v_add_f32_e32 v254, v136, v254
	v_exp_f32_e32 v138, v138
	v_sub_f32_e32 v139, v139, v190
	v_add_f32_e32 v254, v137, v254
	v_exp_f32_e32 v139, v139
	v_sub_f32_e32 v140, v140, v190
	v_add_f32_e32 v254, v138, v254
	v_exp_f32_e32 v140, v140
	v_sub_f32_e32 v141, v141, v190
	v_add_f32_e32 v254, v139, v254
	v_exp_f32_e32 v141, v141
	v_sub_f32_e32 v142, v142, v190
	v_add_f32_e32 v254, v140, v254
	v_exp_f32_e32 v142, v142
	v_sub_f32_e32 v143, v143, v190
	v_add_f32_e32 v254, v141, v254
	v_exp_f32_e32 v143, v143
	v_add_f32_e32 v254, v142, v254
	v_add_f32_e32 v254, v143, v254
	v_cvt_pk_bf16_f32 v242, v128, v129
	v_cvt_pk_bf16_f32 v243, v130, v131
	v_cvt_pk_bf16_f32 v244, v132, v133
	v_cvt_pk_bf16_f32 v245, v134, v135
	v_cvt_pk_bf16_f32 v250, v136, v137
	v_cvt_pk_bf16_f32 v251, v138, v139
	v_cvt_pk_bf16_f32 v252, v140, v141
	v_cvt_pk_bf16_f32 v253, v142, v143
	v_add_f32_e32 v195, v195, v254
	s_nop 1
	ds_read_b64_tr_b16 v[128:129], v205 offset:256
	ds_read_b64_tr_b16 v[130:131], v205 offset:4352
	s_waitcnt lgkmcnt(8)
	v_mfma_f32_32x32x16_bf16 v[112:127], v[206:209], v[242:245], v[112:127]
	ds_read_b64_tr_b16 v[206:207], v218 offset:256
	ds_read_b64_tr_b16 v[208:209], v218 offset:4352
	s_waitcnt lgkmcnt(8)
	v_mfma_f32_32x32x16_bf16 v[96:111], v[210:213], v[242:245], v[96:111]
	ds_read_b64_tr_b16 v[210:211], v219 offset:256
	ds_read_b64_tr_b16 v[212:213], v219 offset:4352
	s_cmp_lg_u64 s[8:9], 0
	s_cbranch_scc1 .Latt_nd0_7B
	s_sub_i32 s100, s11, 1
	s_cmp_eq_u32 s11, 0
	s_cselect_b32 s100, 2, s100
	s_lshl_b32 s101, s100, 14
	s_add_i32 m0, s36, s101
	s_nop 0
	global_load_lds_dwordx4 v178, s[22:23]
.Latt_nd0_7B:
	s_waitcnt lgkmcnt(8)
	v_mfma_f32_32x32x16_bf16 v[80:95], v[214:217], v[242:245], v[80:95]
	ds_read_b64_tr_b16 v[214:215], v221 offset:256
	ds_read_b64_tr_b16 v[216:217], v221 offset:4352
	s_waitcnt lgkmcnt(8)
	v_mfma_f32_32x32x16_bf16 v[64:79], v[238:241], v[242:245], v[64:79]
	ds_read_b64_tr_b16 v[238:239], v205 offset:8192
	ds_read_b64_tr_b16 v[240:241], v205 offset:12288
	s_cmp_lg_u64 s[8:9], 0
	s_cbranch_scc1 .Latt_nd1_7B
	s_add_i32 m0, m0, 0x400
	s_nop 0
	global_load_lds_dwordx4 v180, s[22:23]
.Latt_nd1_7B:
	s_waitcnt lgkmcnt(8)
	v_mfma_f32_32x32x16_bf16 v[48:63], v[128:131], v[242:245], v[48:63]
	ds_read_b64_tr_b16 v[128:129], v218 offset:8192
	ds_read_b64_tr_b16 v[130:131], v218 offset:12288
	s_waitcnt lgkmcnt(8)
	v_mfma_f32_32x32x16_bf16 v[32:47], v[206:209], v[242:245], v[32:47]
	ds_read_b64_tr_b16 v[206:207], v219 offset:8192
	ds_read_b64_tr_b16 v[208:209], v219 offset:12288
	s_cmp_lg_u64 s[8:9], 0
	s_cbranch_scc1 .Latt_nd2_7B
	s_lshl_b32 s101, s100, 15
	s_add_i32 m0, s37, s101
	s_add_u32 s100, s22, 0xf00
	s_addc_u32 s101, s23, 0
	global_load_lds_dwordx4 v182, s[100:101]

.Latt_nr0_7A:
	s_waitcnt lgkmcnt(5)
	v_mfma_f32_32x32x16_bf16 v[222:237], v[214:217], v[152:155], v[222:237]
	ds_read_b64_tr_b16 v[214:215], v205
	ds_read_b64_tr_b16 v[216:217], v205 offset:4096
	v_sub_f32_e32 v128, v128, v190
	v_exp_f32_e32 v128, v128
	v_sub_f32_e32 v129, v129, v190
	v_exp_f32_e32 v129, v129
	v_sub_f32_e32 v130, v130, v190
	v_add_f32_e32 v254, 0, v128
	v_exp_f32_e32 v130, v130
	v_sub_f32_e32 v131, v131, v190
	s_waitcnt lgkmcnt(6)
	v_mfma_f32_32x32x16_bf16 v[222:237], v[238:241], v[156:159], v[222:237]
	ds_read_b64_tr_b16 v[238:239], v218
	ds_read_b64_tr_b16 v[240:241], v218 offset:4096
	v_add_f32_e32 v254, v129, v254
	v_exp_f32_e32 v131, v131
	v_sub_f32_e32 v132, v132, v190
	v_add_f32_e32 v254, v130, v254
	v_exp_f32_e32 v132, v132
	v_sub_f32_e32 v133, v133, v190
	v_add_f32_e32 v254, v131, v254
	v_exp_f32_e32 v133, v133
	s_waitcnt lgkmcnt(7)
	v_mfma_f32_32x32x16_bf16 v[222:237], v[242:245], v[160:163], v[222:237]
	v_sub_f32_e32 v134, v134, v190
	v_add_f32_e32 v254, v132, v254
	v_exp_f32_e32 v134, v134
	v_sub_f32_e32 v135, v135, v190
	v_add_f32_e32 v254, v133, v254
	v_exp_f32_e32 v135, v135
	v_sub_f32_e32 v136, v136, v190
	v_add_f32_e32 v254, v134, v254
	s_waitcnt lgkmcnt(6)
	v_mfma_f32_32x32x16_bf16 v[222:237], v[250:253], v[164:167], v[222:237]
	v_exp_f32_e32 v136, v136
	v_sub_f32_e32 v137, v137, v190
	v_add_f32_e32 v254, v135, v254
	v_exp_f32_e32 v137, v137
	v_sub_f32_e32 v138, v138, v190
	v_add_f32_e32 v254, v136, v254
	v_exp_f32_e32 v138, v138
	v_sub_f32_e32 v139, v139, v190
	s_waitcnt lgkmcnt(5)
	v_mfma_f32_32x32x16_bf16 v[222:237], v[206:209], v[168:171], v[222:237]
	ds_read_b64_tr_b16 v[206:207], v219
	ds_read_b64_tr_b16 v[208:209], v219 offset:4096
	v_add_f32_e32 v254, v137, v254
	v_exp_f32_e32 v139, v139
	v_sub_f32_e32 v140, v140, v190
	v_add_f32_e32 v254, v138, v254
	v_exp_f32_e32 v140, v140
	v_sub_f32_e32 v141, v141, v190
	v_add_f32_e32 v254, v139, v254
	v_exp_f32_e32 v141, v141
	s_waitcnt lgkmcnt(6)
	v_mfma_f32_32x32x16_bf16 v[222:237], v[210:213], v[172:175], v[222:237]
	ds_read_b64_tr_b16 v[210:211], v221
	ds_read_b64_tr_b16 v[212:213], v221 offset:4096
	v_sub_f32_e32 v142, v142, v190
	v_add_f32_e32 v254, v140, v254
	v_exp_f32_e32 v142, v142
	v_sub_f32_e32 v143, v143, v190
	v_add_f32_e32 v254, v141, v254
	v_exp_f32_e32 v143, v143
	v_add_f32_e32 v254, v142, v254
	v_add_f32_e32 v254, v143, v254
	v_cvt_pk_bf16_f32 v242, v128, v129
	v_cvt_pk_bf16_f32 v243, v130, v131
	v_cvt_pk_bf16_f32 v244, v132, v133
	v_cvt_pk_bf16_f32 v245, v134, v135
	v_cvt_pk_bf16_f32 v250, v136, v137
	v_cvt_pk_bf16_f32 v251, v138, v139
	v_cvt_pk_bf16_f32 v252, v140, v141
	v_cvt_pk_bf16_f32 v253, v142, v143
	v_add_f32_e32 v195, v195, v254
	s_nop 1
	ds_read_b64_tr_b16 v[128:129], v205 offset:256
	ds_read_b64_tr_b16 v[130:131], v205 offset:4352
	s_waitcnt lgkmcnt(8)
	v_mfma_f32_32x32x16_bf16 v[112:127], v[214:217], v[242:245], v[112:127]
	ds_read_b64_tr_b16 v[214:215], v218 offset:256
	ds_read_b64_tr_b16 v[216:217], v218 offset:4352
	v_and_or_b32 v246, v204, 31, s68
	v_bfe_u32 v247, v204, 5, 1
	s_add_i32 s100, s14, 32
	v_lshl_add_u32 v247, v247, 2, s100
	v_add_u32_e32 v249, 0, v247
	v_cmp_le_i32_e32 vcc, v249, v246
	v_add_u32_e32 v254, 1, v247
	s_nop 0
	v_cndmask_b32_e32 v222, v192, v222, vcc
	v_cmp_le_i32_e32 vcc, v254, v246
	v_add_u32_e32 v249, 2, v247
	s_nop 0
	v_cndmask_b32_e32 v223, v192, v223, vcc
	v_cmp_le_i32_e32 vcc, v249, v246
	v_add_u32_e32 v254, 3, v247
	s_nop 0
	v_cndmask_b32_e32 v224, v192, v224, vcc
	v_cmp_le_i32_e32 vcc, v254, v246
	v_add_u32_e32 v249, 8, v247
	s_nop 0
	v_cndmask_b32_e32 v225, v192, v225, vcc
	v_cmp_le_i32_e32 vcc, v249, v246
	v_add_u32_e32 v254, 9, v247
	s_nop 0
	v_cndmask_b32_e32 v226, v192, v226, vcc
	v_cmp_le_i32_e32 vcc, v254, v246
	v_add_u32_e32 v249, 10, v247
	s_nop 0
	v_cndmask_b32_e32 v227, v192, v227, vcc
	v_cmp_le_i32_e32 vcc, v249, v246
	v_add_u32_e32 v254, 11, v247
	s_nop 0
	v_cndmask_b32_e32 v228, v192, v228, vcc
	v_cmp_le_i32_e32 vcc, v254, v246
	s_waitcnt lgkmcnt(8)
	v_mfma_f32_32x32x16_bf16 v[96:111], v[238:241], v[242:245], v[96:111]
	ds_read_b64_tr_b16 v[238:239], v219 offset:256
	ds_read_b64_tr_b16 v[240:241], v219 offset:4352
	v_add_u32_e32 v249, 16, v247
	s_nop 0
	v_cndmask_b32_e32 v229, v192, v229, vcc
	v_cmp_le_i32_e32 vcc, v249, v246
	v_add_u32_e32 v254, 17, v247
	s_nop 0
	v_cndmask_b32_e32 v230, v192, v230, vcc
	v_cmp_le_i32_e32 vcc, v254, v246
	v_add_u32_e32 v249, 18, v247
	s_nop 0
	v_cndmask_b32_e32 v231, v192, v231, vcc
	v_cmp_le_i32_e32 vcc, v249, v246
	v_add_u32_e32 v254, 19, v247
	s_nop 0
	v_cndmask_b32_e32 v232, v192, v232, vcc
	v_cmp_le_i32_e32 vcc, v254, v246
	v_add_u32_e32 v249, 24, v247
	s_nop 0
	v_cndmask_b32_e32 v233, v192, v233, vcc
	v_cmp_le_i32_e32 vcc, v249, v246
	v_add_u32_e32 v254, 25, v247
	s_nop 0
	v_cndmask_b32_e32 v234, v192, v234, vcc
	v_cmp_le_i32_e32 vcc, v254, v246
	v_add_u32_e32 v249, 26, v247
	s_nop 0
	v_cndmask_b32_e32 v235, v192, v235, vcc
	v_cmp_le_i32_e32 vcc, v249, v246
	v_add_u32_e32 v254, 27, v247
	s_nop 0
	v_cndmask_b32_e32 v236, v192, v236, vcc
	v_cmp_le_i32_e32 vcc, v254, v246
	s_nop 1
	v_cndmask_b32_e32 v237, v192, v237, vcc
	s_waitcnt lgkmcnt(8)
	v_mfma_f32_32x32x16_bf16 v[80:95], v[206:209], v[242:245], v[80:95]
	ds_read_b64_tr_b16 v[206:207], v221 offset:256
	ds_read_b64_tr_b16 v[208:209], v221 offset:4352
	v_max3_f32 v246, v222, v223, v224
	v_max3_f32 v247, v225, v226, v227
	v_max3_f32 v246, v246, v228, v229
	v_max3_f32 v247, v247, v230, v231
	v_max3_f32 v246, v246, v232, v233
	v_max3_f32 v247, v247, v234, v235
	s_waitcnt lgkmcnt(8)
	v_mfma_f32_32x32x16_bf16 v[64:79], v[210:213], v[242:245], v[64:79]
	ds_read_b64_tr_b16 v[210:211], v205 offset:8192
	ds_read_b64_tr_b16 v[212:213], v205 offset:12288
	v_max3_f32 v246, v246, v236, v237
	v_max_f32_e32 v246, v246, v247
	v_mov_b32_e32 v247, v246
	v_add_f32_e32 v249, 0x41000000, v190
	s_nop 1
	s_waitcnt lgkmcnt(8)
	v_mfma_f32_32x32x16_bf16 v[48:63], v[128:131], v[242:245], v[48:63]
	ds_read_b64_tr_b16 v[128:129], v218 offset:8192
	ds_read_b64_tr_b16 v[130:131], v218 offset:12288
	v_permlane32_swap_b32_e32 v246, v247
	v_max_f32_e32 v246, v246, v247
	v_cmp_gt_f32_e32 vcc, v246, v249
	s_cbranch_vccnz .Latt_rs1_7A
	s_waitcnt lgkmcnt(8)
	v_mfma_f32_32x32x16_bf16 v[32:47], v[214:217], v[242:245], v[32:47]
	ds_read_b64_tr_b16 v[214:215], v219 offset:8192
	ds_read_b64_tr_b16 v[216:217], v219 offset:12288
	v_sub_f32_e32 v222, v222, v190
	v_exp_f32_e32 v222, v222
	v_sub_f32_e32 v223, v223, v190
	v_exp_f32_e32 v223, v223
	v_sub_f32_e32 v224, v224, v190
	s_waitcnt lgkmcnt(8)
	v_mfma_f32_32x32x16_bf16 v[16:31], v[238:241], v[242:245], v[16:31]
	ds_read_b64_tr_b16 v[238:239], v221 offset:8192
	ds_read_b64_tr_b16 v[240:241], v221 offset:12288
	v_add_f32_e32 v254, 0, v222
	v_exp_f32_e32 v224, v224
	v_sub_f32_e32 v225, v225, v190
	v_add_f32_e32 v254, v223, v254
	v_exp_f32_e32 v225, v225
	s_waitcnt lgkmcnt(8)
	v_mfma_f32_32x32x16_bf16 v[0:15], v[206:209], v[242:245], v[0:15]
	ds_read_b64_tr_b16 v[206:207], v205 offset:8448
	ds_read_b64_tr_b16 v[208:209], v205 offset:12544
	v_sub_f32_e32 v226, v226, v190
	v_add_f32_e32 v254, v224, v254
	v_exp_f32_e32 v226, v226
	v_sub_f32_e32 v227, v227, v190
	v_add_f32_e32 v254, v225, v254
	s_waitcnt lgkmcnt(8)
	v_mfma_f32_32x32x16_bf16 v[112:127], v[210:213], v[250:253], v[112:127]
	ds_read_b64_tr_b16 v[210:211], v218 offset:8448
	ds_read_b64_tr_b16 v[212:213], v218 offset:12544
	v_exp_f32_e32 v227, v227
	v_sub_f32_e32 v228, v228, v190
	v_add_f32_e32 v254, v226, v254
	v_exp_f32_e32 v228, v228
	v_sub_f32_e32 v229, v229, v190
	s_waitcnt lgkmcnt(8)
	v_mfma_f32_32x32x16_bf16 v[96:111], v[128:131], v[250:253], v[96:111]
	ds_read_b64_tr_b16 v[128:129], v219 offset:8448
	ds_read_b64_tr_b16 v[130:131], v219 offset:12544
	v_add_f32_e32 v254, v227, v254
	v_exp_f32_e32 v229, v229
	v_sub_f32_e32 v230, v230, v190
	v_add_f32_e32 v254, v228, v254
	s_waitcnt lgkmcnt(8)
	v_mfma_f32_32x32x16_bf16 v[80:95], v[214:217], v[250:253], v[80:95]
	ds_read_b64_tr_b16 v[214:215], v221 offset:8448
	ds_read_b64_tr_b16 v[216:217], v221 offset:12544
	v_exp_f32_e32 v230, v230
	v_sub_f32_e32 v231, v231, v190
	v_add_f32_e32 v254, v229, v254
	v_exp_f32_e32 v231, v231
	s_waitcnt lgkmcnt(8)
	v_mfma_f32_32x32x16_bf16 v[64:79], v[238:241], v[250:253], v[64:79]
	ds_read_b64_tr_b16 v[238:239], v205 offset:16384
	ds_read_b64_tr_b16 v[240:241], v205 offset:20480
	v_sub_f32_e32 v232, v232, v190
	v_add_f32_e32 v254, v230, v254
	v_exp_f32_e32 v232, v232
	v_sub_f32_e32 v233, v233, v190
	s_waitcnt lgkmcnt(8)
	v_mfma_f32_32x32x16_bf16 v[48:63], v[206:209], v[250:253], v[48:63]
	ds_read_b64_tr_b16 v[206:207], v218 offset:16384
	ds_read_b64_tr_b16 v[208:209], v218 offset:20480
	v_add_f32_e32 v254, v231, v254
	v_exp_f32_e32 v233, v233
	v_sub_f32_e32 v234, v234, v190
	v_add_f32_e32 v254, v232, v254
	s_waitcnt lgkmcnt(8)
	v_mfma_f32_32x32x16_bf16 v[32:47], v[210:213], v[250:253], v[32:47]
	ds_read_b64_tr_b16 v[210:211], v219 offset:16384
	ds_read_b64_tr_b16 v[212:213], v219 offset:20480
	v_exp_f32_e32 v234, v234
	v_sub_f32_e32 v235, v235, v190
	v_add_f32_e32 v254, v233, v254
	v_exp_f32_e32 v235, v235
	s_waitcnt lgkmcnt(8)
	v_mfma_f32_32x32x16_bf16 v[16:31], v[128:131], v[250:253], v[16:31]
	ds_read_b64_tr_b16 v[128:129], v221 offset:16384
	ds_read_b64_tr_b16 v[130:131], v221 offset:20480
	v_sub_f32_e32 v236, v236, v190
	v_add_f32_e32 v254, v234, v254
	v_exp_f32_e32 v236, v236
	v_sub_f32_e32 v237, v237, v190
	s_waitcnt lgkmcnt(8)
	v_mfma_f32_32x32x16_bf16 v[0:15], v[214:217], v[250:253], v[0:15]
	ds_read_b64_tr_b16 v[214:215], v205 offset:16640
	ds_read_b64_tr_b16 v[216:217], v205 offset:20736
	v_add_f32_e32 v254, v235, v254
	v_exp_f32_e32 v237, v237
	v_add_f32_e32 v254, v236, v254
	v_add_f32_e32 v254, v237, v254
	v_cvt_pk_bf16_f32 v242, v222, v223
	v_cvt_pk_bf16_f32 v243, v224, v225
	v_cvt_pk_bf16_f32 v244, v226, v227
	v_cvt_pk_bf16_f32 v245, v228, v229
	v_cvt_pk_bf16_f32 v250, v230, v231
	v_cvt_pk_bf16_f32 v251, v232, v233
	v_cvt_pk_bf16_f32 v252, v234, v235
	v_cvt_pk_bf16_f32 v253, v236, v237
	v_add_f32_e32 v195, v195, v254
	s_nop 1

.Latt_rs1_7F:
	s_waitcnt lgkmcnt(8)
	v_mfma_f32_32x32x16_bf16 v[32:47], v[214:217], v[242:245], v[32:47]
	ds_read_b64_tr_b16 v[214:215], v219 offset:8192
	ds_read_b64_tr_b16 v[216:217], v219 offset:12288
	s_waitcnt lgkmcnt(8)
	v_mfma_f32_32x32x16_bf16 v[16:31], v[238:241], v[242:245], v[16:31]
	ds_read_b64_tr_b16 v[238:239], v221 offset:8192
	ds_read_b64_tr_b16 v[240:241], v221 offset:12288
	s_waitcnt lgkmcnt(8)
	v_mfma_f32_32x32x16_bf16 v[0:15], v[206:209], v[242:245], v[0:15]
	ds_read_b64_tr_b16 v[206:207], v205 offset:8448
	ds_read_b64_tr_b16 v[208:209], v205 offset:12544
	s_waitcnt lgkmcnt(8)
	v_mfma_f32_32x32x16_bf16 v[112:127], v[210:213], v[250:253], v[112:127]
	ds_read_b64_tr_b16 v[210:211], v218 offset:8448
	ds_read_b64_tr_b16 v[212:213], v218 offset:12544
	s_waitcnt lgkmcnt(8)
	v_mfma_f32_32x32x16_bf16 v[96:111], v[128:131], v[250:253], v[96:111]
	ds_read_b64_tr_b16 v[128:129], v219 offset:8448
	ds_read_b64_tr_b16 v[130:131], v219 offset:12544
	s_waitcnt lgkmcnt(8)
	v_mfma_f32_32x32x16_bf16 v[80:95], v[214:217], v[250:253], v[80:95]
	ds_read_b64_tr_b16 v[214:215], v221 offset:8448
	ds_read_b64_tr_b16 v[216:217], v221 offset:12544
	s_waitcnt lgkmcnt(8)
	v_mfma_f32_32x32x16_bf16 v[64:79], v[238:241], v[250:253], v[64:79]
	ds_read_b64_tr_b16 v[238:239], v205 offset:16384
	ds_read_b64_tr_b16 v[240:241], v205 offset:20480
	s_waitcnt lgkmcnt(8)
	v_mfma_f32_32x32x16_bf16 v[48:63], v[206:209], v[250:253], v[48:63]
	ds_read_b64_tr_b16 v[206:207], v218 offset:16384
	ds_read_b64_tr_b16 v[208:209], v218 offset:20480
	s_waitcnt lgkmcnt(8)
	v_mfma_f32_32x32x16_bf16 v[32:47], v[210:213], v[250:253], v[32:47]
	ds_read_b64_tr_b16 v[210:211], v219 offset:16384
	ds_read_b64_tr_b16 v[212:213], v219 offset:20480
	s_waitcnt lgkmcnt(8)
	v_mfma_f32_32x32x16_bf16 v[16:31], v[128:131], v[250:253], v[16:31]
	ds_read_b64_tr_b16 v[128:129], v221 offset:16384
	ds_read_b64_tr_b16 v[130:131], v221 offset:20480
	s_waitcnt lgkmcnt(8)
	v_mfma_f32_32x32x16_bf16 v[0:15], v[214:217], v[250:253], v[0:15]
	ds_read_b64_tr_b16 v[214:215], v205 offset:16640
	ds_read_b64_tr_b16 v[216:217], v205 offset:20736
	s_nop 11
	v_max_f32_e32 v246, v190, v246
	v_sub_f32_e32 v190, v190, v246
	v_exp_f32_e32 v190, v190
	s_nop 0
	v_pk_mul_f32 v[126:127], v[126:127], v[190:191] op_sel_hi:[1,0]
	v_pk_mul_f32 v[124:125], v[124:125], v[190:191] op_sel_hi:[1,0]
	v_pk_mul_f32 v[122:123], v[122:123], v[190:191] op_sel_hi:[1,0]
	v_pk_mul_f32 v[120:121], v[120:121], v[190:191] op_sel_hi:[1,0]
	v_pk_mul_f32 v[118:119], v[118:119], v[190:191] op_sel_hi:[1,0]
	v_pk_mul_f32 v[116:117], v[116:117], v[190:191] op_sel_hi:[1,0]
	v_pk_mul_f32 v[114:115], v[114:115], v[190:191] op_sel_hi:[1,0]
	v_pk_mul_f32 v[112:113], v[112:113], v[190:191] op_sel_hi:[1,0]
	v_pk_mul_f32 v[110:111], v[110:111], v[190:191] op_sel_hi:[1,0]
	v_pk_mul_f32 v[108:109], v[108:109], v[190:191] op_sel_hi:[1,0]
	v_pk_mul_f32 v[106:107], v[106:107], v[190:191] op_sel_hi:[1,0]
	v_pk_mul_f32 v[104:105], v[104:105], v[190:191] op_sel_hi:[1,0]
	v_pk_mul_f32 v[102:103], v[102:103], v[190:191] op_sel_hi:[1,0]
	v_pk_mul_f32 v[100:101], v[100:101], v[190:191] op_sel_hi:[1,0]
	v_pk_mul_f32 v[98:99], v[98:99], v[190:191] op_sel_hi:[1,0]
	v_pk_mul_f32 v[96:97], v[96:97], v[190:191] op_sel_hi:[1,0]
	v_pk_mul_f32 v[94:95], v[94:95], v[190:191] op_sel_hi:[1,0]
	v_pk_mul_f32 v[92:93], v[92:93], v[190:191] op_sel_hi:[1,0]
	v_pk_mul_f32 v[90:91], v[90:91], v[190:191] op_sel_hi:[1,0]
	v_pk_mul_f32 v[88:89], v[88:89], v[190:191] op_sel_hi:[1,0]
	v_pk_mul_f32 v[86:87], v[86:87], v[190:191] op_sel_hi:[1,0]
	v_pk_mul_f32 v[84:85], v[84:85], v[190:191] op_sel_hi:[1,0]
	v_pk_mul_f32 v[82:83], v[82:83], v[190:191] op_sel_hi:[1,0]
	v_pk_mul_f32 v[80:81], v[80:81], v[190:191] op_sel_hi:[1,0]
	v_pk_mul_f32 v[78:79], v[78:79], v[190:191] op_sel_hi:[1,0]
	v_pk_mul_f32 v[76:77], v[76:77], v[190:191] op_sel_hi:[1,0]
	v_pk_mul_f32 v[74:75], v[74:75], v[190:191] op_sel_hi:[1,0]
	v_pk_mul_f32 v[72:73], v[72:73], v[190:191] op_sel_hi:[1,0]
	v_pk_mul_f32 v[70:71], v[70:71], v[190:191] op_sel_hi:[1,0]
	v_pk_mul_f32 v[68:69], v[68:69], v[190:191] op_sel_hi:[1,0]
	v_pk_mul_f32 v[66:67], v[66:67], v[190:191] op_sel_hi:[1,0]
	v_pk_mul_f32 v[64:65], v[64:65], v[190:191] op_sel_hi:[1,0]
	v_pk_mul_f32 v[62:63], v[62:63], v[190:191] op_sel_hi:[1,0]
	v_pk_mul_f32 v[60:61], v[60:61], v[190:191] op_sel_hi:[1,0]
	v_pk_mul_f32 v[58:59], v[58:59], v[190:191] op_sel_hi:[1,0]
	v_pk_mul_f32 v[56:57], v[56:57], v[190:191] op_sel_hi:[1,0]
	v_pk_mul_f32 v[54:55], v[54:55], v[190:191] op_sel_hi:[1,0]
	v_pk_mul_f32 v[52:53], v[52:53], v[190:191] op_sel_hi:[1,0]
	v_pk_mul_f32 v[50:51], v[50:51], v[190:191] op_sel_hi:[1,0]
	v_pk_mul_f32 v[48:49], v[48:49], v[190:191] op_sel_hi:[1,0]
	v_pk_mul_f32 v[46:47], v[46:47], v[190:191] op_sel_hi:[1,0]
	v_pk_mul_f32 v[44:45], v[44:45], v[190:191] op_sel_hi:[1,0]
	v_pk_mul_f32 v[42:43], v[42:43], v[190:191] op_sel_hi:[1,0]
	v_pk_mul_f32 v[40:41], v[40:41], v[190:191] op_sel_hi:[1,0]
	v_pk_mul_f32 v[38:39], v[38:39], v[190:191] op_sel_hi:[1,0]
	v_pk_mul_f32 v[36:37], v[36:37], v[190:191] op_sel_hi:[1,0]
	v_pk_mul_f32 v[34:35], v[34:35], v[190:191] op_sel_hi:[1,0]
	v_pk_mul_f32 v[32:33], v[32:33], v[190:191] op_sel_hi:[1,0]
	v_pk_mul_f32 v[30:31], v[30:31], v[190:191] op_sel_hi:[1,0]
	v_pk_mul_f32 v[28:29], v[28:29], v[190:191] op_sel_hi:[1,0]
	v_pk_mul_f32 v[26:27], v[26:27], v[190:191] op_sel_hi:[1,0]
	v_pk_mul_f32 v[24:25], v[24:25], v[190:191] op_sel_hi:[1,0]
	v_pk_mul_f32 v[22:23], v[22:23], v[190:191] op_sel_hi:[1,0]
	v_pk_mul_f32 v[20:21], v[20:21], v[190:191] op_sel_hi:[1,0]
	v_pk_mul_f32 v[18:19], v[18:19], v[190:191] op_sel_hi:[1,0]
	v_pk_mul_f32 v[16:17], v[16:17], v[190:191] op_sel_hi:[1,0]
	v_pk_mul_f32 v[14:15], v[14:15], v[190:191] op_sel_hi:[1,0]
	v_pk_mul_f32 v[12:13], v[12:13], v[190:191] op_sel_hi:[1,0]
	v_pk_mul_f32 v[10:11], v[10:11], v[190:191] op_sel_hi:[1,0]
	v_pk_mul_f32 v[8:9], v[8:9], v[190:191] op_sel_hi:[1,0]
	v_pk_mul_f32 v[6:7], v[6:7], v[190:191] op_sel_hi:[1,0]
	v_pk_mul_f32 v[4:5], v[4:5], v[190:191] op_sel_hi:[1,0]
	v_pk_mul_f32 v[2:3], v[2:3], v[190:191] op_sel_hi:[1,0]
	v_pk_mul_f32 v[0:1], v[0:1], v[190:191] op_sel_hi:[1,0]
	v_mul_f32_e32 v195, v195, v190
	v_mov_b32_e32 v190, v246
	v_sub_f32_e32 v222, v222, v190
	v_exp_f32_e32 v222, v222
	v_sub_f32_e32 v223, v223, v190
	v_exp_f32_e32 v223, v223
	v_sub_f32_e32 v224, v224, v190
	v_add_f32_e32 v254, 0, v222
	v_exp_f32_e32 v224, v224
	v_sub_f32_e32 v225, v225, v190
	v_add_f32_e32 v254, v223, v254
	v_exp_f32_e32 v225, v225
	v_sub_f32_e32 v226, v226, v190
	v_add_f32_e32 v254, v224, v254
	v_exp_f32_e32 v226, v226
	v_sub_f32_e32 v227, v227, v190
	v_add_f32_e32 v254, v225, v254
	v_exp_f32_e32 v227, v227
	v_sub_f32_e32 v228, v228, v190
	v_add_f32_e32 v254, v226, v254
	v_exp_f32_e32 v228, v228
	v_sub_f32_e32 v229, v229, v190
	v_add_f32_e32 v254, v227, v254
	v_exp_f32_e32 v229, v229
	v_sub_f32_e32 v230, v230, v190
	v_add_f32_e32 v254, v228, v254
	v_exp_f32_e32 v230, v230
	v_sub_f32_e32 v231, v231, v190
	v_add_f32_e32 v254, v229, v254
	v_exp_f32_e32 v231, v231
	v_sub_f32_e32 v232, v232, v190
	v_add_f32_e32 v254, v230, v254
	v_exp_f32_e32 v232, v232
	v_sub_f32_e32 v233, v233, v190
	v_add_f32_e32 v254, v231, v254
	v_exp_f32_e32 v233, v233
	v_sub_f32_e32 v234, v234, v190
	v_add_f32_e32 v254, v232, v254
	v_exp_f32_e32 v234, v234
	v_sub_f32_e32 v235, v235, v190
	v_add_f32_e32 v254, v233, v254
	v_exp_f32_e32 v235, v235
	v_sub_f32_e32 v236, v236, v190
	v_add_f32_e32 v254, v234, v254
	v_exp_f32_e32 v236, v236
	v_sub_f32_e32 v237, v237, v190
	v_add_f32_e32 v254, v235, v254
	v_exp_f32_e32 v237, v237
	v_add_f32_e32 v254, v236, v254
	v_add_f32_e32 v254, v237, v254
	v_cvt_pk_bf16_f32 v242, v222, v223
	v_cvt_pk_bf16_f32 v243, v224, v225
	v_cvt_pk_bf16_f32 v244, v226, v227
	v_cvt_pk_bf16_f32 v245, v228, v229
	v_cvt_pk_bf16_f32 v250, v230, v231
	v_cvt_pk_bf16_f32 v251, v232, v233
	v_cvt_pk_bf16_f32 v252, v234, v235
	v_cvt_pk_bf16_f32 v253, v236, v237
	v_add_f32_e32 v195, v195, v254
	s_nop 1
	s_branch .Latt_pv1_7F
	s_lshl_b32 s15, s11, 14
	s_add_i32 s16, s15, 0
	v_add_u32_e32 v207, s16, v196
	ds_read_b128 v[128:131], v207
	v_add_u32_e32 v208, s16, v197
	ds_read_b128 v[210:213], v208
	v_add_u32_e32 v209, s16, v198
	v_lshrrev_b32_e32 v205, 3, v204
	s_add_i32 s17, s14, 31
	v_and_or_b32 v206, v204, 31, s68
	s_cmp_le_i32 s17, s68
	s_waitcnt lgkmcnt(1)
	v_mfma_f32_32x32x16_bf16 v[128:143], v[128:131], v[144:147], 0
	s_waitcnt lgkmcnt(0)
	v_mfma_f32_32x32x16_bf16 v[128:143], v[210:213], v[148:151], v[128:143]
	ds_read_b128 v[212:215], v209
	v_add_u32_e32 v210, s16, v199
	ds_read_b128 v[216:219], v210
	v_add_u32_e32 v211, s16, v200
	s_waitcnt lgkmcnt(1)
	v_mfma_f32_32x32x16_bf16 v[128:143], v[212:215], v[152:155], v[128:143]
	v_add_u32_e32 v213, s16, v201
	v_and_b32_e32 v212, 4, v205
	ds_read_b128 v[222:225], v213
	s_waitcnt lgkmcnt(1)
	v_mfma_f32_32x32x16_bf16 v[128:143], v[216:219], v[156:159], v[128:143]
	ds_read_b128 v[214:217], v211
	s_waitcnt lgkmcnt(0)
	v_mfma_f32_32x32x16_bf16 v[128:143], v[214:217], v[160:163], v[128:143]
	v_add_u32_e32 v214, s16, v202
	ds_read_b128 v[216:219], v214
	v_add_u32_e32 v215, s16, v203
	v_mfma_f32_32x32x16_bf16 v[128:143], v[222:225], v[164:167], v[128:143]
	ds_read_b128 v[222:225], v215
	s_waitcnt lgkmcnt(1)
	v_mfma_f32_32x32x16_bf16 v[128:143], v[216:219], v[168:171], v[128:143]
	s_waitcnt lgkmcnt(0)
	v_mfma_f32_32x32x16_bf16 v[128:143], v[222:225], v[172:175], v[128:143]
	s_cbranch_scc1 .LBB0_1861
	v_add_u32_e32 v205, s14, v212
	v_cmp_lt_i32_e32 vcc, v205, v206
	v_add_u32_e32 v216, 2, v205
	s_nop 7
	v_cndmask_b32_e32 v129, v192, v129, vcc
	v_cmp_le_i32_e32 vcc, v205, v206
	s_nop 1
	v_cndmask_b32_e32 v128, v192, v128, vcc
	v_cmp_le_i32_e32 vcc, v216, v206
	v_add_u32_e32 v216, 3, v205
	s_nop 0
	v_cndmask_b32_e32 v130, v192, v130, vcc
	v_cmp_le_i32_e32 vcc, v216, v206
	v_add_u32_e32 v216, 8, v205
	s_nop 0
	v_cndmask_b32_e32 v131, v192, v131, vcc
	v_cmp_le_i32_e32 vcc, v216, v206
	v_add_u32_e32 v216, 9, v205
	s_nop 0
	v_cndmask_b32_e32 v132, v192, v132, vcc
	v_cmp_le_i32_e32 vcc, v216, v206
	v_add_u32_e32 v216, 10, v205
	s_nop 0
	v_cndmask_b32_e32 v133, v192, v133, vcc
	v_cmp_le_i32_e32 vcc, v216, v206
	v_add_u32_e32 v216, 11, v205
	s_nop 0
	v_cndmask_b32_e32 v134, v192, v134, vcc
	v_cmp_le_i32_e32 vcc, v216, v206
	v_add_u32_e32 v216, 16, v205
	s_nop 0
	v_cndmask_b32_e32 v135, v192, v135, vcc
	v_cmp_le_i32_e32 vcc, v216, v206
	v_add_u32_e32 v216, 17, v205
	s_nop 0
	v_cndmask_b32_e32 v136, v192, v136, vcc
	v_cmp_le_i32_e32 vcc, v216, v206
	v_add_u32_e32 v216, 18, v205
	s_nop 0
	v_cndmask_b32_e32 v137, v192, v137, vcc
	v_cmp_le_i32_e32 vcc, v216, v206
	v_add_u32_e32 v216, 19, v205
	s_nop 0
	v_cndmask_b32_e32 v138, v192, v138, vcc
	v_cmp_le_i32_e32 vcc, v216, v206
	v_add_u32_e32 v216, 24, v205
	s_nop 0
	v_cndmask_b32_e32 v139, v192, v139, vcc
	v_cmp_le_i32_e32 vcc, v216, v206
	v_add_u32_e32 v216, 25, v205
	s_nop 0
	v_cndmask_b32_e32 v140, v192, v140, vcc
	v_cmp_le_i32_e32 vcc, v216, v206
	v_add_u32_e32 v216, 26, v205
	v_add_u32_e32 v205, 27, v205
	v_cndmask_b32_e32 v141, v192, v141, vcc
	v_cmp_le_i32_e32 vcc, v216, v206
	s_nop 1
	v_cndmask_b32_e32 v142, v192, v142, vcc
	v_cmp_le_i32_e32 vcc, v205, v206
	s_nop 1
	v_cndmask_b32_e32 v143, v192, v143, vcc
